# P6b: scan_combine and sample-attention QK moved to f32 MFMA (v_mfma_f32_16x16x4_f32)
# speedup vs baseline: 1.0425x; 1.0112x over previous
; #define LAS __attribute__((address_space(3)))
; __device__ __forceinline__ void scan_combine(LAS unsigned char* lds, CArgsP a) {
;     if (blockIdx.x >= 64) return;
;     const int tid = threadIdx.x, h = blockIdx.x >> 3, rw = tid >> 6, v = (blockIdx.x & 7) * 8 + rw, kq = tid & 63;
;     const float* PM = (const float*)(a->ws + WS_PM); const float* UM = (const float*)(a->ws + WS_UM); float* SS = (float*)(a->ws + WS_SS);
;     LAS float* Sl = (LAS float*)lds;
;     LAS float* Pl = (LAS float*)(lds + 4096);
;     constexpr int GL = NSEG - 2;
;     float cur = SS[((size_t)(1 * 8 + h) * 64 + v) * 64 + kq];
;     f32x4 pa, pb;
;     float u1, u2;
;     {
;         const f32x4* P1 = (const f32x4*)(PM + (size_t)(1 * 8 + h) * 4096);
;         *(LAS f32x4*)(Pl + 1 * 4096 + 4 * tid) = P1[tid]; *(LAS f32x4*)(Pl + 1 * 4096 + 2048 + 4 * tid) = P1[512 + tid];
;         if (GL >= 2) { const f32x4* P2 = (const f32x4*)(PM + (size_t)(2 * 8 + h) * 4096);
;             *(LAS f32x4*)(Pl + 2 * 4096 + 4 * tid) = P2[tid]; *(LAS f32x4*)(Pl + 2 * 4096 + 2048 + 4 * tid) = P2[512 + tid]; }
;         u1 = UM[((size_t)(1 * 8 + h) * 64 + v) * 64 + kq];
;         u2 = GL >= 2 ? UM[((size_t)(2 * 8 + h) * 64 + v) * 64 + kq] : 0.f;
;     }
;     for (int g = 1; g <= GL; ++g) {
;         const bool pf = (g + 2 <= GL);
;         float u3 = 0.f;
;         if (pf) { const f32x4* Pn = (const f32x4*)(PM + (size_t)((g + 2) * 8 + h) * 4096); pa = Pn[tid]; pb = Pn[512 + tid]; u3 = UM[((size_t)((g + 2) * 8 + h) * 64 + v) * 64 + kq]; }
;         asm volatile("s_waitcnt lgkmcnt(0)\n\ts_barrier" ::: "memory");
.LBB0_1217:
	s_or_b64 exec, exec, s[8:9]
	s_mov_b64 s[20:21], s[92:93]
	s_cmp_gt_u32 s2, 63
	v_lshrrev_b32_e32 v50, 6, v164
	s_waitcnt lgkmcnt(0)
	s_barrier
	s_cbranch_scc1 .LBB0_1224
	s_load_dwordx2 s[4:5], s[20:21], 0xf8
	v_readfirstlane_b32 s3, v50
	s_lshr_b32 s12, s2, 3
	s_and_b32 s13, s2, 7
	s_lshl_b32 s12, s12, 14
	s_lshl_b32 s13, s13, 11
	s_add_u32 s13, s13, s12
	v_lshlrev_b32_e32 v0, 4, v164
	v_add_u32_e32 v1, 0x2000, v0
	v_lshrrev_b32_e32 v3, 4, v164
	v_and_b32_e32 v4, 15, v164
	v_mul_u32_u24_e32 v3, 0x140, v3
	v_lshl_add_u32 v3, v4, 4, v3
	v_add_u32_e32 v2, 4352, v3
	v_lshlrev_b32_e32 v3, 8, v50
	v_lshl_add_u32 v3, v148, 2, v3
	v_mul_u32_u24_e32 v5, 0x110, v50
	v_lshl_add_u32 v5, v148, 2, v5
	s_waitcnt lgkmcnt(0)
	s_add_u32 s0, s4, 0xf600000
	s_addc_u32 s1, s5, 0
	s_add_u32 s0, s0, s12
	s_addc_u32 s1, s1, 0
	s_add_u32 s6, s4, 0x300000
	s_addc_u32 s7, s5, 0
	s_add_u32 s6, s6, s13
	s_addc_u32 s7, s7, 0
	s_add_u32 s8, s4, 0xbc00000
	s_addc_u32 s9, s5, 0
	s_add_u32 s8, s8, s13
	s_addc_u32 s9, s9, 0
	s_add_u32 s16, s8, 0x20000
	s_addc_u32 s17, s9, 0
	global_load_dword v4, v3, s[16:17]
	s_add_u32 s10, s0, 0x20000
	s_addc_u32 s11, s1, 0
	global_load_dwordx4 v[60:63], v0, s[10:11]
	global_load_dwordx4 v[64:67], v1, s[10:11]
	s_add_u32 s10, s0, 0x40000
	s_addc_u32 s11, s1, 0
	global_load_dwordx4 v[68:71], v0, s[10:11]
	global_load_dwordx4 v[72:75], v1, s[10:11]
	s_add_u32 s10, s0, 0x60000
	s_addc_u32 s11, s1, 0
	global_load_dwordx4 v[76:79], v0, s[10:11]
	global_load_dwordx4 v[80:83], v1, s[10:11]
	s_add_u32 s10, s0, 0x80000
	s_addc_u32 s11, s1, 0
	global_load_dwordx4 v[84:87], v0, s[10:11]
	global_load_dwordx4 v[88:91], v1, s[10:11]
	s_add_u32 s10, s0, 0xa0000
	s_addc_u32 s11, s1, 0
	global_load_dwordx4 v[92:95], v0, s[10:11]
	global_load_dwordx4 v[96:99], v1, s[10:11]
	s_add_u32 s10, s0, 0xc0000
	s_addc_u32 s11, s1, 0
	global_load_dwordx4 v[52:55], v0, s[10:11]
	global_load_dwordx4 v[56:59], v1, s[10:11]
	v_lshrrev_b32_e32 v6, 4, v148
	v_and_b32_e32 v7, 15, v148
	v_and_b32_e32 v14, 7, v148
	v_mul_u32_u24_e32 v14, 0x110, v14
	v_lshl_add_u32 v8, v6, 2, v14
	v_add_u32_e32 v9, 2176, v8
	s_lshl_b32 s12, s3, 6
	v_lshl_add_u32 v15, v7, 2, s12
	v_mul_u32_u24_e32 v14, 0x140, v6
	v_add_u32_e32 v14, v14, v15
	v_add_u32_e32 v10, 0x1100, v14
	v_add_u32_e32 v11, 0x5000, v10
	v_and_b32_e32 v14, 1, v6
	v_lshl_add_u32 v12, v14, 10, v15
	v_mul_u32_u24_e32 v14, 0x440, v14
	v_add_u32_e32 v13, v14, v15
	s_waitcnt vmcnt(12)
	ds_write_b32 v5, v4 offset:2176
	s_waitcnt vmcnt(10)
	ds_write_b128 v2, v[60:63] offset:20480
	ds_write_b128 v2, v[64:67] offset:30720
	s_add_u32 s10, s0, 0xe0000
	s_addc_u32 s11, s1, 0
	global_load_dwordx4 v[60:63], v0, s[10:11]
	global_load_dwordx4 v[64:67], v1, s[10:11]
	s_cmp_gt_u32 s3, 3
	s_cbranch_scc1 .Lcmb_loader
	s_add_u32 s14, s6, 0x20000
	s_addc_u32 s15, s7, 0
	global_load_dword v208, v12, s[14:15] offset:0
	global_load_dword v209, v12, s[14:15] offset:256
	global_load_dword v210, v12, s[14:15] offset:512
	global_load_dword v211, v12, s[14:15] offset:768
	s_add_u32 s14, s6, 0x40000
	s_addc_u32 s15, s7, 0
	global_load_dword v212, v12, s[14:15] offset:0
	global_load_dword v213, v12, s[14:15] offset:256
	global_load_dword v214, v12, s[14:15] offset:512
	global_load_dword v215, v12, s[14:15] offset:768
	s_add_u32 s14, s6, 0x60000
	s_addc_u32 s15, s7, 0
	global_load_dword v216, v12, s[14:15] offset:0
	global_load_dword v217, v12, s[14:15] offset:256
	global_load_dword v218, v12, s[14:15] offset:512
	global_load_dword v219, v12, s[14:15] offset:768
	s_add_u32 s14, s6, 0x80000
	s_addc_u32 s15, s7, 0
	global_load_dword v220, v12, s[14:15] offset:0
	global_load_dword v221, v12, s[14:15] offset:256
	global_load_dword v222, v12, s[14:15] offset:512
	global_load_dword v223, v12, s[14:15] offset:768
	s_add_u32 s14, s6, 0xa0000
	s_addc_u32 s15, s7, 0
	global_load_dword v224, v12, s[14:15] offset:0
	global_load_dword v225, v12, s[14:15] offset:256
	global_load_dword v226, v12, s[14:15] offset:512
	global_load_dword v227, v12, s[14:15] offset:768
	s_add_u32 s14, s6, 0xc0000
	s_addc_u32 s15, s7, 0
	global_load_dword v204, v12, s[14:15] offset:0
	global_load_dword v205, v12, s[14:15] offset:256
	global_load_dword v206, v12, s[14:15] offset:512
	global_load_dword v207, v12, s[14:15] offset:768
	s_waitcnt lgkmcnt(0)
	s_barrier
; #define LAS __attribute__((address_space(3)))
; __device__ __forceinline__ void scan_combine(LAS unsigned char* lds, CArgsP a) {
;     ...
;     for (int g = 1; g <= GL; ++g) {
;         const bool pf = (g + 2 <= GL);
;         float u3 = 0.f;
;         if (pf) { const f32x4* Pn = (const f32x4*)(PM + (size_t)((g + 2) * 8 + h) * 4096); pa = Pn[tid]; pb = Pn[512 + tid]; u3 = UM[((size_t)((g + 2) * 8 + h) * 64 + v) * 64 + kq]; }
;         asm volatile("s_waitcnt lgkmcnt(0)\n\ts_barrier" ::: "memory");
;         const LAS float* Pg = Pl + (g % 3) * 4096 + kq;
;         float acc0 = u1, acc1 = 0.f, acc2 = 0.f, acc3 = 0.f;
;         const int curi = __builtin_bit_cast(int, cur);
; #pragma unroll
;         for (int k = 0; k < 64; k += 4) {
;             const float s0 = __builtin_bit_cast(float, __builtin_amdgcn_readlane(curi, k)), s1 = __builtin_bit_cast(float, __builtin_amdgcn_readlane(curi, k + 1));
;             const float s2 = __builtin_bit_cast(float, __builtin_amdgcn_readlane(curi, k + 2)), s3 = __builtin_bit_cast(float, __builtin_amdgcn_readlane(curi, k + 3));
;             acc0 += s0 * Pg[(k + 0) * 64]; acc1 += s1 * Pg[(k + 1) * 64]; acc2 += s2 * Pg[(k + 2) * 64]; acc3 += s3 * Pg[(k + 3) * 64];
;         }
;         cur = (acc0 + acc1) + (acc2 + acc3);
;         SS[((size_t)((g + 1) * 8 + h) * 64 + v) * 64 + kq] = cur;
;         if (pf) { LAS float* dst = Pl + ((g + 2) % 3) * 4096; *(LAS f32x4*)(dst + 4 * tid) = pa; *(LAS f32x4*)(dst + 2048 + 4 * tid) = pb; }
;         u1 = u2; u2 = u3;
	ds_read2_b32 v[104:105], v9 offset0:0 offset1:4
	ds_read2st64_b32 v[120:121], v11 offset0:0 offset1:5
	ds_read2_b32 v[106:107], v9 offset0:8 offset1:12
	ds_read2st64_b32 v[122:123], v11 offset0:10 offset1:15
	ds_read2_b32 v[108:109], v9 offset0:16 offset1:20
	ds_read2st64_b32 v[124:125], v11 offset0:20 offset1:25
	ds_read2_b32 v[110:111], v9 offset0:24 offset1:28
	ds_read2st64_b32 v[126:127], v11 offset0:30 offset1:35
	ds_read2_b32 v[112:113], v9 offset0:32 offset1:36
	ds_read2st64_b32 v[128:129], v11 offset0:40 offset1:45
	ds_read2_b32 v[114:115], v9 offset0:40 offset1:44
	ds_read2st64_b32 v[130:131], v11 offset0:50 offset1:55
	ds_read2_b32 v[116:117], v9 offset0:48 offset1:52
	ds_read2st64_b32 v[132:133], v11 offset0:60 offset1:65
	s_waitcnt vmcnt(20)
	s_waitcnt lgkmcnt(12)
	v_mfma_f32_16x16x4_f32 v[136:139], v104, v120, v[208:211]
	v_mfma_f32_16x16x4_f32 v[136:139], v105, v121, v[136:139]
	ds_read2_b32 v[118:119], v9 offset0:56 offset1:60
	ds_read2st64_b32 v[134:135], v11 offset0:70 offset1:75
	s_waitcnt lgkmcnt(12)
	v_mfma_f32_16x16x4_f32 v[136:139], v106, v122, v[136:139]
	v_mfma_f32_16x16x4_f32 v[136:139], v107, v123, v[136:139]
	s_waitcnt lgkmcnt(10)
	v_mfma_f32_16x16x4_f32 v[136:139], v108, v124, v[136:139]
	v_mfma_f32_16x16x4_f32 v[136:139], v109, v125, v[136:139]
	s_add_u32 s14, s6, 0xe0000
	s_addc_u32 s15, s7, 0
	global_load_dword v208, v12, s[14:15] offset:0
	global_load_dword v209, v12, s[14:15] offset:256
	global_load_dword v210, v12, s[14:15] offset:512
	global_load_dword v211, v12, s[14:15] offset:768
	s_waitcnt lgkmcnt(8)
	v_mfma_f32_16x16x4_f32 v[136:139], v110, v126, v[136:139]
	v_mfma_f32_16x16x4_f32 v[136:139], v111, v127, v[136:139]
	s_waitcnt lgkmcnt(6)
	v_mfma_f32_16x16x4_f32 v[136:139], v112, v128, v[136:139]
	v_mfma_f32_16x16x4_f32 v[136:139], v113, v129, v[136:139]
	ds_write_b128 v2, v[68:71] offset:0
	ds_write_b128 v2, v[72:75] offset:10240
	s_add_u32 s10, s0, 0x100000
	s_addc_u32 s11, s1, 0
	global_load_dwordx4 v[68:71], v0, s[10:11]
	global_load_dwordx4 v[72:75], v1, s[10:11]
	s_waitcnt lgkmcnt(6)
	v_mfma_f32_16x16x4_f32 v[136:139], v114, v130, v[136:139]
	v_mfma_f32_16x16x4_f32 v[136:139], v115, v131, v[136:139]
	s_waitcnt lgkmcnt(4)
	v_mfma_f32_16x16x4_f32 v[136:139], v116, v132, v[136:139]
	v_mfma_f32_16x16x4_f32 v[136:139], v117, v133, v[136:139]
	s_waitcnt lgkmcnt(2)
	v_mfma_f32_16x16x4_f32 v[136:139], v118, v134, v[136:139]
	v_mfma_f32_16x16x4_f32 v[136:139], v119, v135, v[136:139]
	s_add_u32 s16, s8, 0x40000
	s_addc_u32 s17, s9, 0
	s_nop 9
	ds_write_b32 v13, v136 offset:0
	ds_write_b32 v13, v137 offset:272
	ds_write_b32 v13, v138 offset:544
	ds_write_b32 v13, v139 offset:816
	global_store_dword v12, v136, s[16:17] offset:0
	global_store_dword v12, v137, s[16:17] offset:256
	global_store_dword v12, v138, s[16:17] offset:512
	global_store_dword v12, v139, s[16:17] offset:768
	s_waitcnt lgkmcnt(0)
	s_barrier
	ds_read2_b32 v[104:105], v8 offset0:0 offset1:4
	ds_read2st64_b32 v[120:121], v10 offset0:0 offset1:5
	ds_read2_b32 v[106:107], v8 offset0:8 offset1:12
	ds_read2st64_b32 v[122:123], v10 offset0:10 offset1:15
	ds_read2_b32 v[108:109], v8 offset0:16 offset1:20
	ds_read2st64_b32 v[124:125], v10 offset0:20 offset1:25
	ds_read2_b32 v[110:111], v8 offset0:24 offset1:28
	ds_read2st64_b32 v[126:127], v10 offset0:30 offset1:35
	ds_read2_b32 v[112:113], v8 offset0:32 offset1:36
	ds_read2st64_b32 v[128:129], v10 offset0:40 offset1:45
	ds_read2_b32 v[114:115], v8 offset0:40 offset1:44
	ds_read2st64_b32 v[130:131], v10 offset0:50 offset1:55
	ds_read2_b32 v[116:117], v8 offset0:48 offset1:52
	ds_read2st64_b32 v[132:133], v10 offset0:60 offset1:65
	s_waitcnt vmcnt(26)
	s_waitcnt lgkmcnt(12)
	v_mfma_f32_16x16x4_f32 v[136:139], v104, v120, v[212:215]
	v_mfma_f32_16x16x4_f32 v[136:139], v105, v121, v[136:139]
	ds_read2_b32 v[118:119], v8 offset0:56 offset1:60
	ds_read2st64_b32 v[134:135], v10 offset0:70 offset1:75
	s_waitcnt lgkmcnt(12)
	v_mfma_f32_16x16x4_f32 v[136:139], v106, v122, v[136:139]
	v_mfma_f32_16x16x4_f32 v[136:139], v107, v123, v[136:139]
	s_waitcnt lgkmcnt(10)
	v_mfma_f32_16x16x4_f32 v[136:139], v108, v124, v[136:139]
	v_mfma_f32_16x16x4_f32 v[136:139], v109, v125, v[136:139]
	s_add_u32 s14, s6, 0x100000
	s_addc_u32 s15, s7, 0
	global_load_dword v212, v12, s[14:15] offset:0
	global_load_dword v213, v12, s[14:15] offset:256
	global_load_dword v214, v12, s[14:15] offset:512
	global_load_dword v215, v12, s[14:15] offset:768
	s_waitcnt lgkmcnt(8)
	v_mfma_f32_16x16x4_f32 v[136:139], v110, v126, v[136:139]
	v_mfma_f32_16x16x4_f32 v[136:139], v111, v127, v[136:139]
	s_waitcnt lgkmcnt(6)
	v_mfma_f32_16x16x4_f32 v[136:139], v112, v128, v[136:139]
	v_mfma_f32_16x16x4_f32 v[136:139], v113, v129, v[136:139]
	ds_write_b128 v2, v[76:79] offset:20480
	ds_write_b128 v2, v[80:83] offset:30720
	s_add_u32 s10, s0, 0x120000
	s_addc_u32 s11, s1, 0
	global_load_dwordx4 v[76:79], v0, s[10:11]
	global_load_dwordx4 v[80:83], v1, s[10:11]
	s_waitcnt lgkmcnt(6)
	v_mfma_f32_16x16x4_f32 v[136:139], v114, v130, v[136:139]
	v_mfma_f32_16x16x4_f32 v[136:139], v115, v131, v[136:139]
	s_waitcnt lgkmcnt(4)
	v_mfma_f32_16x16x4_f32 v[136:139], v116, v132, v[136:139]
	v_mfma_f32_16x16x4_f32 v[136:139], v117, v133, v[136:139]
	s_waitcnt lgkmcnt(2)
	v_mfma_f32_16x16x4_f32 v[136:139], v118, v134, v[136:139]
	v_mfma_f32_16x16x4_f32 v[136:139], v119, v135, v[136:139]
	s_add_u32 s16, s8, 0x60000
	s_addc_u32 s17, s9, 0
	s_nop 9
	ds_write_b32 v13, v136 offset:2176
	ds_write_b32 v13, v137 offset:2448
	ds_write_b32 v13, v138 offset:2720
	ds_write_b32 v13, v139 offset:2992
	global_store_dword v12, v136, s[16:17] offset:0
	global_store_dword v12, v137, s[16:17] offset:256
	global_store_dword v12, v138, s[16:17] offset:512
	global_store_dword v12, v139, s[16:17] offset:768
	s_waitcnt lgkmcnt(0)
	s_barrier
; #define LAS __attribute__((address_space(3)))
; __device__ __forceinline__ void scan_combine(LAS unsigned char* lds, CArgsP a) {
;     ...
;     for (int g = 1; g <= GL; ++g) {
;         const bool pf = (g + 2 <= GL);
;         float u3 = 0.f;
;         if (pf) { const f32x4* Pn = (const f32x4*)(PM + (size_t)((g + 2) * 8 + h) * 4096); pa = Pn[tid]; pb = Pn[512 + tid]; u3 = UM[((size_t)((g + 2) * 8 + h) * 64 + v) * 64 + kq]; }
;         asm volatile("s_waitcnt lgkmcnt(0)\n\ts_barrier" ::: "memory");
;         const LAS float* Pg = Pl + (g % 3) * 4096 + kq;
;         float acc0 = u1, acc1 = 0.f, acc2 = 0.f, acc3 = 0.f;
;         const int curi = __builtin_bit_cast(int, cur);
; #pragma unroll
;         for (int k = 0; k < 64; k += 4) {
;             const float s0 = __builtin_bit_cast(float, __builtin_amdgcn_readlane(curi, k)), s1 = __builtin_bit_cast(float, __builtin_amdgcn_readlane(curi, k + 1));
;             const float s2 = __builtin_bit_cast(float, __builtin_amdgcn_readlane(curi, k + 2)), s3 = __builtin_bit_cast(float, __builtin_amdgcn_readlane(curi, k + 3));
;             acc0 += s0 * Pg[(k + 0) * 64]; acc1 += s1 * Pg[(k + 1) * 64]; acc2 += s2 * Pg[(k + 2) * 64]; acc3 += s3 * Pg[(k + 3) * 64];
;         }
;         cur = (acc0 + acc1) + (acc2 + acc3);
;         SS[((size_t)((g + 1) * 8 + h) * 64 + v) * 64 + kq] = cur;
;         if (pf) { LAS float* dst = Pl + ((g + 2) % 3) * 4096; *(LAS f32x4*)(dst + 4 * tid) = pa; *(LAS f32x4*)(dst + 2048 + 4 * tid) = pb; }
;         u1 = u2; u2 = u3;
	ds_read2_b32 v[104:105], v9 offset0:0 offset1:4
	ds_read2st64_b32 v[120:121], v11 offset0:0 offset1:5
	ds_read2_b32 v[106:107], v9 offset0:8 offset1:12
	ds_read2st64_b32 v[122:123], v11 offset0:10 offset1:15
	ds_read2_b32 v[108:109], v9 offset0:16 offset1:20
	ds_read2st64_b32 v[124:125], v11 offset0:20 offset1:25
	ds_read2_b32 v[110:111], v9 offset0:24 offset1:28
	ds_read2st64_b32 v[126:127], v11 offset0:30 offset1:35
	ds_read2_b32 v[112:113], v9 offset0:32 offset1:36
	ds_read2st64_b32 v[128:129], v11 offset0:40 offset1:45
	ds_read2_b32 v[114:115], v9 offset0:40 offset1:44
	ds_read2st64_b32 v[130:131], v11 offset0:50 offset1:55
	ds_read2_b32 v[116:117], v9 offset0:48 offset1:52
	ds_read2st64_b32 v[132:133], v11 offset0:60 offset1:65
	s_waitcnt vmcnt(32)
	s_waitcnt lgkmcnt(12)
	v_mfma_f32_16x16x4_f32 v[136:139], v104, v120, v[216:219]
	v_mfma_f32_16x16x4_f32 v[136:139], v105, v121, v[136:139]
	ds_read2_b32 v[118:119], v9 offset0:56 offset1:60
	ds_read2st64_b32 v[134:135], v11 offset0:70 offset1:75
	s_waitcnt lgkmcnt(12)
	v_mfma_f32_16x16x4_f32 v[136:139], v106, v122, v[136:139]
	v_mfma_f32_16x16x4_f32 v[136:139], v107, v123, v[136:139]
	s_waitcnt lgkmcnt(10)
	v_mfma_f32_16x16x4_f32 v[136:139], v108, v124, v[136:139]
	v_mfma_f32_16x16x4_f32 v[136:139], v109, v125, v[136:139]
	s_add_u32 s14, s6, 0x120000
	s_addc_u32 s15, s7, 0
	global_load_dword v216, v12, s[14:15] offset:0
	global_load_dword v217, v12, s[14:15] offset:256
	global_load_dword v218, v12, s[14:15] offset:512
	global_load_dword v219, v12, s[14:15] offset:768
	s_waitcnt lgkmcnt(8)
	v_mfma_f32_16x16x4_f32 v[136:139], v110, v126, v[136:139]
	v_mfma_f32_16x16x4_f32 v[136:139], v111, v127, v[136:139]
	s_waitcnt lgkmcnt(6)
	v_mfma_f32_16x16x4_f32 v[136:139], v112, v128, v[136:139]
	v_mfma_f32_16x16x4_f32 v[136:139], v113, v129, v[136:139]
	ds_write_b128 v2, v[84:87] offset:0
	ds_write_b128 v2, v[88:91] offset:10240
	s_add_u32 s10, s0, 0x140000
	s_addc_u32 s11, s1, 0
	global_load_dwordx4 v[84:87], v0, s[10:11]
	global_load_dwordx4 v[88:91], v1, s[10:11]
	s_waitcnt lgkmcnt(6)
	v_mfma_f32_16x16x4_f32 v[136:139], v114, v130, v[136:139]
	v_mfma_f32_16x16x4_f32 v[136:139], v115, v131, v[136:139]
	s_waitcnt lgkmcnt(4)
	v_mfma_f32_16x16x4_f32 v[136:139], v116, v132, v[136:139]
	v_mfma_f32_16x16x4_f32 v[136:139], v117, v133, v[136:139]
	s_waitcnt lgkmcnt(2)
	v_mfma_f32_16x16x4_f32 v[136:139], v118, v134, v[136:139]
	v_mfma_f32_16x16x4_f32 v[136:139], v119, v135, v[136:139]
	s_add_u32 s16, s8, 0x80000
	s_addc_u32 s17, s9, 0
	s_nop 9
	ds_write_b32 v13, v136 offset:0
	ds_write_b32 v13, v137 offset:272
	ds_write_b32 v13, v138 offset:544
	ds_write_b32 v13, v139 offset:816
	global_store_dword v12, v136, s[16:17] offset:0
	global_store_dword v12, v137, s[16:17] offset:256
	global_store_dword v12, v138, s[16:17] offset:512
	global_store_dword v12, v139, s[16:17] offset:768
	s_waitcnt lgkmcnt(0)
	s_barrier
	ds_read2_b32 v[104:105], v8 offset0:0 offset1:4
	ds_read2st64_b32 v[120:121], v10 offset0:0 offset1:5
	ds_read2_b32 v[106:107], v8 offset0:8 offset1:12
	ds_read2st64_b32 v[122:123], v10 offset0:10 offset1:15
	ds_read2_b32 v[108:109], v8 offset0:16 offset1:20
	ds_read2st64_b32 v[124:125], v10 offset0:20 offset1:25
	ds_read2_b32 v[110:111], v8 offset0:24 offset1:28
	ds_read2st64_b32 v[126:127], v10 offset0:30 offset1:35
	ds_read2_b32 v[112:113], v8 offset0:32 offset1:36
	ds_read2st64_b32 v[128:129], v10 offset0:40 offset1:45
	ds_read2_b32 v[114:115], v8 offset0:40 offset1:44
	ds_read2st64_b32 v[130:131], v10 offset0:50 offset1:55
	ds_read2_b32 v[116:117], v8 offset0:48 offset1:52
	ds_read2st64_b32 v[132:133], v10 offset0:60 offset1:65
	s_waitcnt vmcnt(38)
	s_waitcnt lgkmcnt(12)
	v_mfma_f32_16x16x4_f32 v[136:139], v104, v120, v[220:223]
	v_mfma_f32_16x16x4_f32 v[136:139], v105, v121, v[136:139]
	ds_read2_b32 v[118:119], v8 offset0:56 offset1:60
	ds_read2st64_b32 v[134:135], v10 offset0:70 offset1:75
	s_waitcnt lgkmcnt(12)
	v_mfma_f32_16x16x4_f32 v[136:139], v106, v122, v[136:139]
	v_mfma_f32_16x16x4_f32 v[136:139], v107, v123, v[136:139]
	s_waitcnt lgkmcnt(10)
	v_mfma_f32_16x16x4_f32 v[136:139], v108, v124, v[136:139]
	v_mfma_f32_16x16x4_f32 v[136:139], v109, v125, v[136:139]
	s_add_u32 s14, s6, 0x140000
	s_addc_u32 s15, s7, 0
	global_load_dword v220, v12, s[14:15] offset:0
	global_load_dword v221, v12, s[14:15] offset:256
	global_load_dword v222, v12, s[14:15] offset:512
	global_load_dword v223, v12, s[14:15] offset:768
	s_waitcnt lgkmcnt(8)
	v_mfma_f32_16x16x4_f32 v[136:139], v110, v126, v[136:139]
	v_mfma_f32_16x16x4_f32 v[136:139], v111, v127, v[136:139]
	s_waitcnt lgkmcnt(6)
	v_mfma_f32_16x16x4_f32 v[136:139], v112, v128, v[136:139]
	v_mfma_f32_16x16x4_f32 v[136:139], v113, v129, v[136:139]
	ds_write_b128 v2, v[92:95] offset:20480
	ds_write_b128 v2, v[96:99] offset:30720
	s_add_u32 s10, s0, 0x160000
	s_addc_u32 s11, s1, 0
	global_load_dwordx4 v[92:95], v0, s[10:11]
	global_load_dwordx4 v[96:99], v1, s[10:11]
	s_waitcnt lgkmcnt(6)
	v_mfma_f32_16x16x4_f32 v[136:139], v114, v130, v[136:139]
	v_mfma_f32_16x16x4_f32 v[136:139], v115, v131, v[136:139]
	s_waitcnt lgkmcnt(4)
	v_mfma_f32_16x16x4_f32 v[136:139], v116, v132, v[136:139]
	v_mfma_f32_16x16x4_f32 v[136:139], v117, v133, v[136:139]
	s_waitcnt lgkmcnt(2)
	v_mfma_f32_16x16x4_f32 v[136:139], v118, v134, v[136:139]
	v_mfma_f32_16x16x4_f32 v[136:139], v119, v135, v[136:139]
	s_add_u32 s16, s8, 0xa0000
	s_addc_u32 s17, s9, 0
	s_nop 9
	ds_write_b32 v13, v136 offset:2176
	ds_write_b32 v13, v137 offset:2448
	ds_write_b32 v13, v138 offset:2720
	ds_write_b32 v13, v139 offset:2992
	global_store_dword v12, v136, s[16:17] offset:0
	global_store_dword v12, v137, s[16:17] offset:256
	global_store_dword v12, v138, s[16:17] offset:512
	global_store_dword v12, v139, s[16:17] offset:768
	s_waitcnt lgkmcnt(0)
	s_barrier
; #define LAS __attribute__((address_space(3)))
; __device__ __forceinline__ void scan_combine(LAS unsigned char* lds, CArgsP a) {
;     ...
;     for (int g = 1; g <= GL; ++g) {
;         const bool pf = (g + 2 <= GL);
;         float u3 = 0.f;
;         if (pf) { const f32x4* Pn = (const f32x4*)(PM + (size_t)((g + 2) * 8 + h) * 4096); pa = Pn[tid]; pb = Pn[512 + tid]; u3 = UM[((size_t)((g + 2) * 8 + h) * 64 + v) * 64 + kq]; }
;         asm volatile("s_waitcnt lgkmcnt(0)\n\ts_barrier" ::: "memory");
;         const LAS float* Pg = Pl + (g % 3) * 4096 + kq;
;         float acc0 = u1, acc1 = 0.f, acc2 = 0.f, acc3 = 0.f;
;         const int curi = __builtin_bit_cast(int, cur);
; #pragma unroll
;         for (int k = 0; k < 64; k += 4) {
;             const float s0 = __builtin_bit_cast(float, __builtin_amdgcn_readlane(curi, k)), s1 = __builtin_bit_cast(float, __builtin_amdgcn_readlane(curi, k + 1));
;             const float s2 = __builtin_bit_cast(float, __builtin_amdgcn_readlane(curi, k + 2)), s3 = __builtin_bit_cast(float, __builtin_amdgcn_readlane(curi, k + 3));
;             acc0 += s0 * Pg[(k + 0) * 64]; acc1 += s1 * Pg[(k + 1) * 64]; acc2 += s2 * Pg[(k + 2) * 64]; acc3 += s3 * Pg[(k + 3) * 64];
;         }
;         cur = (acc0 + acc1) + (acc2 + acc3);
;         SS[((size_t)((g + 1) * 8 + h) * 64 + v) * 64 + kq] = cur;
;         if (pf) { LAS float* dst = Pl + ((g + 2) % 3) * 4096; *(LAS f32x4*)(dst + 4 * tid) = pa; *(LAS f32x4*)(dst + 2048 + 4 * tid) = pb; }
;         u1 = u2; u2 = u3;
	ds_read2_b32 v[104:105], v9 offset0:0 offset1:4
	ds_read2st64_b32 v[120:121], v11 offset0:0 offset1:5
	ds_read2_b32 v[106:107], v9 offset0:8 offset1:12
	ds_read2st64_b32 v[122:123], v11 offset0:10 offset1:15
	ds_read2_b32 v[108:109], v9 offset0:16 offset1:20
	ds_read2st64_b32 v[124:125], v11 offset0:20 offset1:25
	ds_read2_b32 v[110:111], v9 offset0:24 offset1:28
	ds_read2st64_b32 v[126:127], v11 offset0:30 offset1:35
	ds_read2_b32 v[112:113], v9 offset0:32 offset1:36
	ds_read2st64_b32 v[128:129], v11 offset0:40 offset1:45
	ds_read2_b32 v[114:115], v9 offset0:40 offset1:44
	ds_read2st64_b32 v[130:131], v11 offset0:50 offset1:55
	ds_read2_b32 v[116:117], v9 offset0:48 offset1:52
	ds_read2st64_b32 v[132:133], v11 offset0:60 offset1:65
	s_waitcnt vmcnt(44)
	s_waitcnt lgkmcnt(12)
	v_mfma_f32_16x16x4_f32 v[136:139], v104, v120, v[224:227]
	v_mfma_f32_16x16x4_f32 v[136:139], v105, v121, v[136:139]
	ds_read2_b32 v[118:119], v9 offset0:56 offset1:60
	ds_read2st64_b32 v[134:135], v11 offset0:70 offset1:75
	s_waitcnt lgkmcnt(12)
	v_mfma_f32_16x16x4_f32 v[136:139], v106, v122, v[136:139]
	v_mfma_f32_16x16x4_f32 v[136:139], v107, v123, v[136:139]
	s_waitcnt lgkmcnt(10)
	v_mfma_f32_16x16x4_f32 v[136:139], v108, v124, v[136:139]
	v_mfma_f32_16x16x4_f32 v[136:139], v109, v125, v[136:139]
	s_add_u32 s14, s6, 0x160000
	s_addc_u32 s15, s7, 0
	global_load_dword v224, v12, s[14:15] offset:0
	global_load_dword v225, v12, s[14:15] offset:256
	global_load_dword v226, v12, s[14:15] offset:512
	global_load_dword v227, v12, s[14:15] offset:768
	s_waitcnt lgkmcnt(8)
	v_mfma_f32_16x16x4_f32 v[136:139], v110, v126, v[136:139]
	v_mfma_f32_16x16x4_f32 v[136:139], v111, v127, v[136:139]
	s_waitcnt lgkmcnt(6)
	v_mfma_f32_16x16x4_f32 v[136:139], v112, v128, v[136:139]
	v_mfma_f32_16x16x4_f32 v[136:139], v113, v129, v[136:139]
	ds_write_b128 v2, v[52:55] offset:0
	ds_write_b128 v2, v[56:59] offset:10240
	s_add_u32 s10, s0, 0x180000
	s_addc_u32 s11, s1, 0
	global_load_dwordx4 v[52:55], v0, s[10:11]
	global_load_dwordx4 v[56:59], v1, s[10:11]
	s_waitcnt lgkmcnt(6)
	v_mfma_f32_16x16x4_f32 v[136:139], v114, v130, v[136:139]
	v_mfma_f32_16x16x4_f32 v[136:139], v115, v131, v[136:139]
	s_waitcnt lgkmcnt(4)
	v_mfma_f32_16x16x4_f32 v[136:139], v116, v132, v[136:139]
	v_mfma_f32_16x16x4_f32 v[136:139], v117, v133, v[136:139]
	s_waitcnt lgkmcnt(2)
	v_mfma_f32_16x16x4_f32 v[136:139], v118, v134, v[136:139]
	v_mfma_f32_16x16x4_f32 v[136:139], v119, v135, v[136:139]
	s_add_u32 s16, s8, 0xc0000
	s_addc_u32 s17, s9, 0
	s_nop 9
	ds_write_b32 v13, v136 offset:0
	ds_write_b32 v13, v137 offset:272
	ds_write_b32 v13, v138 offset:544
	ds_write_b32 v13, v139 offset:816
	global_store_dword v12, v136, s[16:17] offset:0
	global_store_dword v12, v137, s[16:17] offset:256
	global_store_dword v12, v138, s[16:17] offset:512
	global_store_dword v12, v139, s[16:17] offset:768
	s_waitcnt lgkmcnt(0)
	s_barrier
	ds_read2_b32 v[104:105], v8 offset0:0 offset1:4
	ds_read2st64_b32 v[120:121], v10 offset0:0 offset1:5
	ds_read2_b32 v[106:107], v8 offset0:8 offset1:12
	ds_read2st64_b32 v[122:123], v10 offset0:10 offset1:15
	ds_read2_b32 v[108:109], v8 offset0:16 offset1:20
	ds_read2st64_b32 v[124:125], v10 offset0:20 offset1:25
	ds_read2_b32 v[110:111], v8 offset0:24 offset1:28
	ds_read2st64_b32 v[126:127], v10 offset0:30 offset1:35
	ds_read2_b32 v[112:113], v8 offset0:32 offset1:36
	ds_read2st64_b32 v[128:129], v10 offset0:40 offset1:45
	ds_read2_b32 v[114:115], v8 offset0:40 offset1:44
	ds_read2st64_b32 v[130:131], v10 offset0:50 offset1:55
	ds_read2_b32 v[116:117], v8 offset0:48 offset1:52
	ds_read2st64_b32 v[132:133], v10 offset0:60 offset1:65
	s_waitcnt vmcnt(50)
	s_waitcnt lgkmcnt(12)
	v_mfma_f32_16x16x4_f32 v[136:139], v104, v120, v[204:207]
	v_mfma_f32_16x16x4_f32 v[136:139], v105, v121, v[136:139]
	ds_read2_b32 v[118:119], v8 offset0:56 offset1:60
	ds_read2st64_b32 v[134:135], v10 offset0:70 offset1:75
	s_waitcnt lgkmcnt(12)
	v_mfma_f32_16x16x4_f32 v[136:139], v106, v122, v[136:139]
	v_mfma_f32_16x16x4_f32 v[136:139], v107, v123, v[136:139]
	s_waitcnt lgkmcnt(10)
	v_mfma_f32_16x16x4_f32 v[136:139], v108, v124, v[136:139]
	v_mfma_f32_16x16x4_f32 v[136:139], v109, v125, v[136:139]
	s_add_u32 s14, s6, 0x180000
	s_addc_u32 s15, s7, 0
	global_load_dword v204, v12, s[14:15] offset:0
	global_load_dword v205, v12, s[14:15] offset:256
	global_load_dword v206, v12, s[14:15] offset:512
	global_load_dword v207, v12, s[14:15] offset:768
	s_waitcnt lgkmcnt(8)
	v_mfma_f32_16x16x4_f32 v[136:139], v110, v126, v[136:139]
	v_mfma_f32_16x16x4_f32 v[136:139], v111, v127, v[136:139]
	s_waitcnt lgkmcnt(6)
	v_mfma_f32_16x16x4_f32 v[136:139], v112, v128, v[136:139]
	v_mfma_f32_16x16x4_f32 v[136:139], v113, v129, v[136:139]
	ds_write_b128 v2, v[60:63] offset:20480
	ds_write_b128 v2, v[64:67] offset:30720
	s_add_u32 s10, s0, 0x1a0000
	s_addc_u32 s11, s1, 0
	global_load_dwordx4 v[60:63], v0, s[10:11]
	global_load_dwordx4 v[64:67], v1, s[10:11]
	s_waitcnt lgkmcnt(6)
	v_mfma_f32_16x16x4_f32 v[136:139], v114, v130, v[136:139]
	v_mfma_f32_16x16x4_f32 v[136:139], v115, v131, v[136:139]
	s_waitcnt lgkmcnt(4)
	v_mfma_f32_16x16x4_f32 v[136:139], v116, v132, v[136:139]
	v_mfma_f32_16x16x4_f32 v[136:139], v117, v133, v[136:139]
	s_waitcnt lgkmcnt(2)
	v_mfma_f32_16x16x4_f32 v[136:139], v118, v134, v[136:139]
	v_mfma_f32_16x16x4_f32 v[136:139], v119, v135, v[136:139]
	s_add_u32 s16, s8, 0xe0000
	s_addc_u32 s17, s9, 0
	s_nop 9
	ds_write_b32 v13, v136 offset:2176
	ds_write_b32 v13, v137 offset:2448
	ds_write_b32 v13, v138 offset:2720
	ds_write_b32 v13, v139 offset:2992
	global_store_dword v12, v136, s[16:17] offset:0
	global_store_dword v12, v137, s[16:17] offset:256
	global_store_dword v12, v138, s[16:17] offset:512
	global_store_dword v12, v139, s[16:17] offset:768
	s_waitcnt lgkmcnt(0)
	s_barrier
; #define LAS __attribute__((address_space(3)))
; __device__ __forceinline__ void scan_combine(LAS unsigned char* lds, CArgsP a) {
;     ...
;     for (int g = 1; g <= GL; ++g) {
;         const bool pf = (g + 2 <= GL);
;         float u3 = 0.f;
;         if (pf) { const f32x4* Pn = (const f32x4*)(PM + (size_t)((g + 2) * 8 + h) * 4096); pa = Pn[tid]; pb = Pn[512 + tid]; u3 = UM[((size_t)((g + 2) * 8 + h) * 64 + v) * 64 + kq]; }
;         asm volatile("s_waitcnt lgkmcnt(0)\n\ts_barrier" ::: "memory");
;         const LAS float* Pg = Pl + (g % 3) * 4096 + kq;
;         float acc0 = u1, acc1 = 0.f, acc2 = 0.f, acc3 = 0.f;
;         const int curi = __builtin_bit_cast(int, cur);
; #pragma unroll
;         for (int k = 0; k < 64; k += 4) {
;             const float s0 = __builtin_bit_cast(float, __builtin_amdgcn_readlane(curi, k)), s1 = __builtin_bit_cast(float, __builtin_amdgcn_readlane(curi, k + 1));
;             const float s2 = __builtin_bit_cast(float, __builtin_amdgcn_readlane(curi, k + 2)), s3 = __builtin_bit_cast(float, __builtin_amdgcn_readlane(curi, k + 3));
;             acc0 += s0 * Pg[(k + 0) * 64]; acc1 += s1 * Pg[(k + 1) * 64]; acc2 += s2 * Pg[(k + 2) * 64]; acc3 += s3 * Pg[(k + 3) * 64];
;         }
;         cur = (acc0 + acc1) + (acc2 + acc3);
;         SS[((size_t)((g + 1) * 8 + h) * 64 + v) * 64 + kq] = cur;
;         if (pf) { LAS float* dst = Pl + ((g + 2) % 3) * 4096; *(LAS f32x4*)(dst + 4 * tid) = pa; *(LAS f32x4*)(dst + 2048 + 4 * tid) = pb; }
;         u1 = u2; u2 = u3;
	ds_read2_b32 v[104:105], v9 offset0:0 offset1:4
	ds_read2st64_b32 v[120:121], v11 offset0:0 offset1:5
	ds_read2_b32 v[106:107], v9 offset0:8 offset1:12
	ds_read2st64_b32 v[122:123], v11 offset0:10 offset1:15
	ds_read2_b32 v[108:109], v9 offset0:16 offset1:20
	ds_read2st64_b32 v[124:125], v11 offset0:20 offset1:25
	ds_read2_b32 v[110:111], v9 offset0:24 offset1:28
	ds_read2st64_b32 v[126:127], v11 offset0:30 offset1:35
	ds_read2_b32 v[112:113], v9 offset0:32 offset1:36
	ds_read2st64_b32 v[128:129], v11 offset0:40 offset1:45
	ds_read2_b32 v[114:115], v9 offset0:40 offset1:44
	ds_read2st64_b32 v[130:131], v11 offset0:50 offset1:55
	ds_read2_b32 v[116:117], v9 offset0:48 offset1:52
	ds_read2st64_b32 v[132:133], v11 offset0:60 offset1:65
	s_waitcnt vmcnt(56)
	s_waitcnt lgkmcnt(12)
	v_mfma_f32_16x16x4_f32 v[136:139], v104, v120, v[208:211]
	v_mfma_f32_16x16x4_f32 v[136:139], v105, v121, v[136:139]
	ds_read2_b32 v[118:119], v9 offset0:56 offset1:60
	ds_read2st64_b32 v[134:135], v11 offset0:70 offset1:75
	s_waitcnt lgkmcnt(12)
	v_mfma_f32_16x16x4_f32 v[136:139], v106, v122, v[136:139]
	v_mfma_f32_16x16x4_f32 v[136:139], v107, v123, v[136:139]
	s_waitcnt lgkmcnt(10)
	v_mfma_f32_16x16x4_f32 v[136:139], v108, v124, v[136:139]
	v_mfma_f32_16x16x4_f32 v[136:139], v109, v125, v[136:139]
	s_add_u32 s14, s6, 0x1a0000
	s_addc_u32 s15, s7, 0
	global_load_dword v208, v12, s[14:15] offset:0
	global_load_dword v209, v12, s[14:15] offset:256
	global_load_dword v210, v12, s[14:15] offset:512
	global_load_dword v211, v12, s[14:15] offset:768
	s_waitcnt lgkmcnt(8)
	v_mfma_f32_16x16x4_f32 v[136:139], v110, v126, v[136:139]
	v_mfma_f32_16x16x4_f32 v[136:139], v111, v127, v[136:139]
	s_waitcnt lgkmcnt(6)
	v_mfma_f32_16x16x4_f32 v[136:139], v112, v128, v[136:139]
	v_mfma_f32_16x16x4_f32 v[136:139], v113, v129, v[136:139]
	s_waitcnt vmcnt(58)
	ds_write_b128 v2, v[68:71] offset:0
	ds_write_b128 v2, v[72:75] offset:10240
	s_add_u32 s10, s0, 0x1c0000
	s_addc_u32 s11, s1, 0
	global_load_dwordx4 v[68:71], v0, s[10:11]
	global_load_dwordx4 v[72:75], v1, s[10:11]
	s_waitcnt lgkmcnt(6)
	v_mfma_f32_16x16x4_f32 v[136:139], v114, v130, v[136:139]
	v_mfma_f32_16x16x4_f32 v[136:139], v115, v131, v[136:139]
	s_waitcnt lgkmcnt(4)
	v_mfma_f32_16x16x4_f32 v[136:139], v116, v132, v[136:139]
	v_mfma_f32_16x16x4_f32 v[136:139], v117, v133, v[136:139]
	s_waitcnt lgkmcnt(2)
	v_mfma_f32_16x16x4_f32 v[136:139], v118, v134, v[136:139]
	v_mfma_f32_16x16x4_f32 v[136:139], v119, v135, v[136:139]
	s_add_u32 s16, s8, 0x100000
	s_addc_u32 s17, s9, 0
	s_nop 9
	ds_write_b32 v13, v136 offset:0
	ds_write_b32 v13, v137 offset:272
	ds_write_b32 v13, v138 offset:544
	ds_write_b32 v13, v139 offset:816
	global_store_dword v12, v136, s[16:17] offset:0
	global_store_dword v12, v137, s[16:17] offset:256
	global_store_dword v12, v138, s[16:17] offset:512
	global_store_dword v12, v139, s[16:17] offset:768
	s_waitcnt lgkmcnt(0)
	s_barrier
	ds_read2_b32 v[104:105], v8 offset0:0 offset1:4
	ds_read2st64_b32 v[120:121], v10 offset0:0 offset1:5
	ds_read2_b32 v[106:107], v8 offset0:8 offset1:12
	ds_read2st64_b32 v[122:123], v10 offset0:10 offset1:15
	ds_read2_b32 v[108:109], v8 offset0:16 offset1:20
	ds_read2st64_b32 v[124:125], v10 offset0:20 offset1:25
	ds_read2_b32 v[110:111], v8 offset0:24 offset1:28
	ds_read2st64_b32 v[126:127], v10 offset0:30 offset1:35
	ds_read2_b32 v[112:113], v8 offset0:32 offset1:36
	ds_read2st64_b32 v[128:129], v10 offset0:40 offset1:45
	ds_read2_b32 v[114:115], v8 offset0:40 offset1:44
	ds_read2st64_b32 v[130:131], v10 offset0:50 offset1:55
	ds_read2_b32 v[116:117], v8 offset0:48 offset1:52
	ds_read2st64_b32 v[132:133], v10 offset0:60 offset1:65
	s_waitcnt vmcnt(56)
	s_waitcnt lgkmcnt(12)
	v_mfma_f32_16x16x4_f32 v[136:139], v104, v120, v[212:215]
	v_mfma_f32_16x16x4_f32 v[136:139], v105, v121, v[136:139]
	ds_read2_b32 v[118:119], v8 offset0:56 offset1:60
	ds_read2st64_b32 v[134:135], v10 offset0:70 offset1:75
	s_waitcnt lgkmcnt(12)
	v_mfma_f32_16x16x4_f32 v[136:139], v106, v122, v[136:139]
	v_mfma_f32_16x16x4_f32 v[136:139], v107, v123, v[136:139]
	s_waitcnt lgkmcnt(10)
	v_mfma_f32_16x16x4_f32 v[136:139], v108, v124, v[136:139]
	v_mfma_f32_16x16x4_f32 v[136:139], v109, v125, v[136:139]
	s_add_u32 s14, s6, 0x1c0000
	s_addc_u32 s15, s7, 0
	global_load_dword v212, v12, s[14:15] offset:0
	global_load_dword v213, v12, s[14:15] offset:256
	global_load_dword v214, v12, s[14:15] offset:512
	global_load_dword v215, v12, s[14:15] offset:768
	s_waitcnt lgkmcnt(8)
	v_mfma_f32_16x16x4_f32 v[136:139], v110, v126, v[136:139]
	v_mfma_f32_16x16x4_f32 v[136:139], v111, v127, v[136:139]
	s_waitcnt lgkmcnt(6)
	v_mfma_f32_16x16x4_f32 v[136:139], v112, v128, v[136:139]
	v_mfma_f32_16x16x4_f32 v[136:139], v113, v129, v[136:139]
	s_waitcnt vmcnt(58)
	ds_write_b128 v2, v[76:79] offset:20480
	ds_write_b128 v2, v[80:83] offset:30720
	s_add_u32 s10, s0, 0x1e0000
	s_addc_u32 s11, s1, 0
	global_load_dwordx4 v[76:79], v0, s[10:11]
	global_load_dwordx4 v[80:83], v1, s[10:11]
	s_waitcnt lgkmcnt(6)
	v_mfma_f32_16x16x4_f32 v[136:139], v114, v130, v[136:139]
	v_mfma_f32_16x16x4_f32 v[136:139], v115, v131, v[136:139]
	s_waitcnt lgkmcnt(4)
	v_mfma_f32_16x16x4_f32 v[136:139], v116, v132, v[136:139]
	v_mfma_f32_16x16x4_f32 v[136:139], v117, v133, v[136:139]
	s_waitcnt lgkmcnt(2)
	v_mfma_f32_16x16x4_f32 v[136:139], v118, v134, v[136:139]
	v_mfma_f32_16x16x4_f32 v[136:139], v119, v135, v[136:139]
	s_add_u32 s16, s8, 0x120000
	s_addc_u32 s17, s9, 0
	s_nop 9
	ds_write_b32 v13, v136 offset:2176
	ds_write_b32 v13, v137 offset:2448
	ds_write_b32 v13, v138 offset:2720
	ds_write_b32 v13, v139 offset:2992
	global_store_dword v12, v136, s[16:17] offset:0
	global_store_dword v12, v137, s[16:17] offset:256
	global_store_dword v12, v138, s[16:17] offset:512
	global_store_dword v12, v139, s[16:17] offset:768
	s_waitcnt lgkmcnt(0)
	s_barrier
; #define LAS __attribute__((address_space(3)))
; __device__ __forceinline__ void scan_combine(LAS unsigned char* lds, CArgsP a) {
;     ...
;     for (int g = 1; g <= GL; ++g) {
;         const bool pf = (g + 2 <= GL);
;         float u3 = 0.f;
;         if (pf) { const f32x4* Pn = (const f32x4*)(PM + (size_t)((g + 2) * 8 + h) * 4096); pa = Pn[tid]; pb = Pn[512 + tid]; u3 = UM[((size_t)((g + 2) * 8 + h) * 64 + v) * 64 + kq]; }
;         asm volatile("s_waitcnt lgkmcnt(0)\n\ts_barrier" ::: "memory");
;         const LAS float* Pg = Pl + (g % 3) * 4096 + kq;
;         float acc0 = u1, acc1 = 0.f, acc2 = 0.f, acc3 = 0.f;
;         const int curi = __builtin_bit_cast(int, cur);
; #pragma unroll
;         for (int k = 0; k < 64; k += 4) {
;             const float s0 = __builtin_bit_cast(float, __builtin_amdgcn_readlane(curi, k)), s1 = __builtin_bit_cast(float, __builtin_amdgcn_readlane(curi, k + 1));
;             const float s2 = __builtin_bit_cast(float, __builtin_amdgcn_readlane(curi, k + 2)), s3 = __builtin_bit_cast(float, __builtin_amdgcn_readlane(curi, k + 3));
;             acc0 += s0 * Pg[(k + 0) * 64]; acc1 += s1 * Pg[(k + 1) * 64]; acc2 += s2 * Pg[(k + 2) * 64]; acc3 += s3 * Pg[(k + 3) * 64];
;         }
;         cur = (acc0 + acc1) + (acc2 + acc3);
;         SS[((size_t)((g + 1) * 8 + h) * 64 + v) * 64 + kq] = cur;
;         if (pf) { LAS float* dst = Pl + ((g + 2) % 3) * 4096; *(LAS f32x4*)(dst + 4 * tid) = pa; *(LAS f32x4*)(dst + 2048 + 4 * tid) = pb; }
;         u1 = u2; u2 = u3;
	ds_read2_b32 v[104:105], v9 offset0:0 offset1:4
	ds_read2st64_b32 v[120:121], v11 offset0:0 offset1:5
	ds_read2_b32 v[106:107], v9 offset0:8 offset1:12
	ds_read2st64_b32 v[122:123], v11 offset0:10 offset1:15
	ds_read2_b32 v[108:109], v9 offset0:16 offset1:20
	ds_read2st64_b32 v[124:125], v11 offset0:20 offset1:25
	ds_read2_b32 v[110:111], v9 offset0:24 offset1:28
	ds_read2st64_b32 v[126:127], v11 offset0:30 offset1:35
	ds_read2_b32 v[112:113], v9 offset0:32 offset1:36
	ds_read2st64_b32 v[128:129], v11 offset0:40 offset1:45
	ds_read2_b32 v[114:115], v9 offset0:40 offset1:44
	ds_read2st64_b32 v[130:131], v11 offset0:50 offset1:55
	ds_read2_b32 v[116:117], v9 offset0:48 offset1:52
	ds_read2st64_b32 v[132:133], v11 offset0:60 offset1:65
	s_waitcnt vmcnt(56)
	s_waitcnt lgkmcnt(12)
	v_mfma_f32_16x16x4_f32 v[136:139], v104, v120, v[216:219]
	v_mfma_f32_16x16x4_f32 v[136:139], v105, v121, v[136:139]
	ds_read2_b32 v[118:119], v9 offset0:56 offset1:60
	ds_read2st64_b32 v[134:135], v11 offset0:70 offset1:75
	s_waitcnt lgkmcnt(12)
	v_mfma_f32_16x16x4_f32 v[136:139], v106, v122, v[136:139]
	v_mfma_f32_16x16x4_f32 v[136:139], v107, v123, v[136:139]
	s_waitcnt lgkmcnt(10)
	v_mfma_f32_16x16x4_f32 v[136:139], v108, v124, v[136:139]
	v_mfma_f32_16x16x4_f32 v[136:139], v109, v125, v[136:139]
	s_add_u32 s14, s6, 0x1e0000
	s_addc_u32 s15, s7, 0
	global_load_dword v216, v12, s[14:15] offset:0
	global_load_dword v217, v12, s[14:15] offset:256
	global_load_dword v218, v12, s[14:15] offset:512
	global_load_dword v219, v12, s[14:15] offset:768
	s_waitcnt lgkmcnt(8)
	v_mfma_f32_16x16x4_f32 v[136:139], v110, v126, v[136:139]
	v_mfma_f32_16x16x4_f32 v[136:139], v111, v127, v[136:139]
	s_waitcnt lgkmcnt(6)
	v_mfma_f32_16x16x4_f32 v[136:139], v112, v128, v[136:139]
	v_mfma_f32_16x16x4_f32 v[136:139], v113, v129, v[136:139]
	s_waitcnt vmcnt(58)
	ds_write_b128 v2, v[84:87] offset:0
	ds_write_b128 v2, v[88:91] offset:10240
	s_add_u32 s10, s0, 0x200000
	s_addc_u32 s11, s1, 0
	global_load_dwordx4 v[84:87], v0, s[10:11]
	global_load_dwordx4 v[88:91], v1, s[10:11]
	s_waitcnt lgkmcnt(6)
	v_mfma_f32_16x16x4_f32 v[136:139], v114, v130, v[136:139]
	v_mfma_f32_16x16x4_f32 v[136:139], v115, v131, v[136:139]
	s_waitcnt lgkmcnt(4)
	v_mfma_f32_16x16x4_f32 v[136:139], v116, v132, v[136:139]
	v_mfma_f32_16x16x4_f32 v[136:139], v117, v133, v[136:139]
	s_waitcnt lgkmcnt(2)
	v_mfma_f32_16x16x4_f32 v[136:139], v118, v134, v[136:139]
	v_mfma_f32_16x16x4_f32 v[136:139], v119, v135, v[136:139]
	s_add_u32 s16, s8, 0x140000
	s_addc_u32 s17, s9, 0
	s_nop 9
	ds_write_b32 v13, v136 offset:0
	ds_write_b32 v13, v137 offset:272
	ds_write_b32 v13, v138 offset:544
	ds_write_b32 v13, v139 offset:816
	global_store_dword v12, v136, s[16:17] offset:0
	global_store_dword v12, v137, s[16:17] offset:256
	global_store_dword v12, v138, s[16:17] offset:512
	global_store_dword v12, v139, s[16:17] offset:768
	s_waitcnt lgkmcnt(0)
	s_barrier
	ds_read2_b32 v[104:105], v8 offset0:0 offset1:4
	ds_read2st64_b32 v[120:121], v10 offset0:0 offset1:5
	ds_read2_b32 v[106:107], v8 offset0:8 offset1:12
	ds_read2st64_b32 v[122:123], v10 offset0:10 offset1:15
	ds_read2_b32 v[108:109], v8 offset0:16 offset1:20
	ds_read2st64_b32 v[124:125], v10 offset0:20 offset1:25
	ds_read2_b32 v[110:111], v8 offset0:24 offset1:28
	ds_read2st64_b32 v[126:127], v10 offset0:30 offset1:35
	ds_read2_b32 v[112:113], v8 offset0:32 offset1:36
	ds_read2st64_b32 v[128:129], v10 offset0:40 offset1:45
	ds_read2_b32 v[114:115], v8 offset0:40 offset1:44
	ds_read2st64_b32 v[130:131], v10 offset0:50 offset1:55
	ds_read2_b32 v[116:117], v8 offset0:48 offset1:52
	ds_read2st64_b32 v[132:133], v10 offset0:60 offset1:65
	s_waitcnt vmcnt(56)
	s_waitcnt lgkmcnt(12)
	v_mfma_f32_16x16x4_f32 v[136:139], v104, v120, v[220:223]
	v_mfma_f32_16x16x4_f32 v[136:139], v105, v121, v[136:139]
	ds_read2_b32 v[118:119], v8 offset0:56 offset1:60
	ds_read2st64_b32 v[134:135], v10 offset0:70 offset1:75
	s_waitcnt lgkmcnt(12)
	v_mfma_f32_16x16x4_f32 v[136:139], v106, v122, v[136:139]
	v_mfma_f32_16x16x4_f32 v[136:139], v107, v123, v[136:139]
	s_waitcnt lgkmcnt(10)
	v_mfma_f32_16x16x4_f32 v[136:139], v108, v124, v[136:139]
	v_mfma_f32_16x16x4_f32 v[136:139], v109, v125, v[136:139]
	s_add_u32 s14, s6, 0x200000
	s_addc_u32 s15, s7, 0
	global_load_dword v220, v12, s[14:15] offset:0
	global_load_dword v221, v12, s[14:15] offset:256
	global_load_dword v222, v12, s[14:15] offset:512
	global_load_dword v223, v12, s[14:15] offset:768
	s_waitcnt lgkmcnt(8)
	v_mfma_f32_16x16x4_f32 v[136:139], v110, v126, v[136:139]
	v_mfma_f32_16x16x4_f32 v[136:139], v111, v127, v[136:139]
	s_waitcnt lgkmcnt(6)
	v_mfma_f32_16x16x4_f32 v[136:139], v112, v128, v[136:139]
	v_mfma_f32_16x16x4_f32 v[136:139], v113, v129, v[136:139]
	s_waitcnt vmcnt(58)
	ds_write_b128 v2, v[92:95] offset:20480
	ds_write_b128 v2, v[96:99] offset:30720
	s_add_u32 s10, s0, 0x220000
	s_addc_u32 s11, s1, 0
	global_load_dwordx4 v[92:95], v0, s[10:11]
	global_load_dwordx4 v[96:99], v1, s[10:11]
	s_waitcnt lgkmcnt(6)
	v_mfma_f32_16x16x4_f32 v[136:139], v114, v130, v[136:139]
	v_mfma_f32_16x16x4_f32 v[136:139], v115, v131, v[136:139]
	s_waitcnt lgkmcnt(4)
	v_mfma_f32_16x16x4_f32 v[136:139], v116, v132, v[136:139]
	v_mfma_f32_16x16x4_f32 v[136:139], v117, v133, v[136:139]
	s_waitcnt lgkmcnt(2)
	v_mfma_f32_16x16x4_f32 v[136:139], v118, v134, v[136:139]
	v_mfma_f32_16x16x4_f32 v[136:139], v119, v135, v[136:139]
	s_add_u32 s16, s8, 0x160000
	s_addc_u32 s17, s9, 0
	s_nop 9
	ds_write_b32 v13, v136 offset:2176
	ds_write_b32 v13, v137 offset:2448
	ds_write_b32 v13, v138 offset:2720
	ds_write_b32 v13, v139 offset:2992
	global_store_dword v12, v136, s[16:17] offset:0
	global_store_dword v12, v137, s[16:17] offset:256
	global_store_dword v12, v138, s[16:17] offset:512
	global_store_dword v12, v139, s[16:17] offset:768
	s_waitcnt lgkmcnt(0)
	s_barrier
; #define LAS __attribute__((address_space(3)))
; __device__ __forceinline__ void scan_combine(LAS unsigned char* lds, CArgsP a) {
;     ...
;     for (int g = 1; g <= GL; ++g) {
;         const bool pf = (g + 2 <= GL);
;         float u3 = 0.f;
;         if (pf) { const f32x4* Pn = (const f32x4*)(PM + (size_t)((g + 2) * 8 + h) * 4096); pa = Pn[tid]; pb = Pn[512 + tid]; u3 = UM[((size_t)((g + 2) * 8 + h) * 64 + v) * 64 + kq]; }
;         asm volatile("s_waitcnt lgkmcnt(0)\n\ts_barrier" ::: "memory");
;         const LAS float* Pg = Pl + (g % 3) * 4096 + kq;
;         float acc0 = u1, acc1 = 0.f, acc2 = 0.f, acc3 = 0.f;
;         const int curi = __builtin_bit_cast(int, cur);
; #pragma unroll
;         for (int k = 0; k < 64; k += 4) {
;             const float s0 = __builtin_bit_cast(float, __builtin_amdgcn_readlane(curi, k)), s1 = __builtin_bit_cast(float, __builtin_amdgcn_readlane(curi, k + 1));
;             const float s2 = __builtin_bit_cast(float, __builtin_amdgcn_readlane(curi, k + 2)), s3 = __builtin_bit_cast(float, __builtin_amdgcn_readlane(curi, k + 3));
;             acc0 += s0 * Pg[(k + 0) * 64]; acc1 += s1 * Pg[(k + 1) * 64]; acc2 += s2 * Pg[(k + 2) * 64]; acc3 += s3 * Pg[(k + 3) * 64];
;         }
;         cur = (acc0 + acc1) + (acc2 + acc3);
;         SS[((size_t)((g + 1) * 8 + h) * 64 + v) * 64 + kq] = cur;
;         if (pf) { LAS float* dst = Pl + ((g + 2) % 3) * 4096; *(LAS f32x4*)(dst + 4 * tid) = pa; *(LAS f32x4*)(dst + 2048 + 4 * tid) = pb; }
;         u1 = u2; u2 = u3;
	ds_read2_b32 v[104:105], v9 offset0:0 offset1:4
	ds_read2st64_b32 v[120:121], v11 offset0:0 offset1:5
	ds_read2_b32 v[106:107], v9 offset0:8 offset1:12
	ds_read2st64_b32 v[122:123], v11 offset0:10 offset1:15
	ds_read2_b32 v[108:109], v9 offset0:16 offset1:20
	ds_read2st64_b32 v[124:125], v11 offset0:20 offset1:25
	ds_read2_b32 v[110:111], v9 offset0:24 offset1:28
	ds_read2st64_b32 v[126:127], v11 offset0:30 offset1:35
	ds_read2_b32 v[112:113], v9 offset0:32 offset1:36
	ds_read2st64_b32 v[128:129], v11 offset0:40 offset1:45
	ds_read2_b32 v[114:115], v9 offset0:40 offset1:44
	ds_read2st64_b32 v[130:131], v11 offset0:50 offset1:55
	ds_read2_b32 v[116:117], v9 offset0:48 offset1:52
	ds_read2st64_b32 v[132:133], v11 offset0:60 offset1:65
	s_waitcnt vmcnt(56)
	s_waitcnt lgkmcnt(12)
	v_mfma_f32_16x16x4_f32 v[136:139], v104, v120, v[224:227]
	v_mfma_f32_16x16x4_f32 v[136:139], v105, v121, v[136:139]
	ds_read2_b32 v[118:119], v9 offset0:56 offset1:60
	ds_read2st64_b32 v[134:135], v11 offset0:70 offset1:75
	s_waitcnt lgkmcnt(12)
	v_mfma_f32_16x16x4_f32 v[136:139], v106, v122, v[136:139]
	v_mfma_f32_16x16x4_f32 v[136:139], v107, v123, v[136:139]
	s_waitcnt lgkmcnt(10)
	v_mfma_f32_16x16x4_f32 v[136:139], v108, v124, v[136:139]
	v_mfma_f32_16x16x4_f32 v[136:139], v109, v125, v[136:139]
	s_add_u32 s14, s6, 0x220000
	s_addc_u32 s15, s7, 0
	global_load_dword v224, v12, s[14:15] offset:0
	global_load_dword v225, v12, s[14:15] offset:256
	global_load_dword v226, v12, s[14:15] offset:512
	global_load_dword v227, v12, s[14:15] offset:768
	s_waitcnt lgkmcnt(8)
	v_mfma_f32_16x16x4_f32 v[136:139], v110, v126, v[136:139]
	v_mfma_f32_16x16x4_f32 v[136:139], v111, v127, v[136:139]
	s_waitcnt lgkmcnt(6)
	v_mfma_f32_16x16x4_f32 v[136:139], v112, v128, v[136:139]
	v_mfma_f32_16x16x4_f32 v[136:139], v113, v129, v[136:139]
	s_waitcnt vmcnt(58)
	ds_write_b128 v2, v[52:55] offset:0
	ds_write_b128 v2, v[56:59] offset:10240
	s_add_u32 s10, s0, 0x240000
	s_addc_u32 s11, s1, 0
	global_load_dwordx4 v[52:55], v0, s[10:11]
	global_load_dwordx4 v[56:59], v1, s[10:11]
	s_waitcnt lgkmcnt(6)
	v_mfma_f32_16x16x4_f32 v[136:139], v114, v130, v[136:139]
	v_mfma_f32_16x16x4_f32 v[136:139], v115, v131, v[136:139]
	s_waitcnt lgkmcnt(4)
	v_mfma_f32_16x16x4_f32 v[136:139], v116, v132, v[136:139]
	v_mfma_f32_16x16x4_f32 v[136:139], v117, v133, v[136:139]
	s_waitcnt lgkmcnt(2)
	v_mfma_f32_16x16x4_f32 v[136:139], v118, v134, v[136:139]
	v_mfma_f32_16x16x4_f32 v[136:139], v119, v135, v[136:139]
	s_add_u32 s16, s8, 0x180000
	s_addc_u32 s17, s9, 0
	s_nop 9
	ds_write_b32 v13, v136 offset:0
	ds_write_b32 v13, v137 offset:272
	ds_write_b32 v13, v138 offset:544
	ds_write_b32 v13, v139 offset:816
	global_store_dword v12, v136, s[16:17] offset:0
	global_store_dword v12, v137, s[16:17] offset:256
	global_store_dword v12, v138, s[16:17] offset:512
	global_store_dword v12, v139, s[16:17] offset:768
	s_waitcnt lgkmcnt(0)
	s_barrier
	ds_read2_b32 v[104:105], v8 offset0:0 offset1:4
	ds_read2st64_b32 v[120:121], v10 offset0:0 offset1:5
	ds_read2_b32 v[106:107], v8 offset0:8 offset1:12
	ds_read2st64_b32 v[122:123], v10 offset0:10 offset1:15
	ds_read2_b32 v[108:109], v8 offset0:16 offset1:20
	ds_read2st64_b32 v[124:125], v10 offset0:20 offset1:25
	ds_read2_b32 v[110:111], v8 offset0:24 offset1:28
	ds_read2st64_b32 v[126:127], v10 offset0:30 offset1:35
	ds_read2_b32 v[112:113], v8 offset0:32 offset1:36
	ds_read2st64_b32 v[128:129], v10 offset0:40 offset1:45
	ds_read2_b32 v[114:115], v8 offset0:40 offset1:44
	ds_read2st64_b32 v[130:131], v10 offset0:50 offset1:55
	ds_read2_b32 v[116:117], v8 offset0:48 offset1:52
	ds_read2st64_b32 v[132:133], v10 offset0:60 offset1:65
	s_waitcnt vmcnt(56)
	s_waitcnt lgkmcnt(12)
	v_mfma_f32_16x16x4_f32 v[136:139], v104, v120, v[204:207]
	v_mfma_f32_16x16x4_f32 v[136:139], v105, v121, v[136:139]
	ds_read2_b32 v[118:119], v8 offset0:56 offset1:60
	ds_read2st64_b32 v[134:135], v10 offset0:70 offset1:75
	s_waitcnt lgkmcnt(12)
	v_mfma_f32_16x16x4_f32 v[136:139], v106, v122, v[136:139]
	v_mfma_f32_16x16x4_f32 v[136:139], v107, v123, v[136:139]
	s_waitcnt lgkmcnt(10)
	v_mfma_f32_16x16x4_f32 v[136:139], v108, v124, v[136:139]
	v_mfma_f32_16x16x4_f32 v[136:139], v109, v125, v[136:139]
	s_add_u32 s14, s6, 0x240000
	s_addc_u32 s15, s7, 0
	global_load_dword v204, v12, s[14:15] offset:0
	global_load_dword v205, v12, s[14:15] offset:256
	global_load_dword v206, v12, s[14:15] offset:512
	global_load_dword v207, v12, s[14:15] offset:768
	s_waitcnt lgkmcnt(8)
	v_mfma_f32_16x16x4_f32 v[136:139], v110, v126, v[136:139]
	v_mfma_f32_16x16x4_f32 v[136:139], v111, v127, v[136:139]
	s_waitcnt lgkmcnt(6)
	v_mfma_f32_16x16x4_f32 v[136:139], v112, v128, v[136:139]
	v_mfma_f32_16x16x4_f32 v[136:139], v113, v129, v[136:139]
	s_waitcnt vmcnt(58)
	ds_write_b128 v2, v[60:63] offset:20480
	ds_write_b128 v2, v[64:67] offset:30720
	s_add_u32 s10, s0, 0x260000
	s_addc_u32 s11, s1, 0
	global_load_dwordx4 v[60:63], v0, s[10:11]
	global_load_dwordx4 v[64:67], v1, s[10:11]
	s_waitcnt lgkmcnt(6)
	v_mfma_f32_16x16x4_f32 v[136:139], v114, v130, v[136:139]
	v_mfma_f32_16x16x4_f32 v[136:139], v115, v131, v[136:139]
	s_waitcnt lgkmcnt(4)
	v_mfma_f32_16x16x4_f32 v[136:139], v116, v132, v[136:139]
	v_mfma_f32_16x16x4_f32 v[136:139], v117, v133, v[136:139]
	s_waitcnt lgkmcnt(2)
	v_mfma_f32_16x16x4_f32 v[136:139], v118, v134, v[136:139]
	v_mfma_f32_16x16x4_f32 v[136:139], v119, v135, v[136:139]
	s_add_u32 s16, s8, 0x1a0000
	s_addc_u32 s17, s9, 0
	s_nop 9
	ds_write_b32 v13, v136 offset:2176
	ds_write_b32 v13, v137 offset:2448
	ds_write_b32 v13, v138 offset:2720
	ds_write_b32 v13, v139 offset:2992
	global_store_dword v12, v136, s[16:17] offset:0
	global_store_dword v12, v137, s[16:17] offset:256
	global_store_dword v12, v138, s[16:17] offset:512
	global_store_dword v12, v139, s[16:17] offset:768
	s_waitcnt lgkmcnt(0)
	s_barrier
; #define LAS __attribute__((address_space(3)))
; __device__ __forceinline__ void scan_combine(LAS unsigned char* lds, CArgsP a) {
;     ...
;     for (int g = 1; g <= GL; ++g) {
;         const bool pf = (g + 2 <= GL);
;         float u3 = 0.f;
;         if (pf) { const f32x4* Pn = (const f32x4*)(PM + (size_t)((g + 2) * 8 + h) * 4096); pa = Pn[tid]; pb = Pn[512 + tid]; u3 = UM[((size_t)((g + 2) * 8 + h) * 64 + v) * 64 + kq]; }
;         asm volatile("s_waitcnt lgkmcnt(0)\n\ts_barrier" ::: "memory");
;         const LAS float* Pg = Pl + (g % 3) * 4096 + kq;
;         float acc0 = u1, acc1 = 0.f, acc2 = 0.f, acc3 = 0.f;
;         const int curi = __builtin_bit_cast(int, cur);
; #pragma unroll
;         for (int k = 0; k < 64; k += 4) {
;             const float s0 = __builtin_bit_cast(float, __builtin_amdgcn_readlane(curi, k)), s1 = __builtin_bit_cast(float, __builtin_amdgcn_readlane(curi, k + 1));
;             const float s2 = __builtin_bit_cast(float, __builtin_amdgcn_readlane(curi, k + 2)), s3 = __builtin_bit_cast(float, __builtin_amdgcn_readlane(curi, k + 3));
;             acc0 += s0 * Pg[(k + 0) * 64]; acc1 += s1 * Pg[(k + 1) * 64]; acc2 += s2 * Pg[(k + 2) * 64]; acc3 += s3 * Pg[(k + 3) * 64];
;         }
;         cur = (acc0 + acc1) + (acc2 + acc3);
;         SS[((size_t)((g + 1) * 8 + h) * 64 + v) * 64 + kq] = cur;
;         if (pf) { LAS float* dst = Pl + ((g + 2) % 3) * 4096; *(LAS f32x4*)(dst + 4 * tid) = pa; *(LAS f32x4*)(dst + 2048 + 4 * tid) = pb; }
;         u1 = u2; u2 = u3;
	ds_read2_b32 v[104:105], v9 offset0:0 offset1:4
	ds_read2st64_b32 v[120:121], v11 offset0:0 offset1:5
	ds_read2_b32 v[106:107], v9 offset0:8 offset1:12
	ds_read2st64_b32 v[122:123], v11 offset0:10 offset1:15
	ds_read2_b32 v[108:109], v9 offset0:16 offset1:20
	ds_read2st64_b32 v[124:125], v11 offset0:20 offset1:25
	ds_read2_b32 v[110:111], v9 offset0:24 offset1:28
	ds_read2st64_b32 v[126:127], v11 offset0:30 offset1:35
	ds_read2_b32 v[112:113], v9 offset0:32 offset1:36
	ds_read2st64_b32 v[128:129], v11 offset0:40 offset1:45
	ds_read2_b32 v[114:115], v9 offset0:40 offset1:44
	ds_read2st64_b32 v[130:131], v11 offset0:50 offset1:55
	ds_read2_b32 v[116:117], v9 offset0:48 offset1:52
	ds_read2st64_b32 v[132:133], v11 offset0:60 offset1:65
	s_waitcnt vmcnt(56)
	s_waitcnt lgkmcnt(12)
	v_mfma_f32_16x16x4_f32 v[136:139], v104, v120, v[208:211]
	v_mfma_f32_16x16x4_f32 v[136:139], v105, v121, v[136:139]
	ds_read2_b32 v[118:119], v9 offset0:56 offset1:60
	ds_read2st64_b32 v[134:135], v11 offset0:70 offset1:75
	s_waitcnt lgkmcnt(12)
	v_mfma_f32_16x16x4_f32 v[136:139], v106, v122, v[136:139]
	v_mfma_f32_16x16x4_f32 v[136:139], v107, v123, v[136:139]
	s_waitcnt lgkmcnt(10)
	v_mfma_f32_16x16x4_f32 v[136:139], v108, v124, v[136:139]
	v_mfma_f32_16x16x4_f32 v[136:139], v109, v125, v[136:139]
	s_add_u32 s14, s6, 0x260000
	s_addc_u32 s15, s7, 0
	global_load_dword v208, v12, s[14:15] offset:0
	global_load_dword v209, v12, s[14:15] offset:256
	global_load_dword v210, v12, s[14:15] offset:512
	global_load_dword v211, v12, s[14:15] offset:768
	s_waitcnt lgkmcnt(8)
	v_mfma_f32_16x16x4_f32 v[136:139], v110, v126, v[136:139]
	v_mfma_f32_16x16x4_f32 v[136:139], v111, v127, v[136:139]
	s_waitcnt lgkmcnt(6)
	v_mfma_f32_16x16x4_f32 v[136:139], v112, v128, v[136:139]
	v_mfma_f32_16x16x4_f32 v[136:139], v113, v129, v[136:139]
	s_waitcnt vmcnt(58)
	ds_write_b128 v2, v[68:71] offset:0
	ds_write_b128 v2, v[72:75] offset:10240
	s_add_u32 s10, s0, 0x280000
	s_addc_u32 s11, s1, 0
	global_load_dwordx4 v[68:71], v0, s[10:11]
	global_load_dwordx4 v[72:75], v1, s[10:11]
	s_waitcnt lgkmcnt(6)
	v_mfma_f32_16x16x4_f32 v[136:139], v114, v130, v[136:139]
	v_mfma_f32_16x16x4_f32 v[136:139], v115, v131, v[136:139]
	s_waitcnt lgkmcnt(4)
	v_mfma_f32_16x16x4_f32 v[136:139], v116, v132, v[136:139]
	v_mfma_f32_16x16x4_f32 v[136:139], v117, v133, v[136:139]
	s_waitcnt lgkmcnt(2)
	v_mfma_f32_16x16x4_f32 v[136:139], v118, v134, v[136:139]
	v_mfma_f32_16x16x4_f32 v[136:139], v119, v135, v[136:139]
	s_add_u32 s16, s8, 0x1c0000
	s_addc_u32 s17, s9, 0
	s_nop 9
	ds_write_b32 v13, v136 offset:0
	ds_write_b32 v13, v137 offset:272
	ds_write_b32 v13, v138 offset:544
	ds_write_b32 v13, v139 offset:816
	global_store_dword v12, v136, s[16:17] offset:0
	global_store_dword v12, v137, s[16:17] offset:256
	global_store_dword v12, v138, s[16:17] offset:512
	global_store_dword v12, v139, s[16:17] offset:768
	s_waitcnt lgkmcnt(0)
	s_barrier
	ds_read2_b32 v[104:105], v8 offset0:0 offset1:4
	ds_read2st64_b32 v[120:121], v10 offset0:0 offset1:5
	ds_read2_b32 v[106:107], v8 offset0:8 offset1:12
	ds_read2st64_b32 v[122:123], v10 offset0:10 offset1:15
	ds_read2_b32 v[108:109], v8 offset0:16 offset1:20
	ds_read2st64_b32 v[124:125], v10 offset0:20 offset1:25
	ds_read2_b32 v[110:111], v8 offset0:24 offset1:28
	ds_read2st64_b32 v[126:127], v10 offset0:30 offset1:35
	ds_read2_b32 v[112:113], v8 offset0:32 offset1:36
	ds_read2st64_b32 v[128:129], v10 offset0:40 offset1:45
	ds_read2_b32 v[114:115], v8 offset0:40 offset1:44
	ds_read2st64_b32 v[130:131], v10 offset0:50 offset1:55
	ds_read2_b32 v[116:117], v8 offset0:48 offset1:52
	ds_read2st64_b32 v[132:133], v10 offset0:60 offset1:65
	s_waitcnt vmcnt(56)
	s_waitcnt lgkmcnt(12)
	v_mfma_f32_16x16x4_f32 v[136:139], v104, v120, v[212:215]
	v_mfma_f32_16x16x4_f32 v[136:139], v105, v121, v[136:139]
	ds_read2_b32 v[118:119], v8 offset0:56 offset1:60
	ds_read2st64_b32 v[134:135], v10 offset0:70 offset1:75
	s_waitcnt lgkmcnt(12)
	v_mfma_f32_16x16x4_f32 v[136:139], v106, v122, v[136:139]
	v_mfma_f32_16x16x4_f32 v[136:139], v107, v123, v[136:139]
	s_waitcnt lgkmcnt(10)
	v_mfma_f32_16x16x4_f32 v[136:139], v108, v124, v[136:139]
	v_mfma_f32_16x16x4_f32 v[136:139], v109, v125, v[136:139]
	s_add_u32 s14, s6, 0x280000
	s_addc_u32 s15, s7, 0
	global_load_dword v212, v12, s[14:15] offset:0
	global_load_dword v213, v12, s[14:15] offset:256
	global_load_dword v214, v12, s[14:15] offset:512
	global_load_dword v215, v12, s[14:15] offset:768
	s_waitcnt lgkmcnt(8)
	v_mfma_f32_16x16x4_f32 v[136:139], v110, v126, v[136:139]
	v_mfma_f32_16x16x4_f32 v[136:139], v111, v127, v[136:139]
	s_waitcnt lgkmcnt(6)
	v_mfma_f32_16x16x4_f32 v[136:139], v112, v128, v[136:139]
	v_mfma_f32_16x16x4_f32 v[136:139], v113, v129, v[136:139]
	s_waitcnt vmcnt(58)
	ds_write_b128 v2, v[76:79] offset:20480
	ds_write_b128 v2, v[80:83] offset:30720
	s_add_u32 s10, s0, 0x2a0000
	s_addc_u32 s11, s1, 0
	global_load_dwordx4 v[76:79], v0, s[10:11]
	global_load_dwordx4 v[80:83], v1, s[10:11]
	s_waitcnt lgkmcnt(6)
	v_mfma_f32_16x16x4_f32 v[136:139], v114, v130, v[136:139]
	v_mfma_f32_16x16x4_f32 v[136:139], v115, v131, v[136:139]
	s_waitcnt lgkmcnt(4)
	v_mfma_f32_16x16x4_f32 v[136:139], v116, v132, v[136:139]
	v_mfma_f32_16x16x4_f32 v[136:139], v117, v133, v[136:139]
	s_waitcnt lgkmcnt(2)
	v_mfma_f32_16x16x4_f32 v[136:139], v118, v134, v[136:139]
	v_mfma_f32_16x16x4_f32 v[136:139], v119, v135, v[136:139]
	s_add_u32 s16, s8, 0x1e0000
	s_addc_u32 s17, s9, 0
	s_nop 9
	ds_write_b32 v13, v136 offset:2176
	ds_write_b32 v13, v137 offset:2448
	ds_write_b32 v13, v138 offset:2720
	ds_write_b32 v13, v139 offset:2992
	global_store_dword v12, v136, s[16:17] offset:0
	global_store_dword v12, v137, s[16:17] offset:256
	global_store_dword v12, v138, s[16:17] offset:512
	global_store_dword v12, v139, s[16:17] offset:768
	s_waitcnt lgkmcnt(0)
	s_barrier
; #define LAS __attribute__((address_space(3)))
; __device__ __forceinline__ void scan_combine(LAS unsigned char* lds, CArgsP a) {
;     ...
;     for (int g = 1; g <= GL; ++g) {
;         const bool pf = (g + 2 <= GL);
;         float u3 = 0.f;
;         if (pf) { const f32x4* Pn = (const f32x4*)(PM + (size_t)((g + 2) * 8 + h) * 4096); pa = Pn[tid]; pb = Pn[512 + tid]; u3 = UM[((size_t)((g + 2) * 8 + h) * 64 + v) * 64 + kq]; }
;         asm volatile("s_waitcnt lgkmcnt(0)\n\ts_barrier" ::: "memory");
;         const LAS float* Pg = Pl + (g % 3) * 4096 + kq;
;         float acc0 = u1, acc1 = 0.f, acc2 = 0.f, acc3 = 0.f;
;         const int curi = __builtin_bit_cast(int, cur);
; #pragma unroll
;         for (int k = 0; k < 64; k += 4) {
;             const float s0 = __builtin_bit_cast(float, __builtin_amdgcn_readlane(curi, k)), s1 = __builtin_bit_cast(float, __builtin_amdgcn_readlane(curi, k + 1));
;             const float s2 = __builtin_bit_cast(float, __builtin_amdgcn_readlane(curi, k + 2)), s3 = __builtin_bit_cast(float, __builtin_amdgcn_readlane(curi, k + 3));
;             acc0 += s0 * Pg[(k + 0) * 64]; acc1 += s1 * Pg[(k + 1) * 64]; acc2 += s2 * Pg[(k + 2) * 64]; acc3 += s3 * Pg[(k + 3) * 64];
;         }
;         cur = (acc0 + acc1) + (acc2 + acc3);
;         SS[((size_t)((g + 1) * 8 + h) * 64 + v) * 64 + kq] = cur;
;         if (pf) { LAS float* dst = Pl + ((g + 2) % 3) * 4096; *(LAS f32x4*)(dst + 4 * tid) = pa; *(LAS f32x4*)(dst + 2048 + 4 * tid) = pb; }
;         u1 = u2; u2 = u3;
	ds_read2_b32 v[104:105], v9 offset0:0 offset1:4
	ds_read2st64_b32 v[120:121], v11 offset0:0 offset1:5
	ds_read2_b32 v[106:107], v9 offset0:8 offset1:12
	ds_read2st64_b32 v[122:123], v11 offset0:10 offset1:15
	ds_read2_b32 v[108:109], v9 offset0:16 offset1:20
	ds_read2st64_b32 v[124:125], v11 offset0:20 offset1:25
	ds_read2_b32 v[110:111], v9 offset0:24 offset1:28
	ds_read2st64_b32 v[126:127], v11 offset0:30 offset1:35
	ds_read2_b32 v[112:113], v9 offset0:32 offset1:36
	ds_read2st64_b32 v[128:129], v11 offset0:40 offset1:45
	ds_read2_b32 v[114:115], v9 offset0:40 offset1:44
	ds_read2st64_b32 v[130:131], v11 offset0:50 offset1:55
	ds_read2_b32 v[116:117], v9 offset0:48 offset1:52
	ds_read2st64_b32 v[132:133], v11 offset0:60 offset1:65
	s_waitcnt vmcnt(56)
	s_waitcnt lgkmcnt(12)
	v_mfma_f32_16x16x4_f32 v[136:139], v104, v120, v[216:219]
	v_mfma_f32_16x16x4_f32 v[136:139], v105, v121, v[136:139]
	ds_read2_b32 v[118:119], v9 offset0:56 offset1:60
	ds_read2st64_b32 v[134:135], v11 offset0:70 offset1:75
	s_waitcnt lgkmcnt(12)
	v_mfma_f32_16x16x4_f32 v[136:139], v106, v122, v[136:139]
	v_mfma_f32_16x16x4_f32 v[136:139], v107, v123, v[136:139]
	s_waitcnt lgkmcnt(10)
	v_mfma_f32_16x16x4_f32 v[136:139], v108, v124, v[136:139]
	v_mfma_f32_16x16x4_f32 v[136:139], v109, v125, v[136:139]
	s_add_u32 s14, s6, 0x2a0000
	s_addc_u32 s15, s7, 0
	global_load_dword v216, v12, s[14:15] offset:0
	global_load_dword v217, v12, s[14:15] offset:256
	global_load_dword v218, v12, s[14:15] offset:512
	global_load_dword v219, v12, s[14:15] offset:768
	s_waitcnt lgkmcnt(8)
	v_mfma_f32_16x16x4_f32 v[136:139], v110, v126, v[136:139]
	v_mfma_f32_16x16x4_f32 v[136:139], v111, v127, v[136:139]
	s_waitcnt lgkmcnt(6)
	v_mfma_f32_16x16x4_f32 v[136:139], v112, v128, v[136:139]
	v_mfma_f32_16x16x4_f32 v[136:139], v113, v129, v[136:139]
	s_waitcnt vmcnt(58)
	ds_write_b128 v2, v[84:87] offset:0
	ds_write_b128 v2, v[88:91] offset:10240
	s_add_u32 s10, s0, 0x2c0000
	s_addc_u32 s11, s1, 0
	global_load_dwordx4 v[84:87], v0, s[10:11]
	global_load_dwordx4 v[88:91], v1, s[10:11]
	s_waitcnt lgkmcnt(6)
	v_mfma_f32_16x16x4_f32 v[136:139], v114, v130, v[136:139]
	v_mfma_f32_16x16x4_f32 v[136:139], v115, v131, v[136:139]
	s_waitcnt lgkmcnt(4)
	v_mfma_f32_16x16x4_f32 v[136:139], v116, v132, v[136:139]
	v_mfma_f32_16x16x4_f32 v[136:139], v117, v133, v[136:139]
	s_waitcnt lgkmcnt(2)
	v_mfma_f32_16x16x4_f32 v[136:139], v118, v134, v[136:139]
	v_mfma_f32_16x16x4_f32 v[136:139], v119, v135, v[136:139]
	s_add_u32 s16, s8, 0x200000
	s_addc_u32 s17, s9, 0
	s_nop 9
	ds_write_b32 v13, v136 offset:0
	ds_write_b32 v13, v137 offset:272
	ds_write_b32 v13, v138 offset:544
	ds_write_b32 v13, v139 offset:816
	global_store_dword v12, v136, s[16:17] offset:0
	global_store_dword v12, v137, s[16:17] offset:256
	global_store_dword v12, v138, s[16:17] offset:512
	global_store_dword v12, v139, s[16:17] offset:768
	s_waitcnt lgkmcnt(0)
	s_barrier
	ds_read2_b32 v[104:105], v8 offset0:0 offset1:4
	ds_read2st64_b32 v[120:121], v10 offset0:0 offset1:5
	ds_read2_b32 v[106:107], v8 offset0:8 offset1:12
	ds_read2st64_b32 v[122:123], v10 offset0:10 offset1:15
	ds_read2_b32 v[108:109], v8 offset0:16 offset1:20
	ds_read2st64_b32 v[124:125], v10 offset0:20 offset1:25
	ds_read2_b32 v[110:111], v8 offset0:24 offset1:28
	ds_read2st64_b32 v[126:127], v10 offset0:30 offset1:35
	ds_read2_b32 v[112:113], v8 offset0:32 offset1:36
	ds_read2st64_b32 v[128:129], v10 offset0:40 offset1:45
	ds_read2_b32 v[114:115], v8 offset0:40 offset1:44
	ds_read2st64_b32 v[130:131], v10 offset0:50 offset1:55
	ds_read2_b32 v[116:117], v8 offset0:48 offset1:52
	ds_read2st64_b32 v[132:133], v10 offset0:60 offset1:65
	s_waitcnt vmcnt(56)
	s_waitcnt lgkmcnt(12)
	v_mfma_f32_16x16x4_f32 v[136:139], v104, v120, v[220:223]
	v_mfma_f32_16x16x4_f32 v[136:139], v105, v121, v[136:139]
	ds_read2_b32 v[118:119], v8 offset0:56 offset1:60
	ds_read2st64_b32 v[134:135], v10 offset0:70 offset1:75
	s_waitcnt lgkmcnt(12)
	v_mfma_f32_16x16x4_f32 v[136:139], v106, v122, v[136:139]
	v_mfma_f32_16x16x4_f32 v[136:139], v107, v123, v[136:139]
	s_waitcnt lgkmcnt(10)
	v_mfma_f32_16x16x4_f32 v[136:139], v108, v124, v[136:139]
	v_mfma_f32_16x16x4_f32 v[136:139], v109, v125, v[136:139]
	s_add_u32 s14, s6, 0x2c0000
	s_addc_u32 s15, s7, 0
	global_load_dword v220, v12, s[14:15] offset:0
	global_load_dword v221, v12, s[14:15] offset:256
	global_load_dword v222, v12, s[14:15] offset:512
	global_load_dword v223, v12, s[14:15] offset:768
	s_waitcnt lgkmcnt(8)
	v_mfma_f32_16x16x4_f32 v[136:139], v110, v126, v[136:139]
	v_mfma_f32_16x16x4_f32 v[136:139], v111, v127, v[136:139]
	s_waitcnt lgkmcnt(6)
	v_mfma_f32_16x16x4_f32 v[136:139], v112, v128, v[136:139]
	v_mfma_f32_16x16x4_f32 v[136:139], v113, v129, v[136:139]
	s_waitcnt vmcnt(58)
	ds_write_b128 v2, v[92:95] offset:20480
	ds_write_b128 v2, v[96:99] offset:30720
	s_add_u32 s10, s0, 0x2e0000
	s_addc_u32 s11, s1, 0
	global_load_dwordx4 v[92:95], v0, s[10:11]
	global_load_dwordx4 v[96:99], v1, s[10:11]
	s_waitcnt lgkmcnt(6)
	v_mfma_f32_16x16x4_f32 v[136:139], v114, v130, v[136:139]
	v_mfma_f32_16x16x4_f32 v[136:139], v115, v131, v[136:139]
	s_waitcnt lgkmcnt(4)
	v_mfma_f32_16x16x4_f32 v[136:139], v116, v132, v[136:139]
	v_mfma_f32_16x16x4_f32 v[136:139], v117, v133, v[136:139]
	s_waitcnt lgkmcnt(2)
	v_mfma_f32_16x16x4_f32 v[136:139], v118, v134, v[136:139]
	v_mfma_f32_16x16x4_f32 v[136:139], v119, v135, v[136:139]
	s_add_u32 s16, s8, 0x220000
	s_addc_u32 s17, s9, 0
	s_nop 9
	ds_write_b32 v13, v136 offset:2176
	ds_write_b32 v13, v137 offset:2448
	ds_write_b32 v13, v138 offset:2720
	ds_write_b32 v13, v139 offset:2992
	global_store_dword v12, v136, s[16:17] offset:0
	global_store_dword v12, v137, s[16:17] offset:256
	global_store_dword v12, v138, s[16:17] offset:512
	global_store_dword v12, v139, s[16:17] offset:768
	s_waitcnt lgkmcnt(0)
	s_barrier
; #define LAS __attribute__((address_space(3)))
; __device__ __forceinline__ void scan_combine(LAS unsigned char* lds, CArgsP a) {
;     ...
;     for (int g = 1; g <= GL; ++g) {
;         const bool pf = (g + 2 <= GL);
;         float u3 = 0.f;
;         if (pf) { const f32x4* Pn = (const f32x4*)(PM + (size_t)((g + 2) * 8 + h) * 4096); pa = Pn[tid]; pb = Pn[512 + tid]; u3 = UM[((size_t)((g + 2) * 8 + h) * 64 + v) * 64 + kq]; }
;         asm volatile("s_waitcnt lgkmcnt(0)\n\ts_barrier" ::: "memory");
;         const LAS float* Pg = Pl + (g % 3) * 4096 + kq;
;         float acc0 = u1, acc1 = 0.f, acc2 = 0.f, acc3 = 0.f;
;         const int curi = __builtin_bit_cast(int, cur);
; #pragma unroll
;         for (int k = 0; k < 64; k += 4) {
;             const float s0 = __builtin_bit_cast(float, __builtin_amdgcn_readlane(curi, k)), s1 = __builtin_bit_cast(float, __builtin_amdgcn_readlane(curi, k + 1));
;             const float s2 = __builtin_bit_cast(float, __builtin_amdgcn_readlane(curi, k + 2)), s3 = __builtin_bit_cast(float, __builtin_amdgcn_readlane(curi, k + 3));
;             acc0 += s0 * Pg[(k + 0) * 64]; acc1 += s1 * Pg[(k + 1) * 64]; acc2 += s2 * Pg[(k + 2) * 64]; acc3 += s3 * Pg[(k + 3) * 64];
;         }
;         cur = (acc0 + acc1) + (acc2 + acc3);
;         SS[((size_t)((g + 1) * 8 + h) * 64 + v) * 64 + kq] = cur;
;         if (pf) { LAS float* dst = Pl + ((g + 2) % 3) * 4096; *(LAS f32x4*)(dst + 4 * tid) = pa; *(LAS f32x4*)(dst + 2048 + 4 * tid) = pb; }
;         u1 = u2; u2 = u3;
	ds_read2_b32 v[104:105], v9 offset0:0 offset1:4
	ds_read2st64_b32 v[120:121], v11 offset0:0 offset1:5
	ds_read2_b32 v[106:107], v9 offset0:8 offset1:12
	ds_read2st64_b32 v[122:123], v11 offset0:10 offset1:15
	ds_read2_b32 v[108:109], v9 offset0:16 offset1:20
	ds_read2st64_b32 v[124:125], v11 offset0:20 offset1:25
	ds_read2_b32 v[110:111], v9 offset0:24 offset1:28
	ds_read2st64_b32 v[126:127], v11 offset0:30 offset1:35
	ds_read2_b32 v[112:113], v9 offset0:32 offset1:36
	ds_read2st64_b32 v[128:129], v11 offset0:40 offset1:45
	ds_read2_b32 v[114:115], v9 offset0:40 offset1:44
	ds_read2st64_b32 v[130:131], v11 offset0:50 offset1:55
	ds_read2_b32 v[116:117], v9 offset0:48 offset1:52
	ds_read2st64_b32 v[132:133], v11 offset0:60 offset1:65
	s_waitcnt vmcnt(56)
	s_waitcnt lgkmcnt(12)
	v_mfma_f32_16x16x4_f32 v[136:139], v104, v120, v[224:227]
	v_mfma_f32_16x16x4_f32 v[136:139], v105, v121, v[136:139]
	ds_read2_b32 v[118:119], v9 offset0:56 offset1:60
	ds_read2st64_b32 v[134:135], v11 offset0:70 offset1:75
	s_waitcnt lgkmcnt(12)
	v_mfma_f32_16x16x4_f32 v[136:139], v106, v122, v[136:139]
	v_mfma_f32_16x16x4_f32 v[136:139], v107, v123, v[136:139]
	s_waitcnt lgkmcnt(10)
	v_mfma_f32_16x16x4_f32 v[136:139], v108, v124, v[136:139]
	v_mfma_f32_16x16x4_f32 v[136:139], v109, v125, v[136:139]
	s_add_u32 s14, s6, 0x2e0000
	s_addc_u32 s15, s7, 0
	global_load_dword v224, v12, s[14:15] offset:0
	global_load_dword v225, v12, s[14:15] offset:256
	global_load_dword v226, v12, s[14:15] offset:512
	global_load_dword v227, v12, s[14:15] offset:768
	s_waitcnt lgkmcnt(8)
	v_mfma_f32_16x16x4_f32 v[136:139], v110, v126, v[136:139]
	v_mfma_f32_16x16x4_f32 v[136:139], v111, v127, v[136:139]
	s_waitcnt lgkmcnt(6)
	v_mfma_f32_16x16x4_f32 v[136:139], v112, v128, v[136:139]
	v_mfma_f32_16x16x4_f32 v[136:139], v113, v129, v[136:139]
	s_waitcnt vmcnt(58)
	ds_write_b128 v2, v[52:55] offset:0
	ds_write_b128 v2, v[56:59] offset:10240
	s_add_u32 s10, s0, 0x300000
	s_addc_u32 s11, s1, 0
	global_load_dwordx4 v[52:55], v0, s[10:11]
	global_load_dwordx4 v[56:59], v1, s[10:11]
	s_waitcnt lgkmcnt(6)
	v_mfma_f32_16x16x4_f32 v[136:139], v114, v130, v[136:139]
	v_mfma_f32_16x16x4_f32 v[136:139], v115, v131, v[136:139]
	s_waitcnt lgkmcnt(4)
	v_mfma_f32_16x16x4_f32 v[136:139], v116, v132, v[136:139]
	v_mfma_f32_16x16x4_f32 v[136:139], v117, v133, v[136:139]
	s_waitcnt lgkmcnt(2)
	v_mfma_f32_16x16x4_f32 v[136:139], v118, v134, v[136:139]
	v_mfma_f32_16x16x4_f32 v[136:139], v119, v135, v[136:139]
	s_add_u32 s16, s8, 0x240000
	s_addc_u32 s17, s9, 0
	s_nop 9
	ds_write_b32 v13, v136 offset:0
	ds_write_b32 v13, v137 offset:272
	ds_write_b32 v13, v138 offset:544
	ds_write_b32 v13, v139 offset:816
	global_store_dword v12, v136, s[16:17] offset:0
	global_store_dword v12, v137, s[16:17] offset:256
	global_store_dword v12, v138, s[16:17] offset:512
	global_store_dword v12, v139, s[16:17] offset:768
	s_waitcnt lgkmcnt(0)
	s_barrier
	ds_read2_b32 v[104:105], v8 offset0:0 offset1:4
	ds_read2st64_b32 v[120:121], v10 offset0:0 offset1:5
	ds_read2_b32 v[106:107], v8 offset0:8 offset1:12
	ds_read2st64_b32 v[122:123], v10 offset0:10 offset1:15
	ds_read2_b32 v[108:109], v8 offset0:16 offset1:20
	ds_read2st64_b32 v[124:125], v10 offset0:20 offset1:25
	ds_read2_b32 v[110:111], v8 offset0:24 offset1:28
	ds_read2st64_b32 v[126:127], v10 offset0:30 offset1:35
	ds_read2_b32 v[112:113], v8 offset0:32 offset1:36
	ds_read2st64_b32 v[128:129], v10 offset0:40 offset1:45
	ds_read2_b32 v[114:115], v8 offset0:40 offset1:44
	ds_read2st64_b32 v[130:131], v10 offset0:50 offset1:55
	ds_read2_b32 v[116:117], v8 offset0:48 offset1:52
	ds_read2st64_b32 v[132:133], v10 offset0:60 offset1:65
	s_waitcnt vmcnt(56)
	s_waitcnt lgkmcnt(12)
	v_mfma_f32_16x16x4_f32 v[136:139], v104, v120, v[204:207]
	v_mfma_f32_16x16x4_f32 v[136:139], v105, v121, v[136:139]
	ds_read2_b32 v[118:119], v8 offset0:56 offset1:60
	ds_read2st64_b32 v[134:135], v10 offset0:70 offset1:75
	s_waitcnt lgkmcnt(12)
	v_mfma_f32_16x16x4_f32 v[136:139], v106, v122, v[136:139]
	v_mfma_f32_16x16x4_f32 v[136:139], v107, v123, v[136:139]
	s_waitcnt lgkmcnt(10)
	v_mfma_f32_16x16x4_f32 v[136:139], v108, v124, v[136:139]
	v_mfma_f32_16x16x4_f32 v[136:139], v109, v125, v[136:139]
	s_add_u32 s14, s6, 0x300000
	s_addc_u32 s15, s7, 0
	global_load_dword v204, v12, s[14:15] offset:0
	global_load_dword v205, v12, s[14:15] offset:256
	global_load_dword v206, v12, s[14:15] offset:512
	global_load_dword v207, v12, s[14:15] offset:768
	s_waitcnt lgkmcnt(8)
	v_mfma_f32_16x16x4_f32 v[136:139], v110, v126, v[136:139]
	v_mfma_f32_16x16x4_f32 v[136:139], v111, v127, v[136:139]
	s_waitcnt lgkmcnt(6)
	v_mfma_f32_16x16x4_f32 v[136:139], v112, v128, v[136:139]
	v_mfma_f32_16x16x4_f32 v[136:139], v113, v129, v[136:139]
	s_waitcnt vmcnt(58)
	ds_write_b128 v2, v[60:63] offset:20480
	ds_write_b128 v2, v[64:67] offset:30720
	s_add_u32 s10, s0, 0x320000
	s_addc_u32 s11, s1, 0
	global_load_dwordx4 v[60:63], v0, s[10:11]
	global_load_dwordx4 v[64:67], v1, s[10:11]
	s_waitcnt lgkmcnt(6)
	v_mfma_f32_16x16x4_f32 v[136:139], v114, v130, v[136:139]
	v_mfma_f32_16x16x4_f32 v[136:139], v115, v131, v[136:139]
	s_waitcnt lgkmcnt(4)
	v_mfma_f32_16x16x4_f32 v[136:139], v116, v132, v[136:139]
	v_mfma_f32_16x16x4_f32 v[136:139], v117, v133, v[136:139]
	s_waitcnt lgkmcnt(2)
	v_mfma_f32_16x16x4_f32 v[136:139], v118, v134, v[136:139]
	v_mfma_f32_16x16x4_f32 v[136:139], v119, v135, v[136:139]
	s_add_u32 s16, s8, 0x260000
	s_addc_u32 s17, s9, 0
	s_nop 9
	ds_write_b32 v13, v136 offset:2176
	ds_write_b32 v13, v137 offset:2448
	ds_write_b32 v13, v138 offset:2720
	ds_write_b32 v13, v139 offset:2992
	global_store_dword v12, v136, s[16:17] offset:0
	global_store_dword v12, v137, s[16:17] offset:256
	global_store_dword v12, v138, s[16:17] offset:512
	global_store_dword v12, v139, s[16:17] offset:768
	s_waitcnt lgkmcnt(0)
	s_barrier
; #define LAS __attribute__((address_space(3)))
; __device__ __forceinline__ void scan_combine(LAS unsigned char* lds, CArgsP a) {
;     ...
;     for (int g = 1; g <= GL; ++g) {
;         const bool pf = (g + 2 <= GL);
;         float u3 = 0.f;
;         if (pf) { const f32x4* Pn = (const f32x4*)(PM + (size_t)((g + 2) * 8 + h) * 4096); pa = Pn[tid]; pb = Pn[512 + tid]; u3 = UM[((size_t)((g + 2) * 8 + h) * 64 + v) * 64 + kq]; }
;         asm volatile("s_waitcnt lgkmcnt(0)\n\ts_barrier" ::: "memory");
;         const LAS float* Pg = Pl + (g % 3) * 4096 + kq;
;         float acc0 = u1, acc1 = 0.f, acc2 = 0.f, acc3 = 0.f;
;         const int curi = __builtin_bit_cast(int, cur);
; #pragma unroll
;         for (int k = 0; k < 64; k += 4) {
;             const float s0 = __builtin_bit_cast(float, __builtin_amdgcn_readlane(curi, k)), s1 = __builtin_bit_cast(float, __builtin_amdgcn_readlane(curi, k + 1));
;             const float s2 = __builtin_bit_cast(float, __builtin_amdgcn_readlane(curi, k + 2)), s3 = __builtin_bit_cast(float, __builtin_amdgcn_readlane(curi, k + 3));
;             acc0 += s0 * Pg[(k + 0) * 64]; acc1 += s1 * Pg[(k + 1) * 64]; acc2 += s2 * Pg[(k + 2) * 64]; acc3 += s3 * Pg[(k + 3) * 64];
;         }
;         cur = (acc0 + acc1) + (acc2 + acc3);
;         SS[((size_t)((g + 1) * 8 + h) * 64 + v) * 64 + kq] = cur;
;         if (pf) { LAS float* dst = Pl + ((g + 2) % 3) * 4096; *(LAS f32x4*)(dst + 4 * tid) = pa; *(LAS f32x4*)(dst + 2048 + 4 * tid) = pb; }
;         u1 = u2; u2 = u3;
	ds_read2_b32 v[104:105], v9 offset0:0 offset1:4
	ds_read2st64_b32 v[120:121], v11 offset0:0 offset1:5
	ds_read2_b32 v[106:107], v9 offset0:8 offset1:12
	ds_read2st64_b32 v[122:123], v11 offset0:10 offset1:15
	ds_read2_b32 v[108:109], v9 offset0:16 offset1:20
	ds_read2st64_b32 v[124:125], v11 offset0:20 offset1:25
	ds_read2_b32 v[110:111], v9 offset0:24 offset1:28
	ds_read2st64_b32 v[126:127], v11 offset0:30 offset1:35
	ds_read2_b32 v[112:113], v9 offset0:32 offset1:36
	ds_read2st64_b32 v[128:129], v11 offset0:40 offset1:45
	ds_read2_b32 v[114:115], v9 offset0:40 offset1:44
	ds_read2st64_b32 v[130:131], v11 offset0:50 offset1:55
	ds_read2_b32 v[116:117], v9 offset0:48 offset1:52
	ds_read2st64_b32 v[132:133], v11 offset0:60 offset1:65
	s_waitcnt vmcnt(56)
	s_waitcnt lgkmcnt(12)
	v_mfma_f32_16x16x4_f32 v[136:139], v104, v120, v[208:211]
	v_mfma_f32_16x16x4_f32 v[136:139], v105, v121, v[136:139]
	ds_read2_b32 v[118:119], v9 offset0:56 offset1:60
	ds_read2st64_b32 v[134:135], v11 offset0:70 offset1:75
	s_waitcnt lgkmcnt(12)
	v_mfma_f32_16x16x4_f32 v[136:139], v106, v122, v[136:139]
	v_mfma_f32_16x16x4_f32 v[136:139], v107, v123, v[136:139]
	s_waitcnt lgkmcnt(10)
	v_mfma_f32_16x16x4_f32 v[136:139], v108, v124, v[136:139]
	v_mfma_f32_16x16x4_f32 v[136:139], v109, v125, v[136:139]
	s_add_u32 s14, s6, 0x320000
	s_addc_u32 s15, s7, 0
	global_load_dword v208, v12, s[14:15] offset:0
	global_load_dword v209, v12, s[14:15] offset:256
	global_load_dword v210, v12, s[14:15] offset:512
	global_load_dword v211, v12, s[14:15] offset:768
	s_waitcnt lgkmcnt(8)
	v_mfma_f32_16x16x4_f32 v[136:139], v110, v126, v[136:139]
	v_mfma_f32_16x16x4_f32 v[136:139], v111, v127, v[136:139]
	s_waitcnt lgkmcnt(6)
	v_mfma_f32_16x16x4_f32 v[136:139], v112, v128, v[136:139]
	v_mfma_f32_16x16x4_f32 v[136:139], v113, v129, v[136:139]
	s_waitcnt vmcnt(58)
	ds_write_b128 v2, v[68:71] offset:0
	ds_write_b128 v2, v[72:75] offset:10240
	s_add_u32 s10, s0, 0x340000
	s_addc_u32 s11, s1, 0
	global_load_dwordx4 v[68:71], v0, s[10:11]
	global_load_dwordx4 v[72:75], v1, s[10:11]
	s_waitcnt lgkmcnt(6)
	v_mfma_f32_16x16x4_f32 v[136:139], v114, v130, v[136:139]
	v_mfma_f32_16x16x4_f32 v[136:139], v115, v131, v[136:139]
	s_waitcnt lgkmcnt(4)
	v_mfma_f32_16x16x4_f32 v[136:139], v116, v132, v[136:139]
	v_mfma_f32_16x16x4_f32 v[136:139], v117, v133, v[136:139]
	s_waitcnt lgkmcnt(2)
	v_mfma_f32_16x16x4_f32 v[136:139], v118, v134, v[136:139]
	v_mfma_f32_16x16x4_f32 v[136:139], v119, v135, v[136:139]
	s_add_u32 s16, s8, 0x280000
	s_addc_u32 s17, s9, 0
	s_nop 9
	ds_write_b32 v13, v136 offset:0
	ds_write_b32 v13, v137 offset:272
	ds_write_b32 v13, v138 offset:544
	ds_write_b32 v13, v139 offset:816
	global_store_dword v12, v136, s[16:17] offset:0
	global_store_dword v12, v137, s[16:17] offset:256
	global_store_dword v12, v138, s[16:17] offset:512
	global_store_dword v12, v139, s[16:17] offset:768
	s_waitcnt lgkmcnt(0)
	s_barrier
	ds_read2_b32 v[104:105], v8 offset0:0 offset1:4
	ds_read2st64_b32 v[120:121], v10 offset0:0 offset1:5
	ds_read2_b32 v[106:107], v8 offset0:8 offset1:12
	ds_read2st64_b32 v[122:123], v10 offset0:10 offset1:15
	ds_read2_b32 v[108:109], v8 offset0:16 offset1:20
	ds_read2st64_b32 v[124:125], v10 offset0:20 offset1:25
	ds_read2_b32 v[110:111], v8 offset0:24 offset1:28
	ds_read2st64_b32 v[126:127], v10 offset0:30 offset1:35
	ds_read2_b32 v[112:113], v8 offset0:32 offset1:36
	ds_read2st64_b32 v[128:129], v10 offset0:40 offset1:45
	ds_read2_b32 v[114:115], v8 offset0:40 offset1:44
	ds_read2st64_b32 v[130:131], v10 offset0:50 offset1:55
	ds_read2_b32 v[116:117], v8 offset0:48 offset1:52
	ds_read2st64_b32 v[132:133], v10 offset0:60 offset1:65
	s_waitcnt vmcnt(56)
	s_waitcnt lgkmcnt(12)
	v_mfma_f32_16x16x4_f32 v[136:139], v104, v120, v[212:215]
	v_mfma_f32_16x16x4_f32 v[136:139], v105, v121, v[136:139]
	ds_read2_b32 v[118:119], v8 offset0:56 offset1:60
	ds_read2st64_b32 v[134:135], v10 offset0:70 offset1:75
	s_waitcnt lgkmcnt(12)
	v_mfma_f32_16x16x4_f32 v[136:139], v106, v122, v[136:139]
	v_mfma_f32_16x16x4_f32 v[136:139], v107, v123, v[136:139]
	s_waitcnt lgkmcnt(10)
	v_mfma_f32_16x16x4_f32 v[136:139], v108, v124, v[136:139]
	v_mfma_f32_16x16x4_f32 v[136:139], v109, v125, v[136:139]
	s_add_u32 s14, s6, 0x340000
	s_addc_u32 s15, s7, 0
	global_load_dword v212, v12, s[14:15] offset:0
	global_load_dword v213, v12, s[14:15] offset:256
	global_load_dword v214, v12, s[14:15] offset:512
	global_load_dword v215, v12, s[14:15] offset:768
	s_waitcnt lgkmcnt(8)
	v_mfma_f32_16x16x4_f32 v[136:139], v110, v126, v[136:139]
	v_mfma_f32_16x16x4_f32 v[136:139], v111, v127, v[136:139]
	s_waitcnt lgkmcnt(6)
	v_mfma_f32_16x16x4_f32 v[136:139], v112, v128, v[136:139]
	v_mfma_f32_16x16x4_f32 v[136:139], v113, v129, v[136:139]
	s_waitcnt vmcnt(58)
	ds_write_b128 v2, v[76:79] offset:20480
	ds_write_b128 v2, v[80:83] offset:30720
	s_add_u32 s10, s0, 0x360000
	s_addc_u32 s11, s1, 0
	global_load_dwordx4 v[76:79], v0, s[10:11]
	global_load_dwordx4 v[80:83], v1, s[10:11]
	s_waitcnt lgkmcnt(6)
	v_mfma_f32_16x16x4_f32 v[136:139], v114, v130, v[136:139]
	v_mfma_f32_16x16x4_f32 v[136:139], v115, v131, v[136:139]
	s_waitcnt lgkmcnt(4)
	v_mfma_f32_16x16x4_f32 v[136:139], v116, v132, v[136:139]
	v_mfma_f32_16x16x4_f32 v[136:139], v117, v133, v[136:139]
	s_waitcnt lgkmcnt(2)
	v_mfma_f32_16x16x4_f32 v[136:139], v118, v134, v[136:139]
	v_mfma_f32_16x16x4_f32 v[136:139], v119, v135, v[136:139]
	s_add_u32 s16, s8, 0x2a0000
	s_addc_u32 s17, s9, 0
	s_nop 9
	ds_write_b32 v13, v136 offset:2176
	ds_write_b32 v13, v137 offset:2448
	ds_write_b32 v13, v138 offset:2720
	ds_write_b32 v13, v139 offset:2992
	global_store_dword v12, v136, s[16:17] offset:0
	global_store_dword v12, v137, s[16:17] offset:256
	global_store_dword v12, v138, s[16:17] offset:512
	global_store_dword v12, v139, s[16:17] offset:768
	s_waitcnt lgkmcnt(0)
	s_barrier
; #define LAS __attribute__((address_space(3)))
; __device__ __forceinline__ void scan_combine(LAS unsigned char* lds, CArgsP a) {
;     ...
;     for (int g = 1; g <= GL; ++g) {
;         const bool pf = (g + 2 <= GL);
;         float u3 = 0.f;
;         if (pf) { const f32x4* Pn = (const f32x4*)(PM + (size_t)((g + 2) * 8 + h) * 4096); pa = Pn[tid]; pb = Pn[512 + tid]; u3 = UM[((size_t)((g + 2) * 8 + h) * 64 + v) * 64 + kq]; }
;         asm volatile("s_waitcnt lgkmcnt(0)\n\ts_barrier" ::: "memory");
;         const LAS float* Pg = Pl + (g % 3) * 4096 + kq;
;         float acc0 = u1, acc1 = 0.f, acc2 = 0.f, acc3 = 0.f;
;         const int curi = __builtin_bit_cast(int, cur);
; #pragma unroll
;         for (int k = 0; k < 64; k += 4) {
;             const float s0 = __builtin_bit_cast(float, __builtin_amdgcn_readlane(curi, k)), s1 = __builtin_bit_cast(float, __builtin_amdgcn_readlane(curi, k + 1));
;             const float s2 = __builtin_bit_cast(float, __builtin_amdgcn_readlane(curi, k + 2)), s3 = __builtin_bit_cast(float, __builtin_amdgcn_readlane(curi, k + 3));
;             acc0 += s0 * Pg[(k + 0) * 64]; acc1 += s1 * Pg[(k + 1) * 64]; acc2 += s2 * Pg[(k + 2) * 64]; acc3 += s3 * Pg[(k + 3) * 64];
;         }
;         cur = (acc0 + acc1) + (acc2 + acc3);
;         SS[((size_t)((g + 1) * 8 + h) * 64 + v) * 64 + kq] = cur;
;         if (pf) { LAS float* dst = Pl + ((g + 2) % 3) * 4096; *(LAS f32x4*)(dst + 4 * tid) = pa; *(LAS f32x4*)(dst + 2048 + 4 * tid) = pb; }
;         u1 = u2; u2 = u3;
	ds_read2_b32 v[104:105], v9 offset0:0 offset1:4
	ds_read2st64_b32 v[120:121], v11 offset0:0 offset1:5
	ds_read2_b32 v[106:107], v9 offset0:8 offset1:12
	ds_read2st64_b32 v[122:123], v11 offset0:10 offset1:15
	ds_read2_b32 v[108:109], v9 offset0:16 offset1:20
	ds_read2st64_b32 v[124:125], v11 offset0:20 offset1:25
	ds_read2_b32 v[110:111], v9 offset0:24 offset1:28
	ds_read2st64_b32 v[126:127], v11 offset0:30 offset1:35
	ds_read2_b32 v[112:113], v9 offset0:32 offset1:36
	ds_read2st64_b32 v[128:129], v11 offset0:40 offset1:45
	ds_read2_b32 v[114:115], v9 offset0:40 offset1:44
	ds_read2st64_b32 v[130:131], v11 offset0:50 offset1:55
	ds_read2_b32 v[116:117], v9 offset0:48 offset1:52
	ds_read2st64_b32 v[132:133], v11 offset0:60 offset1:65
	s_waitcnt vmcnt(56)
	s_waitcnt lgkmcnt(12)
	v_mfma_f32_16x16x4_f32 v[136:139], v104, v120, v[216:219]
	v_mfma_f32_16x16x4_f32 v[136:139], v105, v121, v[136:139]
	ds_read2_b32 v[118:119], v9 offset0:56 offset1:60
	ds_read2st64_b32 v[134:135], v11 offset0:70 offset1:75
	s_waitcnt lgkmcnt(12)
	v_mfma_f32_16x16x4_f32 v[136:139], v106, v122, v[136:139]
	v_mfma_f32_16x16x4_f32 v[136:139], v107, v123, v[136:139]
	s_waitcnt lgkmcnt(10)
	v_mfma_f32_16x16x4_f32 v[136:139], v108, v124, v[136:139]
	v_mfma_f32_16x16x4_f32 v[136:139], v109, v125, v[136:139]
	s_add_u32 s14, s6, 0x360000
	s_addc_u32 s15, s7, 0
	global_load_dword v216, v12, s[14:15] offset:0
	global_load_dword v217, v12, s[14:15] offset:256
	global_load_dword v218, v12, s[14:15] offset:512
	global_load_dword v219, v12, s[14:15] offset:768
	s_waitcnt lgkmcnt(8)
	v_mfma_f32_16x16x4_f32 v[136:139], v110, v126, v[136:139]
	v_mfma_f32_16x16x4_f32 v[136:139], v111, v127, v[136:139]
	s_waitcnt lgkmcnt(6)
	v_mfma_f32_16x16x4_f32 v[136:139], v112, v128, v[136:139]
	v_mfma_f32_16x16x4_f32 v[136:139], v113, v129, v[136:139]
	s_waitcnt vmcnt(58)
	ds_write_b128 v2, v[84:87] offset:0
	ds_write_b128 v2, v[88:91] offset:10240
	s_add_u32 s10, s0, 0x380000
	s_addc_u32 s11, s1, 0
	global_load_dwordx4 v[84:87], v0, s[10:11]
	global_load_dwordx4 v[88:91], v1, s[10:11]
	s_waitcnt lgkmcnt(6)
	v_mfma_f32_16x16x4_f32 v[136:139], v114, v130, v[136:139]
	v_mfma_f32_16x16x4_f32 v[136:139], v115, v131, v[136:139]
	s_waitcnt lgkmcnt(4)
	v_mfma_f32_16x16x4_f32 v[136:139], v116, v132, v[136:139]
	v_mfma_f32_16x16x4_f32 v[136:139], v117, v133, v[136:139]
	s_waitcnt lgkmcnt(2)
	v_mfma_f32_16x16x4_f32 v[136:139], v118, v134, v[136:139]
	v_mfma_f32_16x16x4_f32 v[136:139], v119, v135, v[136:139]
	s_add_u32 s16, s8, 0x2c0000
	s_addc_u32 s17, s9, 0
	s_nop 9
	ds_write_b32 v13, v136 offset:0
	ds_write_b32 v13, v137 offset:272
	ds_write_b32 v13, v138 offset:544
	ds_write_b32 v13, v139 offset:816
	global_store_dword v12, v136, s[16:17] offset:0
	global_store_dword v12, v137, s[16:17] offset:256
	global_store_dword v12, v138, s[16:17] offset:512
	global_store_dword v12, v139, s[16:17] offset:768
	s_waitcnt lgkmcnt(0)
	s_barrier
	ds_read2_b32 v[104:105], v8 offset0:0 offset1:4
	ds_read2st64_b32 v[120:121], v10 offset0:0 offset1:5
	ds_read2_b32 v[106:107], v8 offset0:8 offset1:12
	ds_read2st64_b32 v[122:123], v10 offset0:10 offset1:15
	ds_read2_b32 v[108:109], v8 offset0:16 offset1:20
	ds_read2st64_b32 v[124:125], v10 offset0:20 offset1:25
	ds_read2_b32 v[110:111], v8 offset0:24 offset1:28
	ds_read2st64_b32 v[126:127], v10 offset0:30 offset1:35
	ds_read2_b32 v[112:113], v8 offset0:32 offset1:36
	ds_read2st64_b32 v[128:129], v10 offset0:40 offset1:45
	ds_read2_b32 v[114:115], v8 offset0:40 offset1:44
	ds_read2st64_b32 v[130:131], v10 offset0:50 offset1:55
	ds_read2_b32 v[116:117], v8 offset0:48 offset1:52
	ds_read2st64_b32 v[132:133], v10 offset0:60 offset1:65
	s_waitcnt vmcnt(56)
	s_waitcnt lgkmcnt(12)
	v_mfma_f32_16x16x4_f32 v[136:139], v104, v120, v[220:223]
	v_mfma_f32_16x16x4_f32 v[136:139], v105, v121, v[136:139]
	ds_read2_b32 v[118:119], v8 offset0:56 offset1:60
	ds_read2st64_b32 v[134:135], v10 offset0:70 offset1:75
	s_waitcnt lgkmcnt(12)
	v_mfma_f32_16x16x4_f32 v[136:139], v106, v122, v[136:139]
	v_mfma_f32_16x16x4_f32 v[136:139], v107, v123, v[136:139]
	s_waitcnt lgkmcnt(10)
	v_mfma_f32_16x16x4_f32 v[136:139], v108, v124, v[136:139]
	v_mfma_f32_16x16x4_f32 v[136:139], v109, v125, v[136:139]
	s_add_u32 s14, s6, 0x380000
	s_addc_u32 s15, s7, 0
	global_load_dword v220, v12, s[14:15] offset:0
	global_load_dword v221, v12, s[14:15] offset:256
	global_load_dword v222, v12, s[14:15] offset:512
	global_load_dword v223, v12, s[14:15] offset:768
	s_waitcnt lgkmcnt(8)
	v_mfma_f32_16x16x4_f32 v[136:139], v110, v126, v[136:139]
	v_mfma_f32_16x16x4_f32 v[136:139], v111, v127, v[136:139]
	s_waitcnt lgkmcnt(6)
	v_mfma_f32_16x16x4_f32 v[136:139], v112, v128, v[136:139]
	v_mfma_f32_16x16x4_f32 v[136:139], v113, v129, v[136:139]
	s_waitcnt vmcnt(58)
	ds_write_b128 v2, v[92:95] offset:20480
	ds_write_b128 v2, v[96:99] offset:30720
	s_add_u32 s10, s0, 0x3a0000
	s_addc_u32 s11, s1, 0
	global_load_dwordx4 v[92:95], v0, s[10:11]
	global_load_dwordx4 v[96:99], v1, s[10:11]
	s_waitcnt lgkmcnt(6)
	v_mfma_f32_16x16x4_f32 v[136:139], v114, v130, v[136:139]
	v_mfma_f32_16x16x4_f32 v[136:139], v115, v131, v[136:139]
	s_waitcnt lgkmcnt(4)
	v_mfma_f32_16x16x4_f32 v[136:139], v116, v132, v[136:139]
	v_mfma_f32_16x16x4_f32 v[136:139], v117, v133, v[136:139]
	s_waitcnt lgkmcnt(2)
	v_mfma_f32_16x16x4_f32 v[136:139], v118, v134, v[136:139]
	v_mfma_f32_16x16x4_f32 v[136:139], v119, v135, v[136:139]
	s_add_u32 s16, s8, 0x2e0000
	s_addc_u32 s17, s9, 0
	s_nop 9
	ds_write_b32 v13, v136 offset:2176
	ds_write_b32 v13, v137 offset:2448
	ds_write_b32 v13, v138 offset:2720
	ds_write_b32 v13, v139 offset:2992
	global_store_dword v12, v136, s[16:17] offset:0
	global_store_dword v12, v137, s[16:17] offset:256
	global_store_dword v12, v138, s[16:17] offset:512
	global_store_dword v12, v139, s[16:17] offset:768
	s_waitcnt lgkmcnt(0)
	s_barrier
; #define LAS __attribute__((address_space(3)))
; __device__ __forceinline__ void scan_combine(LAS unsigned char* lds, CArgsP a) {
;     ...
;     for (int g = 1; g <= GL; ++g) {
;         const bool pf = (g + 2 <= GL);
;         float u3 = 0.f;
;         if (pf) { const f32x4* Pn = (const f32x4*)(PM + (size_t)((g + 2) * 8 + h) * 4096); pa = Pn[tid]; pb = Pn[512 + tid]; u3 = UM[((size_t)((g + 2) * 8 + h) * 64 + v) * 64 + kq]; }
;         asm volatile("s_waitcnt lgkmcnt(0)\n\ts_barrier" ::: "memory");
;         const LAS float* Pg = Pl + (g % 3) * 4096 + kq;
;         float acc0 = u1, acc1 = 0.f, acc2 = 0.f, acc3 = 0.f;
;         const int curi = __builtin_bit_cast(int, cur);
; #pragma unroll
;         for (int k = 0; k < 64; k += 4) {
;             const float s0 = __builtin_bit_cast(float, __builtin_amdgcn_readlane(curi, k)), s1 = __builtin_bit_cast(float, __builtin_amdgcn_readlane(curi, k + 1));
;             const float s2 = __builtin_bit_cast(float, __builtin_amdgcn_readlane(curi, k + 2)), s3 = __builtin_bit_cast(float, __builtin_amdgcn_readlane(curi, k + 3));
;             acc0 += s0 * Pg[(k + 0) * 64]; acc1 += s1 * Pg[(k + 1) * 64]; acc2 += s2 * Pg[(k + 2) * 64]; acc3 += s3 * Pg[(k + 3) * 64];
;         }
;         cur = (acc0 + acc1) + (acc2 + acc3);
;         SS[((size_t)((g + 1) * 8 + h) * 64 + v) * 64 + kq] = cur;
;         if (pf) { LAS float* dst = Pl + ((g + 2) % 3) * 4096; *(LAS f32x4*)(dst + 4 * tid) = pa; *(LAS f32x4*)(dst + 2048 + 4 * tid) = pb; }
;         u1 = u2; u2 = u3;
	ds_read2_b32 v[104:105], v9 offset0:0 offset1:4
	ds_read2st64_b32 v[120:121], v11 offset0:0 offset1:5
	ds_read2_b32 v[106:107], v9 offset0:8 offset1:12
	ds_read2st64_b32 v[122:123], v11 offset0:10 offset1:15
	ds_read2_b32 v[108:109], v9 offset0:16 offset1:20
	ds_read2st64_b32 v[124:125], v11 offset0:20 offset1:25
	ds_read2_b32 v[110:111], v9 offset0:24 offset1:28
	ds_read2st64_b32 v[126:127], v11 offset0:30 offset1:35
	ds_read2_b32 v[112:113], v9 offset0:32 offset1:36
	ds_read2st64_b32 v[128:129], v11 offset0:40 offset1:45
	ds_read2_b32 v[114:115], v9 offset0:40 offset1:44
	ds_read2st64_b32 v[130:131], v11 offset0:50 offset1:55
	ds_read2_b32 v[116:117], v9 offset0:48 offset1:52
	ds_read2st64_b32 v[132:133], v11 offset0:60 offset1:65
	s_waitcnt vmcnt(56)
	s_waitcnt lgkmcnt(12)
	v_mfma_f32_16x16x4_f32 v[136:139], v104, v120, v[224:227]
	v_mfma_f32_16x16x4_f32 v[136:139], v105, v121, v[136:139]
	ds_read2_b32 v[118:119], v9 offset0:56 offset1:60
	ds_read2st64_b32 v[134:135], v11 offset0:70 offset1:75
	s_waitcnt lgkmcnt(12)
	v_mfma_f32_16x16x4_f32 v[136:139], v106, v122, v[136:139]
	v_mfma_f32_16x16x4_f32 v[136:139], v107, v123, v[136:139]
	s_waitcnt lgkmcnt(10)
	v_mfma_f32_16x16x4_f32 v[136:139], v108, v124, v[136:139]
	v_mfma_f32_16x16x4_f32 v[136:139], v109, v125, v[136:139]
	s_add_u32 s14, s6, 0x3a0000
	s_addc_u32 s15, s7, 0
	global_load_dword v224, v12, s[14:15] offset:0
	global_load_dword v225, v12, s[14:15] offset:256
	global_load_dword v226, v12, s[14:15] offset:512
	global_load_dword v227, v12, s[14:15] offset:768
	s_waitcnt lgkmcnt(8)
	v_mfma_f32_16x16x4_f32 v[136:139], v110, v126, v[136:139]
	v_mfma_f32_16x16x4_f32 v[136:139], v111, v127, v[136:139]
	s_waitcnt lgkmcnt(6)
	v_mfma_f32_16x16x4_f32 v[136:139], v112, v128, v[136:139]
	v_mfma_f32_16x16x4_f32 v[136:139], v113, v129, v[136:139]
	s_waitcnt vmcnt(58)
	ds_write_b128 v2, v[52:55] offset:0
	ds_write_b128 v2, v[56:59] offset:10240
	s_add_u32 s10, s0, 0x3c0000
	s_addc_u32 s11, s1, 0
	global_load_dwordx4 v[52:55], v0, s[10:11]
	global_load_dwordx4 v[56:59], v1, s[10:11]
	s_waitcnt lgkmcnt(6)
	v_mfma_f32_16x16x4_f32 v[136:139], v114, v130, v[136:139]
	v_mfma_f32_16x16x4_f32 v[136:139], v115, v131, v[136:139]
	s_waitcnt lgkmcnt(4)
	v_mfma_f32_16x16x4_f32 v[136:139], v116, v132, v[136:139]
	v_mfma_f32_16x16x4_f32 v[136:139], v117, v133, v[136:139]
	s_waitcnt lgkmcnt(2)
	v_mfma_f32_16x16x4_f32 v[136:139], v118, v134, v[136:139]
	v_mfma_f32_16x16x4_f32 v[136:139], v119, v135, v[136:139]
	s_add_u32 s16, s8, 0x300000
	s_addc_u32 s17, s9, 0
	s_nop 9
	ds_write_b32 v13, v136 offset:0
	ds_write_b32 v13, v137 offset:272
	ds_write_b32 v13, v138 offset:544
	ds_write_b32 v13, v139 offset:816
	global_store_dword v12, v136, s[16:17] offset:0
	global_store_dword v12, v137, s[16:17] offset:256
	global_store_dword v12, v138, s[16:17] offset:512
	global_store_dword v12, v139, s[16:17] offset:768
	s_waitcnt lgkmcnt(0)
	s_barrier
	ds_read2_b32 v[104:105], v8 offset0:0 offset1:4
	ds_read2st64_b32 v[120:121], v10 offset0:0 offset1:5
	ds_read2_b32 v[106:107], v8 offset0:8 offset1:12
	ds_read2st64_b32 v[122:123], v10 offset0:10 offset1:15
	ds_read2_b32 v[108:109], v8 offset0:16 offset1:20
	ds_read2st64_b32 v[124:125], v10 offset0:20 offset1:25
	ds_read2_b32 v[110:111], v8 offset0:24 offset1:28
	ds_read2st64_b32 v[126:127], v10 offset0:30 offset1:35
	ds_read2_b32 v[112:113], v8 offset0:32 offset1:36
	ds_read2st64_b32 v[128:129], v10 offset0:40 offset1:45
	ds_read2_b32 v[114:115], v8 offset0:40 offset1:44
	ds_read2st64_b32 v[130:131], v10 offset0:50 offset1:55
	ds_read2_b32 v[116:117], v8 offset0:48 offset1:52
	ds_read2st64_b32 v[132:133], v10 offset0:60 offset1:65
	s_waitcnt vmcnt(56)
	s_waitcnt lgkmcnt(12)
	v_mfma_f32_16x16x4_f32 v[136:139], v104, v120, v[204:207]
	v_mfma_f32_16x16x4_f32 v[136:139], v105, v121, v[136:139]
	ds_read2_b32 v[118:119], v8 offset0:56 offset1:60
	ds_read2st64_b32 v[134:135], v10 offset0:70 offset1:75
	s_waitcnt lgkmcnt(12)
	v_mfma_f32_16x16x4_f32 v[136:139], v106, v122, v[136:139]
	v_mfma_f32_16x16x4_f32 v[136:139], v107, v123, v[136:139]
	s_waitcnt lgkmcnt(10)
	v_mfma_f32_16x16x4_f32 v[136:139], v108, v124, v[136:139]
	v_mfma_f32_16x16x4_f32 v[136:139], v109, v125, v[136:139]
	s_add_u32 s14, s6, 0x3c0000
	s_addc_u32 s15, s7, 0
	global_load_dword v204, v12, s[14:15] offset:0
	global_load_dword v205, v12, s[14:15] offset:256
	global_load_dword v206, v12, s[14:15] offset:512
	global_load_dword v207, v12, s[14:15] offset:768
	s_waitcnt lgkmcnt(8)
	v_mfma_f32_16x16x4_f32 v[136:139], v110, v126, v[136:139]
	v_mfma_f32_16x16x4_f32 v[136:139], v111, v127, v[136:139]
	s_waitcnt lgkmcnt(6)
	v_mfma_f32_16x16x4_f32 v[136:139], v112, v128, v[136:139]
	v_mfma_f32_16x16x4_f32 v[136:139], v113, v129, v[136:139]
	s_waitcnt vmcnt(58)
	ds_write_b128 v2, v[60:63] offset:20480
	ds_write_b128 v2, v[64:67] offset:30720
	s_add_u32 s10, s0, 0x3e0000
	s_addc_u32 s11, s1, 0
	global_load_dwordx4 v[60:63], v0, s[10:11]
	global_load_dwordx4 v[64:67], v1, s[10:11]
	s_waitcnt lgkmcnt(6)
	v_mfma_f32_16x16x4_f32 v[136:139], v114, v130, v[136:139]
	v_mfma_f32_16x16x4_f32 v[136:139], v115, v131, v[136:139]
	s_waitcnt lgkmcnt(4)
	v_mfma_f32_16x16x4_f32 v[136:139], v116, v132, v[136:139]
	v_mfma_f32_16x16x4_f32 v[136:139], v117, v133, v[136:139]
	s_waitcnt lgkmcnt(2)
	v_mfma_f32_16x16x4_f32 v[136:139], v118, v134, v[136:139]
	v_mfma_f32_16x16x4_f32 v[136:139], v119, v135, v[136:139]
	s_add_u32 s16, s8, 0x320000
	s_addc_u32 s17, s9, 0
	s_nop 9
	ds_write_b32 v13, v136 offset:2176
	ds_write_b32 v13, v137 offset:2448
	ds_write_b32 v13, v138 offset:2720
	ds_write_b32 v13, v139 offset:2992
	global_store_dword v12, v136, s[16:17] offset:0
	global_store_dword v12, v137, s[16:17] offset:256
	global_store_dword v12, v138, s[16:17] offset:512
	global_store_dword v12, v139, s[16:17] offset:768
	s_waitcnt lgkmcnt(0)
	s_barrier
; #define LAS __attribute__((address_space(3)))
; __device__ __forceinline__ void scan_combine(LAS unsigned char* lds, CArgsP a) {
;     ...
;     for (int g = 1; g <= GL; ++g) {
;         const bool pf = (g + 2 <= GL);
;         float u3 = 0.f;
;         if (pf) { const f32x4* Pn = (const f32x4*)(PM + (size_t)((g + 2) * 8 + h) * 4096); pa = Pn[tid]; pb = Pn[512 + tid]; u3 = UM[((size_t)((g + 2) * 8 + h) * 64 + v) * 64 + kq]; }
;         asm volatile("s_waitcnt lgkmcnt(0)\n\ts_barrier" ::: "memory");
;         const LAS float* Pg = Pl + (g % 3) * 4096 + kq;
;         float acc0 = u1, acc1 = 0.f, acc2 = 0.f, acc3 = 0.f;
;         const int curi = __builtin_bit_cast(int, cur);
; #pragma unroll
;         for (int k = 0; k < 64; k += 4) {
;             const float s0 = __builtin_bit_cast(float, __builtin_amdgcn_readlane(curi, k)), s1 = __builtin_bit_cast(float, __builtin_amdgcn_readlane(curi, k + 1));
;             const float s2 = __builtin_bit_cast(float, __builtin_amdgcn_readlane(curi, k + 2)), s3 = __builtin_bit_cast(float, __builtin_amdgcn_readlane(curi, k + 3));
;             acc0 += s0 * Pg[(k + 0) * 64]; acc1 += s1 * Pg[(k + 1) * 64]; acc2 += s2 * Pg[(k + 2) * 64]; acc3 += s3 * Pg[(k + 3) * 64];
;         }
;         cur = (acc0 + acc1) + (acc2 + acc3);
;         SS[((size_t)((g + 1) * 8 + h) * 64 + v) * 64 + kq] = cur;
;         if (pf) { LAS float* dst = Pl + ((g + 2) % 3) * 4096; *(LAS f32x4*)(dst + 4 * tid) = pa; *(LAS f32x4*)(dst + 2048 + 4 * tid) = pb; }
;         u1 = u2; u2 = u3;
	ds_read2_b32 v[104:105], v9 offset0:0 offset1:4
	ds_read2st64_b32 v[120:121], v11 offset0:0 offset1:5
	ds_read2_b32 v[106:107], v9 offset0:8 offset1:12
	ds_read2st64_b32 v[122:123], v11 offset0:10 offset1:15
	ds_read2_b32 v[108:109], v9 offset0:16 offset1:20
	ds_read2st64_b32 v[124:125], v11 offset0:20 offset1:25
	ds_read2_b32 v[110:111], v9 offset0:24 offset1:28
	ds_read2st64_b32 v[126:127], v11 offset0:30 offset1:35
	ds_read2_b32 v[112:113], v9 offset0:32 offset1:36
	ds_read2st64_b32 v[128:129], v11 offset0:40 offset1:45
	ds_read2_b32 v[114:115], v9 offset0:40 offset1:44
	ds_read2st64_b32 v[130:131], v11 offset0:50 offset1:55
	ds_read2_b32 v[116:117], v9 offset0:48 offset1:52
	ds_read2st64_b32 v[132:133], v11 offset0:60 offset1:65
	s_waitcnt vmcnt(56)
	s_waitcnt lgkmcnt(12)
	v_mfma_f32_16x16x4_f32 v[136:139], v104, v120, v[208:211]
	v_mfma_f32_16x16x4_f32 v[136:139], v105, v121, v[136:139]
	ds_read2_b32 v[118:119], v9 offset0:56 offset1:60
	ds_read2st64_b32 v[134:135], v11 offset0:70 offset1:75
	s_waitcnt lgkmcnt(12)
	v_mfma_f32_16x16x4_f32 v[136:139], v106, v122, v[136:139]
	v_mfma_f32_16x16x4_f32 v[136:139], v107, v123, v[136:139]
	s_waitcnt lgkmcnt(10)
	v_mfma_f32_16x16x4_f32 v[136:139], v108, v124, v[136:139]
	v_mfma_f32_16x16x4_f32 v[136:139], v109, v125, v[136:139]
	s_add_u32 s14, s6, 0x3e0000
	s_addc_u32 s15, s7, 0
	global_load_dword v208, v12, s[14:15] offset:0
	global_load_dword v209, v12, s[14:15] offset:256
	global_load_dword v210, v12, s[14:15] offset:512
	global_load_dword v211, v12, s[14:15] offset:768
	s_waitcnt lgkmcnt(8)
	v_mfma_f32_16x16x4_f32 v[136:139], v110, v126, v[136:139]
	v_mfma_f32_16x16x4_f32 v[136:139], v111, v127, v[136:139]
	s_waitcnt lgkmcnt(6)
	v_mfma_f32_16x16x4_f32 v[136:139], v112, v128, v[136:139]
	v_mfma_f32_16x16x4_f32 v[136:139], v113, v129, v[136:139]
	s_waitcnt vmcnt(58)
	ds_write_b128 v2, v[68:71] offset:0
	ds_write_b128 v2, v[72:75] offset:10240
	s_add_u32 s10, s0, 0x400000
	s_addc_u32 s11, s1, 0
	global_load_dwordx4 v[68:71], v0, s[10:11]
	global_load_dwordx4 v[72:75], v1, s[10:11]
	s_waitcnt lgkmcnt(6)
	v_mfma_f32_16x16x4_f32 v[136:139], v114, v130, v[136:139]
	v_mfma_f32_16x16x4_f32 v[136:139], v115, v131, v[136:139]
	s_waitcnt lgkmcnt(4)
	v_mfma_f32_16x16x4_f32 v[136:139], v116, v132, v[136:139]
	v_mfma_f32_16x16x4_f32 v[136:139], v117, v133, v[136:139]
	s_waitcnt lgkmcnt(2)
	v_mfma_f32_16x16x4_f32 v[136:139], v118, v134, v[136:139]
	v_mfma_f32_16x16x4_f32 v[136:139], v119, v135, v[136:139]
	s_add_u32 s16, s8, 0x340000
	s_addc_u32 s17, s9, 0
	s_nop 9
	ds_write_b32 v13, v136 offset:0
	ds_write_b32 v13, v137 offset:272
	ds_write_b32 v13, v138 offset:544
	ds_write_b32 v13, v139 offset:816
	global_store_dword v12, v136, s[16:17] offset:0
	global_store_dword v12, v137, s[16:17] offset:256
	global_store_dword v12, v138, s[16:17] offset:512
	global_store_dword v12, v139, s[16:17] offset:768
	s_waitcnt lgkmcnt(0)
	s_barrier
	ds_read2_b32 v[104:105], v8 offset0:0 offset1:4
	ds_read2st64_b32 v[120:121], v10 offset0:0 offset1:5
	ds_read2_b32 v[106:107], v8 offset0:8 offset1:12
	ds_read2st64_b32 v[122:123], v10 offset0:10 offset1:15
	ds_read2_b32 v[108:109], v8 offset0:16 offset1:20
	ds_read2st64_b32 v[124:125], v10 offset0:20 offset1:25
	ds_read2_b32 v[110:111], v8 offset0:24 offset1:28
	ds_read2st64_b32 v[126:127], v10 offset0:30 offset1:35
	ds_read2_b32 v[112:113], v8 offset0:32 offset1:36
	ds_read2st64_b32 v[128:129], v10 offset0:40 offset1:45
	ds_read2_b32 v[114:115], v8 offset0:40 offset1:44
	ds_read2st64_b32 v[130:131], v10 offset0:50 offset1:55
	ds_read2_b32 v[116:117], v8 offset0:48 offset1:52
	ds_read2st64_b32 v[132:133], v10 offset0:60 offset1:65
	s_waitcnt vmcnt(56)
	s_waitcnt lgkmcnt(12)
	v_mfma_f32_16x16x4_f32 v[136:139], v104, v120, v[212:215]
	v_mfma_f32_16x16x4_f32 v[136:139], v105, v121, v[136:139]
	ds_read2_b32 v[118:119], v8 offset0:56 offset1:60
	ds_read2st64_b32 v[134:135], v10 offset0:70 offset1:75
	s_waitcnt lgkmcnt(12)
	v_mfma_f32_16x16x4_f32 v[136:139], v106, v122, v[136:139]
	v_mfma_f32_16x16x4_f32 v[136:139], v107, v123, v[136:139]
	s_waitcnt lgkmcnt(10)
	v_mfma_f32_16x16x4_f32 v[136:139], v108, v124, v[136:139]
	v_mfma_f32_16x16x4_f32 v[136:139], v109, v125, v[136:139]
	s_add_u32 s14, s6, 0x400000
	s_addc_u32 s15, s7, 0
	global_load_dword v212, v12, s[14:15] offset:0
	global_load_dword v213, v12, s[14:15] offset:256
	global_load_dword v214, v12, s[14:15] offset:512
	global_load_dword v215, v12, s[14:15] offset:768
	s_waitcnt lgkmcnt(8)
	v_mfma_f32_16x16x4_f32 v[136:139], v110, v126, v[136:139]
	v_mfma_f32_16x16x4_f32 v[136:139], v111, v127, v[136:139]
	s_waitcnt lgkmcnt(6)
	v_mfma_f32_16x16x4_f32 v[136:139], v112, v128, v[136:139]
	v_mfma_f32_16x16x4_f32 v[136:139], v113, v129, v[136:139]
	s_waitcnt vmcnt(58)
	ds_write_b128 v2, v[76:79] offset:20480
	ds_write_b128 v2, v[80:83] offset:30720
	s_add_u32 s10, s0, 0x420000
	s_addc_u32 s11, s1, 0
	global_load_dwordx4 v[76:79], v0, s[10:11]
	global_load_dwordx4 v[80:83], v1, s[10:11]
	s_waitcnt lgkmcnt(6)
	v_mfma_f32_16x16x4_f32 v[136:139], v114, v130, v[136:139]
	v_mfma_f32_16x16x4_f32 v[136:139], v115, v131, v[136:139]
	s_waitcnt lgkmcnt(4)
	v_mfma_f32_16x16x4_f32 v[136:139], v116, v132, v[136:139]
	v_mfma_f32_16x16x4_f32 v[136:139], v117, v133, v[136:139]
	s_waitcnt lgkmcnt(2)
	v_mfma_f32_16x16x4_f32 v[136:139], v118, v134, v[136:139]
	v_mfma_f32_16x16x4_f32 v[136:139], v119, v135, v[136:139]
	s_add_u32 s16, s8, 0x360000
	s_addc_u32 s17, s9, 0
	s_nop 9
	ds_write_b32 v13, v136 offset:2176
	ds_write_b32 v13, v137 offset:2448
	ds_write_b32 v13, v138 offset:2720
	ds_write_b32 v13, v139 offset:2992
	global_store_dword v12, v136, s[16:17] offset:0
	global_store_dword v12, v137, s[16:17] offset:256
	global_store_dword v12, v138, s[16:17] offset:512
	global_store_dword v12, v139, s[16:17] offset:768
	s_waitcnt lgkmcnt(0)
	s_barrier
; #define LAS __attribute__((address_space(3)))
; __device__ __forceinline__ void scan_combine(LAS unsigned char* lds, CArgsP a) {
;     ...
;     for (int g = 1; g <= GL; ++g) {
;         const bool pf = (g + 2 <= GL);
;         float u3 = 0.f;
;         if (pf) { const f32x4* Pn = (const f32x4*)(PM + (size_t)((g + 2) * 8 + h) * 4096); pa = Pn[tid]; pb = Pn[512 + tid]; u3 = UM[((size_t)((g + 2) * 8 + h) * 64 + v) * 64 + kq]; }
;         asm volatile("s_waitcnt lgkmcnt(0)\n\ts_barrier" ::: "memory");
;         const LAS float* Pg = Pl + (g % 3) * 4096 + kq;
;         float acc0 = u1, acc1 = 0.f, acc2 = 0.f, acc3 = 0.f;
;         const int curi = __builtin_bit_cast(int, cur);
; #pragma unroll
;         for (int k = 0; k < 64; k += 4) {
;             const float s0 = __builtin_bit_cast(float, __builtin_amdgcn_readlane(curi, k)), s1 = __builtin_bit_cast(float, __builtin_amdgcn_readlane(curi, k + 1));
;             const float s2 = __builtin_bit_cast(float, __builtin_amdgcn_readlane(curi, k + 2)), s3 = __builtin_bit_cast(float, __builtin_amdgcn_readlane(curi, k + 3));
;             acc0 += s0 * Pg[(k + 0) * 64]; acc1 += s1 * Pg[(k + 1) * 64]; acc2 += s2 * Pg[(k + 2) * 64]; acc3 += s3 * Pg[(k + 3) * 64];
;         }
;         cur = (acc0 + acc1) + (acc2 + acc3);
;         SS[((size_t)((g + 1) * 8 + h) * 64 + v) * 64 + kq] = cur;
;         if (pf) { LAS float* dst = Pl + ((g + 2) % 3) * 4096; *(LAS f32x4*)(dst + 4 * tid) = pa; *(LAS f32x4*)(dst + 2048 + 4 * tid) = pb; }
;         u1 = u2; u2 = u3;
	ds_read2_b32 v[104:105], v9 offset0:0 offset1:4
	ds_read2st64_b32 v[120:121], v11 offset0:0 offset1:5
	ds_read2_b32 v[106:107], v9 offset0:8 offset1:12
	ds_read2st64_b32 v[122:123], v11 offset0:10 offset1:15
	ds_read2_b32 v[108:109], v9 offset0:16 offset1:20
	ds_read2st64_b32 v[124:125], v11 offset0:20 offset1:25
	ds_read2_b32 v[110:111], v9 offset0:24 offset1:28
	ds_read2st64_b32 v[126:127], v11 offset0:30 offset1:35
	ds_read2_b32 v[112:113], v9 offset0:32 offset1:36
	ds_read2st64_b32 v[128:129], v11 offset0:40 offset1:45
	ds_read2_b32 v[114:115], v9 offset0:40 offset1:44
	ds_read2st64_b32 v[130:131], v11 offset0:50 offset1:55
	ds_read2_b32 v[116:117], v9 offset0:48 offset1:52
	ds_read2st64_b32 v[132:133], v11 offset0:60 offset1:65
	s_waitcnt vmcnt(56)
	s_waitcnt lgkmcnt(12)
	v_mfma_f32_16x16x4_f32 v[136:139], v104, v120, v[216:219]
	v_mfma_f32_16x16x4_f32 v[136:139], v105, v121, v[136:139]
	ds_read2_b32 v[118:119], v9 offset0:56 offset1:60
	ds_read2st64_b32 v[134:135], v11 offset0:70 offset1:75
	s_waitcnt lgkmcnt(12)
	v_mfma_f32_16x16x4_f32 v[136:139], v106, v122, v[136:139]
	v_mfma_f32_16x16x4_f32 v[136:139], v107, v123, v[136:139]
	s_waitcnt lgkmcnt(10)
	v_mfma_f32_16x16x4_f32 v[136:139], v108, v124, v[136:139]
	v_mfma_f32_16x16x4_f32 v[136:139], v109, v125, v[136:139]
	s_add_u32 s14, s6, 0x420000
	s_addc_u32 s15, s7, 0
	global_load_dword v216, v12, s[14:15] offset:0
	global_load_dword v217, v12, s[14:15] offset:256
	global_load_dword v218, v12, s[14:15] offset:512
	global_load_dword v219, v12, s[14:15] offset:768
	s_waitcnt lgkmcnt(8)
	v_mfma_f32_16x16x4_f32 v[136:139], v110, v126, v[136:139]
	v_mfma_f32_16x16x4_f32 v[136:139], v111, v127, v[136:139]
	s_waitcnt lgkmcnt(6)
	v_mfma_f32_16x16x4_f32 v[136:139], v112, v128, v[136:139]
	v_mfma_f32_16x16x4_f32 v[136:139], v113, v129, v[136:139]
	s_waitcnt vmcnt(58)
	ds_write_b128 v2, v[84:87] offset:0
	ds_write_b128 v2, v[88:91] offset:10240
	s_add_u32 s10, s0, 0x440000
	s_addc_u32 s11, s1, 0
	global_load_dwordx4 v[84:87], v0, s[10:11]
	global_load_dwordx4 v[88:91], v1, s[10:11]
	s_waitcnt lgkmcnt(6)
	v_mfma_f32_16x16x4_f32 v[136:139], v114, v130, v[136:139]
	v_mfma_f32_16x16x4_f32 v[136:139], v115, v131, v[136:139]
	s_waitcnt lgkmcnt(4)
	v_mfma_f32_16x16x4_f32 v[136:139], v116, v132, v[136:139]
	v_mfma_f32_16x16x4_f32 v[136:139], v117, v133, v[136:139]
	s_waitcnt lgkmcnt(2)
	v_mfma_f32_16x16x4_f32 v[136:139], v118, v134, v[136:139]
	v_mfma_f32_16x16x4_f32 v[136:139], v119, v135, v[136:139]
	s_add_u32 s16, s8, 0x380000
	s_addc_u32 s17, s9, 0
	s_nop 9
	ds_write_b32 v13, v136 offset:0
	ds_write_b32 v13, v137 offset:272
	ds_write_b32 v13, v138 offset:544
	ds_write_b32 v13, v139 offset:816
	global_store_dword v12, v136, s[16:17] offset:0
	global_store_dword v12, v137, s[16:17] offset:256
	global_store_dword v12, v138, s[16:17] offset:512
	global_store_dword v12, v139, s[16:17] offset:768
	s_waitcnt lgkmcnt(0)
	s_barrier
	ds_read2_b32 v[104:105], v8 offset0:0 offset1:4
	ds_read2st64_b32 v[120:121], v10 offset0:0 offset1:5
	ds_read2_b32 v[106:107], v8 offset0:8 offset1:12
	ds_read2st64_b32 v[122:123], v10 offset0:10 offset1:15
	ds_read2_b32 v[108:109], v8 offset0:16 offset1:20
	ds_read2st64_b32 v[124:125], v10 offset0:20 offset1:25
	ds_read2_b32 v[110:111], v8 offset0:24 offset1:28
	ds_read2st64_b32 v[126:127], v10 offset0:30 offset1:35
	ds_read2_b32 v[112:113], v8 offset0:32 offset1:36
	ds_read2st64_b32 v[128:129], v10 offset0:40 offset1:45
	ds_read2_b32 v[114:115], v8 offset0:40 offset1:44
	ds_read2st64_b32 v[130:131], v10 offset0:50 offset1:55
	ds_read2_b32 v[116:117], v8 offset0:48 offset1:52
	ds_read2st64_b32 v[132:133], v10 offset0:60 offset1:65
	s_waitcnt vmcnt(56)
	s_waitcnt lgkmcnt(12)
	v_mfma_f32_16x16x4_f32 v[136:139], v104, v120, v[220:223]
	v_mfma_f32_16x16x4_f32 v[136:139], v105, v121, v[136:139]
	ds_read2_b32 v[118:119], v8 offset0:56 offset1:60
	ds_read2st64_b32 v[134:135], v10 offset0:70 offset1:75
	s_waitcnt lgkmcnt(12)
	v_mfma_f32_16x16x4_f32 v[136:139], v106, v122, v[136:139]
	v_mfma_f32_16x16x4_f32 v[136:139], v107, v123, v[136:139]
	s_waitcnt lgkmcnt(10)
	v_mfma_f32_16x16x4_f32 v[136:139], v108, v124, v[136:139]
	v_mfma_f32_16x16x4_f32 v[136:139], v109, v125, v[136:139]
	s_add_u32 s14, s6, 0x440000
	s_addc_u32 s15, s7, 0
	global_load_dword v220, v12, s[14:15] offset:0
	global_load_dword v221, v12, s[14:15] offset:256
	global_load_dword v222, v12, s[14:15] offset:512
	global_load_dword v223, v12, s[14:15] offset:768
	s_waitcnt lgkmcnt(8)
	v_mfma_f32_16x16x4_f32 v[136:139], v110, v126, v[136:139]
	v_mfma_f32_16x16x4_f32 v[136:139], v111, v127, v[136:139]
	s_waitcnt lgkmcnt(6)
	v_mfma_f32_16x16x4_f32 v[136:139], v112, v128, v[136:139]
	v_mfma_f32_16x16x4_f32 v[136:139], v113, v129, v[136:139]
	s_waitcnt vmcnt(58)
	ds_write_b128 v2, v[92:95] offset:20480
	ds_write_b128 v2, v[96:99] offset:30720
	s_add_u32 s10, s0, 0x460000
	s_addc_u32 s11, s1, 0
	global_load_dwordx4 v[92:95], v0, s[10:11]
	global_load_dwordx4 v[96:99], v1, s[10:11]
	s_waitcnt lgkmcnt(6)
	v_mfma_f32_16x16x4_f32 v[136:139], v114, v130, v[136:139]
	v_mfma_f32_16x16x4_f32 v[136:139], v115, v131, v[136:139]
	s_waitcnt lgkmcnt(4)
	v_mfma_f32_16x16x4_f32 v[136:139], v116, v132, v[136:139]
	v_mfma_f32_16x16x4_f32 v[136:139], v117, v133, v[136:139]
	s_waitcnt lgkmcnt(2)
	v_mfma_f32_16x16x4_f32 v[136:139], v118, v134, v[136:139]
	v_mfma_f32_16x16x4_f32 v[136:139], v119, v135, v[136:139]
	s_add_u32 s16, s8, 0x3a0000
	s_addc_u32 s17, s9, 0
	s_nop 9
	ds_write_b32 v13, v136 offset:2176
	ds_write_b32 v13, v137 offset:2448
	ds_write_b32 v13, v138 offset:2720
	ds_write_b32 v13, v139 offset:2992
	global_store_dword v12, v136, s[16:17] offset:0
	global_store_dword v12, v137, s[16:17] offset:256
	global_store_dword v12, v138, s[16:17] offset:512
	global_store_dword v12, v139, s[16:17] offset:768
	s_waitcnt lgkmcnt(0)
	s_barrier
; #define LAS __attribute__((address_space(3)))
; __device__ __forceinline__ void scan_combine(LAS unsigned char* lds, CArgsP a) {
;     ...
;     for (int g = 1; g <= GL; ++g) {
;         const bool pf = (g + 2 <= GL);
;         float u3 = 0.f;
;         if (pf) { const f32x4* Pn = (const f32x4*)(PM + (size_t)((g + 2) * 8 + h) * 4096); pa = Pn[tid]; pb = Pn[512 + tid]; u3 = UM[((size_t)((g + 2) * 8 + h) * 64 + v) * 64 + kq]; }
;         asm volatile("s_waitcnt lgkmcnt(0)\n\ts_barrier" ::: "memory");
;         const LAS float* Pg = Pl + (g % 3) * 4096 + kq;
;         float acc0 = u1, acc1 = 0.f, acc2 = 0.f, acc3 = 0.f;
;         const int curi = __builtin_bit_cast(int, cur);
; #pragma unroll
;         for (int k = 0; k < 64; k += 4) {
;             const float s0 = __builtin_bit_cast(float, __builtin_amdgcn_readlane(curi, k)), s1 = __builtin_bit_cast(float, __builtin_amdgcn_readlane(curi, k + 1));
;             const float s2 = __builtin_bit_cast(float, __builtin_amdgcn_readlane(curi, k + 2)), s3 = __builtin_bit_cast(float, __builtin_amdgcn_readlane(curi, k + 3));
;             acc0 += s0 * Pg[(k + 0) * 64]; acc1 += s1 * Pg[(k + 1) * 64]; acc2 += s2 * Pg[(k + 2) * 64]; acc3 += s3 * Pg[(k + 3) * 64];
;         }
;         cur = (acc0 + acc1) + (acc2 + acc3);
;         SS[((size_t)((g + 1) * 8 + h) * 64 + v) * 64 + kq] = cur;
;         if (pf) { LAS float* dst = Pl + ((g + 2) % 3) * 4096; *(LAS f32x4*)(dst + 4 * tid) = pa; *(LAS f32x4*)(dst + 2048 + 4 * tid) = pb; }
;         u1 = u2; u2 = u3;
	ds_read2_b32 v[104:105], v9 offset0:0 offset1:4
	ds_read2st64_b32 v[120:121], v11 offset0:0 offset1:5
	ds_read2_b32 v[106:107], v9 offset0:8 offset1:12
	ds_read2st64_b32 v[122:123], v11 offset0:10 offset1:15
	ds_read2_b32 v[108:109], v9 offset0:16 offset1:20
	ds_read2st64_b32 v[124:125], v11 offset0:20 offset1:25
	ds_read2_b32 v[110:111], v9 offset0:24 offset1:28
	ds_read2st64_b32 v[126:127], v11 offset0:30 offset1:35
	ds_read2_b32 v[112:113], v9 offset0:32 offset1:36
	ds_read2st64_b32 v[128:129], v11 offset0:40 offset1:45
	ds_read2_b32 v[114:115], v9 offset0:40 offset1:44
	ds_read2st64_b32 v[130:131], v11 offset0:50 offset1:55
	ds_read2_b32 v[116:117], v9 offset0:48 offset1:52
	ds_read2st64_b32 v[132:133], v11 offset0:60 offset1:65
	s_waitcnt vmcnt(56)
	s_waitcnt lgkmcnt(12)
	v_mfma_f32_16x16x4_f32 v[136:139], v104, v120, v[224:227]
	v_mfma_f32_16x16x4_f32 v[136:139], v105, v121, v[136:139]
	ds_read2_b32 v[118:119], v9 offset0:56 offset1:60
	ds_read2st64_b32 v[134:135], v11 offset0:70 offset1:75
	s_waitcnt lgkmcnt(12)
	v_mfma_f32_16x16x4_f32 v[136:139], v106, v122, v[136:139]
	v_mfma_f32_16x16x4_f32 v[136:139], v107, v123, v[136:139]
	s_waitcnt lgkmcnt(10)
	v_mfma_f32_16x16x4_f32 v[136:139], v108, v124, v[136:139]
	v_mfma_f32_16x16x4_f32 v[136:139], v109, v125, v[136:139]
	s_add_u32 s14, s6, 0x460000
	s_addc_u32 s15, s7, 0
	global_load_dword v224, v12, s[14:15] offset:0
	global_load_dword v225, v12, s[14:15] offset:256
	global_load_dword v226, v12, s[14:15] offset:512
	global_load_dword v227, v12, s[14:15] offset:768
	s_waitcnt lgkmcnt(8)
	v_mfma_f32_16x16x4_f32 v[136:139], v110, v126, v[136:139]
	v_mfma_f32_16x16x4_f32 v[136:139], v111, v127, v[136:139]
	s_waitcnt lgkmcnt(6)
	v_mfma_f32_16x16x4_f32 v[136:139], v112, v128, v[136:139]
	v_mfma_f32_16x16x4_f32 v[136:139], v113, v129, v[136:139]
	s_waitcnt vmcnt(58)
	ds_write_b128 v2, v[52:55] offset:0
	ds_write_b128 v2, v[56:59] offset:10240
	s_add_u32 s10, s0, 0x480000
	s_addc_u32 s11, s1, 0
	global_load_dwordx4 v[52:55], v0, s[10:11]
	global_load_dwordx4 v[56:59], v1, s[10:11]
	s_waitcnt lgkmcnt(6)
	v_mfma_f32_16x16x4_f32 v[136:139], v114, v130, v[136:139]
	v_mfma_f32_16x16x4_f32 v[136:139], v115, v131, v[136:139]
	s_waitcnt lgkmcnt(4)
	v_mfma_f32_16x16x4_f32 v[136:139], v116, v132, v[136:139]
	v_mfma_f32_16x16x4_f32 v[136:139], v117, v133, v[136:139]
	s_waitcnt lgkmcnt(2)
	v_mfma_f32_16x16x4_f32 v[136:139], v118, v134, v[136:139]
	v_mfma_f32_16x16x4_f32 v[136:139], v119, v135, v[136:139]
	s_add_u32 s16, s8, 0x3c0000
	s_addc_u32 s17, s9, 0
	s_nop 9
	ds_write_b32 v13, v136 offset:0
	ds_write_b32 v13, v137 offset:272
	ds_write_b32 v13, v138 offset:544
	ds_write_b32 v13, v139 offset:816
	global_store_dword v12, v136, s[16:17] offset:0
	global_store_dword v12, v137, s[16:17] offset:256
	global_store_dword v12, v138, s[16:17] offset:512
	global_store_dword v12, v139, s[16:17] offset:768
	s_waitcnt lgkmcnt(0)
	s_barrier
	ds_read2_b32 v[104:105], v8 offset0:0 offset1:4
	ds_read2st64_b32 v[120:121], v10 offset0:0 offset1:5
	ds_read2_b32 v[106:107], v8 offset0:8 offset1:12
	ds_read2st64_b32 v[122:123], v10 offset0:10 offset1:15
	ds_read2_b32 v[108:109], v8 offset0:16 offset1:20
	ds_read2st64_b32 v[124:125], v10 offset0:20 offset1:25
	ds_read2_b32 v[110:111], v8 offset0:24 offset1:28
	ds_read2st64_b32 v[126:127], v10 offset0:30 offset1:35
	ds_read2_b32 v[112:113], v8 offset0:32 offset1:36
	ds_read2st64_b32 v[128:129], v10 offset0:40 offset1:45
	ds_read2_b32 v[114:115], v8 offset0:40 offset1:44
	ds_read2st64_b32 v[130:131], v10 offset0:50 offset1:55
	ds_read2_b32 v[116:117], v8 offset0:48 offset1:52
	ds_read2st64_b32 v[132:133], v10 offset0:60 offset1:65
	s_waitcnt vmcnt(56)
	s_waitcnt lgkmcnt(12)
	v_mfma_f32_16x16x4_f32 v[136:139], v104, v120, v[204:207]
	v_mfma_f32_16x16x4_f32 v[136:139], v105, v121, v[136:139]
	ds_read2_b32 v[118:119], v8 offset0:56 offset1:60
	ds_read2st64_b32 v[134:135], v10 offset0:70 offset1:75
	s_waitcnt lgkmcnt(12)
	v_mfma_f32_16x16x4_f32 v[136:139], v106, v122, v[136:139]
	v_mfma_f32_16x16x4_f32 v[136:139], v107, v123, v[136:139]
	s_waitcnt lgkmcnt(10)
	v_mfma_f32_16x16x4_f32 v[136:139], v108, v124, v[136:139]
	v_mfma_f32_16x16x4_f32 v[136:139], v109, v125, v[136:139]
	s_add_u32 s14, s6, 0x480000
	s_addc_u32 s15, s7, 0
	global_load_dword v204, v12, s[14:15] offset:0
	global_load_dword v205, v12, s[14:15] offset:256
	global_load_dword v206, v12, s[14:15] offset:512
	global_load_dword v207, v12, s[14:15] offset:768
	s_waitcnt lgkmcnt(8)
	v_mfma_f32_16x16x4_f32 v[136:139], v110, v126, v[136:139]
	v_mfma_f32_16x16x4_f32 v[136:139], v111, v127, v[136:139]
	s_waitcnt lgkmcnt(6)
	v_mfma_f32_16x16x4_f32 v[136:139], v112, v128, v[136:139]
	v_mfma_f32_16x16x4_f32 v[136:139], v113, v129, v[136:139]
	s_waitcnt vmcnt(58)
	ds_write_b128 v2, v[60:63] offset:20480
	ds_write_b128 v2, v[64:67] offset:30720
	s_add_u32 s10, s0, 0x4a0000
	s_addc_u32 s11, s1, 0
	global_load_dwordx4 v[60:63], v0, s[10:11]
	global_load_dwordx4 v[64:67], v1, s[10:11]
	s_waitcnt lgkmcnt(6)
	v_mfma_f32_16x16x4_f32 v[136:139], v114, v130, v[136:139]
	v_mfma_f32_16x16x4_f32 v[136:139], v115, v131, v[136:139]
	s_waitcnt lgkmcnt(4)
	v_mfma_f32_16x16x4_f32 v[136:139], v116, v132, v[136:139]
	v_mfma_f32_16x16x4_f32 v[136:139], v117, v133, v[136:139]
	s_waitcnt lgkmcnt(2)
	v_mfma_f32_16x16x4_f32 v[136:139], v118, v134, v[136:139]
	v_mfma_f32_16x16x4_f32 v[136:139], v119, v135, v[136:139]
	s_add_u32 s16, s8, 0x3e0000
	s_addc_u32 s17, s9, 0
	s_nop 9
	ds_write_b32 v13, v136 offset:2176
	ds_write_b32 v13, v137 offset:2448
	ds_write_b32 v13, v138 offset:2720
	ds_write_b32 v13, v139 offset:2992
	global_store_dword v12, v136, s[16:17] offset:0
	global_store_dword v12, v137, s[16:17] offset:256
	global_store_dword v12, v138, s[16:17] offset:512
	global_store_dword v12, v139, s[16:17] offset:768
	s_waitcnt lgkmcnt(0)
	s_barrier
; #define LAS __attribute__((address_space(3)))
; __device__ __forceinline__ void scan_combine(LAS unsigned char* lds, CArgsP a) {
;     ...
;     for (int g = 1; g <= GL; ++g) {
;         const bool pf = (g + 2 <= GL);
;         float u3 = 0.f;
;         if (pf) { const f32x4* Pn = (const f32x4*)(PM + (size_t)((g + 2) * 8 + h) * 4096); pa = Pn[tid]; pb = Pn[512 + tid]; u3 = UM[((size_t)((g + 2) * 8 + h) * 64 + v) * 64 + kq]; }
;         asm volatile("s_waitcnt lgkmcnt(0)\n\ts_barrier" ::: "memory");
;         const LAS float* Pg = Pl + (g % 3) * 4096 + kq;
;         float acc0 = u1, acc1 = 0.f, acc2 = 0.f, acc3 = 0.f;
;         const int curi = __builtin_bit_cast(int, cur);
; #pragma unroll
;         for (int k = 0; k < 64; k += 4) {
;             const float s0 = __builtin_bit_cast(float, __builtin_amdgcn_readlane(curi, k)), s1 = __builtin_bit_cast(float, __builtin_amdgcn_readlane(curi, k + 1));
;             const float s2 = __builtin_bit_cast(float, __builtin_amdgcn_readlane(curi, k + 2)), s3 = __builtin_bit_cast(float, __builtin_amdgcn_readlane(curi, k + 3));
;             acc0 += s0 * Pg[(k + 0) * 64]; acc1 += s1 * Pg[(k + 1) * 64]; acc2 += s2 * Pg[(k + 2) * 64]; acc3 += s3 * Pg[(k + 3) * 64];
;         }
;         cur = (acc0 + acc1) + (acc2 + acc3);
;         SS[((size_t)((g + 1) * 8 + h) * 64 + v) * 64 + kq] = cur;
;         if (pf) { LAS float* dst = Pl + ((g + 2) % 3) * 4096; *(LAS f32x4*)(dst + 4 * tid) = pa; *(LAS f32x4*)(dst + 2048 + 4 * tid) = pb; }
;         u1 = u2; u2 = u3;
	ds_read2_b32 v[104:105], v9 offset0:0 offset1:4
	ds_read2st64_b32 v[120:121], v11 offset0:0 offset1:5
	ds_read2_b32 v[106:107], v9 offset0:8 offset1:12
	ds_read2st64_b32 v[122:123], v11 offset0:10 offset1:15
	ds_read2_b32 v[108:109], v9 offset0:16 offset1:20
	ds_read2st64_b32 v[124:125], v11 offset0:20 offset1:25
	ds_read2_b32 v[110:111], v9 offset0:24 offset1:28
	ds_read2st64_b32 v[126:127], v11 offset0:30 offset1:35
	ds_read2_b32 v[112:113], v9 offset0:32 offset1:36
	ds_read2st64_b32 v[128:129], v11 offset0:40 offset1:45
	ds_read2_b32 v[114:115], v9 offset0:40 offset1:44
	ds_read2st64_b32 v[130:131], v11 offset0:50 offset1:55
	ds_read2_b32 v[116:117], v9 offset0:48 offset1:52
	ds_read2st64_b32 v[132:133], v11 offset0:60 offset1:65
	s_waitcnt vmcnt(56)
	s_waitcnt lgkmcnt(12)
	v_mfma_f32_16x16x4_f32 v[136:139], v104, v120, v[208:211]
	v_mfma_f32_16x16x4_f32 v[136:139], v105, v121, v[136:139]
	ds_read2_b32 v[118:119], v9 offset0:56 offset1:60
	ds_read2st64_b32 v[134:135], v11 offset0:70 offset1:75
	s_waitcnt lgkmcnt(12)
	v_mfma_f32_16x16x4_f32 v[136:139], v106, v122, v[136:139]
	v_mfma_f32_16x16x4_f32 v[136:139], v107, v123, v[136:139]
	s_waitcnt lgkmcnt(10)
	v_mfma_f32_16x16x4_f32 v[136:139], v108, v124, v[136:139]
	v_mfma_f32_16x16x4_f32 v[136:139], v109, v125, v[136:139]
	s_add_u32 s14, s6, 0x4a0000
	s_addc_u32 s15, s7, 0
	global_load_dword v208, v12, s[14:15] offset:0
	global_load_dword v209, v12, s[14:15] offset:256
	global_load_dword v210, v12, s[14:15] offset:512
	global_load_dword v211, v12, s[14:15] offset:768
	s_waitcnt lgkmcnt(8)
	v_mfma_f32_16x16x4_f32 v[136:139], v110, v126, v[136:139]
	v_mfma_f32_16x16x4_f32 v[136:139], v111, v127, v[136:139]
	s_waitcnt lgkmcnt(6)
	v_mfma_f32_16x16x4_f32 v[136:139], v112, v128, v[136:139]
	v_mfma_f32_16x16x4_f32 v[136:139], v113, v129, v[136:139]
	s_waitcnt vmcnt(58)
	ds_write_b128 v2, v[68:71] offset:0
	ds_write_b128 v2, v[72:75] offset:10240
	s_add_u32 s10, s0, 0x4c0000
	s_addc_u32 s11, s1, 0
	global_load_dwordx4 v[68:71], v0, s[10:11]
	global_load_dwordx4 v[72:75], v1, s[10:11]
	s_waitcnt lgkmcnt(6)
	v_mfma_f32_16x16x4_f32 v[136:139], v114, v130, v[136:139]
	v_mfma_f32_16x16x4_f32 v[136:139], v115, v131, v[136:139]
	s_waitcnt lgkmcnt(4)
	v_mfma_f32_16x16x4_f32 v[136:139], v116, v132, v[136:139]
	v_mfma_f32_16x16x4_f32 v[136:139], v117, v133, v[136:139]
	s_waitcnt lgkmcnt(2)
	v_mfma_f32_16x16x4_f32 v[136:139], v118, v134, v[136:139]
	v_mfma_f32_16x16x4_f32 v[136:139], v119, v135, v[136:139]
	s_add_u32 s16, s8, 0x400000
	s_addc_u32 s17, s9, 0
	s_nop 9
	ds_write_b32 v13, v136 offset:0
	ds_write_b32 v13, v137 offset:272
	ds_write_b32 v13, v138 offset:544
	ds_write_b32 v13, v139 offset:816
	global_store_dword v12, v136, s[16:17] offset:0
	global_store_dword v12, v137, s[16:17] offset:256
	global_store_dword v12, v138, s[16:17] offset:512
	global_store_dword v12, v139, s[16:17] offset:768
	s_waitcnt lgkmcnt(0)
	s_barrier
	ds_read2_b32 v[104:105], v8 offset0:0 offset1:4
	ds_read2st64_b32 v[120:121], v10 offset0:0 offset1:5
	ds_read2_b32 v[106:107], v8 offset0:8 offset1:12
	ds_read2st64_b32 v[122:123], v10 offset0:10 offset1:15
	ds_read2_b32 v[108:109], v8 offset0:16 offset1:20
	ds_read2st64_b32 v[124:125], v10 offset0:20 offset1:25
	ds_read2_b32 v[110:111], v8 offset0:24 offset1:28
	ds_read2st64_b32 v[126:127], v10 offset0:30 offset1:35
	ds_read2_b32 v[112:113], v8 offset0:32 offset1:36
	ds_read2st64_b32 v[128:129], v10 offset0:40 offset1:45
	ds_read2_b32 v[114:115], v8 offset0:40 offset1:44
	ds_read2st64_b32 v[130:131], v10 offset0:50 offset1:55
	ds_read2_b32 v[116:117], v8 offset0:48 offset1:52
	ds_read2st64_b32 v[132:133], v10 offset0:60 offset1:65
	s_waitcnt vmcnt(56)
	s_waitcnt lgkmcnt(12)
	v_mfma_f32_16x16x4_f32 v[136:139], v104, v120, v[212:215]
	v_mfma_f32_16x16x4_f32 v[136:139], v105, v121, v[136:139]
	ds_read2_b32 v[118:119], v8 offset0:56 offset1:60
	ds_read2st64_b32 v[134:135], v10 offset0:70 offset1:75
	s_waitcnt lgkmcnt(12)
	v_mfma_f32_16x16x4_f32 v[136:139], v106, v122, v[136:139]
	v_mfma_f32_16x16x4_f32 v[136:139], v107, v123, v[136:139]
	s_waitcnt lgkmcnt(10)
	v_mfma_f32_16x16x4_f32 v[136:139], v108, v124, v[136:139]
	v_mfma_f32_16x16x4_f32 v[136:139], v109, v125, v[136:139]
	s_add_u32 s14, s6, 0x4c0000
	s_addc_u32 s15, s7, 0
	global_load_dword v212, v12, s[14:15] offset:0
	global_load_dword v213, v12, s[14:15] offset:256
	global_load_dword v214, v12, s[14:15] offset:512
	global_load_dword v215, v12, s[14:15] offset:768
	s_waitcnt lgkmcnt(8)
	v_mfma_f32_16x16x4_f32 v[136:139], v110, v126, v[136:139]
	v_mfma_f32_16x16x4_f32 v[136:139], v111, v127, v[136:139]
	s_waitcnt lgkmcnt(6)
	v_mfma_f32_16x16x4_f32 v[136:139], v112, v128, v[136:139]
	v_mfma_f32_16x16x4_f32 v[136:139], v113, v129, v[136:139]
	s_waitcnt vmcnt(58)
	ds_write_b128 v2, v[76:79] offset:20480
	ds_write_b128 v2, v[80:83] offset:30720
	s_add_u32 s10, s0, 0x4e0000
	s_addc_u32 s11, s1, 0
	global_load_dwordx4 v[76:79], v0, s[10:11]
	global_load_dwordx4 v[80:83], v1, s[10:11]
	s_waitcnt lgkmcnt(6)
	v_mfma_f32_16x16x4_f32 v[136:139], v114, v130, v[136:139]
	v_mfma_f32_16x16x4_f32 v[136:139], v115, v131, v[136:139]
	s_waitcnt lgkmcnt(4)
	v_mfma_f32_16x16x4_f32 v[136:139], v116, v132, v[136:139]
	v_mfma_f32_16x16x4_f32 v[136:139], v117, v133, v[136:139]
	s_waitcnt lgkmcnt(2)
	v_mfma_f32_16x16x4_f32 v[136:139], v118, v134, v[136:139]
	v_mfma_f32_16x16x4_f32 v[136:139], v119, v135, v[136:139]
	s_add_u32 s16, s8, 0x420000
	s_addc_u32 s17, s9, 0
	s_nop 9
	ds_write_b32 v13, v136 offset:2176
	ds_write_b32 v13, v137 offset:2448
	ds_write_b32 v13, v138 offset:2720
	ds_write_b32 v13, v139 offset:2992
	global_store_dword v12, v136, s[16:17] offset:0
	global_store_dword v12, v137, s[16:17] offset:256
	global_store_dword v12, v138, s[16:17] offset:512
	global_store_dword v12, v139, s[16:17] offset:768
	s_waitcnt lgkmcnt(0)
	s_barrier
; #define LAS __attribute__((address_space(3)))
; __device__ __forceinline__ void scan_combine(LAS unsigned char* lds, CArgsP a) {
;     ...
;     for (int g = 1; g <= GL; ++g) {
;         const bool pf = (g + 2 <= GL);
;         float u3 = 0.f;
;         if (pf) { const f32x4* Pn = (const f32x4*)(PM + (size_t)((g + 2) * 8 + h) * 4096); pa = Pn[tid]; pb = Pn[512 + tid]; u3 = UM[((size_t)((g + 2) * 8 + h) * 64 + v) * 64 + kq]; }
;         asm volatile("s_waitcnt lgkmcnt(0)\n\ts_barrier" ::: "memory");
;         const LAS float* Pg = Pl + (g % 3) * 4096 + kq;
;         float acc0 = u1, acc1 = 0.f, acc2 = 0.f, acc3 = 0.f;
;         const int curi = __builtin_bit_cast(int, cur);
; #pragma unroll
;         for (int k = 0; k < 64; k += 4) {
;             const float s0 = __builtin_bit_cast(float, __builtin_amdgcn_readlane(curi, k)), s1 = __builtin_bit_cast(float, __builtin_amdgcn_readlane(curi, k + 1));
;             const float s2 = __builtin_bit_cast(float, __builtin_amdgcn_readlane(curi, k + 2)), s3 = __builtin_bit_cast(float, __builtin_amdgcn_readlane(curi, k + 3));
;             acc0 += s0 * Pg[(k + 0) * 64]; acc1 += s1 * Pg[(k + 1) * 64]; acc2 += s2 * Pg[(k + 2) * 64]; acc3 += s3 * Pg[(k + 3) * 64];
;         }
;         cur = (acc0 + acc1) + (acc2 + acc3);
;         SS[((size_t)((g + 1) * 8 + h) * 64 + v) * 64 + kq] = cur;
;         if (pf) { LAS float* dst = Pl + ((g + 2) % 3) * 4096; *(LAS f32x4*)(dst + 4 * tid) = pa; *(LAS f32x4*)(dst + 2048 + 4 * tid) = pb; }
;         u1 = u2; u2 = u3;
	ds_read2_b32 v[104:105], v9 offset0:0 offset1:4
	ds_read2st64_b32 v[120:121], v11 offset0:0 offset1:5
	ds_read2_b32 v[106:107], v9 offset0:8 offset1:12
	ds_read2st64_b32 v[122:123], v11 offset0:10 offset1:15
	ds_read2_b32 v[108:109], v9 offset0:16 offset1:20
	ds_read2st64_b32 v[124:125], v11 offset0:20 offset1:25
	ds_read2_b32 v[110:111], v9 offset0:24 offset1:28
	ds_read2st64_b32 v[126:127], v11 offset0:30 offset1:35
	ds_read2_b32 v[112:113], v9 offset0:32 offset1:36
	ds_read2st64_b32 v[128:129], v11 offset0:40 offset1:45
	ds_read2_b32 v[114:115], v9 offset0:40 offset1:44
	ds_read2st64_b32 v[130:131], v11 offset0:50 offset1:55
	ds_read2_b32 v[116:117], v9 offset0:48 offset1:52
	ds_read2st64_b32 v[132:133], v11 offset0:60 offset1:65
	s_waitcnt vmcnt(56)
	s_waitcnt lgkmcnt(12)
	v_mfma_f32_16x16x4_f32 v[136:139], v104, v120, v[216:219]
	v_mfma_f32_16x16x4_f32 v[136:139], v105, v121, v[136:139]
	ds_read2_b32 v[118:119], v9 offset0:56 offset1:60
	ds_read2st64_b32 v[134:135], v11 offset0:70 offset1:75
	s_waitcnt lgkmcnt(12)
	v_mfma_f32_16x16x4_f32 v[136:139], v106, v122, v[136:139]
	v_mfma_f32_16x16x4_f32 v[136:139], v107, v123, v[136:139]
	s_waitcnt lgkmcnt(10)
	v_mfma_f32_16x16x4_f32 v[136:139], v108, v124, v[136:139]
	v_mfma_f32_16x16x4_f32 v[136:139], v109, v125, v[136:139]
	s_add_u32 s14, s6, 0x4e0000
	s_addc_u32 s15, s7, 0
	global_load_dword v216, v12, s[14:15] offset:0
	global_load_dword v217, v12, s[14:15] offset:256
	global_load_dword v218, v12, s[14:15] offset:512
	global_load_dword v219, v12, s[14:15] offset:768
	s_waitcnt lgkmcnt(8)
	v_mfma_f32_16x16x4_f32 v[136:139], v110, v126, v[136:139]
	v_mfma_f32_16x16x4_f32 v[136:139], v111, v127, v[136:139]
	s_waitcnt lgkmcnt(6)
	v_mfma_f32_16x16x4_f32 v[136:139], v112, v128, v[136:139]
	v_mfma_f32_16x16x4_f32 v[136:139], v113, v129, v[136:139]
	s_waitcnt vmcnt(58)
	ds_write_b128 v2, v[84:87] offset:0
	ds_write_b128 v2, v[88:91] offset:10240
	s_add_u32 s10, s0, 0x500000
	s_addc_u32 s11, s1, 0
	global_load_dwordx4 v[84:87], v0, s[10:11]
	global_load_dwordx4 v[88:91], v1, s[10:11]
	s_waitcnt lgkmcnt(6)
	v_mfma_f32_16x16x4_f32 v[136:139], v114, v130, v[136:139]
	v_mfma_f32_16x16x4_f32 v[136:139], v115, v131, v[136:139]
	s_waitcnt lgkmcnt(4)
	v_mfma_f32_16x16x4_f32 v[136:139], v116, v132, v[136:139]
	v_mfma_f32_16x16x4_f32 v[136:139], v117, v133, v[136:139]
	s_waitcnt lgkmcnt(2)
	v_mfma_f32_16x16x4_f32 v[136:139], v118, v134, v[136:139]
	v_mfma_f32_16x16x4_f32 v[136:139], v119, v135, v[136:139]
	s_add_u32 s16, s8, 0x440000
	s_addc_u32 s17, s9, 0
	s_nop 9
	ds_write_b32 v13, v136 offset:0
	ds_write_b32 v13, v137 offset:272
	ds_write_b32 v13, v138 offset:544
	ds_write_b32 v13, v139 offset:816
	global_store_dword v12, v136, s[16:17] offset:0
	global_store_dword v12, v137, s[16:17] offset:256
	global_store_dword v12, v138, s[16:17] offset:512
	global_store_dword v12, v139, s[16:17] offset:768
	s_waitcnt lgkmcnt(0)
	s_barrier
	ds_read2_b32 v[104:105], v8 offset0:0 offset1:4
	ds_read2st64_b32 v[120:121], v10 offset0:0 offset1:5
	ds_read2_b32 v[106:107], v8 offset0:8 offset1:12
	ds_read2st64_b32 v[122:123], v10 offset0:10 offset1:15
	ds_read2_b32 v[108:109], v8 offset0:16 offset1:20
	ds_read2st64_b32 v[124:125], v10 offset0:20 offset1:25
	ds_read2_b32 v[110:111], v8 offset0:24 offset1:28
	ds_read2st64_b32 v[126:127], v10 offset0:30 offset1:35
	ds_read2_b32 v[112:113], v8 offset0:32 offset1:36
	ds_read2st64_b32 v[128:129], v10 offset0:40 offset1:45
	ds_read2_b32 v[114:115], v8 offset0:40 offset1:44
	ds_read2st64_b32 v[130:131], v10 offset0:50 offset1:55
	ds_read2_b32 v[116:117], v8 offset0:48 offset1:52
	ds_read2st64_b32 v[132:133], v10 offset0:60 offset1:65
	s_waitcnt vmcnt(56)
	s_waitcnt lgkmcnt(12)
	v_mfma_f32_16x16x4_f32 v[136:139], v104, v120, v[220:223]
	v_mfma_f32_16x16x4_f32 v[136:139], v105, v121, v[136:139]
	ds_read2_b32 v[118:119], v8 offset0:56 offset1:60
	ds_read2st64_b32 v[134:135], v10 offset0:70 offset1:75
	s_waitcnt lgkmcnt(12)
	v_mfma_f32_16x16x4_f32 v[136:139], v106, v122, v[136:139]
	v_mfma_f32_16x16x4_f32 v[136:139], v107, v123, v[136:139]
	s_waitcnt lgkmcnt(10)
	v_mfma_f32_16x16x4_f32 v[136:139], v108, v124, v[136:139]
	v_mfma_f32_16x16x4_f32 v[136:139], v109, v125, v[136:139]
	s_add_u32 s14, s6, 0x500000
	s_addc_u32 s15, s7, 0
	global_load_dword v220, v12, s[14:15] offset:0
	global_load_dword v221, v12, s[14:15] offset:256
	global_load_dword v222, v12, s[14:15] offset:512
	global_load_dword v223, v12, s[14:15] offset:768
	s_waitcnt lgkmcnt(8)
	v_mfma_f32_16x16x4_f32 v[136:139], v110, v126, v[136:139]
	v_mfma_f32_16x16x4_f32 v[136:139], v111, v127, v[136:139]
	s_waitcnt lgkmcnt(6)
	v_mfma_f32_16x16x4_f32 v[136:139], v112, v128, v[136:139]
	v_mfma_f32_16x16x4_f32 v[136:139], v113, v129, v[136:139]
	s_waitcnt vmcnt(58)
	ds_write_b128 v2, v[92:95] offset:20480
	ds_write_b128 v2, v[96:99] offset:30720
	s_add_u32 s10, s0, 0x520000
	s_addc_u32 s11, s1, 0
	global_load_dwordx4 v[92:95], v0, s[10:11]
	global_load_dwordx4 v[96:99], v1, s[10:11]
	s_waitcnt lgkmcnt(6)
	v_mfma_f32_16x16x4_f32 v[136:139], v114, v130, v[136:139]
	v_mfma_f32_16x16x4_f32 v[136:139], v115, v131, v[136:139]
	s_waitcnt lgkmcnt(4)
	v_mfma_f32_16x16x4_f32 v[136:139], v116, v132, v[136:139]
	v_mfma_f32_16x16x4_f32 v[136:139], v117, v133, v[136:139]
	s_waitcnt lgkmcnt(2)
	v_mfma_f32_16x16x4_f32 v[136:139], v118, v134, v[136:139]
	v_mfma_f32_16x16x4_f32 v[136:139], v119, v135, v[136:139]
	s_add_u32 s16, s8, 0x460000
	s_addc_u32 s17, s9, 0
	s_nop 9
	ds_write_b32 v13, v136 offset:2176
	ds_write_b32 v13, v137 offset:2448
	ds_write_b32 v13, v138 offset:2720
	ds_write_b32 v13, v139 offset:2992
	global_store_dword v12, v136, s[16:17] offset:0
	global_store_dword v12, v137, s[16:17] offset:256
	global_store_dword v12, v138, s[16:17] offset:512
	global_store_dword v12, v139, s[16:17] offset:768
	s_waitcnt lgkmcnt(0)
	s_barrier
; #define LAS __attribute__((address_space(3)))
; __device__ __forceinline__ void scan_combine(LAS unsigned char* lds, CArgsP a) {
;     ...
;     for (int g = 1; g <= GL; ++g) {
;         const bool pf = (g + 2 <= GL);
;         float u3 = 0.f;
;         if (pf) { const f32x4* Pn = (const f32x4*)(PM + (size_t)((g + 2) * 8 + h) * 4096); pa = Pn[tid]; pb = Pn[512 + tid]; u3 = UM[((size_t)((g + 2) * 8 + h) * 64 + v) * 64 + kq]; }
;         asm volatile("s_waitcnt lgkmcnt(0)\n\ts_barrier" ::: "memory");
;         const LAS float* Pg = Pl + (g % 3) * 4096 + kq;
;         float acc0 = u1, acc1 = 0.f, acc2 = 0.f, acc3 = 0.f;
;         const int curi = __builtin_bit_cast(int, cur);
; #pragma unroll
;         for (int k = 0; k < 64; k += 4) {
;             const float s0 = __builtin_bit_cast(float, __builtin_amdgcn_readlane(curi, k)), s1 = __builtin_bit_cast(float, __builtin_amdgcn_readlane(curi, k + 1));
;             const float s2 = __builtin_bit_cast(float, __builtin_amdgcn_readlane(curi, k + 2)), s3 = __builtin_bit_cast(float, __builtin_amdgcn_readlane(curi, k + 3));
;             acc0 += s0 * Pg[(k + 0) * 64]; acc1 += s1 * Pg[(k + 1) * 64]; acc2 += s2 * Pg[(k + 2) * 64]; acc3 += s3 * Pg[(k + 3) * 64];
;         }
;         cur = (acc0 + acc1) + (acc2 + acc3);
;         SS[((size_t)((g + 1) * 8 + h) * 64 + v) * 64 + kq] = cur;
;         if (pf) { LAS float* dst = Pl + ((g + 2) % 3) * 4096; *(LAS f32x4*)(dst + 4 * tid) = pa; *(LAS f32x4*)(dst + 2048 + 4 * tid) = pb; }
;         u1 = u2; u2 = u3;
	ds_read2_b32 v[104:105], v9 offset0:0 offset1:4
	ds_read2st64_b32 v[120:121], v11 offset0:0 offset1:5
	ds_read2_b32 v[106:107], v9 offset0:8 offset1:12
	ds_read2st64_b32 v[122:123], v11 offset0:10 offset1:15
	ds_read2_b32 v[108:109], v9 offset0:16 offset1:20
	ds_read2st64_b32 v[124:125], v11 offset0:20 offset1:25
	ds_read2_b32 v[110:111], v9 offset0:24 offset1:28
	ds_read2st64_b32 v[126:127], v11 offset0:30 offset1:35
	ds_read2_b32 v[112:113], v9 offset0:32 offset1:36
	ds_read2st64_b32 v[128:129], v11 offset0:40 offset1:45
	ds_read2_b32 v[114:115], v9 offset0:40 offset1:44
	ds_read2st64_b32 v[130:131], v11 offset0:50 offset1:55
	ds_read2_b32 v[116:117], v9 offset0:48 offset1:52
	ds_read2st64_b32 v[132:133], v11 offset0:60 offset1:65
	s_waitcnt vmcnt(56)
	s_waitcnt lgkmcnt(12)
	v_mfma_f32_16x16x4_f32 v[136:139], v104, v120, v[224:227]
	v_mfma_f32_16x16x4_f32 v[136:139], v105, v121, v[136:139]
	ds_read2_b32 v[118:119], v9 offset0:56 offset1:60
	ds_read2st64_b32 v[134:135], v11 offset0:70 offset1:75
	s_waitcnt lgkmcnt(12)
	v_mfma_f32_16x16x4_f32 v[136:139], v106, v122, v[136:139]
	v_mfma_f32_16x16x4_f32 v[136:139], v107, v123, v[136:139]
	s_waitcnt lgkmcnt(10)
	v_mfma_f32_16x16x4_f32 v[136:139], v108, v124, v[136:139]
	v_mfma_f32_16x16x4_f32 v[136:139], v109, v125, v[136:139]
	s_add_u32 s14, s6, 0x520000
	s_addc_u32 s15, s7, 0
	global_load_dword v224, v12, s[14:15] offset:0
	global_load_dword v225, v12, s[14:15] offset:256
	global_load_dword v226, v12, s[14:15] offset:512
	global_load_dword v227, v12, s[14:15] offset:768
	s_waitcnt lgkmcnt(8)
	v_mfma_f32_16x16x4_f32 v[136:139], v110, v126, v[136:139]
	v_mfma_f32_16x16x4_f32 v[136:139], v111, v127, v[136:139]
	s_waitcnt lgkmcnt(6)
	v_mfma_f32_16x16x4_f32 v[136:139], v112, v128, v[136:139]
	v_mfma_f32_16x16x4_f32 v[136:139], v113, v129, v[136:139]
	s_waitcnt vmcnt(58)
	ds_write_b128 v2, v[52:55] offset:0
	ds_write_b128 v2, v[56:59] offset:10240
	s_add_u32 s10, s0, 0x540000
	s_addc_u32 s11, s1, 0
	global_load_dwordx4 v[52:55], v0, s[10:11]
	global_load_dwordx4 v[56:59], v1, s[10:11]
	s_waitcnt lgkmcnt(6)
	v_mfma_f32_16x16x4_f32 v[136:139], v114, v130, v[136:139]
	v_mfma_f32_16x16x4_f32 v[136:139], v115, v131, v[136:139]
	s_waitcnt lgkmcnt(4)
	v_mfma_f32_16x16x4_f32 v[136:139], v116, v132, v[136:139]
	v_mfma_f32_16x16x4_f32 v[136:139], v117, v133, v[136:139]
	s_waitcnt lgkmcnt(2)
	v_mfma_f32_16x16x4_f32 v[136:139], v118, v134, v[136:139]
	v_mfma_f32_16x16x4_f32 v[136:139], v119, v135, v[136:139]
	s_add_u32 s16, s8, 0x480000
	s_addc_u32 s17, s9, 0
	s_nop 9
	ds_write_b32 v13, v136 offset:0
	ds_write_b32 v13, v137 offset:272
	ds_write_b32 v13, v138 offset:544
	ds_write_b32 v13, v139 offset:816
	global_store_dword v12, v136, s[16:17] offset:0
	global_store_dword v12, v137, s[16:17] offset:256
	global_store_dword v12, v138, s[16:17] offset:512
	global_store_dword v12, v139, s[16:17] offset:768
	s_waitcnt lgkmcnt(0)
	s_barrier
	ds_read2_b32 v[104:105], v8 offset0:0 offset1:4
	ds_read2st64_b32 v[120:121], v10 offset0:0 offset1:5
	ds_read2_b32 v[106:107], v8 offset0:8 offset1:12
	ds_read2st64_b32 v[122:123], v10 offset0:10 offset1:15
	ds_read2_b32 v[108:109], v8 offset0:16 offset1:20
	ds_read2st64_b32 v[124:125], v10 offset0:20 offset1:25
	ds_read2_b32 v[110:111], v8 offset0:24 offset1:28
	ds_read2st64_b32 v[126:127], v10 offset0:30 offset1:35
	ds_read2_b32 v[112:113], v8 offset0:32 offset1:36
	ds_read2st64_b32 v[128:129], v10 offset0:40 offset1:45
	ds_read2_b32 v[114:115], v8 offset0:40 offset1:44
	ds_read2st64_b32 v[130:131], v10 offset0:50 offset1:55
	ds_read2_b32 v[116:117], v8 offset0:48 offset1:52
	ds_read2st64_b32 v[132:133], v10 offset0:60 offset1:65
	s_waitcnt vmcnt(56)
	s_waitcnt lgkmcnt(12)
	v_mfma_f32_16x16x4_f32 v[136:139], v104, v120, v[204:207]
	v_mfma_f32_16x16x4_f32 v[136:139], v105, v121, v[136:139]
	ds_read2_b32 v[118:119], v8 offset0:56 offset1:60
	ds_read2st64_b32 v[134:135], v10 offset0:70 offset1:75
	s_waitcnt lgkmcnt(12)
	v_mfma_f32_16x16x4_f32 v[136:139], v106, v122, v[136:139]
	v_mfma_f32_16x16x4_f32 v[136:139], v107, v123, v[136:139]
	s_waitcnt lgkmcnt(10)
	v_mfma_f32_16x16x4_f32 v[136:139], v108, v124, v[136:139]
	v_mfma_f32_16x16x4_f32 v[136:139], v109, v125, v[136:139]
	s_add_u32 s14, s6, 0x540000
	s_addc_u32 s15, s7, 0
	global_load_dword v204, v12, s[14:15] offset:0
	global_load_dword v205, v12, s[14:15] offset:256
	global_load_dword v206, v12, s[14:15] offset:512
	global_load_dword v207, v12, s[14:15] offset:768
	s_waitcnt lgkmcnt(8)
	v_mfma_f32_16x16x4_f32 v[136:139], v110, v126, v[136:139]
	v_mfma_f32_16x16x4_f32 v[136:139], v111, v127, v[136:139]
	s_waitcnt lgkmcnt(6)
	v_mfma_f32_16x16x4_f32 v[136:139], v112, v128, v[136:139]
	v_mfma_f32_16x16x4_f32 v[136:139], v113, v129, v[136:139]
	s_waitcnt vmcnt(58)
	ds_write_b128 v2, v[60:63] offset:20480
	ds_write_b128 v2, v[64:67] offset:30720
	s_add_u32 s10, s0, 0x560000
	s_addc_u32 s11, s1, 0
	global_load_dwordx4 v[60:63], v0, s[10:11]
	global_load_dwordx4 v[64:67], v1, s[10:11]
	s_waitcnt lgkmcnt(6)
	v_mfma_f32_16x16x4_f32 v[136:139], v114, v130, v[136:139]
	v_mfma_f32_16x16x4_f32 v[136:139], v115, v131, v[136:139]
	s_waitcnt lgkmcnt(4)
	v_mfma_f32_16x16x4_f32 v[136:139], v116, v132, v[136:139]
	v_mfma_f32_16x16x4_f32 v[136:139], v117, v133, v[136:139]
	s_waitcnt lgkmcnt(2)
	v_mfma_f32_16x16x4_f32 v[136:139], v118, v134, v[136:139]
	v_mfma_f32_16x16x4_f32 v[136:139], v119, v135, v[136:139]
	s_add_u32 s16, s8, 0x4a0000
	s_addc_u32 s17, s9, 0
	s_nop 9
	ds_write_b32 v13, v136 offset:2176
	ds_write_b32 v13, v137 offset:2448
	ds_write_b32 v13, v138 offset:2720
	ds_write_b32 v13, v139 offset:2992
	global_store_dword v12, v136, s[16:17] offset:0
	global_store_dword v12, v137, s[16:17] offset:256
	global_store_dword v12, v138, s[16:17] offset:512
	global_store_dword v12, v139, s[16:17] offset:768
	s_waitcnt lgkmcnt(0)
	s_barrier
; #define LAS __attribute__((address_space(3)))
; __device__ __forceinline__ void scan_combine(LAS unsigned char* lds, CArgsP a) {
;     ...
;     for (int g = 1; g <= GL; ++g) {
;         const bool pf = (g + 2 <= GL);
;         float u3 = 0.f;
;         if (pf) { const f32x4* Pn = (const f32x4*)(PM + (size_t)((g + 2) * 8 + h) * 4096); pa = Pn[tid]; pb = Pn[512 + tid]; u3 = UM[((size_t)((g + 2) * 8 + h) * 64 + v) * 64 + kq]; }
;         asm volatile("s_waitcnt lgkmcnt(0)\n\ts_barrier" ::: "memory");
;         const LAS float* Pg = Pl + (g % 3) * 4096 + kq;
;         float acc0 = u1, acc1 = 0.f, acc2 = 0.f, acc3 = 0.f;
;         const int curi = __builtin_bit_cast(int, cur);
; #pragma unroll
;         for (int k = 0; k < 64; k += 4) {
;             const float s0 = __builtin_bit_cast(float, __builtin_amdgcn_readlane(curi, k)), s1 = __builtin_bit_cast(float, __builtin_amdgcn_readlane(curi, k + 1));
;             const float s2 = __builtin_bit_cast(float, __builtin_amdgcn_readlane(curi, k + 2)), s3 = __builtin_bit_cast(float, __builtin_amdgcn_readlane(curi, k + 3));
;             acc0 += s0 * Pg[(k + 0) * 64]; acc1 += s1 * Pg[(k + 1) * 64]; acc2 += s2 * Pg[(k + 2) * 64]; acc3 += s3 * Pg[(k + 3) * 64];
;         }
;         cur = (acc0 + acc1) + (acc2 + acc3);
;         SS[((size_t)((g + 1) * 8 + h) * 64 + v) * 64 + kq] = cur;
;         if (pf) { LAS float* dst = Pl + ((g + 2) % 3) * 4096; *(LAS f32x4*)(dst + 4 * tid) = pa; *(LAS f32x4*)(dst + 2048 + 4 * tid) = pb; }
;         u1 = u2; u2 = u3;
	ds_read2_b32 v[104:105], v9 offset0:0 offset1:4
	ds_read2st64_b32 v[120:121], v11 offset0:0 offset1:5
	ds_read2_b32 v[106:107], v9 offset0:8 offset1:12
	ds_read2st64_b32 v[122:123], v11 offset0:10 offset1:15
	ds_read2_b32 v[108:109], v9 offset0:16 offset1:20
	ds_read2st64_b32 v[124:125], v11 offset0:20 offset1:25
	ds_read2_b32 v[110:111], v9 offset0:24 offset1:28
	ds_read2st64_b32 v[126:127], v11 offset0:30 offset1:35
	ds_read2_b32 v[112:113], v9 offset0:32 offset1:36
	ds_read2st64_b32 v[128:129], v11 offset0:40 offset1:45
	ds_read2_b32 v[114:115], v9 offset0:40 offset1:44
	ds_read2st64_b32 v[130:131], v11 offset0:50 offset1:55
	ds_read2_b32 v[116:117], v9 offset0:48 offset1:52
	ds_read2st64_b32 v[132:133], v11 offset0:60 offset1:65
	s_waitcnt vmcnt(56)
	s_waitcnt lgkmcnt(12)
	v_mfma_f32_16x16x4_f32 v[136:139], v104, v120, v[208:211]
	v_mfma_f32_16x16x4_f32 v[136:139], v105, v121, v[136:139]
	ds_read2_b32 v[118:119], v9 offset0:56 offset1:60
	ds_read2st64_b32 v[134:135], v11 offset0:70 offset1:75
	s_waitcnt lgkmcnt(12)
	v_mfma_f32_16x16x4_f32 v[136:139], v106, v122, v[136:139]
	v_mfma_f32_16x16x4_f32 v[136:139], v107, v123, v[136:139]
	s_waitcnt lgkmcnt(10)
	v_mfma_f32_16x16x4_f32 v[136:139], v108, v124, v[136:139]
	v_mfma_f32_16x16x4_f32 v[136:139], v109, v125, v[136:139]
	s_add_u32 s14, s6, 0x560000
	s_addc_u32 s15, s7, 0
	global_load_dword v208, v12, s[14:15] offset:0
	global_load_dword v209, v12, s[14:15] offset:256
	global_load_dword v210, v12, s[14:15] offset:512
	global_load_dword v211, v12, s[14:15] offset:768
	s_waitcnt lgkmcnt(8)
	v_mfma_f32_16x16x4_f32 v[136:139], v110, v126, v[136:139]
	v_mfma_f32_16x16x4_f32 v[136:139], v111, v127, v[136:139]
	s_waitcnt lgkmcnt(6)
	v_mfma_f32_16x16x4_f32 v[136:139], v112, v128, v[136:139]
	v_mfma_f32_16x16x4_f32 v[136:139], v113, v129, v[136:139]
	s_waitcnt vmcnt(58)
	ds_write_b128 v2, v[68:71] offset:0
	ds_write_b128 v2, v[72:75] offset:10240
	s_add_u32 s10, s0, 0x580000
	s_addc_u32 s11, s1, 0
	global_load_dwordx4 v[68:71], v0, s[10:11]
	global_load_dwordx4 v[72:75], v1, s[10:11]
	s_waitcnt lgkmcnt(6)
	v_mfma_f32_16x16x4_f32 v[136:139], v114, v130, v[136:139]
	v_mfma_f32_16x16x4_f32 v[136:139], v115, v131, v[136:139]
	s_waitcnt lgkmcnt(4)
	v_mfma_f32_16x16x4_f32 v[136:139], v116, v132, v[136:139]
	v_mfma_f32_16x16x4_f32 v[136:139], v117, v133, v[136:139]
	s_waitcnt lgkmcnt(2)
	v_mfma_f32_16x16x4_f32 v[136:139], v118, v134, v[136:139]
	v_mfma_f32_16x16x4_f32 v[136:139], v119, v135, v[136:139]
	s_add_u32 s16, s8, 0x4c0000
	s_addc_u32 s17, s9, 0
	s_nop 9
	ds_write_b32 v13, v136 offset:0
	ds_write_b32 v13, v137 offset:272
	ds_write_b32 v13, v138 offset:544
	ds_write_b32 v13, v139 offset:816
	global_store_dword v12, v136, s[16:17] offset:0
	global_store_dword v12, v137, s[16:17] offset:256
	global_store_dword v12, v138, s[16:17] offset:512
	global_store_dword v12, v139, s[16:17] offset:768
	s_waitcnt lgkmcnt(0)
	s_barrier
	ds_read2_b32 v[104:105], v8 offset0:0 offset1:4
	ds_read2st64_b32 v[120:121], v10 offset0:0 offset1:5
	ds_read2_b32 v[106:107], v8 offset0:8 offset1:12
	ds_read2st64_b32 v[122:123], v10 offset0:10 offset1:15
	ds_read2_b32 v[108:109], v8 offset0:16 offset1:20
	ds_read2st64_b32 v[124:125], v10 offset0:20 offset1:25
	ds_read2_b32 v[110:111], v8 offset0:24 offset1:28
	ds_read2st64_b32 v[126:127], v10 offset0:30 offset1:35
	ds_read2_b32 v[112:113], v8 offset0:32 offset1:36
	ds_read2st64_b32 v[128:129], v10 offset0:40 offset1:45
	ds_read2_b32 v[114:115], v8 offset0:40 offset1:44
	ds_read2st64_b32 v[130:131], v10 offset0:50 offset1:55
	ds_read2_b32 v[116:117], v8 offset0:48 offset1:52
	ds_read2st64_b32 v[132:133], v10 offset0:60 offset1:65
	s_waitcnt vmcnt(56)
	s_waitcnt lgkmcnt(12)
	v_mfma_f32_16x16x4_f32 v[136:139], v104, v120, v[212:215]
	v_mfma_f32_16x16x4_f32 v[136:139], v105, v121, v[136:139]
	ds_read2_b32 v[118:119], v8 offset0:56 offset1:60
	ds_read2st64_b32 v[134:135], v10 offset0:70 offset1:75
	s_waitcnt lgkmcnt(12)
	v_mfma_f32_16x16x4_f32 v[136:139], v106, v122, v[136:139]
	v_mfma_f32_16x16x4_f32 v[136:139], v107, v123, v[136:139]
	s_waitcnt lgkmcnt(10)
	v_mfma_f32_16x16x4_f32 v[136:139], v108, v124, v[136:139]
	v_mfma_f32_16x16x4_f32 v[136:139], v109, v125, v[136:139]
	s_add_u32 s14, s6, 0x580000
	s_addc_u32 s15, s7, 0
	global_load_dword v212, v12, s[14:15] offset:0
	global_load_dword v213, v12, s[14:15] offset:256
	global_load_dword v214, v12, s[14:15] offset:512
	global_load_dword v215, v12, s[14:15] offset:768
	s_waitcnt lgkmcnt(8)
	v_mfma_f32_16x16x4_f32 v[136:139], v110, v126, v[136:139]
	v_mfma_f32_16x16x4_f32 v[136:139], v111, v127, v[136:139]
	s_waitcnt lgkmcnt(6)
	v_mfma_f32_16x16x4_f32 v[136:139], v112, v128, v[136:139]
	v_mfma_f32_16x16x4_f32 v[136:139], v113, v129, v[136:139]
	s_waitcnt vmcnt(58)
	ds_write_b128 v2, v[76:79] offset:20480
	ds_write_b128 v2, v[80:83] offset:30720
	s_add_u32 s10, s0, 0x5a0000
	s_addc_u32 s11, s1, 0
	global_load_dwordx4 v[76:79], v0, s[10:11]
	global_load_dwordx4 v[80:83], v1, s[10:11]
	s_waitcnt lgkmcnt(6)
	v_mfma_f32_16x16x4_f32 v[136:139], v114, v130, v[136:139]
	v_mfma_f32_16x16x4_f32 v[136:139], v115, v131, v[136:139]
	s_waitcnt lgkmcnt(4)
	v_mfma_f32_16x16x4_f32 v[136:139], v116, v132, v[136:139]
	v_mfma_f32_16x16x4_f32 v[136:139], v117, v133, v[136:139]
	s_waitcnt lgkmcnt(2)
	v_mfma_f32_16x16x4_f32 v[136:139], v118, v134, v[136:139]
	v_mfma_f32_16x16x4_f32 v[136:139], v119, v135, v[136:139]
	s_add_u32 s16, s8, 0x4e0000
	s_addc_u32 s17, s9, 0
	s_nop 9
	ds_write_b32 v13, v136 offset:2176
	ds_write_b32 v13, v137 offset:2448
	ds_write_b32 v13, v138 offset:2720
	ds_write_b32 v13, v139 offset:2992
	global_store_dword v12, v136, s[16:17] offset:0
	global_store_dword v12, v137, s[16:17] offset:256
	global_store_dword v12, v138, s[16:17] offset:512
	global_store_dword v12, v139, s[16:17] offset:768
	s_waitcnt lgkmcnt(0)
	s_barrier
; #define LAS __attribute__((address_space(3)))
; __device__ __forceinline__ void scan_combine(LAS unsigned char* lds, CArgsP a) {
;     ...
;     for (int g = 1; g <= GL; ++g) {
;         const bool pf = (g + 2 <= GL);
;         float u3 = 0.f;
;         if (pf) { const f32x4* Pn = (const f32x4*)(PM + (size_t)((g + 2) * 8 + h) * 4096); pa = Pn[tid]; pb = Pn[512 + tid]; u3 = UM[((size_t)((g + 2) * 8 + h) * 64 + v) * 64 + kq]; }
;         asm volatile("s_waitcnt lgkmcnt(0)\n\ts_barrier" ::: "memory");
;         const LAS float* Pg = Pl + (g % 3) * 4096 + kq;
;         float acc0 = u1, acc1 = 0.f, acc2 = 0.f, acc3 = 0.f;
;         const int curi = __builtin_bit_cast(int, cur);
; #pragma unroll
;         for (int k = 0; k < 64; k += 4) {
;             const float s0 = __builtin_bit_cast(float, __builtin_amdgcn_readlane(curi, k)), s1 = __builtin_bit_cast(float, __builtin_amdgcn_readlane(curi, k + 1));
;             const float s2 = __builtin_bit_cast(float, __builtin_amdgcn_readlane(curi, k + 2)), s3 = __builtin_bit_cast(float, __builtin_amdgcn_readlane(curi, k + 3));
;             acc0 += s0 * Pg[(k + 0) * 64]; acc1 += s1 * Pg[(k + 1) * 64]; acc2 += s2 * Pg[(k + 2) * 64]; acc3 += s3 * Pg[(k + 3) * 64];
;         }
;         cur = (acc0 + acc1) + (acc2 + acc3);
;         SS[((size_t)((g + 1) * 8 + h) * 64 + v) * 64 + kq] = cur;
;         if (pf) { LAS float* dst = Pl + ((g + 2) % 3) * 4096; *(LAS f32x4*)(dst + 4 * tid) = pa; *(LAS f32x4*)(dst + 2048 + 4 * tid) = pb; }
;         u1 = u2; u2 = u3;
	ds_read2_b32 v[104:105], v9 offset0:0 offset1:4
	ds_read2st64_b32 v[120:121], v11 offset0:0 offset1:5
	ds_read2_b32 v[106:107], v9 offset0:8 offset1:12
	ds_read2st64_b32 v[122:123], v11 offset0:10 offset1:15
	ds_read2_b32 v[108:109], v9 offset0:16 offset1:20
	ds_read2st64_b32 v[124:125], v11 offset0:20 offset1:25
	ds_read2_b32 v[110:111], v9 offset0:24 offset1:28
	ds_read2st64_b32 v[126:127], v11 offset0:30 offset1:35
	ds_read2_b32 v[112:113], v9 offset0:32 offset1:36
	ds_read2st64_b32 v[128:129], v11 offset0:40 offset1:45
	ds_read2_b32 v[114:115], v9 offset0:40 offset1:44
	ds_read2st64_b32 v[130:131], v11 offset0:50 offset1:55
	ds_read2_b32 v[116:117], v9 offset0:48 offset1:52
	ds_read2st64_b32 v[132:133], v11 offset0:60 offset1:65
	s_waitcnt vmcnt(56)
	s_waitcnt lgkmcnt(12)
	v_mfma_f32_16x16x4_f32 v[136:139], v104, v120, v[216:219]
	v_mfma_f32_16x16x4_f32 v[136:139], v105, v121, v[136:139]
	ds_read2_b32 v[118:119], v9 offset0:56 offset1:60
	ds_read2st64_b32 v[134:135], v11 offset0:70 offset1:75
	s_waitcnt lgkmcnt(12)
	v_mfma_f32_16x16x4_f32 v[136:139], v106, v122, v[136:139]
	v_mfma_f32_16x16x4_f32 v[136:139], v107, v123, v[136:139]
	s_waitcnt lgkmcnt(10)
	v_mfma_f32_16x16x4_f32 v[136:139], v108, v124, v[136:139]
	v_mfma_f32_16x16x4_f32 v[136:139], v109, v125, v[136:139]
	s_add_u32 s14, s6, 0x5a0000
	s_addc_u32 s15, s7, 0
	global_load_dword v216, v12, s[14:15] offset:0
	global_load_dword v217, v12, s[14:15] offset:256
	global_load_dword v218, v12, s[14:15] offset:512
	global_load_dword v219, v12, s[14:15] offset:768
	s_waitcnt lgkmcnt(8)
	v_mfma_f32_16x16x4_f32 v[136:139], v110, v126, v[136:139]
	v_mfma_f32_16x16x4_f32 v[136:139], v111, v127, v[136:139]
	s_waitcnt lgkmcnt(6)
	v_mfma_f32_16x16x4_f32 v[136:139], v112, v128, v[136:139]
	v_mfma_f32_16x16x4_f32 v[136:139], v113, v129, v[136:139]
	s_waitcnt vmcnt(58)
	ds_write_b128 v2, v[84:87] offset:0
	ds_write_b128 v2, v[88:91] offset:10240
	s_add_u32 s10, s0, 0x5c0000
	s_addc_u32 s11, s1, 0
	global_load_dwordx4 v[84:87], v0, s[10:11]
	global_load_dwordx4 v[88:91], v1, s[10:11]
	s_waitcnt lgkmcnt(6)
	v_mfma_f32_16x16x4_f32 v[136:139], v114, v130, v[136:139]
	v_mfma_f32_16x16x4_f32 v[136:139], v115, v131, v[136:139]
	s_waitcnt lgkmcnt(4)
	v_mfma_f32_16x16x4_f32 v[136:139], v116, v132, v[136:139]
	v_mfma_f32_16x16x4_f32 v[136:139], v117, v133, v[136:139]
	s_waitcnt lgkmcnt(2)
	v_mfma_f32_16x16x4_f32 v[136:139], v118, v134, v[136:139]
	v_mfma_f32_16x16x4_f32 v[136:139], v119, v135, v[136:139]
	s_add_u32 s16, s8, 0x500000
	s_addc_u32 s17, s9, 0
	s_nop 9
	ds_write_b32 v13, v136 offset:0
	ds_write_b32 v13, v137 offset:272
	ds_write_b32 v13, v138 offset:544
	ds_write_b32 v13, v139 offset:816
	global_store_dword v12, v136, s[16:17] offset:0
	global_store_dword v12, v137, s[16:17] offset:256
	global_store_dword v12, v138, s[16:17] offset:512
	global_store_dword v12, v139, s[16:17] offset:768
	s_waitcnt lgkmcnt(0)
	s_barrier
	ds_read2_b32 v[104:105], v8 offset0:0 offset1:4
	ds_read2st64_b32 v[120:121], v10 offset0:0 offset1:5
	ds_read2_b32 v[106:107], v8 offset0:8 offset1:12
	ds_read2st64_b32 v[122:123], v10 offset0:10 offset1:15
	ds_read2_b32 v[108:109], v8 offset0:16 offset1:20
	ds_read2st64_b32 v[124:125], v10 offset0:20 offset1:25
	ds_read2_b32 v[110:111], v8 offset0:24 offset1:28
	ds_read2st64_b32 v[126:127], v10 offset0:30 offset1:35
	ds_read2_b32 v[112:113], v8 offset0:32 offset1:36
	ds_read2st64_b32 v[128:129], v10 offset0:40 offset1:45
	ds_read2_b32 v[114:115], v8 offset0:40 offset1:44
	ds_read2st64_b32 v[130:131], v10 offset0:50 offset1:55
	ds_read2_b32 v[116:117], v8 offset0:48 offset1:52
	ds_read2st64_b32 v[132:133], v10 offset0:60 offset1:65
	s_waitcnt vmcnt(56)
	s_waitcnt lgkmcnt(12)
	v_mfma_f32_16x16x4_f32 v[136:139], v104, v120, v[220:223]
	v_mfma_f32_16x16x4_f32 v[136:139], v105, v121, v[136:139]
	ds_read2_b32 v[118:119], v8 offset0:56 offset1:60
	ds_read2st64_b32 v[134:135], v10 offset0:70 offset1:75
	s_waitcnt lgkmcnt(12)
	v_mfma_f32_16x16x4_f32 v[136:139], v106, v122, v[136:139]
	v_mfma_f32_16x16x4_f32 v[136:139], v107, v123, v[136:139]
	s_waitcnt lgkmcnt(10)
	v_mfma_f32_16x16x4_f32 v[136:139], v108, v124, v[136:139]
	v_mfma_f32_16x16x4_f32 v[136:139], v109, v125, v[136:139]
	s_add_u32 s14, s6, 0x5c0000
	s_addc_u32 s15, s7, 0
	global_load_dword v220, v12, s[14:15] offset:0
	global_load_dword v221, v12, s[14:15] offset:256
	global_load_dword v222, v12, s[14:15] offset:512
	global_load_dword v223, v12, s[14:15] offset:768
	s_waitcnt lgkmcnt(8)
	v_mfma_f32_16x16x4_f32 v[136:139], v110, v126, v[136:139]
	v_mfma_f32_16x16x4_f32 v[136:139], v111, v127, v[136:139]
	s_waitcnt lgkmcnt(6)
	v_mfma_f32_16x16x4_f32 v[136:139], v112, v128, v[136:139]
	v_mfma_f32_16x16x4_f32 v[136:139], v113, v129, v[136:139]
	s_waitcnt vmcnt(58)
	ds_write_b128 v2, v[92:95] offset:20480
	ds_write_b128 v2, v[96:99] offset:30720
	s_add_u32 s10, s0, 0x5e0000
	s_addc_u32 s11, s1, 0
	global_load_dwordx4 v[92:95], v0, s[10:11]
	global_load_dwordx4 v[96:99], v1, s[10:11]
	s_waitcnt lgkmcnt(6)
	v_mfma_f32_16x16x4_f32 v[136:139], v114, v130, v[136:139]
	v_mfma_f32_16x16x4_f32 v[136:139], v115, v131, v[136:139]
	s_waitcnt lgkmcnt(4)
	v_mfma_f32_16x16x4_f32 v[136:139], v116, v132, v[136:139]
	v_mfma_f32_16x16x4_f32 v[136:139], v117, v133, v[136:139]
	s_waitcnt lgkmcnt(2)
	v_mfma_f32_16x16x4_f32 v[136:139], v118, v134, v[136:139]
	v_mfma_f32_16x16x4_f32 v[136:139], v119, v135, v[136:139]
	s_add_u32 s16, s8, 0x520000
	s_addc_u32 s17, s9, 0
	s_nop 9
	ds_write_b32 v13, v136 offset:2176
	ds_write_b32 v13, v137 offset:2448
	ds_write_b32 v13, v138 offset:2720
	ds_write_b32 v13, v139 offset:2992
	global_store_dword v12, v136, s[16:17] offset:0
	global_store_dword v12, v137, s[16:17] offset:256
	global_store_dword v12, v138, s[16:17] offset:512
	global_store_dword v12, v139, s[16:17] offset:768
	s_waitcnt lgkmcnt(0)
	s_barrier
; #define LAS __attribute__((address_space(3)))
; __device__ __forceinline__ void scan_combine(LAS unsigned char* lds, CArgsP a) {
;     ...
;     for (int g = 1; g <= GL; ++g) {
;         const bool pf = (g + 2 <= GL);
;         float u3 = 0.f;
;         if (pf) { const f32x4* Pn = (const f32x4*)(PM + (size_t)((g + 2) * 8 + h) * 4096); pa = Pn[tid]; pb = Pn[512 + tid]; u3 = UM[((size_t)((g + 2) * 8 + h) * 64 + v) * 64 + kq]; }
;         asm volatile("s_waitcnt lgkmcnt(0)\n\ts_barrier" ::: "memory");
;         const LAS float* Pg = Pl + (g % 3) * 4096 + kq;
;         float acc0 = u1, acc1 = 0.f, acc2 = 0.f, acc3 = 0.f;
;         const int curi = __builtin_bit_cast(int, cur);
; #pragma unroll
;         for (int k = 0; k < 64; k += 4) {
;             const float s0 = __builtin_bit_cast(float, __builtin_amdgcn_readlane(curi, k)), s1 = __builtin_bit_cast(float, __builtin_amdgcn_readlane(curi, k + 1));
;             const float s2 = __builtin_bit_cast(float, __builtin_amdgcn_readlane(curi, k + 2)), s3 = __builtin_bit_cast(float, __builtin_amdgcn_readlane(curi, k + 3));
;             acc0 += s0 * Pg[(k + 0) * 64]; acc1 += s1 * Pg[(k + 1) * 64]; acc2 += s2 * Pg[(k + 2) * 64]; acc3 += s3 * Pg[(k + 3) * 64];
;         }
;         cur = (acc0 + acc1) + (acc2 + acc3);
;         SS[((size_t)((g + 1) * 8 + h) * 64 + v) * 64 + kq] = cur;
;         if (pf) { LAS float* dst = Pl + ((g + 2) % 3) * 4096; *(LAS f32x4*)(dst + 4 * tid) = pa; *(LAS f32x4*)(dst + 2048 + 4 * tid) = pb; }
;         u1 = u2; u2 = u3;
	ds_read2_b32 v[104:105], v9 offset0:0 offset1:4
	ds_read2st64_b32 v[120:121], v11 offset0:0 offset1:5
	ds_read2_b32 v[106:107], v9 offset0:8 offset1:12
	ds_read2st64_b32 v[122:123], v11 offset0:10 offset1:15
	ds_read2_b32 v[108:109], v9 offset0:16 offset1:20
	ds_read2st64_b32 v[124:125], v11 offset0:20 offset1:25
	ds_read2_b32 v[110:111], v9 offset0:24 offset1:28
	ds_read2st64_b32 v[126:127], v11 offset0:30 offset1:35
	ds_read2_b32 v[112:113], v9 offset0:32 offset1:36
	ds_read2st64_b32 v[128:129], v11 offset0:40 offset1:45
	ds_read2_b32 v[114:115], v9 offset0:40 offset1:44
	ds_read2st64_b32 v[130:131], v11 offset0:50 offset1:55
	ds_read2_b32 v[116:117], v9 offset0:48 offset1:52
	ds_read2st64_b32 v[132:133], v11 offset0:60 offset1:65
	s_waitcnt vmcnt(56)
	s_waitcnt lgkmcnt(12)
	v_mfma_f32_16x16x4_f32 v[136:139], v104, v120, v[224:227]
	v_mfma_f32_16x16x4_f32 v[136:139], v105, v121, v[136:139]
	ds_read2_b32 v[118:119], v9 offset0:56 offset1:60
	ds_read2st64_b32 v[134:135], v11 offset0:70 offset1:75
	s_waitcnt lgkmcnt(12)
	v_mfma_f32_16x16x4_f32 v[136:139], v106, v122, v[136:139]
	v_mfma_f32_16x16x4_f32 v[136:139], v107, v123, v[136:139]
	s_waitcnt lgkmcnt(10)
	v_mfma_f32_16x16x4_f32 v[136:139], v108, v124, v[136:139]
	v_mfma_f32_16x16x4_f32 v[136:139], v109, v125, v[136:139]
	s_add_u32 s14, s6, 0x5e0000
	s_addc_u32 s15, s7, 0
	global_load_dword v224, v12, s[14:15] offset:0
	global_load_dword v225, v12, s[14:15] offset:256
	global_load_dword v226, v12, s[14:15] offset:512
	global_load_dword v227, v12, s[14:15] offset:768
	s_waitcnt lgkmcnt(8)
	v_mfma_f32_16x16x4_f32 v[136:139], v110, v126, v[136:139]
	v_mfma_f32_16x16x4_f32 v[136:139], v111, v127, v[136:139]
	s_waitcnt lgkmcnt(6)
	v_mfma_f32_16x16x4_f32 v[136:139], v112, v128, v[136:139]
	v_mfma_f32_16x16x4_f32 v[136:139], v113, v129, v[136:139]
	s_waitcnt vmcnt(58)
	ds_write_b128 v2, v[52:55] offset:0
	ds_write_b128 v2, v[56:59] offset:10240
	s_add_u32 s10, s0, 0x600000
	s_addc_u32 s11, s1, 0
	global_load_dwordx4 v[52:55], v0, s[10:11]
	global_load_dwordx4 v[56:59], v1, s[10:11]
	s_waitcnt lgkmcnt(6)
	v_mfma_f32_16x16x4_f32 v[136:139], v114, v130, v[136:139]
	v_mfma_f32_16x16x4_f32 v[136:139], v115, v131, v[136:139]
	s_waitcnt lgkmcnt(4)
	v_mfma_f32_16x16x4_f32 v[136:139], v116, v132, v[136:139]
	v_mfma_f32_16x16x4_f32 v[136:139], v117, v133, v[136:139]
	s_waitcnt lgkmcnt(2)
	v_mfma_f32_16x16x4_f32 v[136:139], v118, v134, v[136:139]
	v_mfma_f32_16x16x4_f32 v[136:139], v119, v135, v[136:139]
	s_add_u32 s16, s8, 0x540000
	s_addc_u32 s17, s9, 0
	s_nop 9
	ds_write_b32 v13, v136 offset:0
	ds_write_b32 v13, v137 offset:272
	ds_write_b32 v13, v138 offset:544
	ds_write_b32 v13, v139 offset:816
	global_store_dword v12, v136, s[16:17] offset:0
	global_store_dword v12, v137, s[16:17] offset:256
	global_store_dword v12, v138, s[16:17] offset:512
	global_store_dword v12, v139, s[16:17] offset:768
	s_waitcnt lgkmcnt(0)
	s_barrier
	ds_read2_b32 v[104:105], v8 offset0:0 offset1:4
	ds_read2st64_b32 v[120:121], v10 offset0:0 offset1:5
	ds_read2_b32 v[106:107], v8 offset0:8 offset1:12
	ds_read2st64_b32 v[122:123], v10 offset0:10 offset1:15
	ds_read2_b32 v[108:109], v8 offset0:16 offset1:20
	ds_read2st64_b32 v[124:125], v10 offset0:20 offset1:25
	ds_read2_b32 v[110:111], v8 offset0:24 offset1:28
	ds_read2st64_b32 v[126:127], v10 offset0:30 offset1:35
	ds_read2_b32 v[112:113], v8 offset0:32 offset1:36
	ds_read2st64_b32 v[128:129], v10 offset0:40 offset1:45
	ds_read2_b32 v[114:115], v8 offset0:40 offset1:44
	ds_read2st64_b32 v[130:131], v10 offset0:50 offset1:55
	ds_read2_b32 v[116:117], v8 offset0:48 offset1:52
	ds_read2st64_b32 v[132:133], v10 offset0:60 offset1:65
	s_waitcnt vmcnt(56)
	s_waitcnt lgkmcnt(12)
	v_mfma_f32_16x16x4_f32 v[136:139], v104, v120, v[204:207]
	v_mfma_f32_16x16x4_f32 v[136:139], v105, v121, v[136:139]
	ds_read2_b32 v[118:119], v8 offset0:56 offset1:60
	ds_read2st64_b32 v[134:135], v10 offset0:70 offset1:75
	s_waitcnt lgkmcnt(12)
	v_mfma_f32_16x16x4_f32 v[136:139], v106, v122, v[136:139]
	v_mfma_f32_16x16x4_f32 v[136:139], v107, v123, v[136:139]
	s_waitcnt lgkmcnt(10)
	v_mfma_f32_16x16x4_f32 v[136:139], v108, v124, v[136:139]
	v_mfma_f32_16x16x4_f32 v[136:139], v109, v125, v[136:139]
	s_add_u32 s14, s6, 0x600000
	s_addc_u32 s15, s7, 0
	global_load_dword v204, v12, s[14:15] offset:0
	global_load_dword v205, v12, s[14:15] offset:256
	global_load_dword v206, v12, s[14:15] offset:512
	global_load_dword v207, v12, s[14:15] offset:768
	s_waitcnt lgkmcnt(8)
	v_mfma_f32_16x16x4_f32 v[136:139], v110, v126, v[136:139]
	v_mfma_f32_16x16x4_f32 v[136:139], v111, v127, v[136:139]
	s_waitcnt lgkmcnt(6)
	v_mfma_f32_16x16x4_f32 v[136:139], v112, v128, v[136:139]
	v_mfma_f32_16x16x4_f32 v[136:139], v113, v129, v[136:139]
	s_waitcnt vmcnt(58)
	ds_write_b128 v2, v[60:63] offset:20480
	ds_write_b128 v2, v[64:67] offset:30720
	s_add_u32 s10, s0, 0x620000
	s_addc_u32 s11, s1, 0
	global_load_dwordx4 v[60:63], v0, s[10:11]
	global_load_dwordx4 v[64:67], v1, s[10:11]
	s_waitcnt lgkmcnt(6)
	v_mfma_f32_16x16x4_f32 v[136:139], v114, v130, v[136:139]
	v_mfma_f32_16x16x4_f32 v[136:139], v115, v131, v[136:139]
	s_waitcnt lgkmcnt(4)
	v_mfma_f32_16x16x4_f32 v[136:139], v116, v132, v[136:139]
	v_mfma_f32_16x16x4_f32 v[136:139], v117, v133, v[136:139]
	s_waitcnt lgkmcnt(2)
	v_mfma_f32_16x16x4_f32 v[136:139], v118, v134, v[136:139]
	v_mfma_f32_16x16x4_f32 v[136:139], v119, v135, v[136:139]
	s_add_u32 s16, s8, 0x560000
	s_addc_u32 s17, s9, 0
	s_nop 9
	ds_write_b32 v13, v136 offset:2176
	ds_write_b32 v13, v137 offset:2448
	ds_write_b32 v13, v138 offset:2720
	ds_write_b32 v13, v139 offset:2992
	global_store_dword v12, v136, s[16:17] offset:0
	global_store_dword v12, v137, s[16:17] offset:256
	global_store_dword v12, v138, s[16:17] offset:512
	global_store_dword v12, v139, s[16:17] offset:768
	s_waitcnt lgkmcnt(0)
	s_barrier
; #define LAS __attribute__((address_space(3)))
; __device__ __forceinline__ void scan_combine(LAS unsigned char* lds, CArgsP a) {
;     ...
;     for (int g = 1; g <= GL; ++g) {
;         const bool pf = (g + 2 <= GL);
;         float u3 = 0.f;
;         if (pf) { const f32x4* Pn = (const f32x4*)(PM + (size_t)((g + 2) * 8 + h) * 4096); pa = Pn[tid]; pb = Pn[512 + tid]; u3 = UM[((size_t)((g + 2) * 8 + h) * 64 + v) * 64 + kq]; }
;         asm volatile("s_waitcnt lgkmcnt(0)\n\ts_barrier" ::: "memory");
;         const LAS float* Pg = Pl + (g % 3) * 4096 + kq;
;         float acc0 = u1, acc1 = 0.f, acc2 = 0.f, acc3 = 0.f;
;         const int curi = __builtin_bit_cast(int, cur);
; #pragma unroll
;         for (int k = 0; k < 64; k += 4) {
;             const float s0 = __builtin_bit_cast(float, __builtin_amdgcn_readlane(curi, k)), s1 = __builtin_bit_cast(float, __builtin_amdgcn_readlane(curi, k + 1));
;             const float s2 = __builtin_bit_cast(float, __builtin_amdgcn_readlane(curi, k + 2)), s3 = __builtin_bit_cast(float, __builtin_amdgcn_readlane(curi, k + 3));
;             acc0 += s0 * Pg[(k + 0) * 64]; acc1 += s1 * Pg[(k + 1) * 64]; acc2 += s2 * Pg[(k + 2) * 64]; acc3 += s3 * Pg[(k + 3) * 64];
;         }
;         cur = (acc0 + acc1) + (acc2 + acc3);
;         SS[((size_t)((g + 1) * 8 + h) * 64 + v) * 64 + kq] = cur;
;         if (pf) { LAS float* dst = Pl + ((g + 2) % 3) * 4096; *(LAS f32x4*)(dst + 4 * tid) = pa; *(LAS f32x4*)(dst + 2048 + 4 * tid) = pb; }
;         u1 = u2; u2 = u3;
	ds_read2_b32 v[104:105], v9 offset0:0 offset1:4
	ds_read2st64_b32 v[120:121], v11 offset0:0 offset1:5
	ds_read2_b32 v[106:107], v9 offset0:8 offset1:12
	ds_read2st64_b32 v[122:123], v11 offset0:10 offset1:15
	ds_read2_b32 v[108:109], v9 offset0:16 offset1:20
	ds_read2st64_b32 v[124:125], v11 offset0:20 offset1:25
	ds_read2_b32 v[110:111], v9 offset0:24 offset1:28
	ds_read2st64_b32 v[126:127], v11 offset0:30 offset1:35
	ds_read2_b32 v[112:113], v9 offset0:32 offset1:36
	ds_read2st64_b32 v[128:129], v11 offset0:40 offset1:45
	ds_read2_b32 v[114:115], v9 offset0:40 offset1:44
	ds_read2st64_b32 v[130:131], v11 offset0:50 offset1:55
	ds_read2_b32 v[116:117], v9 offset0:48 offset1:52
	ds_read2st64_b32 v[132:133], v11 offset0:60 offset1:65
	s_waitcnt vmcnt(56)
	s_waitcnt lgkmcnt(12)
	v_mfma_f32_16x16x4_f32 v[136:139], v104, v120, v[208:211]
	v_mfma_f32_16x16x4_f32 v[136:139], v105, v121, v[136:139]
	ds_read2_b32 v[118:119], v9 offset0:56 offset1:60
	ds_read2st64_b32 v[134:135], v11 offset0:70 offset1:75
	s_waitcnt lgkmcnt(12)
	v_mfma_f32_16x16x4_f32 v[136:139], v106, v122, v[136:139]
	v_mfma_f32_16x16x4_f32 v[136:139], v107, v123, v[136:139]
	s_waitcnt lgkmcnt(10)
	v_mfma_f32_16x16x4_f32 v[136:139], v108, v124, v[136:139]
	v_mfma_f32_16x16x4_f32 v[136:139], v109, v125, v[136:139]
	s_add_u32 s14, s6, 0x620000
	s_addc_u32 s15, s7, 0
	global_load_dword v208, v12, s[14:15] offset:0
	global_load_dword v209, v12, s[14:15] offset:256
	global_load_dword v210, v12, s[14:15] offset:512
	global_load_dword v211, v12, s[14:15] offset:768
	s_waitcnt lgkmcnt(8)
	v_mfma_f32_16x16x4_f32 v[136:139], v110, v126, v[136:139]
	v_mfma_f32_16x16x4_f32 v[136:139], v111, v127, v[136:139]
	s_waitcnt lgkmcnt(6)
	v_mfma_f32_16x16x4_f32 v[136:139], v112, v128, v[136:139]
	v_mfma_f32_16x16x4_f32 v[136:139], v113, v129, v[136:139]
	s_waitcnt vmcnt(58)
	ds_write_b128 v2, v[68:71] offset:0
	ds_write_b128 v2, v[72:75] offset:10240
	s_add_u32 s10, s0, 0x640000
	s_addc_u32 s11, s1, 0
	global_load_dwordx4 v[68:71], v0, s[10:11]
	global_load_dwordx4 v[72:75], v1, s[10:11]
	s_waitcnt lgkmcnt(6)
	v_mfma_f32_16x16x4_f32 v[136:139], v114, v130, v[136:139]
	v_mfma_f32_16x16x4_f32 v[136:139], v115, v131, v[136:139]
	s_waitcnt lgkmcnt(4)
	v_mfma_f32_16x16x4_f32 v[136:139], v116, v132, v[136:139]
	v_mfma_f32_16x16x4_f32 v[136:139], v117, v133, v[136:139]
	s_waitcnt lgkmcnt(2)
	v_mfma_f32_16x16x4_f32 v[136:139], v118, v134, v[136:139]
	v_mfma_f32_16x16x4_f32 v[136:139], v119, v135, v[136:139]
	s_add_u32 s16, s8, 0x580000
	s_addc_u32 s17, s9, 0
	s_nop 9
	ds_write_b32 v13, v136 offset:0
	ds_write_b32 v13, v137 offset:272
	ds_write_b32 v13, v138 offset:544
	ds_write_b32 v13, v139 offset:816
	global_store_dword v12, v136, s[16:17] offset:0
	global_store_dword v12, v137, s[16:17] offset:256
	global_store_dword v12, v138, s[16:17] offset:512
	global_store_dword v12, v139, s[16:17] offset:768
	s_waitcnt lgkmcnt(0)
	s_barrier
	ds_read2_b32 v[104:105], v8 offset0:0 offset1:4
	ds_read2st64_b32 v[120:121], v10 offset0:0 offset1:5
	ds_read2_b32 v[106:107], v8 offset0:8 offset1:12
	ds_read2st64_b32 v[122:123], v10 offset0:10 offset1:15
	ds_read2_b32 v[108:109], v8 offset0:16 offset1:20
	ds_read2st64_b32 v[124:125], v10 offset0:20 offset1:25
	ds_read2_b32 v[110:111], v8 offset0:24 offset1:28
	ds_read2st64_b32 v[126:127], v10 offset0:30 offset1:35
	ds_read2_b32 v[112:113], v8 offset0:32 offset1:36
	ds_read2st64_b32 v[128:129], v10 offset0:40 offset1:45
	ds_read2_b32 v[114:115], v8 offset0:40 offset1:44
	ds_read2st64_b32 v[130:131], v10 offset0:50 offset1:55
	ds_read2_b32 v[116:117], v8 offset0:48 offset1:52
	ds_read2st64_b32 v[132:133], v10 offset0:60 offset1:65
	s_waitcnt vmcnt(56)
	s_waitcnt lgkmcnt(12)
	v_mfma_f32_16x16x4_f32 v[136:139], v104, v120, v[212:215]
	v_mfma_f32_16x16x4_f32 v[136:139], v105, v121, v[136:139]
	ds_read2_b32 v[118:119], v8 offset0:56 offset1:60
	ds_read2st64_b32 v[134:135], v10 offset0:70 offset1:75
	s_waitcnt lgkmcnt(12)
	v_mfma_f32_16x16x4_f32 v[136:139], v106, v122, v[136:139]
	v_mfma_f32_16x16x4_f32 v[136:139], v107, v123, v[136:139]
	s_waitcnt lgkmcnt(10)
	v_mfma_f32_16x16x4_f32 v[136:139], v108, v124, v[136:139]
	v_mfma_f32_16x16x4_f32 v[136:139], v109, v125, v[136:139]
	s_add_u32 s14, s6, 0x640000
	s_addc_u32 s15, s7, 0
	global_load_dword v212, v12, s[14:15] offset:0
	global_load_dword v213, v12, s[14:15] offset:256
	global_load_dword v214, v12, s[14:15] offset:512
	global_load_dword v215, v12, s[14:15] offset:768
	s_waitcnt lgkmcnt(8)
	v_mfma_f32_16x16x4_f32 v[136:139], v110, v126, v[136:139]
	v_mfma_f32_16x16x4_f32 v[136:139], v111, v127, v[136:139]
	s_waitcnt lgkmcnt(6)
	v_mfma_f32_16x16x4_f32 v[136:139], v112, v128, v[136:139]
	v_mfma_f32_16x16x4_f32 v[136:139], v113, v129, v[136:139]
	s_waitcnt vmcnt(58)
	ds_write_b128 v2, v[76:79] offset:20480
	ds_write_b128 v2, v[80:83] offset:30720
	s_add_u32 s10, s0, 0x660000
	s_addc_u32 s11, s1, 0
	global_load_dwordx4 v[76:79], v0, s[10:11]
	global_load_dwordx4 v[80:83], v1, s[10:11]
	s_waitcnt lgkmcnt(6)
	v_mfma_f32_16x16x4_f32 v[136:139], v114, v130, v[136:139]
	v_mfma_f32_16x16x4_f32 v[136:139], v115, v131, v[136:139]
	s_waitcnt lgkmcnt(4)
	v_mfma_f32_16x16x4_f32 v[136:139], v116, v132, v[136:139]
	v_mfma_f32_16x16x4_f32 v[136:139], v117, v133, v[136:139]
	s_waitcnt lgkmcnt(2)
	v_mfma_f32_16x16x4_f32 v[136:139], v118, v134, v[136:139]
	v_mfma_f32_16x16x4_f32 v[136:139], v119, v135, v[136:139]
	s_add_u32 s16, s8, 0x5a0000
	s_addc_u32 s17, s9, 0
	s_nop 9
	ds_write_b32 v13, v136 offset:2176
	ds_write_b32 v13, v137 offset:2448
	ds_write_b32 v13, v138 offset:2720
	ds_write_b32 v13, v139 offset:2992
	global_store_dword v12, v136, s[16:17] offset:0
	global_store_dword v12, v137, s[16:17] offset:256
	global_store_dword v12, v138, s[16:17] offset:512
	global_store_dword v12, v139, s[16:17] offset:768
	s_waitcnt lgkmcnt(0)
	s_barrier
; #define LAS __attribute__((address_space(3)))
; __device__ __forceinline__ void scan_combine(LAS unsigned char* lds, CArgsP a) {
;     ...
;     for (int g = 1; g <= GL; ++g) {
;         const bool pf = (g + 2 <= GL);
;         float u3 = 0.f;
;         if (pf) { const f32x4* Pn = (const f32x4*)(PM + (size_t)((g + 2) * 8 + h) * 4096); pa = Pn[tid]; pb = Pn[512 + tid]; u3 = UM[((size_t)((g + 2) * 8 + h) * 64 + v) * 64 + kq]; }
;         asm volatile("s_waitcnt lgkmcnt(0)\n\ts_barrier" ::: "memory");
;         const LAS float* Pg = Pl + (g % 3) * 4096 + kq;
;         float acc0 = u1, acc1 = 0.f, acc2 = 0.f, acc3 = 0.f;
;         const int curi = __builtin_bit_cast(int, cur);
; #pragma unroll
;         for (int k = 0; k < 64; k += 4) {
;             const float s0 = __builtin_bit_cast(float, __builtin_amdgcn_readlane(curi, k)), s1 = __builtin_bit_cast(float, __builtin_amdgcn_readlane(curi, k + 1));
;             const float s2 = __builtin_bit_cast(float, __builtin_amdgcn_readlane(curi, k + 2)), s3 = __builtin_bit_cast(float, __builtin_amdgcn_readlane(curi, k + 3));
;             acc0 += s0 * Pg[(k + 0) * 64]; acc1 += s1 * Pg[(k + 1) * 64]; acc2 += s2 * Pg[(k + 2) * 64]; acc3 += s3 * Pg[(k + 3) * 64];
;         }
;         cur = (acc0 + acc1) + (acc2 + acc3);
;         SS[((size_t)((g + 1) * 8 + h) * 64 + v) * 64 + kq] = cur;
;         if (pf) { LAS float* dst = Pl + ((g + 2) % 3) * 4096; *(LAS f32x4*)(dst + 4 * tid) = pa; *(LAS f32x4*)(dst + 2048 + 4 * tid) = pb; }
;         u1 = u2; u2 = u3;
	ds_read2_b32 v[104:105], v9 offset0:0 offset1:4
	ds_read2st64_b32 v[120:121], v11 offset0:0 offset1:5
	ds_read2_b32 v[106:107], v9 offset0:8 offset1:12
	ds_read2st64_b32 v[122:123], v11 offset0:10 offset1:15
	ds_read2_b32 v[108:109], v9 offset0:16 offset1:20
	ds_read2st64_b32 v[124:125], v11 offset0:20 offset1:25
	ds_read2_b32 v[110:111], v9 offset0:24 offset1:28
	ds_read2st64_b32 v[126:127], v11 offset0:30 offset1:35
	ds_read2_b32 v[112:113], v9 offset0:32 offset1:36
	ds_read2st64_b32 v[128:129], v11 offset0:40 offset1:45
	ds_read2_b32 v[114:115], v9 offset0:40 offset1:44
	ds_read2st64_b32 v[130:131], v11 offset0:50 offset1:55
	ds_read2_b32 v[116:117], v9 offset0:48 offset1:52
	ds_read2st64_b32 v[132:133], v11 offset0:60 offset1:65
	s_waitcnt vmcnt(56)
	s_waitcnt lgkmcnt(12)
	v_mfma_f32_16x16x4_f32 v[136:139], v104, v120, v[216:219]
	v_mfma_f32_16x16x4_f32 v[136:139], v105, v121, v[136:139]
	ds_read2_b32 v[118:119], v9 offset0:56 offset1:60
	ds_read2st64_b32 v[134:135], v11 offset0:70 offset1:75
	s_waitcnt lgkmcnt(12)
	v_mfma_f32_16x16x4_f32 v[136:139], v106, v122, v[136:139]
	v_mfma_f32_16x16x4_f32 v[136:139], v107, v123, v[136:139]
	s_waitcnt lgkmcnt(10)
	v_mfma_f32_16x16x4_f32 v[136:139], v108, v124, v[136:139]
	v_mfma_f32_16x16x4_f32 v[136:139], v109, v125, v[136:139]
	s_add_u32 s14, s6, 0x660000
	s_addc_u32 s15, s7, 0
	global_load_dword v216, v12, s[14:15] offset:0
	global_load_dword v217, v12, s[14:15] offset:256
	global_load_dword v218, v12, s[14:15] offset:512
	global_load_dword v219, v12, s[14:15] offset:768
	s_waitcnt lgkmcnt(8)
	v_mfma_f32_16x16x4_f32 v[136:139], v110, v126, v[136:139]
	v_mfma_f32_16x16x4_f32 v[136:139], v111, v127, v[136:139]
	s_waitcnt lgkmcnt(6)
	v_mfma_f32_16x16x4_f32 v[136:139], v112, v128, v[136:139]
	v_mfma_f32_16x16x4_f32 v[136:139], v113, v129, v[136:139]
	s_waitcnt vmcnt(58)
	ds_write_b128 v2, v[84:87] offset:0
	ds_write_b128 v2, v[88:91] offset:10240
	s_add_u32 s10, s0, 0x680000
	s_addc_u32 s11, s1, 0
	global_load_dwordx4 v[84:87], v0, s[10:11]
	global_load_dwordx4 v[88:91], v1, s[10:11]
	s_waitcnt lgkmcnt(6)
	v_mfma_f32_16x16x4_f32 v[136:139], v114, v130, v[136:139]
	v_mfma_f32_16x16x4_f32 v[136:139], v115, v131, v[136:139]
	s_waitcnt lgkmcnt(4)
	v_mfma_f32_16x16x4_f32 v[136:139], v116, v132, v[136:139]
	v_mfma_f32_16x16x4_f32 v[136:139], v117, v133, v[136:139]
	s_waitcnt lgkmcnt(2)
	v_mfma_f32_16x16x4_f32 v[136:139], v118, v134, v[136:139]
	v_mfma_f32_16x16x4_f32 v[136:139], v119, v135, v[136:139]
	s_add_u32 s16, s8, 0x5c0000
	s_addc_u32 s17, s9, 0
	s_nop 9
	ds_write_b32 v13, v136 offset:0
	ds_write_b32 v13, v137 offset:272
	ds_write_b32 v13, v138 offset:544
	ds_write_b32 v13, v139 offset:816
	global_store_dword v12, v136, s[16:17] offset:0
	global_store_dword v12, v137, s[16:17] offset:256
	global_store_dword v12, v138, s[16:17] offset:512
	global_store_dword v12, v139, s[16:17] offset:768
	s_waitcnt lgkmcnt(0)
	s_barrier
	ds_read2_b32 v[104:105], v8 offset0:0 offset1:4
	ds_read2st64_b32 v[120:121], v10 offset0:0 offset1:5
	ds_read2_b32 v[106:107], v8 offset0:8 offset1:12
	ds_read2st64_b32 v[122:123], v10 offset0:10 offset1:15
	ds_read2_b32 v[108:109], v8 offset0:16 offset1:20
	ds_read2st64_b32 v[124:125], v10 offset0:20 offset1:25
	ds_read2_b32 v[110:111], v8 offset0:24 offset1:28
	ds_read2st64_b32 v[126:127], v10 offset0:30 offset1:35
	ds_read2_b32 v[112:113], v8 offset0:32 offset1:36
	ds_read2st64_b32 v[128:129], v10 offset0:40 offset1:45
	ds_read2_b32 v[114:115], v8 offset0:40 offset1:44
	ds_read2st64_b32 v[130:131], v10 offset0:50 offset1:55
	ds_read2_b32 v[116:117], v8 offset0:48 offset1:52
	ds_read2st64_b32 v[132:133], v10 offset0:60 offset1:65
	s_waitcnt vmcnt(56)
	s_waitcnt lgkmcnt(12)
	v_mfma_f32_16x16x4_f32 v[136:139], v104, v120, v[220:223]
	v_mfma_f32_16x16x4_f32 v[136:139], v105, v121, v[136:139]
	ds_read2_b32 v[118:119], v8 offset0:56 offset1:60
	ds_read2st64_b32 v[134:135], v10 offset0:70 offset1:75
	s_waitcnt lgkmcnt(12)
	v_mfma_f32_16x16x4_f32 v[136:139], v106, v122, v[136:139]
	v_mfma_f32_16x16x4_f32 v[136:139], v107, v123, v[136:139]
	s_waitcnt lgkmcnt(10)
	v_mfma_f32_16x16x4_f32 v[136:139], v108, v124, v[136:139]
	v_mfma_f32_16x16x4_f32 v[136:139], v109, v125, v[136:139]
	s_add_u32 s14, s6, 0x680000
	s_addc_u32 s15, s7, 0
	global_load_dword v220, v12, s[14:15] offset:0
	global_load_dword v221, v12, s[14:15] offset:256
	global_load_dword v222, v12, s[14:15] offset:512
	global_load_dword v223, v12, s[14:15] offset:768
	s_waitcnt lgkmcnt(8)
	v_mfma_f32_16x16x4_f32 v[136:139], v110, v126, v[136:139]
	v_mfma_f32_16x16x4_f32 v[136:139], v111, v127, v[136:139]
	s_waitcnt lgkmcnt(6)
	v_mfma_f32_16x16x4_f32 v[136:139], v112, v128, v[136:139]
	v_mfma_f32_16x16x4_f32 v[136:139], v113, v129, v[136:139]
	s_waitcnt vmcnt(58)
	ds_write_b128 v2, v[92:95] offset:20480
	ds_write_b128 v2, v[96:99] offset:30720
	s_add_u32 s10, s0, 0x6a0000
	s_addc_u32 s11, s1, 0
	global_load_dwordx4 v[92:95], v0, s[10:11]
	global_load_dwordx4 v[96:99], v1, s[10:11]
	s_waitcnt lgkmcnt(6)
	v_mfma_f32_16x16x4_f32 v[136:139], v114, v130, v[136:139]
	v_mfma_f32_16x16x4_f32 v[136:139], v115, v131, v[136:139]
	s_waitcnt lgkmcnt(4)
	v_mfma_f32_16x16x4_f32 v[136:139], v116, v132, v[136:139]
	v_mfma_f32_16x16x4_f32 v[136:139], v117, v133, v[136:139]
	s_waitcnt lgkmcnt(2)
	v_mfma_f32_16x16x4_f32 v[136:139], v118, v134, v[136:139]
	v_mfma_f32_16x16x4_f32 v[136:139], v119, v135, v[136:139]
	s_add_u32 s16, s8, 0x5e0000
	s_addc_u32 s17, s9, 0
	s_nop 9
	ds_write_b32 v13, v136 offset:2176
	ds_write_b32 v13, v137 offset:2448
	ds_write_b32 v13, v138 offset:2720
	ds_write_b32 v13, v139 offset:2992
	global_store_dword v12, v136, s[16:17] offset:0
	global_store_dword v12, v137, s[16:17] offset:256
	global_store_dword v12, v138, s[16:17] offset:512
	global_store_dword v12, v139, s[16:17] offset:768
	s_waitcnt lgkmcnt(0)
	s_barrier
; #define LAS __attribute__((address_space(3)))
; __device__ __forceinline__ void scan_combine(LAS unsigned char* lds, CArgsP a) {
;     ...
;     for (int g = 1; g <= GL; ++g) {
;         const bool pf = (g + 2 <= GL);
;         float u3 = 0.f;
;         if (pf) { const f32x4* Pn = (const f32x4*)(PM + (size_t)((g + 2) * 8 + h) * 4096); pa = Pn[tid]; pb = Pn[512 + tid]; u3 = UM[((size_t)((g + 2) * 8 + h) * 64 + v) * 64 + kq]; }
;         asm volatile("s_waitcnt lgkmcnt(0)\n\ts_barrier" ::: "memory");
;         const LAS float* Pg = Pl + (g % 3) * 4096 + kq;
;         float acc0 = u1, acc1 = 0.f, acc2 = 0.f, acc3 = 0.f;
;         const int curi = __builtin_bit_cast(int, cur);
; #pragma unroll
;         for (int k = 0; k < 64; k += 4) {
;             const float s0 = __builtin_bit_cast(float, __builtin_amdgcn_readlane(curi, k)), s1 = __builtin_bit_cast(float, __builtin_amdgcn_readlane(curi, k + 1));
;             const float s2 = __builtin_bit_cast(float, __builtin_amdgcn_readlane(curi, k + 2)), s3 = __builtin_bit_cast(float, __builtin_amdgcn_readlane(curi, k + 3));
;             acc0 += s0 * Pg[(k + 0) * 64]; acc1 += s1 * Pg[(k + 1) * 64]; acc2 += s2 * Pg[(k + 2) * 64]; acc3 += s3 * Pg[(k + 3) * 64];
;         }
;         cur = (acc0 + acc1) + (acc2 + acc3);
;         SS[((size_t)((g + 1) * 8 + h) * 64 + v) * 64 + kq] = cur;
;         if (pf) { LAS float* dst = Pl + ((g + 2) % 3) * 4096; *(LAS f32x4*)(dst + 4 * tid) = pa; *(LAS f32x4*)(dst + 2048 + 4 * tid) = pb; }
;         u1 = u2; u2 = u3;
	ds_read2_b32 v[104:105], v9 offset0:0 offset1:4
	ds_read2st64_b32 v[120:121], v11 offset0:0 offset1:5
	ds_read2_b32 v[106:107], v9 offset0:8 offset1:12
	ds_read2st64_b32 v[122:123], v11 offset0:10 offset1:15
	ds_read2_b32 v[108:109], v9 offset0:16 offset1:20
	ds_read2st64_b32 v[124:125], v11 offset0:20 offset1:25
	ds_read2_b32 v[110:111], v9 offset0:24 offset1:28
	ds_read2st64_b32 v[126:127], v11 offset0:30 offset1:35
	ds_read2_b32 v[112:113], v9 offset0:32 offset1:36
	ds_read2st64_b32 v[128:129], v11 offset0:40 offset1:45
	ds_read2_b32 v[114:115], v9 offset0:40 offset1:44
	ds_read2st64_b32 v[130:131], v11 offset0:50 offset1:55
	ds_read2_b32 v[116:117], v9 offset0:48 offset1:52
	ds_read2st64_b32 v[132:133], v11 offset0:60 offset1:65
	s_waitcnt vmcnt(56)
	s_waitcnt lgkmcnt(12)
	v_mfma_f32_16x16x4_f32 v[136:139], v104, v120, v[224:227]
	v_mfma_f32_16x16x4_f32 v[136:139], v105, v121, v[136:139]
	ds_read2_b32 v[118:119], v9 offset0:56 offset1:60
	ds_read2st64_b32 v[134:135], v11 offset0:70 offset1:75
	s_waitcnt lgkmcnt(12)
	v_mfma_f32_16x16x4_f32 v[136:139], v106, v122, v[136:139]
	v_mfma_f32_16x16x4_f32 v[136:139], v107, v123, v[136:139]
	s_waitcnt lgkmcnt(10)
	v_mfma_f32_16x16x4_f32 v[136:139], v108, v124, v[136:139]
	v_mfma_f32_16x16x4_f32 v[136:139], v109, v125, v[136:139]
	s_add_u32 s14, s6, 0x6a0000
	s_addc_u32 s15, s7, 0
	global_load_dword v224, v12, s[14:15] offset:0
	global_load_dword v225, v12, s[14:15] offset:256
	global_load_dword v226, v12, s[14:15] offset:512
	global_load_dword v227, v12, s[14:15] offset:768
	s_waitcnt lgkmcnt(8)
	v_mfma_f32_16x16x4_f32 v[136:139], v110, v126, v[136:139]
	v_mfma_f32_16x16x4_f32 v[136:139], v111, v127, v[136:139]
	s_waitcnt lgkmcnt(6)
	v_mfma_f32_16x16x4_f32 v[136:139], v112, v128, v[136:139]
	v_mfma_f32_16x16x4_f32 v[136:139], v113, v129, v[136:139]
	s_waitcnt vmcnt(58)
	ds_write_b128 v2, v[52:55] offset:0
	ds_write_b128 v2, v[56:59] offset:10240
	s_add_u32 s10, s0, 0x6c0000
	s_addc_u32 s11, s1, 0
	global_load_dwordx4 v[52:55], v0, s[10:11]
	global_load_dwordx4 v[56:59], v1, s[10:11]
	s_waitcnt lgkmcnt(6)
	v_mfma_f32_16x16x4_f32 v[136:139], v114, v130, v[136:139]
	v_mfma_f32_16x16x4_f32 v[136:139], v115, v131, v[136:139]
	s_waitcnt lgkmcnt(4)
	v_mfma_f32_16x16x4_f32 v[136:139], v116, v132, v[136:139]
	v_mfma_f32_16x16x4_f32 v[136:139], v117, v133, v[136:139]
	s_waitcnt lgkmcnt(2)
	v_mfma_f32_16x16x4_f32 v[136:139], v118, v134, v[136:139]
	v_mfma_f32_16x16x4_f32 v[136:139], v119, v135, v[136:139]
	s_add_u32 s16, s8, 0x600000
	s_addc_u32 s17, s9, 0
	s_nop 9
	ds_write_b32 v13, v136 offset:0
	ds_write_b32 v13, v137 offset:272
	ds_write_b32 v13, v138 offset:544
	ds_write_b32 v13, v139 offset:816
	global_store_dword v12, v136, s[16:17] offset:0
	global_store_dword v12, v137, s[16:17] offset:256
	global_store_dword v12, v138, s[16:17] offset:512
	global_store_dword v12, v139, s[16:17] offset:768
	s_waitcnt lgkmcnt(0)
	s_barrier
	ds_read2_b32 v[104:105], v8 offset0:0 offset1:4
	ds_read2st64_b32 v[120:121], v10 offset0:0 offset1:5
	ds_read2_b32 v[106:107], v8 offset0:8 offset1:12
	ds_read2st64_b32 v[122:123], v10 offset0:10 offset1:15
	ds_read2_b32 v[108:109], v8 offset0:16 offset1:20
	ds_read2st64_b32 v[124:125], v10 offset0:20 offset1:25
	ds_read2_b32 v[110:111], v8 offset0:24 offset1:28
	ds_read2st64_b32 v[126:127], v10 offset0:30 offset1:35
	ds_read2_b32 v[112:113], v8 offset0:32 offset1:36
	ds_read2st64_b32 v[128:129], v10 offset0:40 offset1:45
	ds_read2_b32 v[114:115], v8 offset0:40 offset1:44
	ds_read2st64_b32 v[130:131], v10 offset0:50 offset1:55
	ds_read2_b32 v[116:117], v8 offset0:48 offset1:52
	ds_read2st64_b32 v[132:133], v10 offset0:60 offset1:65
	s_waitcnt vmcnt(56)
	s_waitcnt lgkmcnt(12)
	v_mfma_f32_16x16x4_f32 v[136:139], v104, v120, v[204:207]
	v_mfma_f32_16x16x4_f32 v[136:139], v105, v121, v[136:139]
	ds_read2_b32 v[118:119], v8 offset0:56 offset1:60
	ds_read2st64_b32 v[134:135], v10 offset0:70 offset1:75
	s_waitcnt lgkmcnt(12)
	v_mfma_f32_16x16x4_f32 v[136:139], v106, v122, v[136:139]
	v_mfma_f32_16x16x4_f32 v[136:139], v107, v123, v[136:139]
	s_waitcnt lgkmcnt(10)
	v_mfma_f32_16x16x4_f32 v[136:139], v108, v124, v[136:139]
	v_mfma_f32_16x16x4_f32 v[136:139], v109, v125, v[136:139]
	s_add_u32 s14, s6, 0x6c0000
	s_addc_u32 s15, s7, 0
	global_load_dword v204, v12, s[14:15] offset:0
	global_load_dword v205, v12, s[14:15] offset:256
	global_load_dword v206, v12, s[14:15] offset:512
	global_load_dword v207, v12, s[14:15] offset:768
	s_waitcnt lgkmcnt(8)
	v_mfma_f32_16x16x4_f32 v[136:139], v110, v126, v[136:139]
	v_mfma_f32_16x16x4_f32 v[136:139], v111, v127, v[136:139]
	s_waitcnt lgkmcnt(6)
	v_mfma_f32_16x16x4_f32 v[136:139], v112, v128, v[136:139]
	v_mfma_f32_16x16x4_f32 v[136:139], v113, v129, v[136:139]
	s_waitcnt vmcnt(58)
	ds_write_b128 v2, v[60:63] offset:20480
	ds_write_b128 v2, v[64:67] offset:30720
	s_add_u32 s10, s0, 0x6e0000
	s_addc_u32 s11, s1, 0
	global_load_dwordx4 v[60:63], v0, s[10:11]
	global_load_dwordx4 v[64:67], v1, s[10:11]
	s_waitcnt lgkmcnt(6)
	v_mfma_f32_16x16x4_f32 v[136:139], v114, v130, v[136:139]
	v_mfma_f32_16x16x4_f32 v[136:139], v115, v131, v[136:139]
	s_waitcnt lgkmcnt(4)
	v_mfma_f32_16x16x4_f32 v[136:139], v116, v132, v[136:139]
	v_mfma_f32_16x16x4_f32 v[136:139], v117, v133, v[136:139]
	s_waitcnt lgkmcnt(2)
	v_mfma_f32_16x16x4_f32 v[136:139], v118, v134, v[136:139]
	v_mfma_f32_16x16x4_f32 v[136:139], v119, v135, v[136:139]
	s_add_u32 s16, s8, 0x620000
	s_addc_u32 s17, s9, 0
	s_nop 9
	ds_write_b32 v13, v136 offset:2176
	ds_write_b32 v13, v137 offset:2448
	ds_write_b32 v13, v138 offset:2720
	ds_write_b32 v13, v139 offset:2992
	global_store_dword v12, v136, s[16:17] offset:0
	global_store_dword v12, v137, s[16:17] offset:256
	global_store_dword v12, v138, s[16:17] offset:512
	global_store_dword v12, v139, s[16:17] offset:768
	s_waitcnt lgkmcnt(0)
	s_barrier
; #define LAS __attribute__((address_space(3)))
; __device__ __forceinline__ void scan_combine(LAS unsigned char* lds, CArgsP a) {
;     ...
;     for (int g = 1; g <= GL; ++g) {
;         const bool pf = (g + 2 <= GL);
;         float u3 = 0.f;
;         if (pf) { const f32x4* Pn = (const f32x4*)(PM + (size_t)((g + 2) * 8 + h) * 4096); pa = Pn[tid]; pb = Pn[512 + tid]; u3 = UM[((size_t)((g + 2) * 8 + h) * 64 + v) * 64 + kq]; }
;         asm volatile("s_waitcnt lgkmcnt(0)\n\ts_barrier" ::: "memory");
;         const LAS float* Pg = Pl + (g % 3) * 4096 + kq;
;         float acc0 = u1, acc1 = 0.f, acc2 = 0.f, acc3 = 0.f;
;         const int curi = __builtin_bit_cast(int, cur);
; #pragma unroll
;         for (int k = 0; k < 64; k += 4) {
;             const float s0 = __builtin_bit_cast(float, __builtin_amdgcn_readlane(curi, k)), s1 = __builtin_bit_cast(float, __builtin_amdgcn_readlane(curi, k + 1));
;             const float s2 = __builtin_bit_cast(float, __builtin_amdgcn_readlane(curi, k + 2)), s3 = __builtin_bit_cast(float, __builtin_amdgcn_readlane(curi, k + 3));
;             acc0 += s0 * Pg[(k + 0) * 64]; acc1 += s1 * Pg[(k + 1) * 64]; acc2 += s2 * Pg[(k + 2) * 64]; acc3 += s3 * Pg[(k + 3) * 64];
;         }
;         cur = (acc0 + acc1) + (acc2 + acc3);
;         SS[((size_t)((g + 1) * 8 + h) * 64 + v) * 64 + kq] = cur;
;         if (pf) { LAS float* dst = Pl + ((g + 2) % 3) * 4096; *(LAS f32x4*)(dst + 4 * tid) = pa; *(LAS f32x4*)(dst + 2048 + 4 * tid) = pb; }
;         u1 = u2; u2 = u3;
	ds_read2_b32 v[104:105], v9 offset0:0 offset1:4
	ds_read2st64_b32 v[120:121], v11 offset0:0 offset1:5
	ds_read2_b32 v[106:107], v9 offset0:8 offset1:12
	ds_read2st64_b32 v[122:123], v11 offset0:10 offset1:15
	ds_read2_b32 v[108:109], v9 offset0:16 offset1:20
	ds_read2st64_b32 v[124:125], v11 offset0:20 offset1:25
	ds_read2_b32 v[110:111], v9 offset0:24 offset1:28
	ds_read2st64_b32 v[126:127], v11 offset0:30 offset1:35
	ds_read2_b32 v[112:113], v9 offset0:32 offset1:36
	ds_read2st64_b32 v[128:129], v11 offset0:40 offset1:45
	ds_read2_b32 v[114:115], v9 offset0:40 offset1:44
	ds_read2st64_b32 v[130:131], v11 offset0:50 offset1:55
	ds_read2_b32 v[116:117], v9 offset0:48 offset1:52
	ds_read2st64_b32 v[132:133], v11 offset0:60 offset1:65
	s_waitcnt vmcnt(56)
	s_waitcnt lgkmcnt(12)
	v_mfma_f32_16x16x4_f32 v[136:139], v104, v120, v[208:211]
	v_mfma_f32_16x16x4_f32 v[136:139], v105, v121, v[136:139]
	ds_read2_b32 v[118:119], v9 offset0:56 offset1:60
	ds_read2st64_b32 v[134:135], v11 offset0:70 offset1:75
	s_waitcnt lgkmcnt(12)
	v_mfma_f32_16x16x4_f32 v[136:139], v106, v122, v[136:139]
	v_mfma_f32_16x16x4_f32 v[136:139], v107, v123, v[136:139]
	s_waitcnt lgkmcnt(10)
	v_mfma_f32_16x16x4_f32 v[136:139], v108, v124, v[136:139]
	v_mfma_f32_16x16x4_f32 v[136:139], v109, v125, v[136:139]
	s_add_u32 s14, s6, 0x6e0000
	s_addc_u32 s15, s7, 0
	global_load_dword v208, v12, s[14:15] offset:0
	global_load_dword v209, v12, s[14:15] offset:256
	global_load_dword v210, v12, s[14:15] offset:512
	global_load_dword v211, v12, s[14:15] offset:768
	s_waitcnt lgkmcnt(8)
	v_mfma_f32_16x16x4_f32 v[136:139], v110, v126, v[136:139]
	v_mfma_f32_16x16x4_f32 v[136:139], v111, v127, v[136:139]
	s_waitcnt lgkmcnt(6)
	v_mfma_f32_16x16x4_f32 v[136:139], v112, v128, v[136:139]
	v_mfma_f32_16x16x4_f32 v[136:139], v113, v129, v[136:139]
	s_waitcnt vmcnt(58)
	ds_write_b128 v2, v[68:71] offset:0
	ds_write_b128 v2, v[72:75] offset:10240
	s_add_u32 s10, s0, 0x700000
	s_addc_u32 s11, s1, 0
	global_load_dwordx4 v[68:71], v0, s[10:11]
	global_load_dwordx4 v[72:75], v1, s[10:11]
	s_waitcnt lgkmcnt(6)
	v_mfma_f32_16x16x4_f32 v[136:139], v114, v130, v[136:139]
	v_mfma_f32_16x16x4_f32 v[136:139], v115, v131, v[136:139]
	s_waitcnt lgkmcnt(4)
	v_mfma_f32_16x16x4_f32 v[136:139], v116, v132, v[136:139]
	v_mfma_f32_16x16x4_f32 v[136:139], v117, v133, v[136:139]
	s_waitcnt lgkmcnt(2)
	v_mfma_f32_16x16x4_f32 v[136:139], v118, v134, v[136:139]
	v_mfma_f32_16x16x4_f32 v[136:139], v119, v135, v[136:139]
	s_add_u32 s16, s8, 0x640000
	s_addc_u32 s17, s9, 0
	s_nop 9
	ds_write_b32 v13, v136 offset:0
	ds_write_b32 v13, v137 offset:272
	ds_write_b32 v13, v138 offset:544
	ds_write_b32 v13, v139 offset:816
	global_store_dword v12, v136, s[16:17] offset:0
	global_store_dword v12, v137, s[16:17] offset:256
	global_store_dword v12, v138, s[16:17] offset:512
	global_store_dword v12, v139, s[16:17] offset:768
	s_waitcnt lgkmcnt(0)
	s_barrier
	ds_read2_b32 v[104:105], v8 offset0:0 offset1:4
	ds_read2st64_b32 v[120:121], v10 offset0:0 offset1:5
	ds_read2_b32 v[106:107], v8 offset0:8 offset1:12
	ds_read2st64_b32 v[122:123], v10 offset0:10 offset1:15
	ds_read2_b32 v[108:109], v8 offset0:16 offset1:20
	ds_read2st64_b32 v[124:125], v10 offset0:20 offset1:25
	ds_read2_b32 v[110:111], v8 offset0:24 offset1:28
	ds_read2st64_b32 v[126:127], v10 offset0:30 offset1:35
	ds_read2_b32 v[112:113], v8 offset0:32 offset1:36
	ds_read2st64_b32 v[128:129], v10 offset0:40 offset1:45
	ds_read2_b32 v[114:115], v8 offset0:40 offset1:44
	ds_read2st64_b32 v[130:131], v10 offset0:50 offset1:55
	ds_read2_b32 v[116:117], v8 offset0:48 offset1:52
	ds_read2st64_b32 v[132:133], v10 offset0:60 offset1:65
	s_waitcnt vmcnt(56)
	s_waitcnt lgkmcnt(12)
	v_mfma_f32_16x16x4_f32 v[136:139], v104, v120, v[212:215]
	v_mfma_f32_16x16x4_f32 v[136:139], v105, v121, v[136:139]
	ds_read2_b32 v[118:119], v8 offset0:56 offset1:60
	ds_read2st64_b32 v[134:135], v10 offset0:70 offset1:75
	s_waitcnt lgkmcnt(12)
	v_mfma_f32_16x16x4_f32 v[136:139], v106, v122, v[136:139]
	v_mfma_f32_16x16x4_f32 v[136:139], v107, v123, v[136:139]
	s_waitcnt lgkmcnt(10)
	v_mfma_f32_16x16x4_f32 v[136:139], v108, v124, v[136:139]
	v_mfma_f32_16x16x4_f32 v[136:139], v109, v125, v[136:139]
	s_add_u32 s14, s6, 0x700000
	s_addc_u32 s15, s7, 0
	global_load_dword v212, v12, s[14:15] offset:0
	global_load_dword v213, v12, s[14:15] offset:256
	global_load_dword v214, v12, s[14:15] offset:512
	global_load_dword v215, v12, s[14:15] offset:768
	s_waitcnt lgkmcnt(8)
	v_mfma_f32_16x16x4_f32 v[136:139], v110, v126, v[136:139]
	v_mfma_f32_16x16x4_f32 v[136:139], v111, v127, v[136:139]
	s_waitcnt lgkmcnt(6)
	v_mfma_f32_16x16x4_f32 v[136:139], v112, v128, v[136:139]
	v_mfma_f32_16x16x4_f32 v[136:139], v113, v129, v[136:139]
	s_waitcnt vmcnt(58)
	ds_write_b128 v2, v[76:79] offset:20480
	ds_write_b128 v2, v[80:83] offset:30720
	s_add_u32 s10, s0, 0x720000
	s_addc_u32 s11, s1, 0
	global_load_dwordx4 v[76:79], v0, s[10:11]
	global_load_dwordx4 v[80:83], v1, s[10:11]
	s_waitcnt lgkmcnt(6)
	v_mfma_f32_16x16x4_f32 v[136:139], v114, v130, v[136:139]
	v_mfma_f32_16x16x4_f32 v[136:139], v115, v131, v[136:139]
	s_waitcnt lgkmcnt(4)
	v_mfma_f32_16x16x4_f32 v[136:139], v116, v132, v[136:139]
	v_mfma_f32_16x16x4_f32 v[136:139], v117, v133, v[136:139]
	s_waitcnt lgkmcnt(2)
	v_mfma_f32_16x16x4_f32 v[136:139], v118, v134, v[136:139]
	v_mfma_f32_16x16x4_f32 v[136:139], v119, v135, v[136:139]
	s_add_u32 s16, s8, 0x660000
	s_addc_u32 s17, s9, 0
	s_nop 9
	ds_write_b32 v13, v136 offset:2176
	ds_write_b32 v13, v137 offset:2448
	ds_write_b32 v13, v138 offset:2720
	ds_write_b32 v13, v139 offset:2992
	global_store_dword v12, v136, s[16:17] offset:0
	global_store_dword v12, v137, s[16:17] offset:256
	global_store_dword v12, v138, s[16:17] offset:512
	global_store_dword v12, v139, s[16:17] offset:768
	s_waitcnt lgkmcnt(0)
	s_barrier
; #define LAS __attribute__((address_space(3)))
; __device__ __forceinline__ void scan_combine(LAS unsigned char* lds, CArgsP a) {
;     ...
;     for (int g = 1; g <= GL; ++g) {
;         const bool pf = (g + 2 <= GL);
;         float u3 = 0.f;
;         if (pf) { const f32x4* Pn = (const f32x4*)(PM + (size_t)((g + 2) * 8 + h) * 4096); pa = Pn[tid]; pb = Pn[512 + tid]; u3 = UM[((size_t)((g + 2) * 8 + h) * 64 + v) * 64 + kq]; }
;         asm volatile("s_waitcnt lgkmcnt(0)\n\ts_barrier" ::: "memory");
;         const LAS float* Pg = Pl + (g % 3) * 4096 + kq;
;         float acc0 = u1, acc1 = 0.f, acc2 = 0.f, acc3 = 0.f;
;         const int curi = __builtin_bit_cast(int, cur);
; #pragma unroll
;         for (int k = 0; k < 64; k += 4) {
;             const float s0 = __builtin_bit_cast(float, __builtin_amdgcn_readlane(curi, k)), s1 = __builtin_bit_cast(float, __builtin_amdgcn_readlane(curi, k + 1));
;             const float s2 = __builtin_bit_cast(float, __builtin_amdgcn_readlane(curi, k + 2)), s3 = __builtin_bit_cast(float, __builtin_amdgcn_readlane(curi, k + 3));
;             acc0 += s0 * Pg[(k + 0) * 64]; acc1 += s1 * Pg[(k + 1) * 64]; acc2 += s2 * Pg[(k + 2) * 64]; acc3 += s3 * Pg[(k + 3) * 64];
;         }
;         cur = (acc0 + acc1) + (acc2 + acc3);
;         SS[((size_t)((g + 1) * 8 + h) * 64 + v) * 64 + kq] = cur;
;         if (pf) { LAS float* dst = Pl + ((g + 2) % 3) * 4096; *(LAS f32x4*)(dst + 4 * tid) = pa; *(LAS f32x4*)(dst + 2048 + 4 * tid) = pb; }
;         u1 = u2; u2 = u3;
	ds_read2_b32 v[104:105], v9 offset0:0 offset1:4
	ds_read2st64_b32 v[120:121], v11 offset0:0 offset1:5
	ds_read2_b32 v[106:107], v9 offset0:8 offset1:12
	ds_read2st64_b32 v[122:123], v11 offset0:10 offset1:15
	ds_read2_b32 v[108:109], v9 offset0:16 offset1:20
	ds_read2st64_b32 v[124:125], v11 offset0:20 offset1:25
	ds_read2_b32 v[110:111], v9 offset0:24 offset1:28
	ds_read2st64_b32 v[126:127], v11 offset0:30 offset1:35
	ds_read2_b32 v[112:113], v9 offset0:32 offset1:36
	ds_read2st64_b32 v[128:129], v11 offset0:40 offset1:45
	ds_read2_b32 v[114:115], v9 offset0:40 offset1:44
	ds_read2st64_b32 v[130:131], v11 offset0:50 offset1:55
	ds_read2_b32 v[116:117], v9 offset0:48 offset1:52
	ds_read2st64_b32 v[132:133], v11 offset0:60 offset1:65
	s_waitcnt vmcnt(56)
	s_waitcnt lgkmcnt(12)
	v_mfma_f32_16x16x4_f32 v[136:139], v104, v120, v[216:219]
	v_mfma_f32_16x16x4_f32 v[136:139], v105, v121, v[136:139]
	ds_read2_b32 v[118:119], v9 offset0:56 offset1:60
	ds_read2st64_b32 v[134:135], v11 offset0:70 offset1:75
	s_waitcnt lgkmcnt(12)
	v_mfma_f32_16x16x4_f32 v[136:139], v106, v122, v[136:139]
	v_mfma_f32_16x16x4_f32 v[136:139], v107, v123, v[136:139]
	s_waitcnt lgkmcnt(10)
	v_mfma_f32_16x16x4_f32 v[136:139], v108, v124, v[136:139]
	v_mfma_f32_16x16x4_f32 v[136:139], v109, v125, v[136:139]
	s_add_u32 s14, s6, 0x720000
	s_addc_u32 s15, s7, 0
	global_load_dword v216, v12, s[14:15] offset:0
	global_load_dword v217, v12, s[14:15] offset:256
	global_load_dword v218, v12, s[14:15] offset:512
	global_load_dword v219, v12, s[14:15] offset:768
	s_waitcnt lgkmcnt(8)
	v_mfma_f32_16x16x4_f32 v[136:139], v110, v126, v[136:139]
	v_mfma_f32_16x16x4_f32 v[136:139], v111, v127, v[136:139]
	s_waitcnt lgkmcnt(6)
	v_mfma_f32_16x16x4_f32 v[136:139], v112, v128, v[136:139]
	v_mfma_f32_16x16x4_f32 v[136:139], v113, v129, v[136:139]
	s_waitcnt vmcnt(58)
	ds_write_b128 v2, v[84:87] offset:0
	ds_write_b128 v2, v[88:91] offset:10240
	s_add_u32 s10, s0, 0x740000
	s_addc_u32 s11, s1, 0
	global_load_dwordx4 v[84:87], v0, s[10:11]
	global_load_dwordx4 v[88:91], v1, s[10:11]
	s_waitcnt lgkmcnt(6)
	v_mfma_f32_16x16x4_f32 v[136:139], v114, v130, v[136:139]
	v_mfma_f32_16x16x4_f32 v[136:139], v115, v131, v[136:139]
	s_waitcnt lgkmcnt(4)
	v_mfma_f32_16x16x4_f32 v[136:139], v116, v132, v[136:139]
	v_mfma_f32_16x16x4_f32 v[136:139], v117, v133, v[136:139]
	s_waitcnt lgkmcnt(2)
	v_mfma_f32_16x16x4_f32 v[136:139], v118, v134, v[136:139]
	v_mfma_f32_16x16x4_f32 v[136:139], v119, v135, v[136:139]
	s_add_u32 s16, s8, 0x680000
	s_addc_u32 s17, s9, 0
	s_nop 9
	ds_write_b32 v13, v136 offset:0
	ds_write_b32 v13, v137 offset:272
	ds_write_b32 v13, v138 offset:544
	ds_write_b32 v13, v139 offset:816
	global_store_dword v12, v136, s[16:17] offset:0
	global_store_dword v12, v137, s[16:17] offset:256
	global_store_dword v12, v138, s[16:17] offset:512
	global_store_dword v12, v139, s[16:17] offset:768
	s_waitcnt lgkmcnt(0)
	s_barrier
	ds_read2_b32 v[104:105], v8 offset0:0 offset1:4
	ds_read2st64_b32 v[120:121], v10 offset0:0 offset1:5
	ds_read2_b32 v[106:107], v8 offset0:8 offset1:12
	ds_read2st64_b32 v[122:123], v10 offset0:10 offset1:15
	ds_read2_b32 v[108:109], v8 offset0:16 offset1:20
	ds_read2st64_b32 v[124:125], v10 offset0:20 offset1:25
	ds_read2_b32 v[110:111], v8 offset0:24 offset1:28
	ds_read2st64_b32 v[126:127], v10 offset0:30 offset1:35
	ds_read2_b32 v[112:113], v8 offset0:32 offset1:36
	ds_read2st64_b32 v[128:129], v10 offset0:40 offset1:45
	ds_read2_b32 v[114:115], v8 offset0:40 offset1:44
	ds_read2st64_b32 v[130:131], v10 offset0:50 offset1:55
	ds_read2_b32 v[116:117], v8 offset0:48 offset1:52
	ds_read2st64_b32 v[132:133], v10 offset0:60 offset1:65
	s_waitcnt vmcnt(56)
	s_waitcnt lgkmcnt(12)
	v_mfma_f32_16x16x4_f32 v[136:139], v104, v120, v[220:223]
	v_mfma_f32_16x16x4_f32 v[136:139], v105, v121, v[136:139]
	ds_read2_b32 v[118:119], v8 offset0:56 offset1:60
	ds_read2st64_b32 v[134:135], v10 offset0:70 offset1:75
	s_waitcnt lgkmcnt(12)
	v_mfma_f32_16x16x4_f32 v[136:139], v106, v122, v[136:139]
	v_mfma_f32_16x16x4_f32 v[136:139], v107, v123, v[136:139]
	s_waitcnt lgkmcnt(10)
	v_mfma_f32_16x16x4_f32 v[136:139], v108, v124, v[136:139]
	v_mfma_f32_16x16x4_f32 v[136:139], v109, v125, v[136:139]
	s_add_u32 s14, s6, 0x740000
	s_addc_u32 s15, s7, 0
	global_load_dword v220, v12, s[14:15] offset:0
	global_load_dword v221, v12, s[14:15] offset:256
	global_load_dword v222, v12, s[14:15] offset:512
	global_load_dword v223, v12, s[14:15] offset:768
	s_waitcnt lgkmcnt(8)
	v_mfma_f32_16x16x4_f32 v[136:139], v110, v126, v[136:139]
	v_mfma_f32_16x16x4_f32 v[136:139], v111, v127, v[136:139]
	s_waitcnt lgkmcnt(6)
	v_mfma_f32_16x16x4_f32 v[136:139], v112, v128, v[136:139]
	v_mfma_f32_16x16x4_f32 v[136:139], v113, v129, v[136:139]
	s_waitcnt vmcnt(58)
	ds_write_b128 v2, v[92:95] offset:20480
	ds_write_b128 v2, v[96:99] offset:30720
	s_add_u32 s10, s0, 0x760000
	s_addc_u32 s11, s1, 0
	global_load_dwordx4 v[92:95], v0, s[10:11]
	global_load_dwordx4 v[96:99], v1, s[10:11]
	s_waitcnt lgkmcnt(6)
	v_mfma_f32_16x16x4_f32 v[136:139], v114, v130, v[136:139]
	v_mfma_f32_16x16x4_f32 v[136:139], v115, v131, v[136:139]
	s_waitcnt lgkmcnt(4)
	v_mfma_f32_16x16x4_f32 v[136:139], v116, v132, v[136:139]
	v_mfma_f32_16x16x4_f32 v[136:139], v117, v133, v[136:139]
	s_waitcnt lgkmcnt(2)
	v_mfma_f32_16x16x4_f32 v[136:139], v118, v134, v[136:139]
	v_mfma_f32_16x16x4_f32 v[136:139], v119, v135, v[136:139]
	s_add_u32 s16, s8, 0x6a0000
	s_addc_u32 s17, s9, 0
	s_nop 9
	ds_write_b32 v13, v136 offset:2176
	ds_write_b32 v13, v137 offset:2448
	ds_write_b32 v13, v138 offset:2720
	ds_write_b32 v13, v139 offset:2992
	global_store_dword v12, v136, s[16:17] offset:0
	global_store_dword v12, v137, s[16:17] offset:256
	global_store_dword v12, v138, s[16:17] offset:512
	global_store_dword v12, v139, s[16:17] offset:768
	s_waitcnt lgkmcnt(0)
	s_barrier
; #define LAS __attribute__((address_space(3)))
; __device__ __forceinline__ void scan_combine(LAS unsigned char* lds, CArgsP a) {
;     ...
;     for (int g = 1; g <= GL; ++g) {
;         const bool pf = (g + 2 <= GL);
;         float u3 = 0.f;
;         if (pf) { const f32x4* Pn = (const f32x4*)(PM + (size_t)((g + 2) * 8 + h) * 4096); pa = Pn[tid]; pb = Pn[512 + tid]; u3 = UM[((size_t)((g + 2) * 8 + h) * 64 + v) * 64 + kq]; }
;         asm volatile("s_waitcnt lgkmcnt(0)\n\ts_barrier" ::: "memory");
;         const LAS float* Pg = Pl + (g % 3) * 4096 + kq;
;         float acc0 = u1, acc1 = 0.f, acc2 = 0.f, acc3 = 0.f;
;         const int curi = __builtin_bit_cast(int, cur);
; #pragma unroll
;         for (int k = 0; k < 64; k += 4) {
;             const float s0 = __builtin_bit_cast(float, __builtin_amdgcn_readlane(curi, k)), s1 = __builtin_bit_cast(float, __builtin_amdgcn_readlane(curi, k + 1));
;             const float s2 = __builtin_bit_cast(float, __builtin_amdgcn_readlane(curi, k + 2)), s3 = __builtin_bit_cast(float, __builtin_amdgcn_readlane(curi, k + 3));
;             acc0 += s0 * Pg[(k + 0) * 64]; acc1 += s1 * Pg[(k + 1) * 64]; acc2 += s2 * Pg[(k + 2) * 64]; acc3 += s3 * Pg[(k + 3) * 64];
;         }
;         cur = (acc0 + acc1) + (acc2 + acc3);
;         SS[((size_t)((g + 1) * 8 + h) * 64 + v) * 64 + kq] = cur;
;         if (pf) { LAS float* dst = Pl + ((g + 2) % 3) * 4096; *(LAS f32x4*)(dst + 4 * tid) = pa; *(LAS f32x4*)(dst + 2048 + 4 * tid) = pb; }
;         u1 = u2; u2 = u3;
	ds_read2_b32 v[104:105], v9 offset0:0 offset1:4
	ds_read2st64_b32 v[120:121], v11 offset0:0 offset1:5
	ds_read2_b32 v[106:107], v9 offset0:8 offset1:12
	ds_read2st64_b32 v[122:123], v11 offset0:10 offset1:15
	ds_read2_b32 v[108:109], v9 offset0:16 offset1:20
	ds_read2st64_b32 v[124:125], v11 offset0:20 offset1:25
	ds_read2_b32 v[110:111], v9 offset0:24 offset1:28
	ds_read2st64_b32 v[126:127], v11 offset0:30 offset1:35
	ds_read2_b32 v[112:113], v9 offset0:32 offset1:36
	ds_read2st64_b32 v[128:129], v11 offset0:40 offset1:45
	ds_read2_b32 v[114:115], v9 offset0:40 offset1:44
	ds_read2st64_b32 v[130:131], v11 offset0:50 offset1:55
	ds_read2_b32 v[116:117], v9 offset0:48 offset1:52
	ds_read2st64_b32 v[132:133], v11 offset0:60 offset1:65
	s_waitcnt vmcnt(56)
	s_waitcnt lgkmcnt(12)
	v_mfma_f32_16x16x4_f32 v[136:139], v104, v120, v[224:227]
	v_mfma_f32_16x16x4_f32 v[136:139], v105, v121, v[136:139]
	ds_read2_b32 v[118:119], v9 offset0:56 offset1:60
	ds_read2st64_b32 v[134:135], v11 offset0:70 offset1:75
	s_waitcnt lgkmcnt(12)
	v_mfma_f32_16x16x4_f32 v[136:139], v106, v122, v[136:139]
	v_mfma_f32_16x16x4_f32 v[136:139], v107, v123, v[136:139]
	s_waitcnt lgkmcnt(10)
	v_mfma_f32_16x16x4_f32 v[136:139], v108, v124, v[136:139]
	v_mfma_f32_16x16x4_f32 v[136:139], v109, v125, v[136:139]
	s_add_u32 s14, s6, 0x760000
	s_addc_u32 s15, s7, 0
	global_load_dword v224, v12, s[14:15] offset:0
	global_load_dword v225, v12, s[14:15] offset:256
	global_load_dword v226, v12, s[14:15] offset:512
	global_load_dword v227, v12, s[14:15] offset:768
	s_waitcnt lgkmcnt(8)
	v_mfma_f32_16x16x4_f32 v[136:139], v110, v126, v[136:139]
	v_mfma_f32_16x16x4_f32 v[136:139], v111, v127, v[136:139]
	s_waitcnt lgkmcnt(6)
	v_mfma_f32_16x16x4_f32 v[136:139], v112, v128, v[136:139]
	v_mfma_f32_16x16x4_f32 v[136:139], v113, v129, v[136:139]
	s_waitcnt vmcnt(58)
	ds_write_b128 v2, v[52:55] offset:0
	ds_write_b128 v2, v[56:59] offset:10240
	s_add_u32 s10, s0, 0x780000
	s_addc_u32 s11, s1, 0
	global_load_dwordx4 v[52:55], v0, s[10:11]
	global_load_dwordx4 v[56:59], v1, s[10:11]
	s_waitcnt lgkmcnt(6)
	v_mfma_f32_16x16x4_f32 v[136:139], v114, v130, v[136:139]
	v_mfma_f32_16x16x4_f32 v[136:139], v115, v131, v[136:139]
	s_waitcnt lgkmcnt(4)
	v_mfma_f32_16x16x4_f32 v[136:139], v116, v132, v[136:139]
	v_mfma_f32_16x16x4_f32 v[136:139], v117, v133, v[136:139]
	s_waitcnt lgkmcnt(2)
	v_mfma_f32_16x16x4_f32 v[136:139], v118, v134, v[136:139]
	v_mfma_f32_16x16x4_f32 v[136:139], v119, v135, v[136:139]
	s_add_u32 s16, s8, 0x6c0000
	s_addc_u32 s17, s9, 0
	s_nop 9
	ds_write_b32 v13, v136 offset:0
	ds_write_b32 v13, v137 offset:272
	ds_write_b32 v13, v138 offset:544
	ds_write_b32 v13, v139 offset:816
	global_store_dword v12, v136, s[16:17] offset:0
	global_store_dword v12, v137, s[16:17] offset:256
	global_store_dword v12, v138, s[16:17] offset:512
	global_store_dword v12, v139, s[16:17] offset:768
	s_waitcnt lgkmcnt(0)
	s_barrier
	ds_read2_b32 v[104:105], v8 offset0:0 offset1:4
	ds_read2st64_b32 v[120:121], v10 offset0:0 offset1:5
	ds_read2_b32 v[106:107], v8 offset0:8 offset1:12
	ds_read2st64_b32 v[122:123], v10 offset0:10 offset1:15
	ds_read2_b32 v[108:109], v8 offset0:16 offset1:20
	ds_read2st64_b32 v[124:125], v10 offset0:20 offset1:25
	ds_read2_b32 v[110:111], v8 offset0:24 offset1:28
	ds_read2st64_b32 v[126:127], v10 offset0:30 offset1:35
	ds_read2_b32 v[112:113], v8 offset0:32 offset1:36
	ds_read2st64_b32 v[128:129], v10 offset0:40 offset1:45
	ds_read2_b32 v[114:115], v8 offset0:40 offset1:44
	ds_read2st64_b32 v[130:131], v10 offset0:50 offset1:55
	ds_read2_b32 v[116:117], v8 offset0:48 offset1:52
	ds_read2st64_b32 v[132:133], v10 offset0:60 offset1:65
	s_waitcnt vmcnt(56)
	s_waitcnt lgkmcnt(12)
	v_mfma_f32_16x16x4_f32 v[136:139], v104, v120, v[204:207]
	v_mfma_f32_16x16x4_f32 v[136:139], v105, v121, v[136:139]
	ds_read2_b32 v[118:119], v8 offset0:56 offset1:60
	ds_read2st64_b32 v[134:135], v10 offset0:70 offset1:75
	s_waitcnt lgkmcnt(12)
	v_mfma_f32_16x16x4_f32 v[136:139], v106, v122, v[136:139]
	v_mfma_f32_16x16x4_f32 v[136:139], v107, v123, v[136:139]
	s_waitcnt lgkmcnt(10)
	v_mfma_f32_16x16x4_f32 v[136:139], v108, v124, v[136:139]
	v_mfma_f32_16x16x4_f32 v[136:139], v109, v125, v[136:139]
	s_add_u32 s14, s6, 0x780000
	s_addc_u32 s15, s7, 0
	global_load_dword v204, v12, s[14:15] offset:0
	global_load_dword v205, v12, s[14:15] offset:256
	global_load_dword v206, v12, s[14:15] offset:512
	global_load_dword v207, v12, s[14:15] offset:768
	s_waitcnt lgkmcnt(8)
	v_mfma_f32_16x16x4_f32 v[136:139], v110, v126, v[136:139]
	v_mfma_f32_16x16x4_f32 v[136:139], v111, v127, v[136:139]
	s_waitcnt lgkmcnt(6)
	v_mfma_f32_16x16x4_f32 v[136:139], v112, v128, v[136:139]
	v_mfma_f32_16x16x4_f32 v[136:139], v113, v129, v[136:139]
	s_waitcnt vmcnt(58)
	ds_write_b128 v2, v[60:63] offset:20480
	ds_write_b128 v2, v[64:67] offset:30720
	s_add_u32 s10, s0, 0x7a0000
	s_addc_u32 s11, s1, 0
	global_load_dwordx4 v[60:63], v0, s[10:11]
	global_load_dwordx4 v[64:67], v1, s[10:11]
	s_waitcnt lgkmcnt(6)
	v_mfma_f32_16x16x4_f32 v[136:139], v114, v130, v[136:139]
	v_mfma_f32_16x16x4_f32 v[136:139], v115, v131, v[136:139]
	s_waitcnt lgkmcnt(4)
	v_mfma_f32_16x16x4_f32 v[136:139], v116, v132, v[136:139]
	v_mfma_f32_16x16x4_f32 v[136:139], v117, v133, v[136:139]
	s_waitcnt lgkmcnt(2)
	v_mfma_f32_16x16x4_f32 v[136:139], v118, v134, v[136:139]
	v_mfma_f32_16x16x4_f32 v[136:139], v119, v135, v[136:139]
	s_add_u32 s16, s8, 0x6e0000
	s_addc_u32 s17, s9, 0
	s_nop 9
	ds_write_b32 v13, v136 offset:2176
	ds_write_b32 v13, v137 offset:2448
	ds_write_b32 v13, v138 offset:2720
	ds_write_b32 v13, v139 offset:2992
	global_store_dword v12, v136, s[16:17] offset:0
	global_store_dword v12, v137, s[16:17] offset:256
	global_store_dword v12, v138, s[16:17] offset:512
	global_store_dword v12, v139, s[16:17] offset:768
	s_waitcnt lgkmcnt(0)
	s_barrier
; #define LAS __attribute__((address_space(3)))
; __device__ __forceinline__ void scan_combine(LAS unsigned char* lds, CArgsP a) {
;     ...
;     for (int g = 1; g <= GL; ++g) {
;         const bool pf = (g + 2 <= GL);
;         float u3 = 0.f;
;         if (pf) { const f32x4* Pn = (const f32x4*)(PM + (size_t)((g + 2) * 8 + h) * 4096); pa = Pn[tid]; pb = Pn[512 + tid]; u3 = UM[((size_t)((g + 2) * 8 + h) * 64 + v) * 64 + kq]; }
;         asm volatile("s_waitcnt lgkmcnt(0)\n\ts_barrier" ::: "memory");
;         const LAS float* Pg = Pl + (g % 3) * 4096 + kq;
;         float acc0 = u1, acc1 = 0.f, acc2 = 0.f, acc3 = 0.f;
;         const int curi = __builtin_bit_cast(int, cur);
; #pragma unroll
;         for (int k = 0; k < 64; k += 4) {
;             const float s0 = __builtin_bit_cast(float, __builtin_amdgcn_readlane(curi, k)), s1 = __builtin_bit_cast(float, __builtin_amdgcn_readlane(curi, k + 1));
;             const float s2 = __builtin_bit_cast(float, __builtin_amdgcn_readlane(curi, k + 2)), s3 = __builtin_bit_cast(float, __builtin_amdgcn_readlane(curi, k + 3));
;             acc0 += s0 * Pg[(k + 0) * 64]; acc1 += s1 * Pg[(k + 1) * 64]; acc2 += s2 * Pg[(k + 2) * 64]; acc3 += s3 * Pg[(k + 3) * 64];
;         }
;         cur = (acc0 + acc1) + (acc2 + acc3);
;         SS[((size_t)((g + 1) * 8 + h) * 64 + v) * 64 + kq] = cur;
;         if (pf) { LAS float* dst = Pl + ((g + 2) % 3) * 4096; *(LAS f32x4*)(dst + 4 * tid) = pa; *(LAS f32x4*)(dst + 2048 + 4 * tid) = pb; }
;         u1 = u2; u2 = u3;
	ds_read2_b32 v[104:105], v9 offset0:0 offset1:4
	ds_read2st64_b32 v[120:121], v11 offset0:0 offset1:5
	ds_read2_b32 v[106:107], v9 offset0:8 offset1:12
	ds_read2st64_b32 v[122:123], v11 offset0:10 offset1:15
	ds_read2_b32 v[108:109], v9 offset0:16 offset1:20
	ds_read2st64_b32 v[124:125], v11 offset0:20 offset1:25
	ds_read2_b32 v[110:111], v9 offset0:24 offset1:28
	ds_read2st64_b32 v[126:127], v11 offset0:30 offset1:35
	ds_read2_b32 v[112:113], v9 offset0:32 offset1:36
	ds_read2st64_b32 v[128:129], v11 offset0:40 offset1:45
	ds_read2_b32 v[114:115], v9 offset0:40 offset1:44
	ds_read2st64_b32 v[130:131], v11 offset0:50 offset1:55
	ds_read2_b32 v[116:117], v9 offset0:48 offset1:52
	ds_read2st64_b32 v[132:133], v11 offset0:60 offset1:65
	s_waitcnt vmcnt(56)
	s_waitcnt lgkmcnt(12)
	v_mfma_f32_16x16x4_f32 v[136:139], v104, v120, v[208:211]
	v_mfma_f32_16x16x4_f32 v[136:139], v105, v121, v[136:139]
	ds_read2_b32 v[118:119], v9 offset0:56 offset1:60
	ds_read2st64_b32 v[134:135], v11 offset0:70 offset1:75
	s_waitcnt lgkmcnt(12)
	v_mfma_f32_16x16x4_f32 v[136:139], v106, v122, v[136:139]
	v_mfma_f32_16x16x4_f32 v[136:139], v107, v123, v[136:139]
	s_waitcnt lgkmcnt(10)
	v_mfma_f32_16x16x4_f32 v[136:139], v108, v124, v[136:139]
	v_mfma_f32_16x16x4_f32 v[136:139], v109, v125, v[136:139]
	s_add_u32 s14, s6, 0x7a0000
	s_addc_u32 s15, s7, 0
	global_load_dword v208, v12, s[14:15] offset:0
	global_load_dword v209, v12, s[14:15] offset:256
	global_load_dword v210, v12, s[14:15] offset:512
	global_load_dword v211, v12, s[14:15] offset:768
	s_waitcnt lgkmcnt(8)
	v_mfma_f32_16x16x4_f32 v[136:139], v110, v126, v[136:139]
	v_mfma_f32_16x16x4_f32 v[136:139], v111, v127, v[136:139]
	s_waitcnt lgkmcnt(6)
	v_mfma_f32_16x16x4_f32 v[136:139], v112, v128, v[136:139]
	v_mfma_f32_16x16x4_f32 v[136:139], v113, v129, v[136:139]
	s_waitcnt vmcnt(58)
	ds_write_b128 v2, v[68:71] offset:0
	ds_write_b128 v2, v[72:75] offset:10240
	s_add_u32 s10, s0, 0x7c0000
	s_addc_u32 s11, s1, 0
	global_load_dwordx4 v[68:71], v0, s[10:11]
	global_load_dwordx4 v[72:75], v1, s[10:11]
	s_waitcnt lgkmcnt(6)
	v_mfma_f32_16x16x4_f32 v[136:139], v114, v130, v[136:139]
	v_mfma_f32_16x16x4_f32 v[136:139], v115, v131, v[136:139]
	s_waitcnt lgkmcnt(4)
	v_mfma_f32_16x16x4_f32 v[136:139], v116, v132, v[136:139]
	v_mfma_f32_16x16x4_f32 v[136:139], v117, v133, v[136:139]
	s_waitcnt lgkmcnt(2)
	v_mfma_f32_16x16x4_f32 v[136:139], v118, v134, v[136:139]
	v_mfma_f32_16x16x4_f32 v[136:139], v119, v135, v[136:139]
	s_add_u32 s16, s8, 0x700000
	s_addc_u32 s17, s9, 0
	s_nop 9
	ds_write_b32 v13, v136 offset:0
	ds_write_b32 v13, v137 offset:272
	ds_write_b32 v13, v138 offset:544
	ds_write_b32 v13, v139 offset:816
	global_store_dword v12, v136, s[16:17] offset:0
	global_store_dword v12, v137, s[16:17] offset:256
	global_store_dword v12, v138, s[16:17] offset:512
	global_store_dword v12, v139, s[16:17] offset:768
	s_waitcnt lgkmcnt(0)
	s_barrier
	ds_read2_b32 v[104:105], v8 offset0:0 offset1:4
	ds_read2st64_b32 v[120:121], v10 offset0:0 offset1:5
	ds_read2_b32 v[106:107], v8 offset0:8 offset1:12
	ds_read2st64_b32 v[122:123], v10 offset0:10 offset1:15
	ds_read2_b32 v[108:109], v8 offset0:16 offset1:20
	ds_read2st64_b32 v[124:125], v10 offset0:20 offset1:25
	ds_read2_b32 v[110:111], v8 offset0:24 offset1:28
	ds_read2st64_b32 v[126:127], v10 offset0:30 offset1:35
	ds_read2_b32 v[112:113], v8 offset0:32 offset1:36
	ds_read2st64_b32 v[128:129], v10 offset0:40 offset1:45
	ds_read2_b32 v[114:115], v8 offset0:40 offset1:44
	ds_read2st64_b32 v[130:131], v10 offset0:50 offset1:55
	ds_read2_b32 v[116:117], v8 offset0:48 offset1:52
	ds_read2st64_b32 v[132:133], v10 offset0:60 offset1:65
	s_waitcnt vmcnt(56)
	s_waitcnt lgkmcnt(12)
	v_mfma_f32_16x16x4_f32 v[136:139], v104, v120, v[212:215]
	v_mfma_f32_16x16x4_f32 v[136:139], v105, v121, v[136:139]
	ds_read2_b32 v[118:119], v8 offset0:56 offset1:60
	ds_read2st64_b32 v[134:135], v10 offset0:70 offset1:75
	s_waitcnt lgkmcnt(12)
	v_mfma_f32_16x16x4_f32 v[136:139], v106, v122, v[136:139]
	v_mfma_f32_16x16x4_f32 v[136:139], v107, v123, v[136:139]
	s_waitcnt lgkmcnt(10)
	v_mfma_f32_16x16x4_f32 v[136:139], v108, v124, v[136:139]
	v_mfma_f32_16x16x4_f32 v[136:139], v109, v125, v[136:139]
	s_add_u32 s14, s6, 0x7c0000
	s_addc_u32 s15, s7, 0
	global_load_dword v212, v12, s[14:15] offset:0
	global_load_dword v213, v12, s[14:15] offset:256
	global_load_dword v214, v12, s[14:15] offset:512
	global_load_dword v215, v12, s[14:15] offset:768
	s_waitcnt lgkmcnt(8)
	v_mfma_f32_16x16x4_f32 v[136:139], v110, v126, v[136:139]
	v_mfma_f32_16x16x4_f32 v[136:139], v111, v127, v[136:139]
	s_waitcnt lgkmcnt(6)
	v_mfma_f32_16x16x4_f32 v[136:139], v112, v128, v[136:139]
	v_mfma_f32_16x16x4_f32 v[136:139], v113, v129, v[136:139]
	s_waitcnt vmcnt(58)
	ds_write_b128 v2, v[76:79] offset:20480
	ds_write_b128 v2, v[80:83] offset:30720
	s_waitcnt lgkmcnt(6)
	v_mfma_f32_16x16x4_f32 v[136:139], v114, v130, v[136:139]
	v_mfma_f32_16x16x4_f32 v[136:139], v115, v131, v[136:139]
	s_waitcnt lgkmcnt(4)
	v_mfma_f32_16x16x4_f32 v[136:139], v116, v132, v[136:139]
	v_mfma_f32_16x16x4_f32 v[136:139], v117, v133, v[136:139]
	s_waitcnt lgkmcnt(2)
	v_mfma_f32_16x16x4_f32 v[136:139], v118, v134, v[136:139]
	v_mfma_f32_16x16x4_f32 v[136:139], v119, v135, v[136:139]
	s_add_u32 s16, s8, 0x720000
	s_addc_u32 s17, s9, 0
	s_nop 9
	ds_write_b32 v13, v136 offset:2176
	ds_write_b32 v13, v137 offset:2448
	ds_write_b32 v13, v138 offset:2720
	ds_write_b32 v13, v139 offset:2992
	global_store_dword v12, v136, s[16:17] offset:0
	global_store_dword v12, v137, s[16:17] offset:256
	global_store_dword v12, v138, s[16:17] offset:512
	global_store_dword v12, v139, s[16:17] offset:768
	s_waitcnt lgkmcnt(0)
	s_barrier
; #define LAS __attribute__((address_space(3)))
; __device__ __forceinline__ void scan_combine(LAS unsigned char* lds, CArgsP a) {
;     ...
;     for (int g = 1; g <= GL; ++g) {
;         const bool pf = (g + 2 <= GL);
;         float u3 = 0.f;
;         if (pf) { const f32x4* Pn = (const f32x4*)(PM + (size_t)((g + 2) * 8 + h) * 4096); pa = Pn[tid]; pb = Pn[512 + tid]; u3 = UM[((size_t)((g + 2) * 8 + h) * 64 + v) * 64 + kq]; }
;         asm volatile("s_waitcnt lgkmcnt(0)\n\ts_barrier" ::: "memory");
;         const LAS float* Pg = Pl + (g % 3) * 4096 + kq;
;         float acc0 = u1, acc1 = 0.f, acc2 = 0.f, acc3 = 0.f;
;         const int curi = __builtin_bit_cast(int, cur);
; #pragma unroll
;         for (int k = 0; k < 64; k += 4) {
;             const float s0 = __builtin_bit_cast(float, __builtin_amdgcn_readlane(curi, k)), s1 = __builtin_bit_cast(float, __builtin_amdgcn_readlane(curi, k + 1));
;             const float s2 = __builtin_bit_cast(float, __builtin_amdgcn_readlane(curi, k + 2)), s3 = __builtin_bit_cast(float, __builtin_amdgcn_readlane(curi, k + 3));
;             acc0 += s0 * Pg[(k + 0) * 64]; acc1 += s1 * Pg[(k + 1) * 64]; acc2 += s2 * Pg[(k + 2) * 64]; acc3 += s3 * Pg[(k + 3) * 64];
;         }
;         cur = (acc0 + acc1) + (acc2 + acc3);
;         SS[((size_t)((g + 1) * 8 + h) * 64 + v) * 64 + kq] = cur;
;         if (pf) { LAS float* dst = Pl + ((g + 2) % 3) * 4096; *(LAS f32x4*)(dst + 4 * tid) = pa; *(LAS f32x4*)(dst + 2048 + 4 * tid) = pb; }
;         u1 = u2; u2 = u3;
	ds_read2_b32 v[104:105], v9 offset0:0 offset1:4
	ds_read2st64_b32 v[120:121], v11 offset0:0 offset1:5
	ds_read2_b32 v[106:107], v9 offset0:8 offset1:12
	ds_read2st64_b32 v[122:123], v11 offset0:10 offset1:15
	ds_read2_b32 v[108:109], v9 offset0:16 offset1:20
	ds_read2st64_b32 v[124:125], v11 offset0:20 offset1:25
	ds_read2_b32 v[110:111], v9 offset0:24 offset1:28
	ds_read2st64_b32 v[126:127], v11 offset0:30 offset1:35
	ds_read2_b32 v[112:113], v9 offset0:32 offset1:36
	ds_read2st64_b32 v[128:129], v11 offset0:40 offset1:45
	ds_read2_b32 v[114:115], v9 offset0:40 offset1:44
	ds_read2st64_b32 v[130:131], v11 offset0:50 offset1:55
	ds_read2_b32 v[116:117], v9 offset0:48 offset1:52
	ds_read2st64_b32 v[132:133], v11 offset0:60 offset1:65
	s_waitcnt vmcnt(54)
	s_waitcnt lgkmcnt(12)
	v_mfma_f32_16x16x4_f32 v[136:139], v104, v120, v[216:219]
	v_mfma_f32_16x16x4_f32 v[136:139], v105, v121, v[136:139]
	ds_read2_b32 v[118:119], v9 offset0:56 offset1:60
	ds_read2st64_b32 v[134:135], v11 offset0:70 offset1:75
	s_waitcnt lgkmcnt(12)
	v_mfma_f32_16x16x4_f32 v[136:139], v106, v122, v[136:139]
	v_mfma_f32_16x16x4_f32 v[136:139], v107, v123, v[136:139]
	s_waitcnt lgkmcnt(10)
	v_mfma_f32_16x16x4_f32 v[136:139], v108, v124, v[136:139]
	v_mfma_f32_16x16x4_f32 v[136:139], v109, v125, v[136:139]
	s_waitcnt lgkmcnt(8)
	v_mfma_f32_16x16x4_f32 v[136:139], v110, v126, v[136:139]
	v_mfma_f32_16x16x4_f32 v[136:139], v111, v127, v[136:139]
	s_waitcnt lgkmcnt(6)
	v_mfma_f32_16x16x4_f32 v[136:139], v112, v128, v[136:139]
	v_mfma_f32_16x16x4_f32 v[136:139], v113, v129, v[136:139]
	s_waitcnt vmcnt(52)
	ds_write_b128 v2, v[84:87] offset:0
	ds_write_b128 v2, v[88:91] offset:10240
	s_waitcnt lgkmcnt(6)
	v_mfma_f32_16x16x4_f32 v[136:139], v114, v130, v[136:139]
	v_mfma_f32_16x16x4_f32 v[136:139], v115, v131, v[136:139]
	s_waitcnt lgkmcnt(4)
	v_mfma_f32_16x16x4_f32 v[136:139], v116, v132, v[136:139]
	v_mfma_f32_16x16x4_f32 v[136:139], v117, v133, v[136:139]
	s_waitcnt lgkmcnt(2)
	v_mfma_f32_16x16x4_f32 v[136:139], v118, v134, v[136:139]
	v_mfma_f32_16x16x4_f32 v[136:139], v119, v135, v[136:139]
	s_add_u32 s16, s8, 0x740000
	s_addc_u32 s17, s9, 0
	s_nop 9
	ds_write_b32 v13, v136 offset:0
	ds_write_b32 v13, v137 offset:272
	ds_write_b32 v13, v138 offset:544
	ds_write_b32 v13, v139 offset:816
	global_store_dword v12, v136, s[16:17] offset:0
	global_store_dword v12, v137, s[16:17] offset:256
	global_store_dword v12, v138, s[16:17] offset:512
	global_store_dword v12, v139, s[16:17] offset:768
	s_waitcnt lgkmcnt(0)
	s_barrier
	ds_read2_b32 v[104:105], v8 offset0:0 offset1:4
	ds_read2st64_b32 v[120:121], v10 offset0:0 offset1:5
	ds_read2_b32 v[106:107], v8 offset0:8 offset1:12
	ds_read2st64_b32 v[122:123], v10 offset0:10 offset1:15
	ds_read2_b32 v[108:109], v8 offset0:16 offset1:20
	ds_read2st64_b32 v[124:125], v10 offset0:20 offset1:25
	ds_read2_b32 v[110:111], v8 offset0:24 offset1:28
	ds_read2st64_b32 v[126:127], v10 offset0:30 offset1:35
	ds_read2_b32 v[112:113], v8 offset0:32 offset1:36
	ds_read2st64_b32 v[128:129], v10 offset0:40 offset1:45
	ds_read2_b32 v[114:115], v8 offset0:40 offset1:44
	ds_read2st64_b32 v[130:131], v10 offset0:50 offset1:55
	ds_read2_b32 v[116:117], v8 offset0:48 offset1:52
	ds_read2st64_b32 v[132:133], v10 offset0:60 offset1:65
	s_waitcnt vmcnt(48)
	s_waitcnt lgkmcnt(12)
	v_mfma_f32_16x16x4_f32 v[136:139], v104, v120, v[220:223]
	v_mfma_f32_16x16x4_f32 v[136:139], v105, v121, v[136:139]
	ds_read2_b32 v[118:119], v8 offset0:56 offset1:60
	ds_read2st64_b32 v[134:135], v10 offset0:70 offset1:75
	s_waitcnt lgkmcnt(12)
	v_mfma_f32_16x16x4_f32 v[136:139], v106, v122, v[136:139]
	v_mfma_f32_16x16x4_f32 v[136:139], v107, v123, v[136:139]
	s_waitcnt lgkmcnt(10)
	v_mfma_f32_16x16x4_f32 v[136:139], v108, v124, v[136:139]
	v_mfma_f32_16x16x4_f32 v[136:139], v109, v125, v[136:139]
	s_waitcnt lgkmcnt(8)
	v_mfma_f32_16x16x4_f32 v[136:139], v110, v126, v[136:139]
	v_mfma_f32_16x16x4_f32 v[136:139], v111, v127, v[136:139]
	s_waitcnt lgkmcnt(6)
	v_mfma_f32_16x16x4_f32 v[136:139], v112, v128, v[136:139]
	v_mfma_f32_16x16x4_f32 v[136:139], v113, v129, v[136:139]
	s_waitcnt vmcnt(46)
	ds_write_b128 v2, v[92:95] offset:20480
	ds_write_b128 v2, v[96:99] offset:30720
	s_waitcnt lgkmcnt(6)
	v_mfma_f32_16x16x4_f32 v[136:139], v114, v130, v[136:139]
	v_mfma_f32_16x16x4_f32 v[136:139], v115, v131, v[136:139]
	s_waitcnt lgkmcnt(4)
	v_mfma_f32_16x16x4_f32 v[136:139], v116, v132, v[136:139]
	v_mfma_f32_16x16x4_f32 v[136:139], v117, v133, v[136:139]
	s_waitcnt lgkmcnt(2)
	v_mfma_f32_16x16x4_f32 v[136:139], v118, v134, v[136:139]
	v_mfma_f32_16x16x4_f32 v[136:139], v119, v135, v[136:139]
	s_add_u32 s16, s8, 0x760000
	s_addc_u32 s17, s9, 0
	s_nop 9
	ds_write_b32 v13, v136 offset:2176
	ds_write_b32 v13, v137 offset:2448
	ds_write_b32 v13, v138 offset:2720
	ds_write_b32 v13, v139 offset:2992
	global_store_dword v12, v136, s[16:17] offset:0
	global_store_dword v12, v137, s[16:17] offset:256
	global_store_dword v12, v138, s[16:17] offset:512
	global_store_dword v12, v139, s[16:17] offset:768
	s_waitcnt lgkmcnt(0)
	s_barrier
; #define LAS __attribute__((address_space(3)))
; __device__ __forceinline__ void scan_combine(LAS unsigned char* lds, CArgsP a) {
;     ...
;     for (int g = 1; g <= GL; ++g) {
;         const bool pf = (g + 2 <= GL);
;         float u3 = 0.f;
;         if (pf) { const f32x4* Pn = (const f32x4*)(PM + (size_t)((g + 2) * 8 + h) * 4096); pa = Pn[tid]; pb = Pn[512 + tid]; u3 = UM[((size_t)((g + 2) * 8 + h) * 64 + v) * 64 + kq]; }
;         asm volatile("s_waitcnt lgkmcnt(0)\n\ts_barrier" ::: "memory");
;         const LAS float* Pg = Pl + (g % 3) * 4096 + kq;
;         float acc0 = u1, acc1 = 0.f, acc2 = 0.f, acc3 = 0.f;
;         const int curi = __builtin_bit_cast(int, cur);
; #pragma unroll
;         for (int k = 0; k < 64; k += 4) {
;             const float s0 = __builtin_bit_cast(float, __builtin_amdgcn_readlane(curi, k)), s1 = __builtin_bit_cast(float, __builtin_amdgcn_readlane(curi, k + 1));
;             const float s2 = __builtin_bit_cast(float, __builtin_amdgcn_readlane(curi, k + 2)), s3 = __builtin_bit_cast(float, __builtin_amdgcn_readlane(curi, k + 3));
;             acc0 += s0 * Pg[(k + 0) * 64]; acc1 += s1 * Pg[(k + 1) * 64]; acc2 += s2 * Pg[(k + 2) * 64]; acc3 += s3 * Pg[(k + 3) * 64];
;         }
;         cur = (acc0 + acc1) + (acc2 + acc3);
;         SS[((size_t)((g + 1) * 8 + h) * 64 + v) * 64 + kq] = cur;
;         if (pf) { LAS float* dst = Pl + ((g + 2) % 3) * 4096; *(LAS f32x4*)(dst + 4 * tid) = pa; *(LAS f32x4*)(dst + 2048 + 4 * tid) = pb; }
;         u1 = u2; u2 = u3;
	ds_read2_b32 v[104:105], v9 offset0:0 offset1:4
	ds_read2st64_b32 v[120:121], v11 offset0:0 offset1:5
	ds_read2_b32 v[106:107], v9 offset0:8 offset1:12
	ds_read2st64_b32 v[122:123], v11 offset0:10 offset1:15
	ds_read2_b32 v[108:109], v9 offset0:16 offset1:20
	ds_read2st64_b32 v[124:125], v11 offset0:20 offset1:25
	ds_read2_b32 v[110:111], v9 offset0:24 offset1:28
	ds_read2st64_b32 v[126:127], v11 offset0:30 offset1:35
	ds_read2_b32 v[112:113], v9 offset0:32 offset1:36
	ds_read2st64_b32 v[128:129], v11 offset0:40 offset1:45
	ds_read2_b32 v[114:115], v9 offset0:40 offset1:44
	ds_read2st64_b32 v[130:131], v11 offset0:50 offset1:55
	ds_read2_b32 v[116:117], v9 offset0:48 offset1:52
	ds_read2st64_b32 v[132:133], v11 offset0:60 offset1:65
	s_waitcnt vmcnt(42)
	s_waitcnt lgkmcnt(12)
	v_mfma_f32_16x16x4_f32 v[136:139], v104, v120, v[224:227]
	v_mfma_f32_16x16x4_f32 v[136:139], v105, v121, v[136:139]
	ds_read2_b32 v[118:119], v9 offset0:56 offset1:60
	ds_read2st64_b32 v[134:135], v11 offset0:70 offset1:75
	s_waitcnt lgkmcnt(12)
	v_mfma_f32_16x16x4_f32 v[136:139], v106, v122, v[136:139]
	v_mfma_f32_16x16x4_f32 v[136:139], v107, v123, v[136:139]
	s_waitcnt lgkmcnt(10)
	v_mfma_f32_16x16x4_f32 v[136:139], v108, v124, v[136:139]
	v_mfma_f32_16x16x4_f32 v[136:139], v109, v125, v[136:139]
	s_waitcnt lgkmcnt(8)
	v_mfma_f32_16x16x4_f32 v[136:139], v110, v126, v[136:139]
	v_mfma_f32_16x16x4_f32 v[136:139], v111, v127, v[136:139]
	s_waitcnt lgkmcnt(6)
	v_mfma_f32_16x16x4_f32 v[136:139], v112, v128, v[136:139]
	v_mfma_f32_16x16x4_f32 v[136:139], v113, v129, v[136:139]
	s_waitcnt vmcnt(40)
	ds_write_b128 v2, v[52:55] offset:0
	ds_write_b128 v2, v[56:59] offset:10240
	s_waitcnt lgkmcnt(6)
	v_mfma_f32_16x16x4_f32 v[136:139], v114, v130, v[136:139]
	v_mfma_f32_16x16x4_f32 v[136:139], v115, v131, v[136:139]
	s_waitcnt lgkmcnt(4)
	v_mfma_f32_16x16x4_f32 v[136:139], v116, v132, v[136:139]
	v_mfma_f32_16x16x4_f32 v[136:139], v117, v133, v[136:139]
	s_waitcnt lgkmcnt(2)
	v_mfma_f32_16x16x4_f32 v[136:139], v118, v134, v[136:139]
	v_mfma_f32_16x16x4_f32 v[136:139], v119, v135, v[136:139]
	s_add_u32 s16, s8, 0x780000
	s_addc_u32 s17, s9, 0
	s_nop 9
	ds_write_b32 v13, v136 offset:0
	ds_write_b32 v13, v137 offset:272
	ds_write_b32 v13, v138 offset:544
	ds_write_b32 v13, v139 offset:816
	global_store_dword v12, v136, s[16:17] offset:0
	global_store_dword v12, v137, s[16:17] offset:256
	global_store_dword v12, v138, s[16:17] offset:512
	global_store_dword v12, v139, s[16:17] offset:768
	s_waitcnt lgkmcnt(0)
	s_barrier
	ds_read2_b32 v[104:105], v8 offset0:0 offset1:4
	ds_read2st64_b32 v[120:121], v10 offset0:0 offset1:5
	ds_read2_b32 v[106:107], v8 offset0:8 offset1:12
	ds_read2st64_b32 v[122:123], v10 offset0:10 offset1:15
	ds_read2_b32 v[108:109], v8 offset0:16 offset1:20
	ds_read2st64_b32 v[124:125], v10 offset0:20 offset1:25
	ds_read2_b32 v[110:111], v8 offset0:24 offset1:28
	ds_read2st64_b32 v[126:127], v10 offset0:30 offset1:35
	ds_read2_b32 v[112:113], v8 offset0:32 offset1:36
	ds_read2st64_b32 v[128:129], v10 offset0:40 offset1:45
	ds_read2_b32 v[114:115], v8 offset0:40 offset1:44
	ds_read2st64_b32 v[130:131], v10 offset0:50 offset1:55
	ds_read2_b32 v[116:117], v8 offset0:48 offset1:52
	ds_read2st64_b32 v[132:133], v10 offset0:60 offset1:65
	s_waitcnt vmcnt(36)
	s_waitcnt lgkmcnt(12)
	v_mfma_f32_16x16x4_f32 v[136:139], v104, v120, v[204:207]
	v_mfma_f32_16x16x4_f32 v[136:139], v105, v121, v[136:139]
	ds_read2_b32 v[118:119], v8 offset0:56 offset1:60
	ds_read2st64_b32 v[134:135], v10 offset0:70 offset1:75
	s_waitcnt lgkmcnt(12)
	v_mfma_f32_16x16x4_f32 v[136:139], v106, v122, v[136:139]
	v_mfma_f32_16x16x4_f32 v[136:139], v107, v123, v[136:139]
	s_waitcnt lgkmcnt(10)
	v_mfma_f32_16x16x4_f32 v[136:139], v108, v124, v[136:139]
	v_mfma_f32_16x16x4_f32 v[136:139], v109, v125, v[136:139]
	s_waitcnt lgkmcnt(8)
	v_mfma_f32_16x16x4_f32 v[136:139], v110, v126, v[136:139]
	v_mfma_f32_16x16x4_f32 v[136:139], v111, v127, v[136:139]
	s_waitcnt lgkmcnt(6)
	v_mfma_f32_16x16x4_f32 v[136:139], v112, v128, v[136:139]
	v_mfma_f32_16x16x4_f32 v[136:139], v113, v129, v[136:139]
	s_waitcnt vmcnt(34)
	ds_write_b128 v2, v[60:63] offset:20480
	ds_write_b128 v2, v[64:67] offset:30720
	s_waitcnt lgkmcnt(6)
	v_mfma_f32_16x16x4_f32 v[136:139], v114, v130, v[136:139]
	v_mfma_f32_16x16x4_f32 v[136:139], v115, v131, v[136:139]
	s_waitcnt lgkmcnt(4)
	v_mfma_f32_16x16x4_f32 v[136:139], v116, v132, v[136:139]
	v_mfma_f32_16x16x4_f32 v[136:139], v117, v133, v[136:139]
	s_waitcnt lgkmcnt(2)
	v_mfma_f32_16x16x4_f32 v[136:139], v118, v134, v[136:139]
	v_mfma_f32_16x16x4_f32 v[136:139], v119, v135, v[136:139]
	s_add_u32 s16, s8, 0x7a0000
	s_addc_u32 s17, s9, 0
	s_nop 9
	ds_write_b32 v13, v136 offset:2176
	ds_write_b32 v13, v137 offset:2448
	ds_write_b32 v13, v138 offset:2720
	ds_write_b32 v13, v139 offset:2992
	global_store_dword v12, v136, s[16:17] offset:0
	global_store_dword v12, v137, s[16:17] offset:256
	global_store_dword v12, v138, s[16:17] offset:512
	global_store_dword v12, v139, s[16:17] offset:768
	s_waitcnt lgkmcnt(0)
	s_barrier
; #define LAS __attribute__((address_space(3)))
; __device__ __forceinline__ void scan_combine(LAS unsigned char* lds, CArgsP a) {
;     ...
;     for (int g = 1; g <= GL; ++g) {
;         const bool pf = (g + 2 <= GL);
;         float u3 = 0.f;
;         if (pf) { const f32x4* Pn = (const f32x4*)(PM + (size_t)((g + 2) * 8 + h) * 4096); pa = Pn[tid]; pb = Pn[512 + tid]; u3 = UM[((size_t)((g + 2) * 8 + h) * 64 + v) * 64 + kq]; }
;         asm volatile("s_waitcnt lgkmcnt(0)\n\ts_barrier" ::: "memory");
;         const LAS float* Pg = Pl + (g % 3) * 4096 + kq;
;         float acc0 = u1, acc1 = 0.f, acc2 = 0.f, acc3 = 0.f;
;         const int curi = __builtin_bit_cast(int, cur);
; #pragma unroll
;         for (int k = 0; k < 64; k += 4) {
;             const float s0 = __builtin_bit_cast(float, __builtin_amdgcn_readlane(curi, k)), s1 = __builtin_bit_cast(float, __builtin_amdgcn_readlane(curi, k + 1));
;             const float s2 = __builtin_bit_cast(float, __builtin_amdgcn_readlane(curi, k + 2)), s3 = __builtin_bit_cast(float, __builtin_amdgcn_readlane(curi, k + 3));
;             acc0 += s0 * Pg[(k + 0) * 64]; acc1 += s1 * Pg[(k + 1) * 64]; acc2 += s2 * Pg[(k + 2) * 64]; acc3 += s3 * Pg[(k + 3) * 64];
;         }
;         cur = (acc0 + acc1) + (acc2 + acc3);
;         SS[((size_t)((g + 1) * 8 + h) * 64 + v) * 64 + kq] = cur;
;         if (pf) { LAS float* dst = Pl + ((g + 2) % 3) * 4096; *(LAS f32x4*)(dst + 4 * tid) = pa; *(LAS f32x4*)(dst + 2048 + 4 * tid) = pb; }
;         u1 = u2; u2 = u3;
	ds_read2_b32 v[104:105], v9 offset0:0 offset1:4
	ds_read2st64_b32 v[120:121], v11 offset0:0 offset1:5
	ds_read2_b32 v[106:107], v9 offset0:8 offset1:12
	ds_read2st64_b32 v[122:123], v11 offset0:10 offset1:15
	ds_read2_b32 v[108:109], v9 offset0:16 offset1:20
	ds_read2st64_b32 v[124:125], v11 offset0:20 offset1:25
	ds_read2_b32 v[110:111], v9 offset0:24 offset1:28
	ds_read2st64_b32 v[126:127], v11 offset0:30 offset1:35
	ds_read2_b32 v[112:113], v9 offset0:32 offset1:36
	ds_read2st64_b32 v[128:129], v11 offset0:40 offset1:45
	ds_read2_b32 v[114:115], v9 offset0:40 offset1:44
	ds_read2st64_b32 v[130:131], v11 offset0:50 offset1:55
	ds_read2_b32 v[116:117], v9 offset0:48 offset1:52
	ds_read2st64_b32 v[132:133], v11 offset0:60 offset1:65
	s_waitcnt vmcnt(30)
	s_waitcnt lgkmcnt(12)
	v_mfma_f32_16x16x4_f32 v[136:139], v104, v120, v[208:211]
	v_mfma_f32_16x16x4_f32 v[136:139], v105, v121, v[136:139]
	ds_read2_b32 v[118:119], v9 offset0:56 offset1:60
	ds_read2st64_b32 v[134:135], v11 offset0:70 offset1:75
	s_waitcnt lgkmcnt(12)
	v_mfma_f32_16x16x4_f32 v[136:139], v106, v122, v[136:139]
	v_mfma_f32_16x16x4_f32 v[136:139], v107, v123, v[136:139]
	s_waitcnt lgkmcnt(10)
	v_mfma_f32_16x16x4_f32 v[136:139], v108, v124, v[136:139]
	v_mfma_f32_16x16x4_f32 v[136:139], v109, v125, v[136:139]
	s_waitcnt lgkmcnt(8)
	v_mfma_f32_16x16x4_f32 v[136:139], v110, v126, v[136:139]
	v_mfma_f32_16x16x4_f32 v[136:139], v111, v127, v[136:139]
	s_waitcnt lgkmcnt(6)
	v_mfma_f32_16x16x4_f32 v[136:139], v112, v128, v[136:139]
	v_mfma_f32_16x16x4_f32 v[136:139], v113, v129, v[136:139]
	s_waitcnt vmcnt(28)
	ds_write_b128 v2, v[68:71] offset:0
	ds_write_b128 v2, v[72:75] offset:10240
	s_waitcnt lgkmcnt(6)
	v_mfma_f32_16x16x4_f32 v[136:139], v114, v130, v[136:139]
	v_mfma_f32_16x16x4_f32 v[136:139], v115, v131, v[136:139]
	s_waitcnt lgkmcnt(4)
	v_mfma_f32_16x16x4_f32 v[136:139], v116, v132, v[136:139]
	v_mfma_f32_16x16x4_f32 v[136:139], v117, v133, v[136:139]
	s_waitcnt lgkmcnt(2)
	v_mfma_f32_16x16x4_f32 v[136:139], v118, v134, v[136:139]
	v_mfma_f32_16x16x4_f32 v[136:139], v119, v135, v[136:139]
	s_add_u32 s16, s8, 0x7c0000
	s_addc_u32 s17, s9, 0
	s_nop 9
	ds_write_b32 v13, v136 offset:0
	ds_write_b32 v13, v137 offset:272
	ds_write_b32 v13, v138 offset:544
	ds_write_b32 v13, v139 offset:816
	global_store_dword v12, v136, s[16:17] offset:0
	global_store_dword v12, v137, s[16:17] offset:256
	global_store_dword v12, v138, s[16:17] offset:512
	global_store_dword v12, v139, s[16:17] offset:768
	s_waitcnt lgkmcnt(0)
	s_barrier
	ds_read2_b32 v[104:105], v8 offset0:0 offset1:4
	ds_read2st64_b32 v[120:121], v10 offset0:0 offset1:5
	ds_read2_b32 v[106:107], v8 offset0:8 offset1:12
	ds_read2st64_b32 v[122:123], v10 offset0:10 offset1:15
	ds_read2_b32 v[108:109], v8 offset0:16 offset1:20
	ds_read2st64_b32 v[124:125], v10 offset0:20 offset1:25
	ds_read2_b32 v[110:111], v8 offset0:24 offset1:28
	ds_read2st64_b32 v[126:127], v10 offset0:30 offset1:35
	ds_read2_b32 v[112:113], v8 offset0:32 offset1:36
	ds_read2st64_b32 v[128:129], v10 offset0:40 offset1:45
	ds_read2_b32 v[114:115], v8 offset0:40 offset1:44
	ds_read2st64_b32 v[130:131], v10 offset0:50 offset1:55
	ds_read2_b32 v[116:117], v8 offset0:48 offset1:52
	ds_read2st64_b32 v[132:133], v10 offset0:60 offset1:65
	s_waitcnt vmcnt(24)
	s_waitcnt lgkmcnt(12)
	v_mfma_f32_16x16x4_f32 v[136:139], v104, v120, v[212:215]
	v_mfma_f32_16x16x4_f32 v[136:139], v105, v121, v[136:139]
	ds_read2_b32 v[118:119], v8 offset0:56 offset1:60
	ds_read2st64_b32 v[134:135], v10 offset0:70 offset1:75
	s_waitcnt lgkmcnt(12)
	v_mfma_f32_16x16x4_f32 v[136:139], v106, v122, v[136:139]
	v_mfma_f32_16x16x4_f32 v[136:139], v107, v123, v[136:139]
	s_waitcnt lgkmcnt(10)
	v_mfma_f32_16x16x4_f32 v[136:139], v108, v124, v[136:139]
	v_mfma_f32_16x16x4_f32 v[136:139], v109, v125, v[136:139]
	s_waitcnt lgkmcnt(8)
	v_mfma_f32_16x16x4_f32 v[136:139], v110, v126, v[136:139]
	v_mfma_f32_16x16x4_f32 v[136:139], v111, v127, v[136:139]
	s_waitcnt lgkmcnt(6)
	v_mfma_f32_16x16x4_f32 v[136:139], v112, v128, v[136:139]
	v_mfma_f32_16x16x4_f32 v[136:139], v113, v129, v[136:139]
	s_waitcnt lgkmcnt(4)
	v_mfma_f32_16x16x4_f32 v[136:139], v114, v130, v[136:139]
	v_mfma_f32_16x16x4_f32 v[136:139], v115, v131, v[136:139]
	s_waitcnt lgkmcnt(2)
	v_mfma_f32_16x16x4_f32 v[136:139], v116, v132, v[136:139]
	v_mfma_f32_16x16x4_f32 v[136:139], v117, v133, v[136:139]
	s_waitcnt lgkmcnt(0)
	v_mfma_f32_16x16x4_f32 v[136:139], v118, v134, v[136:139]
	v_mfma_f32_16x16x4_f32 v[136:139], v119, v135, v[136:139]
	s_add_u32 s16, s8, 0x7e0000
	s_addc_u32 s17, s9, 0
	s_nop 9
	global_store_dword v12, v136, s[16:17] offset:0
	global_store_dword v12, v137, s[16:17] offset:256
	global_store_dword v12, v138, s[16:17] offset:512
	global_store_dword v12, v139, s[16:17] offset:768
	s_branch .Lcmb_done
; #define LAS __attribute__((address_space(3)))
; __device__ __forceinline__ void scan_combine(LAS unsigned char* lds, CArgsP a) {
;     ...
;     for (int g = 1; g <= GL; ++g) {
;         const bool pf = (g + 2 <= GL);
;         float u3 = 0.f;
;         if (pf) { const f32x4* Pn = (const f32x4*)(PM + (size_t)((g + 2) * 8 + h) * 4096); pa = Pn[tid]; pb = Pn[512 + tid]; u3 = UM[((size_t)((g + 2) * 8 + h) * 64 + v) * 64 + kq]; }
;         asm volatile("s_waitcnt lgkmcnt(0)\n\ts_barrier" ::: "memory");
;         const LAS float* Pg = Pl + (g % 3) * 4096 + kq;
;         float acc0 = u1, acc1 = 0.f, acc2 = 0.f, acc3 = 0.f;
;         const int curi = __builtin_bit_cast(int, cur);
; #pragma unroll
;         for (int k = 0; k < 64; k += 4) {
;             const float s0 = __builtin_bit_cast(float, __builtin_amdgcn_readlane(curi, k)), s1 = __builtin_bit_cast(float, __builtin_amdgcn_readlane(curi, k + 1));
;             const float s2 = __builtin_bit_cast(float, __builtin_amdgcn_readlane(curi, k + 2)), s3 = __builtin_bit_cast(float, __builtin_amdgcn_readlane(curi, k + 3));
;             acc0 += s0 * Pg[(k + 0) * 64]; acc1 += s1 * Pg[(k + 1) * 64]; acc2 += s2 * Pg[(k + 2) * 64]; acc3 += s3 * Pg[(k + 3) * 64];
;         }
;         cur = (acc0 + acc1) + (acc2 + acc3);
;         SS[((size_t)((g + 1) * 8 + h) * 64 + v) * 64 + kq] = cur;
;         if (pf) { LAS float* dst = Pl + ((g + 2) % 3) * 4096; *(LAS f32x4*)(dst + 4 * tid) = pa; *(LAS f32x4*)(dst + 2048 + 4 * tid) = pb; }
;         u1 = u2; u2 = u3;
.Lcmb_loader:
	s_waitcnt lgkmcnt(0)
	s_barrier
	s_waitcnt vmcnt(10)
	ds_write_b128 v2, v[68:71] offset:0
	ds_write_b128 v2, v[72:75] offset:10240
	s_add_u32 s10, s0, 0x100000
	s_addc_u32 s11, s1, 0
	global_load_dwordx4 v[68:71], v0, s[10:11]
	global_load_dwordx4 v[72:75], v1, s[10:11]
	s_waitcnt lgkmcnt(0)
	s_barrier
	s_waitcnt vmcnt(10)
	ds_write_b128 v2, v[76:79] offset:20480
	ds_write_b128 v2, v[80:83] offset:30720
	s_add_u32 s10, s0, 0x120000
	s_addc_u32 s11, s1, 0
	global_load_dwordx4 v[76:79], v0, s[10:11]
	global_load_dwordx4 v[80:83], v1, s[10:11]
	s_waitcnt lgkmcnt(0)
	s_barrier
	s_waitcnt vmcnt(10)
	ds_write_b128 v2, v[84:87] offset:0
	ds_write_b128 v2, v[88:91] offset:10240
	s_add_u32 s10, s0, 0x140000
	s_addc_u32 s11, s1, 0
	global_load_dwordx4 v[84:87], v0, s[10:11]
	global_load_dwordx4 v[88:91], v1, s[10:11]
	s_waitcnt lgkmcnt(0)
	s_barrier
	s_waitcnt vmcnt(10)
	ds_write_b128 v2, v[92:95] offset:20480
	ds_write_b128 v2, v[96:99] offset:30720
	s_add_u32 s10, s0, 0x160000
	s_addc_u32 s11, s1, 0
	global_load_dwordx4 v[92:95], v0, s[10:11]
	global_load_dwordx4 v[96:99], v1, s[10:11]
	s_waitcnt lgkmcnt(0)
	s_barrier
	s_waitcnt vmcnt(10)
	ds_write_b128 v2, v[52:55] offset:0
	ds_write_b128 v2, v[56:59] offset:10240
	s_add_u32 s10, s0, 0x180000
	s_addc_u32 s11, s1, 0
	global_load_dwordx4 v[52:55], v0, s[10:11]
	global_load_dwordx4 v[56:59], v1, s[10:11]
	s_waitcnt lgkmcnt(0)
	s_barrier
	s_waitcnt vmcnt(10)
	ds_write_b128 v2, v[60:63] offset:20480
	ds_write_b128 v2, v[64:67] offset:30720
	s_add_u32 s10, s0, 0x1a0000
	s_addc_u32 s11, s1, 0
	global_load_dwordx4 v[60:63], v0, s[10:11]
	global_load_dwordx4 v[64:67], v1, s[10:11]
	s_waitcnt lgkmcnt(0)
	s_barrier
	s_waitcnt vmcnt(10)
	ds_write_b128 v2, v[68:71] offset:0
	ds_write_b128 v2, v[72:75] offset:10240
	s_add_u32 s10, s0, 0x1c0000
	s_addc_u32 s11, s1, 0
	global_load_dwordx4 v[68:71], v0, s[10:11]
	global_load_dwordx4 v[72:75], v1, s[10:11]
	s_waitcnt lgkmcnt(0)
	s_barrier
	s_waitcnt vmcnt(10)
	ds_write_b128 v2, v[76:79] offset:20480
	ds_write_b128 v2, v[80:83] offset:30720
	s_add_u32 s10, s0, 0x1e0000
	s_addc_u32 s11, s1, 0
	global_load_dwordx4 v[76:79], v0, s[10:11]
	global_load_dwordx4 v[80:83], v1, s[10:11]
	s_waitcnt lgkmcnt(0)
	s_barrier
	s_waitcnt vmcnt(10)
	ds_write_b128 v2, v[84:87] offset:0
	ds_write_b128 v2, v[88:91] offset:10240
	s_add_u32 s10, s0, 0x200000
	s_addc_u32 s11, s1, 0
	global_load_dwordx4 v[84:87], v0, s[10:11]
	global_load_dwordx4 v[88:91], v1, s[10:11]
	s_waitcnt lgkmcnt(0)
	s_barrier
	s_waitcnt vmcnt(10)
	ds_write_b128 v2, v[92:95] offset:20480
	ds_write_b128 v2, v[96:99] offset:30720
	s_add_u32 s10, s0, 0x220000
	s_addc_u32 s11, s1, 0
	global_load_dwordx4 v[92:95], v0, s[10:11]
	global_load_dwordx4 v[96:99], v1, s[10:11]
	s_waitcnt lgkmcnt(0)
	s_barrier
	s_waitcnt vmcnt(10)
	ds_write_b128 v2, v[52:55] offset:0
	ds_write_b128 v2, v[56:59] offset:10240
	s_add_u32 s10, s0, 0x240000
	s_addc_u32 s11, s1, 0
	global_load_dwordx4 v[52:55], v0, s[10:11]
	global_load_dwordx4 v[56:59], v1, s[10:11]
	s_waitcnt lgkmcnt(0)
	s_barrier
	s_waitcnt vmcnt(10)
	ds_write_b128 v2, v[60:63] offset:20480
	ds_write_b128 v2, v[64:67] offset:30720
	s_add_u32 s10, s0, 0x260000
	s_addc_u32 s11, s1, 0
	global_load_dwordx4 v[60:63], v0, s[10:11]
	global_load_dwordx4 v[64:67], v1, s[10:11]
	s_waitcnt lgkmcnt(0)
	s_barrier
	s_waitcnt vmcnt(10)
	ds_write_b128 v2, v[68:71] offset:0
	ds_write_b128 v2, v[72:75] offset:10240
	s_add_u32 s10, s0, 0x280000
	s_addc_u32 s11, s1, 0
	global_load_dwordx4 v[68:71], v0, s[10:11]
	global_load_dwordx4 v[72:75], v1, s[10:11]
	s_waitcnt lgkmcnt(0)
	s_barrier
	s_waitcnt vmcnt(10)
	ds_write_b128 v2, v[76:79] offset:20480
	ds_write_b128 v2, v[80:83] offset:30720
	s_add_u32 s10, s0, 0x2a0000
	s_addc_u32 s11, s1, 0
	global_load_dwordx4 v[76:79], v0, s[10:11]
	global_load_dwordx4 v[80:83], v1, s[10:11]
	s_waitcnt lgkmcnt(0)
	s_barrier
	s_waitcnt vmcnt(10)
	ds_write_b128 v2, v[84:87] offset:0
	ds_write_b128 v2, v[88:91] offset:10240
	s_add_u32 s10, s0, 0x2c0000
	s_addc_u32 s11, s1, 0
	global_load_dwordx4 v[84:87], v0, s[10:11]
	global_load_dwordx4 v[88:91], v1, s[10:11]
	s_waitcnt lgkmcnt(0)
	s_barrier
	s_waitcnt vmcnt(10)
	ds_write_b128 v2, v[92:95] offset:20480
	ds_write_b128 v2, v[96:99] offset:30720
	s_add_u32 s10, s0, 0x2e0000
	s_addc_u32 s11, s1, 0
	global_load_dwordx4 v[92:95], v0, s[10:11]
	global_load_dwordx4 v[96:99], v1, s[10:11]
	s_waitcnt lgkmcnt(0)
	s_barrier
	s_waitcnt vmcnt(10)
	ds_write_b128 v2, v[52:55] offset:0
	ds_write_b128 v2, v[56:59] offset:10240
	s_add_u32 s10, s0, 0x300000
	s_addc_u32 s11, s1, 0
	global_load_dwordx4 v[52:55], v0, s[10:11]
	global_load_dwordx4 v[56:59], v1, s[10:11]
	s_waitcnt lgkmcnt(0)
	s_barrier
	s_waitcnt vmcnt(10)
	ds_write_b128 v2, v[60:63] offset:20480
	ds_write_b128 v2, v[64:67] offset:30720
	s_add_u32 s10, s0, 0x320000
	s_addc_u32 s11, s1, 0
	global_load_dwordx4 v[60:63], v0, s[10:11]
	global_load_dwordx4 v[64:67], v1, s[10:11]
	s_waitcnt lgkmcnt(0)
	s_barrier
	s_waitcnt vmcnt(10)
	ds_write_b128 v2, v[68:71] offset:0
	ds_write_b128 v2, v[72:75] offset:10240
	s_add_u32 s10, s0, 0x340000
	s_addc_u32 s11, s1, 0
	global_load_dwordx4 v[68:71], v0, s[10:11]
	global_load_dwordx4 v[72:75], v1, s[10:11]
	s_waitcnt lgkmcnt(0)
	s_barrier
	s_waitcnt vmcnt(10)
	ds_write_b128 v2, v[76:79] offset:20480
	ds_write_b128 v2, v[80:83] offset:30720
	s_add_u32 s10, s0, 0x360000
	s_addc_u32 s11, s1, 0
	global_load_dwordx4 v[76:79], v0, s[10:11]
	global_load_dwordx4 v[80:83], v1, s[10:11]
	s_waitcnt lgkmcnt(0)
	s_barrier
; #define LAS __attribute__((address_space(3)))
; __device__ __forceinline__ void scan_combine(LAS unsigned char* lds, CArgsP a) {
;     ...
;         if (pf) { const f32x4* Pn = (const f32x4*)(PM + (size_t)((g + 2) * 8 + h) * 4096); pa = Pn[tid]; pb = Pn[512 + tid]; u3 = UM[((size_t)((g + 2) * 8 + h) * 64 + v) * 64 + kq]; }
;         asm volatile("s_waitcnt lgkmcnt(0)\n\ts_barrier" ::: "memory");
;         const LAS float* Pg = Pl + (g % 3) * 4096 + kq;
;         float acc0 = u1, acc1 = 0.f, acc2 = 0.f, acc3 = 0.f;
;         const int curi = __builtin_bit_cast(int, cur);
; #pragma unroll
;         for (int k = 0; k < 64; k += 4) {
;             const float s0 = __builtin_bit_cast(float, __builtin_amdgcn_readlane(curi, k)), s1 = __builtin_bit_cast(float, __builtin_amdgcn_readlane(curi, k + 1));
;             const float s2 = __builtin_bit_cast(float, __builtin_amdgcn_readlane(curi, k + 2)), s3 = __builtin_bit_cast(float, __builtin_amdgcn_readlane(curi, k + 3));
;             acc0 += s0 * Pg[(k + 0) * 64]; acc1 += s1 * Pg[(k + 1) * 64]; acc2 += s2 * Pg[(k + 2) * 64]; acc3 += s3 * Pg[(k + 3) * 64];
;         }
;         cur = (acc0 + acc1) + (acc2 + acc3);
;         SS[((size_t)((g + 1) * 8 + h) * 64 + v) * 64 + kq] = cur;
;         if (pf) { LAS float* dst = Pl + ((g + 2) % 3) * 4096; *(LAS f32x4*)(dst + 4 * tid) = pa; *(LAS f32x4*)(dst + 2048 + 4 * tid) = pb; }
	s_waitcnt vmcnt(10)
	ds_write_b128 v2, v[84:87] offset:0
	ds_write_b128 v2, v[88:91] offset:10240
	s_add_u32 s10, s0, 0x380000
	s_addc_u32 s11, s1, 0
	global_load_dwordx4 v[84:87], v0, s[10:11]
	global_load_dwordx4 v[88:91], v1, s[10:11]
	s_waitcnt lgkmcnt(0)
	s_barrier
	s_waitcnt vmcnt(10)
	ds_write_b128 v2, v[92:95] offset:20480
	ds_write_b128 v2, v[96:99] offset:30720
	s_add_u32 s10, s0, 0x3a0000
	s_addc_u32 s11, s1, 0
	global_load_dwordx4 v[92:95], v0, s[10:11]
	global_load_dwordx4 v[96:99], v1, s[10:11]
	s_waitcnt lgkmcnt(0)
	s_barrier
	s_waitcnt vmcnt(10)
	ds_write_b128 v2, v[52:55] offset:0
	ds_write_b128 v2, v[56:59] offset:10240
	s_add_u32 s10, s0, 0x3c0000
	s_addc_u32 s11, s1, 0
	global_load_dwordx4 v[52:55], v0, s[10:11]
	global_load_dwordx4 v[56:59], v1, s[10:11]
	s_waitcnt lgkmcnt(0)
	s_barrier
	s_waitcnt vmcnt(10)
	ds_write_b128 v2, v[60:63] offset:20480
	ds_write_b128 v2, v[64:67] offset:30720
	s_add_u32 s10, s0, 0x3e0000
	s_addc_u32 s11, s1, 0
	global_load_dwordx4 v[60:63], v0, s[10:11]
	global_load_dwordx4 v[64:67], v1, s[10:11]
	s_waitcnt lgkmcnt(0)
	s_barrier
	s_waitcnt vmcnt(10)
	ds_write_b128 v2, v[68:71] offset:0
	ds_write_b128 v2, v[72:75] offset:10240
	s_add_u32 s10, s0, 0x400000
	s_addc_u32 s11, s1, 0
	global_load_dwordx4 v[68:71], v0, s[10:11]
	global_load_dwordx4 v[72:75], v1, s[10:11]
	s_waitcnt lgkmcnt(0)
	s_barrier
	s_waitcnt vmcnt(10)
	ds_write_b128 v2, v[76:79] offset:20480
	ds_write_b128 v2, v[80:83] offset:30720
	s_add_u32 s10, s0, 0x420000
	s_addc_u32 s11, s1, 0
	global_load_dwordx4 v[76:79], v0, s[10:11]
	global_load_dwordx4 v[80:83], v1, s[10:11]
	s_waitcnt lgkmcnt(0)
	s_barrier
	s_waitcnt vmcnt(10)
	ds_write_b128 v2, v[84:87] offset:0
	ds_write_b128 v2, v[88:91] offset:10240
	s_add_u32 s10, s0, 0x440000
	s_addc_u32 s11, s1, 0
	global_load_dwordx4 v[84:87], v0, s[10:11]
	global_load_dwordx4 v[88:91], v1, s[10:11]
	s_waitcnt lgkmcnt(0)
	s_barrier
	s_waitcnt vmcnt(10)
	ds_write_b128 v2, v[92:95] offset:20480
	ds_write_b128 v2, v[96:99] offset:30720
	s_add_u32 s10, s0, 0x460000
	s_addc_u32 s11, s1, 0
	global_load_dwordx4 v[92:95], v0, s[10:11]
	global_load_dwordx4 v[96:99], v1, s[10:11]
	s_waitcnt lgkmcnt(0)
	s_barrier
	s_waitcnt vmcnt(10)
	ds_write_b128 v2, v[52:55] offset:0
	ds_write_b128 v2, v[56:59] offset:10240
	s_add_u32 s10, s0, 0x480000
	s_addc_u32 s11, s1, 0
	global_load_dwordx4 v[52:55], v0, s[10:11]
	global_load_dwordx4 v[56:59], v1, s[10:11]
	s_waitcnt lgkmcnt(0)
	s_barrier
	s_waitcnt vmcnt(10)
	ds_write_b128 v2, v[60:63] offset:20480
	ds_write_b128 v2, v[64:67] offset:30720
	s_add_u32 s10, s0, 0x4a0000
	s_addc_u32 s11, s1, 0
	global_load_dwordx4 v[60:63], v0, s[10:11]
	global_load_dwordx4 v[64:67], v1, s[10:11]
	s_waitcnt lgkmcnt(0)
	s_barrier
	s_waitcnt vmcnt(10)
	ds_write_b128 v2, v[68:71] offset:0
	ds_write_b128 v2, v[72:75] offset:10240
	s_add_u32 s10, s0, 0x4c0000
	s_addc_u32 s11, s1, 0
	global_load_dwordx4 v[68:71], v0, s[10:11]
	global_load_dwordx4 v[72:75], v1, s[10:11]
	s_waitcnt lgkmcnt(0)
	s_barrier
	s_waitcnt vmcnt(10)
	ds_write_b128 v2, v[76:79] offset:20480
	ds_write_b128 v2, v[80:83] offset:30720
	s_add_u32 s10, s0, 0x4e0000
	s_addc_u32 s11, s1, 0
	global_load_dwordx4 v[76:79], v0, s[10:11]
	global_load_dwordx4 v[80:83], v1, s[10:11]
	s_waitcnt lgkmcnt(0)
	s_barrier
	s_waitcnt vmcnt(10)
	ds_write_b128 v2, v[84:87] offset:0
	ds_write_b128 v2, v[88:91] offset:10240
	s_add_u32 s10, s0, 0x500000
	s_addc_u32 s11, s1, 0
	global_load_dwordx4 v[84:87], v0, s[10:11]
	global_load_dwordx4 v[88:91], v1, s[10:11]
	s_waitcnt lgkmcnt(0)
	s_barrier
	s_waitcnt vmcnt(10)
	ds_write_b128 v2, v[92:95] offset:20480
	ds_write_b128 v2, v[96:99] offset:30720
	s_add_u32 s10, s0, 0x520000
	s_addc_u32 s11, s1, 0
	global_load_dwordx4 v[92:95], v0, s[10:11]
	global_load_dwordx4 v[96:99], v1, s[10:11]
	s_waitcnt lgkmcnt(0)
	s_barrier
	s_waitcnt vmcnt(10)
	ds_write_b128 v2, v[52:55] offset:0
	ds_write_b128 v2, v[56:59] offset:10240
	s_add_u32 s10, s0, 0x540000
	s_addc_u32 s11, s1, 0
	global_load_dwordx4 v[52:55], v0, s[10:11]
	global_load_dwordx4 v[56:59], v1, s[10:11]
	s_waitcnt lgkmcnt(0)
	s_barrier
	s_waitcnt vmcnt(10)
	ds_write_b128 v2, v[60:63] offset:20480
	ds_write_b128 v2, v[64:67] offset:30720
	s_add_u32 s10, s0, 0x560000
	s_addc_u32 s11, s1, 0
	global_load_dwordx4 v[60:63], v0, s[10:11]
	global_load_dwordx4 v[64:67], v1, s[10:11]
	s_waitcnt lgkmcnt(0)
	s_barrier
	s_waitcnt vmcnt(10)
	ds_write_b128 v2, v[68:71] offset:0
	ds_write_b128 v2, v[72:75] offset:10240
	s_add_u32 s10, s0, 0x580000
	s_addc_u32 s11, s1, 0
	global_load_dwordx4 v[68:71], v0, s[10:11]
	global_load_dwordx4 v[72:75], v1, s[10:11]
	s_waitcnt lgkmcnt(0)
	s_barrier
	s_waitcnt vmcnt(10)
	ds_write_b128 v2, v[76:79] offset:20480
	ds_write_b128 v2, v[80:83] offset:30720
	s_add_u32 s10, s0, 0x5a0000
	s_addc_u32 s11, s1, 0
	global_load_dwordx4 v[76:79], v0, s[10:11]
	global_load_dwordx4 v[80:83], v1, s[10:11]
	s_waitcnt lgkmcnt(0)
	s_barrier
	s_waitcnt vmcnt(10)
	ds_write_b128 v2, v[84:87] offset:0
	ds_write_b128 v2, v[88:91] offset:10240
	s_add_u32 s10, s0, 0x5c0000
	s_addc_u32 s11, s1, 0
	global_load_dwordx4 v[84:87], v0, s[10:11]
	global_load_dwordx4 v[88:91], v1, s[10:11]
	s_waitcnt lgkmcnt(0)
	s_barrier
	s_waitcnt vmcnt(10)
	ds_write_b128 v2, v[92:95] offset:20480
	ds_write_b128 v2, v[96:99] offset:30720
	s_add_u32 s10, s0, 0x5e0000
	s_addc_u32 s11, s1, 0
	global_load_dwordx4 v[92:95], v0, s[10:11]
	global_load_dwordx4 v[96:99], v1, s[10:11]
	s_waitcnt lgkmcnt(0)
	s_barrier
	s_waitcnt vmcnt(10)
	ds_write_b128 v2, v[52:55] offset:0
	ds_write_b128 v2, v[56:59] offset:10240
	s_add_u32 s10, s0, 0x600000
	s_addc_u32 s11, s1, 0
	global_load_dwordx4 v[52:55], v0, s[10:11]
	global_load_dwordx4 v[56:59], v1, s[10:11]
	s_waitcnt lgkmcnt(0)
	s_barrier
; #define LAS __attribute__((address_space(3)))
; __device__ __forceinline__ CArgsP get_args() { CArgsP p = (CArgsP)__builtin_amdgcn_kernarg_segment_ptr(); asm volatile("" : "+s"(p)); return p; }
; #define PH(k) for (int r_ = 0, n_ = probe_reps(k); r_ < n_; ++r_)
; __device__ __forceinline__ void scan_combine(LAS unsigned char* lds, CArgsP a) {
;     ...
;         if (pf) { const f32x4* Pn = (const f32x4*)(PM + (size_t)((g + 2) * 8 + h) * 4096); pa = Pn[tid]; pb = Pn[512 + tid]; u3 = UM[((size_t)((g + 2) * 8 + h) * 64 + v) * 64 + kq]; }
;         asm volatile("s_waitcnt lgkmcnt(0)\n\ts_barrier" ::: "memory");
;         const LAS float* Pg = Pl + (g % 3) * 4096 + kq;
;         float acc0 = u1, acc1 = 0.f, acc2 = 0.f, acc3 = 0.f;
;         const int curi = __builtin_bit_cast(int, cur);
; #pragma unroll
;         for (int k = 0; k < 64; k += 4) {
;             const float s0 = __builtin_bit_cast(float, __builtin_amdgcn_readlane(curi, k)), s1 = __builtin_bit_cast(float, __builtin_amdgcn_readlane(curi, k + 1));
;             const float s2 = __builtin_bit_cast(float, __builtin_amdgcn_readlane(curi, k + 2)), s3 = __builtin_bit_cast(float, __builtin_amdgcn_readlane(curi, k + 3));
;             acc0 += s0 * Pg[(k + 0) * 64]; acc1 += s1 * Pg[(k + 1) * 64]; acc2 += s2 * Pg[(k + 2) * 64]; acc3 += s3 * Pg[(k + 3) * 64];
;         }
;         cur = (acc0 + acc1) + (acc2 + acc3);
;         SS[((size_t)((g + 1) * 8 + h) * 64 + v) * 64 + kq] = cur;
;         if (pf) { LAS float* dst = Pl + ((g + 2) % 3) * 4096; *(LAS f32x4*)(dst + 4 * tid) = pa; *(LAS f32x4*)(dst + 2048 + 4 * tid) = pb; }
;         u1 = u2; u2 = u3;
;     }
; __global__ void __launch_bounds__(512, 2) mega_fwd(Args a_unused) {
;     ...
;     PH(7) { CArgsP a = get_args(); if (bx < 64 || G <= 64) scan_combine(lds, a); __syncthreads(); if (G != 256 && (bx >= 64 || G <= 64)) convert_weights(a, lds, wave, lane, 1, G <= 64 ? bx : bx - 64, G <= 64 ? G : G - 64); if (G == 256 && bx >= 64 && bx < 192) attn_sample_unit(lds, a, (bx - 64) >> 3, (bx - 64) & 7);
	s_waitcnt vmcnt(10)
	ds_write_b128 v2, v[60:63] offset:20480
	ds_write_b128 v2, v[64:67] offset:30720
	s_add_u32 s10, s0, 0x620000
	s_addc_u32 s11, s1, 0
	global_load_dwordx4 v[60:63], v0, s[10:11]
	global_load_dwordx4 v[64:67], v1, s[10:11]
	s_waitcnt lgkmcnt(0)
	s_barrier
	s_waitcnt vmcnt(10)
	ds_write_b128 v2, v[68:71] offset:0
	ds_write_b128 v2, v[72:75] offset:10240
	s_add_u32 s10, s0, 0x640000
	s_addc_u32 s11, s1, 0
	global_load_dwordx4 v[68:71], v0, s[10:11]
	global_load_dwordx4 v[72:75], v1, s[10:11]
	s_waitcnt lgkmcnt(0)
	s_barrier
	s_waitcnt vmcnt(10)
	ds_write_b128 v2, v[76:79] offset:20480
	ds_write_b128 v2, v[80:83] offset:30720
	s_add_u32 s10, s0, 0x660000
	s_addc_u32 s11, s1, 0
	global_load_dwordx4 v[76:79], v0, s[10:11]
	global_load_dwordx4 v[80:83], v1, s[10:11]
	s_waitcnt lgkmcnt(0)
	s_barrier
	s_waitcnt vmcnt(10)
	ds_write_b128 v2, v[84:87] offset:0
	ds_write_b128 v2, v[88:91] offset:10240
	s_add_u32 s10, s0, 0x680000
	s_addc_u32 s11, s1, 0
	global_load_dwordx4 v[84:87], v0, s[10:11]
	global_load_dwordx4 v[88:91], v1, s[10:11]
	s_waitcnt lgkmcnt(0)
	s_barrier
	s_waitcnt vmcnt(10)
	ds_write_b128 v2, v[92:95] offset:20480
	ds_write_b128 v2, v[96:99] offset:30720
	s_add_u32 s10, s0, 0x6a0000
	s_addc_u32 s11, s1, 0
	global_load_dwordx4 v[92:95], v0, s[10:11]
	global_load_dwordx4 v[96:99], v1, s[10:11]
	s_waitcnt lgkmcnt(0)
	s_barrier
	s_waitcnt vmcnt(10)
	ds_write_b128 v2, v[52:55] offset:0
	ds_write_b128 v2, v[56:59] offset:10240
	s_add_u32 s10, s0, 0x6c0000
	s_addc_u32 s11, s1, 0
	global_load_dwordx4 v[52:55], v0, s[10:11]
	global_load_dwordx4 v[56:59], v1, s[10:11]
	s_waitcnt lgkmcnt(0)
	s_barrier
	s_waitcnt vmcnt(10)
	ds_write_b128 v2, v[60:63] offset:20480
	ds_write_b128 v2, v[64:67] offset:30720
	s_add_u32 s10, s0, 0x6e0000
	s_addc_u32 s11, s1, 0
	global_load_dwordx4 v[60:63], v0, s[10:11]
	global_load_dwordx4 v[64:67], v1, s[10:11]
	s_waitcnt lgkmcnt(0)
	s_barrier
	s_waitcnt vmcnt(10)
	ds_write_b128 v2, v[68:71] offset:0
	ds_write_b128 v2, v[72:75] offset:10240
	s_add_u32 s10, s0, 0x700000
	s_addc_u32 s11, s1, 0
	global_load_dwordx4 v[68:71], v0, s[10:11]
	global_load_dwordx4 v[72:75], v1, s[10:11]
	s_waitcnt lgkmcnt(0)
	s_barrier
	s_waitcnt vmcnt(10)
	ds_write_b128 v2, v[76:79] offset:20480
	ds_write_b128 v2, v[80:83] offset:30720
	s_add_u32 s10, s0, 0x720000
	s_addc_u32 s11, s1, 0
	global_load_dwordx4 v[76:79], v0, s[10:11]
	global_load_dwordx4 v[80:83], v1, s[10:11]
	s_waitcnt lgkmcnt(0)
	s_barrier
	s_waitcnt vmcnt(10)
	ds_write_b128 v2, v[84:87] offset:0
	ds_write_b128 v2, v[88:91] offset:10240
	s_add_u32 s10, s0, 0x740000
	s_addc_u32 s11, s1, 0
	global_load_dwordx4 v[84:87], v0, s[10:11]
	global_load_dwordx4 v[88:91], v1, s[10:11]
	s_waitcnt lgkmcnt(0)
	s_barrier
	s_waitcnt vmcnt(10)
	ds_write_b128 v2, v[92:95] offset:20480
	ds_write_b128 v2, v[96:99] offset:30720
	s_add_u32 s10, s0, 0x760000
	s_addc_u32 s11, s1, 0
	global_load_dwordx4 v[92:95], v0, s[10:11]
	global_load_dwordx4 v[96:99], v1, s[10:11]
	s_waitcnt lgkmcnt(0)
	s_barrier
	s_waitcnt vmcnt(10)
	ds_write_b128 v2, v[52:55] offset:0
	ds_write_b128 v2, v[56:59] offset:10240
	s_add_u32 s10, s0, 0x780000
	s_addc_u32 s11, s1, 0
	global_load_dwordx4 v[52:55], v0, s[10:11]
	global_load_dwordx4 v[56:59], v1, s[10:11]
	s_waitcnt lgkmcnt(0)
	s_barrier
	s_waitcnt vmcnt(10)
	ds_write_b128 v2, v[60:63] offset:20480
	ds_write_b128 v2, v[64:67] offset:30720
	s_add_u32 s10, s0, 0x7a0000
	s_addc_u32 s11, s1, 0
	global_load_dwordx4 v[60:63], v0, s[10:11]
	global_load_dwordx4 v[64:67], v1, s[10:11]
	s_waitcnt lgkmcnt(0)
	s_barrier
	s_waitcnt vmcnt(10)
	ds_write_b128 v2, v[68:71] offset:0
	ds_write_b128 v2, v[72:75] offset:10240
	s_add_u32 s10, s0, 0x7c0000
	s_addc_u32 s11, s1, 0
	global_load_dwordx4 v[68:71], v0, s[10:11]
	global_load_dwordx4 v[72:75], v1, s[10:11]
	s_waitcnt lgkmcnt(0)
	s_barrier
	s_waitcnt vmcnt(10)
	ds_write_b128 v2, v[76:79] offset:20480
	ds_write_b128 v2, v[80:83] offset:30720
	s_waitcnt lgkmcnt(0)
	s_barrier
	s_waitcnt vmcnt(8)
	ds_write_b128 v2, v[84:87] offset:0
	ds_write_b128 v2, v[88:91] offset:10240
	s_waitcnt lgkmcnt(0)
	s_barrier
	s_waitcnt vmcnt(6)
	ds_write_b128 v2, v[92:95] offset:20480
	ds_write_b128 v2, v[96:99] offset:30720
	s_waitcnt lgkmcnt(0)
	s_barrier
	s_waitcnt vmcnt(4)
	ds_write_b128 v2, v[52:55] offset:0
	ds_write_b128 v2, v[56:59] offset:10240
	s_waitcnt lgkmcnt(0)
	s_barrier
	s_waitcnt vmcnt(2)
	ds_write_b128 v2, v[60:63] offset:20480
	ds_write_b128 v2, v[64:67] offset:30720
	s_waitcnt lgkmcnt(0)
	s_barrier
	s_waitcnt vmcnt(0)
	ds_write_b128 v2, v[68:71] offset:0
	ds_write_b128 v2, v[72:75] offset:10240
	s_waitcnt lgkmcnt(0)
	s_barrier
.Lcmb_done:
.LBB0_1224:
	s_waitcnt vmcnt(0)
	s_cmpk_lt_i32 s60, 0x41
	s_cselect_b64 s[8:9], -1, 0
	s_xor_b64 s[22:23], s[66:67], -1
	s_cmp_gt_i32 s2, 63
	s_cselect_b64 s[0:1], -1, 0
	s_or_b64 s[0:1], s[0:1], s[8:9]
	s_and_b64 s[0:1], s[0:1], s[22:23]
	s_andn2_b64 vcc, exec, s[0:1]
	s_sub_i32 s0, s2, 64
	s_waitcnt lgkmcnt(0)
	s_barrier
	s_cbranch_vccnz .LBB0_1241
	s_and_b64 s[4:5], s[8:9], exec
	s_cselect_b32 s1, s2, s0
	s_cmpk_gt_i32 s1, 0x24f
	s_cbranch_scc1 .LBB0_1240
	s_load_dwordx2 s[6:7], s[20:21], 0xf8
	s_sub_i32 s3, s60, 64
	s_and_b64 s[4:5], s[8:9], exec
	s_cselect_b32 s3, s60, s3
	v_readlane_b32 s5, v250, 3
	s_waitcnt lgkmcnt(0)
	s_add_u32 s12, s6, 0x1b00000
	s_addc_u32 s13, s7, 0
	s_lshl_b32 s4, s79, 3
	s_and_b32 s5, s5, 0xc0
	v_or_b32_e32 v53, s5, v148
	s_or_b32 s5, s4, 24
	s_and_b32 s9, s4, 0x1fffffe0
	s_mul_i32 s11, s5, 0x410
	s_or_b32 s5, s4, 1
	s_add_u32 s16, s6, 0x2800000
	s_addc_u32 s17, s7, 0
	s_add_u32 s18, s6, 0x1d00000
	v_lshrrev_b32_e32 v2, 5, v148
	v_and_b32_e32 v0, 28, v165
	v_lshl_add_u32 v52, v165, 2, 0
	s_mul_i32 s8, s79, 0x2080
	v_lshl_add_u32 v1, v53, 2, 0
	s_mul_i32 s10, s9, 0x410
	s_addc_u32 s19, s7, 0
	v_mul_u32_u24_e32 v2, 0xb00, v2
	s_movk_i32 s6, 0x60
	s_lshl_b32 s14, s1, 4
	v_and_b32_e32 v51, 0xe0, v165
	s_mov_b32 s15, 0
	v_mov_b32_e32 v49, 0
	s_mulk_i32 s5, 0x410
	v_and_or_b32 v54, v165, s6, v2
	s_lshl_b32 s6, s1, 6
	s_lshl_b32 s7, s3, 6
	s_add_i32 s24, s14, 0x7fffdf00
	s_lshl_b32 s25, s3, 4
	v_add_u32_e32 v55, s8, v52
	v_add_u32_e32 v56, s10, v1
	s_movk_i32 s26, 0x7fff
	s_mov_b32 s27, 0xffff0000
	v_add_u32_e32 v57, s11, v1
	s_lshl_b32 s14, s9, 1
	v_lshlrev_b32_e32 v48, 2, v0
	v_mov_b32_e32 v58, 0x5800
	s_branch .LBB0_1230

; #define LAS __attribute__((address_space(3)))
; __device__ __forceinline__ void attn_sample_unit(LAS unsigned char* lds, CArgsP a, int b, int h) {
;     ...
;     for (int j = tid; j < SA_NK; j += 512) {
;         const float* kp = j < PAST ? ck + (((size_t)b * PAST + j) * 8 + h) * 64 : nk + (size_t)(16 * b + (j - PAST)) * 512 + h * 64;
;         float acc[16];
; #pragma unroll
;         for (int t = 0; t < 16; ++t) acc[t] = 0.f;
; #pragma unroll
;         for (int hb = 0; hb < 2; ++hb) {
;             f32x4 kr[8];
; #pragma unroll
;             for (int i = 0; i < 8; ++i) kr[i] = *(const f32x4*)(kp + 32 * hb + 4 * i);
; #pragma unroll
;             for (int i = 0; i < 8; ++i) {
;                 asm volatile("" ::: "memory");
;                 const f32x4 k4 = kr[i];
; #pragma unroll
;                 for (int t = 0; t < 16; ++t) { const f32x4 q4 = *(const LAS f32x4*)(Qs + t * 64 + 32 * hb + 4 * i); acc[t] += (q4[0] * k4[0] + q4[1] * k4[1]) + (q4[2] * k4[2] + q4[3] * k4[3]); }
;             }
;         }
;         const float cj = C[j];
; #pragma unroll
;         for (int t = 0; t < 16; ++t) SC[t * SA_NK + j] = acc[t] + (C[PAST + t] - cj) * LOG2E;
.LBB0_1348:
	s_or_b64 exec, exec, s[26:27]
	s_lshl_b32 s1, s10, 6
	s_lshl_b32 s3, s10, 8
	s_add_u32 s3, s12, s3
	s_addc_u32 s4, s13, 0
	s_mov_b32 s25, 0
	s_add_u32 s6, s3, 0x81a1c00
	s_addc_u32 s7, s4, 0
	s_lshl_b64 s[4:5], s[24:25], 13
	v_lshl_add_u64 v[0:1], v[0:1], 0, s[4:5]
	v_mov_b32_e32 v151, 0
	v_lshl_add_u64 v[0:1], v[0:1], 0, v[150:151]
	v_lshlrev_b64 v[0:1], 8, v[0:1]
	s_add_i32 s3, s0, 0xfffffc00
	v_lshl_add_u64 v[34:35], s[16:17], 0, v[0:1]
	s_mov_b64 s[8:9], 0
	s_movk_i32 s4, 0x3ff
	s_mov_b64 s[10:11], 0x100000
	s_movk_i32 s5, 0x20f
	v_mov_b32_e32 v38, v164
	s_waitcnt lgkmcnt(0)
	s_barrier
	v_readfirstlane_b32 s3, v50
	v_lshrrev_b32_e32 v140, 4, v148
	v_and_b32_e32 v141, 15, v148
	v_lshlrev_b32_e32 v246, 11, v141
	v_lshl_add_u32 v246, v140, 4, v246
	v_lshlrev_b32_e32 v247, 8, v141
	v_lshl_add_u32 v247, v140, 4, v247
	v_lshlrev_b32_e32 v142, 4, v140
	s_lshl_b32 s4, s24, 21
	s_lshl_b32 s5, s1, 2
	s_add_u32 s4, s4, s5
	s_add_u32 s16, s16, s4
	s_addc_u32 s17, s17, 0
	s_lshl_b32 s4, s24, 15
	s_add_u32 s6, s6, s4
	s_addc_u32 s7, s7, 0
	s_lshl_b32 s4, s3, 15
	s_add_u32 s16, s16, s4
	s_addc_u32 s17, s17, 0
	s_mov_b32 s29, 0x3fb8aa3b
	s_cmp_lg_u32 s3, 0
	s_cbranch_scc1 .Lqk_noext0
	global_load_dwordx4 v[202:205], v246, s[6:7] offset:0
	global_load_dwordx4 v[206:209], v246, s[6:7] offset:64
	global_load_dwordx4 v[210:213], v246, s[6:7] offset:128
	global_load_dwordx4 v[214:217], v246, s[6:7] offset:192
.Lqk_noext0:
	s_add_u32 s10, s16, 0x0
	s_addc_u32 s11, s17, 0
	global_load_dwordx4 v[0:3], v246, s[10:11] offset:0
	global_load_dwordx4 v[4:7], v246, s[10:11] offset:64
	global_load_dwordx4 v[8:11], v246, s[10:11] offset:128
	global_load_dwordx4 v[12:15], v246, s[10:11] offset:192
	s_add_u32 s10, s16, 0x40000
	s_addc_u32 s11, s17, 0
	global_load_dwordx4 v[16:19], v246, s[10:11] offset:0
	global_load_dwordx4 v[20:23], v246, s[10:11] offset:64
	global_load_dwordx4 v[24:27], v246, s[10:11] offset:128
	global_load_dwordx4 v[28:31], v246, s[10:11] offset:192
	s_add_u32 s10, s16, 0x80000
	s_addc_u32 s11, s17, 0
	global_load_dwordx4 v[32:35], v246, s[10:11] offset:0
	global_load_dwordx4 v[36:39], v246, s[10:11] offset:64
	global_load_dwordx4 v[40:43], v246, s[10:11] offset:128
	global_load_dwordx4 v[44:47], v246, s[10:11] offset:192
	s_add_u32 s10, s16, 0xc0000
	s_addc_u32 s11, s17, 0
	global_load_dwordx4 v[52:55], v246, s[10:11] offset:0
	global_load_dwordx4 v[56:59], v246, s[10:11] offset:64
	global_load_dwordx4 v[60:63], v246, s[10:11] offset:128
	global_load_dwordx4 v[64:67], v246, s[10:11] offset:192
	s_add_u32 s10, s16, 0x100000
	s_addc_u32 s11, s17, 0
	global_load_dwordx4 v[68:71], v246, s[10:11] offset:0
	global_load_dwordx4 v[72:75], v246, s[10:11] offset:64
	global_load_dwordx4 v[76:79], v246, s[10:11] offset:128
	global_load_dwordx4 v[80:83], v246, s[10:11] offset:192
	s_add_u32 s10, s16, 0x140000
	s_addc_u32 s11, s17, 0
	global_load_dwordx4 v[84:87], v246, s[10:11] offset:0
	global_load_dwordx4 v[88:91], v246, s[10:11] offset:64
	global_load_dwordx4 v[92:95], v246, s[10:11] offset:128
	global_load_dwordx4 v[96:99], v246, s[10:11] offset:192
	s_add_u32 s10, s16, 0x180000
	s_addc_u32 s11, s17, 0
	global_load_dwordx4 v[104:107], v246, s[10:11] offset:0
	global_load_dwordx4 v[108:111], v246, s[10:11] offset:64
	global_load_dwordx4 v[112:115], v246, s[10:11] offset:128
	global_load_dwordx4 v[116:119], v246, s[10:11] offset:192
	s_add_u32 s10, s16, 0x1c0000
	s_addc_u32 s11, s17, 0
	global_load_dwordx4 v[120:123], v246, s[10:11] offset:0
	global_load_dwordx4 v[124:127], v246, s[10:11] offset:64
	global_load_dwordx4 v[128:131], v246, s[10:11] offset:128
	global_load_dwordx4 v[132:135], v246, s[10:11] offset:192
	ds_read_b128 v[218:221], v247 offset:4352
	ds_read_b128 v[222:225], v247 offset:4416
	ds_read_b128 v[226:229], v247 offset:4480
	ds_read_b128 v[230:233], v247 offset:4544
	ds_read_b128 v[242:245], v142 offset:4096
	s_lshl_b32 s4, s3, 6
	v_lshl_add_u32 v248, v141, 2, s4
	v_mul_u32_u24_e32 v249, 0x4100, v140
	v_add_u32_e32 v249, v249, v248
	v_add_u32_e32 v249, 0x2100, v249
	ds_read_b32 v136, v248 offset:0
	ds_read_b32 v137, v248 offset:512
	s_waitcnt vmcnt(24)
	s_waitcnt lgkmcnt(2)
	v_mfma_f32_16x16x4_f32 v[234:237], v218, v0, 0
	v_mfma_f32_16x16x4_f32 v[238:241], v218, v16, 0
	v_mfma_f32_16x16x4_f32 v[234:237], v219, v1, v[234:237]
	v_mfma_f32_16x16x4_f32 v[238:241], v219, v17, v[238:241]
	v_mfma_f32_16x16x4_f32 v[234:237], v220, v2, v[234:237]
	v_mfma_f32_16x16x4_f32 v[238:241], v220, v18, v[238:241]
	v_mfma_f32_16x16x4_f32 v[234:237], v221, v3, v[234:237]
	v_mfma_f32_16x16x4_f32 v[238:241], v221, v19, v[238:241]
	v_mfma_f32_16x16x4_f32 v[234:237], v222, v4, v[234:237]
	v_mfma_f32_16x16x4_f32 v[238:241], v222, v20, v[238:241]
	v_mfma_f32_16x16x4_f32 v[234:237], v223, v5, v[234:237]
	v_mfma_f32_16x16x4_f32 v[238:241], v223, v21, v[238:241]
	v_mfma_f32_16x16x4_f32 v[234:237], v224, v6, v[234:237]
	v_mfma_f32_16x16x4_f32 v[238:241], v224, v22, v[238:241]
	v_mfma_f32_16x16x4_f32 v[234:237], v225, v7, v[234:237]
	v_mfma_f32_16x16x4_f32 v[238:241], v225, v23, v[238:241]
	v_mfma_f32_16x16x4_f32 v[234:237], v226, v8, v[234:237]
	v_mfma_f32_16x16x4_f32 v[238:241], v226, v24, v[238:241]
	v_mfma_f32_16x16x4_f32 v[234:237], v227, v9, v[234:237]
	v_mfma_f32_16x16x4_f32 v[238:241], v227, v25, v[238:241]
	v_mfma_f32_16x16x4_f32 v[234:237], v228, v10, v[234:237]
	v_mfma_f32_16x16x4_f32 v[238:241], v228, v26, v[238:241]
	v_mfma_f32_16x16x4_f32 v[234:237], v229, v11, v[234:237]
	v_mfma_f32_16x16x4_f32 v[238:241], v229, v27, v[238:241]
	v_mfma_f32_16x16x4_f32 v[234:237], v230, v12, v[234:237]
	v_mfma_f32_16x16x4_f32 v[238:241], v230, v28, v[238:241]
	v_mfma_f32_16x16x4_f32 v[234:237], v231, v13, v[234:237]
	v_mfma_f32_16x16x4_f32 v[238:241], v231, v29, v[238:241]
	v_mfma_f32_16x16x4_f32 v[234:237], v232, v14, v[234:237]
	v_mfma_f32_16x16x4_f32 v[238:241], v232, v30, v[238:241]
	v_mfma_f32_16x16x4_f32 v[234:237], v233, v15, v[234:237]
	v_mfma_f32_16x16x4_f32 v[238:241], v233, v31, v[238:241]
	s_waitcnt lgkmcnt(0)
; #define LAS __attribute__((address_space(3)))
; __device__ __forceinline__ void attn_sample_unit(LAS unsigned char* lds, CArgsP a, int b, int h) {
;     ...
;     for (int j = tid; j < SA_NK; j += 512) {
;         const float* kp = j < PAST ? ck + (((size_t)b * PAST + j) * 8 + h) * 64 : nk + (size_t)(16 * b + (j - PAST)) * 512 + h * 64;
;         float acc[16];
; #pragma unroll
;         for (int t = 0; t < 16; ++t) acc[t] = 0.f;
; #pragma unroll
;         for (int hb = 0; hb < 2; ++hb) {
;             f32x4 kr[8];
; #pragma unroll
;             for (int i = 0; i < 8; ++i) kr[i] = *(const f32x4*)(kp + 32 * hb + 4 * i);
; #pragma unroll
;             for (int i = 0; i < 8; ++i) {
;                 asm volatile("" ::: "memory");
;                 const f32x4 k4 = kr[i];
; #pragma unroll
;                 for (int t = 0; t < 16; ++t) { const f32x4 q4 = *(const LAS f32x4*)(Qs + t * 64 + 32 * hb + 4 * i); acc[t] += (q4[0] * k4[0] + q4[1] * k4[1]) + (q4[2] * k4[2] + q4[3] * k4[3]); }
;             }
;         }
;         const float cj = C[j];
; #pragma unroll
;         for (int t = 0; t < 16; ++t) SC[t * SA_NK + j] = acc[t] + (C[PAST + t] - cj) * LOG2E;
	s_nop 9
	v_sub_f32_e32 v140, v242, v136
	v_sub_f32_e32 v141, v243, v136
	v_sub_f32_e32 v142, v244, v136
	v_sub_f32_e32 v143, v245, v136
	v_fma_f32 v140, v140, s29, v234
	v_fma_f32 v141, v141, s29, v235
	v_fma_f32 v142, v142, s29, v236
	v_fma_f32 v143, v143, s29, v237
	ds_write_b32 v249, v140 offset:0
	ds_write_b32 v249, v141 offset:4160
	ds_write_b32 v249, v142 offset:8320
	ds_write_b32 v249, v143 offset:12480
	v_sub_f32_e32 v140, v242, v137
	v_sub_f32_e32 v141, v243, v137
	v_sub_f32_e32 v142, v244, v137
	v_sub_f32_e32 v143, v245, v137
	v_fma_f32 v140, v140, s29, v238
	v_fma_f32 v141, v141, s29, v239
	v_fma_f32 v142, v142, s29, v240
	v_fma_f32 v143, v143, s29, v241
	ds_write_b32 v249, v140 offset:512
	ds_write_b32 v249, v141 offset:4672
	ds_write_b32 v249, v142 offset:8832
	ds_write_b32 v249, v143 offset:12992
	ds_read_b32 v136, v248 offset:1024
	ds_read_b32 v137, v248 offset:1536
	s_waitcnt vmcnt(16)
	v_mfma_f32_16x16x4_f32 v[234:237], v218, v32, 0
	v_mfma_f32_16x16x4_f32 v[238:241], v218, v52, 0
	v_mfma_f32_16x16x4_f32 v[234:237], v219, v33, v[234:237]
	v_mfma_f32_16x16x4_f32 v[238:241], v219, v53, v[238:241]
	v_mfma_f32_16x16x4_f32 v[234:237], v220, v34, v[234:237]
	v_mfma_f32_16x16x4_f32 v[238:241], v220, v54, v[238:241]
	v_mfma_f32_16x16x4_f32 v[234:237], v221, v35, v[234:237]
	v_mfma_f32_16x16x4_f32 v[238:241], v221, v55, v[238:241]
	v_mfma_f32_16x16x4_f32 v[234:237], v222, v36, v[234:237]
	v_mfma_f32_16x16x4_f32 v[238:241], v222, v56, v[238:241]
	v_mfma_f32_16x16x4_f32 v[234:237], v223, v37, v[234:237]
	v_mfma_f32_16x16x4_f32 v[238:241], v223, v57, v[238:241]
	v_mfma_f32_16x16x4_f32 v[234:237], v224, v38, v[234:237]
	v_mfma_f32_16x16x4_f32 v[238:241], v224, v58, v[238:241]
	v_mfma_f32_16x16x4_f32 v[234:237], v225, v39, v[234:237]
	v_mfma_f32_16x16x4_f32 v[238:241], v225, v59, v[238:241]
	v_mfma_f32_16x16x4_f32 v[234:237], v226, v40, v[234:237]
	v_mfma_f32_16x16x4_f32 v[238:241], v226, v60, v[238:241]
	v_mfma_f32_16x16x4_f32 v[234:237], v227, v41, v[234:237]
	v_mfma_f32_16x16x4_f32 v[238:241], v227, v61, v[238:241]
	v_mfma_f32_16x16x4_f32 v[234:237], v228, v42, v[234:237]
	v_mfma_f32_16x16x4_f32 v[238:241], v228, v62, v[238:241]
	v_mfma_f32_16x16x4_f32 v[234:237], v229, v43, v[234:237]
	v_mfma_f32_16x16x4_f32 v[238:241], v229, v63, v[238:241]
	v_mfma_f32_16x16x4_f32 v[234:237], v230, v44, v[234:237]
	v_mfma_f32_16x16x4_f32 v[238:241], v230, v64, v[238:241]
	v_mfma_f32_16x16x4_f32 v[234:237], v231, v45, v[234:237]
	v_mfma_f32_16x16x4_f32 v[238:241], v231, v65, v[238:241]
	v_mfma_f32_16x16x4_f32 v[234:237], v232, v46, v[234:237]
	v_mfma_f32_16x16x4_f32 v[238:241], v232, v66, v[238:241]
	v_mfma_f32_16x16x4_f32 v[234:237], v233, v47, v[234:237]
	v_mfma_f32_16x16x4_f32 v[238:241], v233, v67, v[238:241]
	s_waitcnt lgkmcnt(0)
	s_nop 9
	v_sub_f32_e32 v140, v242, v136
	v_sub_f32_e32 v141, v243, v136
	v_sub_f32_e32 v142, v244, v136
	v_sub_f32_e32 v143, v245, v136
	v_fma_f32 v140, v140, s29, v234
	v_fma_f32 v141, v141, s29, v235
	v_fma_f32 v142, v142, s29, v236
	v_fma_f32 v143, v143, s29, v237
	ds_write_b32 v249, v140 offset:1024
	ds_write_b32 v249, v141 offset:5184
	ds_write_b32 v249, v142 offset:9344
	ds_write_b32 v249, v143 offset:13504
	v_sub_f32_e32 v140, v242, v137
	v_sub_f32_e32 v141, v243, v137
	v_sub_f32_e32 v142, v244, v137
	v_sub_f32_e32 v143, v245, v137
	v_fma_f32 v140, v140, s29, v238
	v_fma_f32 v141, v141, s29, v239
	v_fma_f32 v142, v142, s29, v240
	v_fma_f32 v143, v143, s29, v241
	ds_write_b32 v249, v140 offset:1536
	ds_write_b32 v249, v141 offset:5696
	ds_write_b32 v249, v142 offset:9856
	ds_write_b32 v249, v143 offset:14016
	ds_read_b32 v136, v248 offset:2048
	ds_read_b32 v137, v248 offset:2560
	s_waitcnt vmcnt(8)
	v_mfma_f32_16x16x4_f32 v[234:237], v218, v68, 0
	v_mfma_f32_16x16x4_f32 v[238:241], v218, v84, 0
	v_mfma_f32_16x16x4_f32 v[234:237], v219, v69, v[234:237]
	v_mfma_f32_16x16x4_f32 v[238:241], v219, v85, v[238:241]
	v_mfma_f32_16x16x4_f32 v[234:237], v220, v70, v[234:237]
	v_mfma_f32_16x16x4_f32 v[238:241], v220, v86, v[238:241]
	v_mfma_f32_16x16x4_f32 v[234:237], v221, v71, v[234:237]
	v_mfma_f32_16x16x4_f32 v[238:241], v221, v87, v[238:241]
	v_mfma_f32_16x16x4_f32 v[234:237], v222, v72, v[234:237]
	v_mfma_f32_16x16x4_f32 v[238:241], v222, v88, v[238:241]
	v_mfma_f32_16x16x4_f32 v[234:237], v223, v73, v[234:237]
	v_mfma_f32_16x16x4_f32 v[238:241], v223, v89, v[238:241]
	v_mfma_f32_16x16x4_f32 v[234:237], v224, v74, v[234:237]
	v_mfma_f32_16x16x4_f32 v[238:241], v224, v90, v[238:241]
	v_mfma_f32_16x16x4_f32 v[234:237], v225, v75, v[234:237]
	v_mfma_f32_16x16x4_f32 v[238:241], v225, v91, v[238:241]
	v_mfma_f32_16x16x4_f32 v[234:237], v226, v76, v[234:237]
	v_mfma_f32_16x16x4_f32 v[238:241], v226, v92, v[238:241]
	v_mfma_f32_16x16x4_f32 v[234:237], v227, v77, v[234:237]
	v_mfma_f32_16x16x4_f32 v[238:241], v227, v93, v[238:241]
	v_mfma_f32_16x16x4_f32 v[234:237], v228, v78, v[234:237]
	v_mfma_f32_16x16x4_f32 v[238:241], v228, v94, v[238:241]
	v_mfma_f32_16x16x4_f32 v[234:237], v229, v79, v[234:237]
	v_mfma_f32_16x16x4_f32 v[238:241], v229, v95, v[238:241]
	v_mfma_f32_16x16x4_f32 v[234:237], v230, v80, v[234:237]
	v_mfma_f32_16x16x4_f32 v[238:241], v230, v96, v[238:241]
	v_mfma_f32_16x16x4_f32 v[234:237], v231, v81, v[234:237]
	v_mfma_f32_16x16x4_f32 v[238:241], v231, v97, v[238:241]
	v_mfma_f32_16x16x4_f32 v[234:237], v232, v82, v[234:237]
	v_mfma_f32_16x16x4_f32 v[238:241], v232, v98, v[238:241]
	v_mfma_f32_16x16x4_f32 v[234:237], v233, v83, v[234:237]
	v_mfma_f32_16x16x4_f32 v[238:241], v233, v99, v[238:241]
	s_waitcnt lgkmcnt(0)
; #define LAS __attribute__((address_space(3)))
; __device__ __forceinline__ void attn_sample_unit(LAS unsigned char* lds, CArgsP a, int b, int h) {
;     ...
;     for (int j = tid; j < SA_NK; j += 512) {
;         const float* kp = j < PAST ? ck + (((size_t)b * PAST + j) * 8 + h) * 64 : nk + (size_t)(16 * b + (j - PAST)) * 512 + h * 64;
;         float acc[16];
; #pragma unroll
;         for (int t = 0; t < 16; ++t) acc[t] = 0.f;
; #pragma unroll
;         for (int hb = 0; hb < 2; ++hb) {
;             f32x4 kr[8];
; #pragma unroll
;             for (int i = 0; i < 8; ++i) kr[i] = *(const f32x4*)(kp + 32 * hb + 4 * i);
; #pragma unroll
;             for (int i = 0; i < 8; ++i) {
;                 asm volatile("" ::: "memory");
;                 const f32x4 k4 = kr[i];
; #pragma unroll
;                 for (int t = 0; t < 16; ++t) { const f32x4 q4 = *(const LAS f32x4*)(Qs + t * 64 + 32 * hb + 4 * i); acc[t] += (q4[0] * k4[0] + q4[1] * k4[1]) + (q4[2] * k4[2] + q4[3] * k4[3]); }
;             }
;         }
;         const float cj = C[j];
; #pragma unroll
;         for (int t = 0; t < 16; ++t) SC[t * SA_NK + j] = acc[t] + (C[PAST + t] - cj) * LOG2E;
	s_nop 9
	v_sub_f32_e32 v140, v242, v136
	v_sub_f32_e32 v141, v243, v136
	v_sub_f32_e32 v142, v244, v136
	v_sub_f32_e32 v143, v245, v136
	v_fma_f32 v140, v140, s29, v234
	v_fma_f32 v141, v141, s29, v235
	v_fma_f32 v142, v142, s29, v236
	v_fma_f32 v143, v143, s29, v237
	ds_write_b32 v249, v140 offset:2048
	ds_write_b32 v249, v141 offset:6208
	ds_write_b32 v249, v142 offset:10368
	ds_write_b32 v249, v143 offset:14528
	v_sub_f32_e32 v140, v242, v137
	v_sub_f32_e32 v141, v243, v137
	v_sub_f32_e32 v142, v244, v137
	v_sub_f32_e32 v143, v245, v137
	v_fma_f32 v140, v140, s29, v238
	v_fma_f32 v141, v141, s29, v239
	v_fma_f32 v142, v142, s29, v240
	v_fma_f32 v143, v143, s29, v241
	ds_write_b32 v249, v140 offset:2560
	ds_write_b32 v249, v141 offset:6720
	ds_write_b32 v249, v142 offset:10880
	ds_write_b32 v249, v143 offset:15040
	ds_read_b32 v136, v248 offset:3072
	ds_read_b32 v137, v248 offset:3584
	s_waitcnt vmcnt(0)
	v_mfma_f32_16x16x4_f32 v[234:237], v218, v104, 0
	v_mfma_f32_16x16x4_f32 v[238:241], v218, v120, 0
	v_mfma_f32_16x16x4_f32 v[234:237], v219, v105, v[234:237]
	v_mfma_f32_16x16x4_f32 v[238:241], v219, v121, v[238:241]
	v_mfma_f32_16x16x4_f32 v[234:237], v220, v106, v[234:237]
	v_mfma_f32_16x16x4_f32 v[238:241], v220, v122, v[238:241]
	v_mfma_f32_16x16x4_f32 v[234:237], v221, v107, v[234:237]
	v_mfma_f32_16x16x4_f32 v[238:241], v221, v123, v[238:241]
	v_mfma_f32_16x16x4_f32 v[234:237], v222, v108, v[234:237]
	v_mfma_f32_16x16x4_f32 v[238:241], v222, v124, v[238:241]
	v_mfma_f32_16x16x4_f32 v[234:237], v223, v109, v[234:237]
	v_mfma_f32_16x16x4_f32 v[238:241], v223, v125, v[238:241]
	v_mfma_f32_16x16x4_f32 v[234:237], v224, v110, v[234:237]
	v_mfma_f32_16x16x4_f32 v[238:241], v224, v126, v[238:241]
	v_mfma_f32_16x16x4_f32 v[234:237], v225, v111, v[234:237]
	v_mfma_f32_16x16x4_f32 v[238:241], v225, v127, v[238:241]
	v_mfma_f32_16x16x4_f32 v[234:237], v226, v112, v[234:237]
	v_mfma_f32_16x16x4_f32 v[238:241], v226, v128, v[238:241]
	v_mfma_f32_16x16x4_f32 v[234:237], v227, v113, v[234:237]
	v_mfma_f32_16x16x4_f32 v[238:241], v227, v129, v[238:241]
	v_mfma_f32_16x16x4_f32 v[234:237], v228, v114, v[234:237]
	v_mfma_f32_16x16x4_f32 v[238:241], v228, v130, v[238:241]
	v_mfma_f32_16x16x4_f32 v[234:237], v229, v115, v[234:237]
	v_mfma_f32_16x16x4_f32 v[238:241], v229, v131, v[238:241]
	v_mfma_f32_16x16x4_f32 v[234:237], v230, v116, v[234:237]
	v_mfma_f32_16x16x4_f32 v[238:241], v230, v132, v[238:241]
	v_mfma_f32_16x16x4_f32 v[234:237], v231, v117, v[234:237]
	v_mfma_f32_16x16x4_f32 v[238:241], v231, v133, v[238:241]
	v_mfma_f32_16x16x4_f32 v[234:237], v232, v118, v[234:237]
	v_mfma_f32_16x16x4_f32 v[238:241], v232, v134, v[238:241]
	v_mfma_f32_16x16x4_f32 v[234:237], v233, v119, v[234:237]
	v_mfma_f32_16x16x4_f32 v[238:241], v233, v135, v[238:241]
	s_waitcnt lgkmcnt(0)
	s_nop 9
	v_sub_f32_e32 v140, v242, v136
	v_sub_f32_e32 v141, v243, v136
	v_sub_f32_e32 v142, v244, v136
	v_sub_f32_e32 v143, v245, v136
	v_fma_f32 v140, v140, s29, v234
	v_fma_f32 v141, v141, s29, v235
	v_fma_f32 v142, v142, s29, v236
	v_fma_f32 v143, v143, s29, v237
	ds_write_b32 v249, v140 offset:3072
	ds_write_b32 v249, v141 offset:7232
	ds_write_b32 v249, v142 offset:11392
	ds_write_b32 v249, v143 offset:15552
	v_sub_f32_e32 v140, v242, v137
	v_sub_f32_e32 v141, v243, v137
	v_sub_f32_e32 v142, v244, v137
	v_sub_f32_e32 v143, v245, v137
	v_fma_f32 v140, v140, s29, v238
	v_fma_f32 v141, v141, s29, v239
	v_fma_f32 v142, v142, s29, v240
	v_fma_f32 v143, v143, s29, v241
	ds_write_b32 v249, v140 offset:3584
	ds_write_b32 v249, v141 offset:7744
	ds_write_b32 v249, v142 offset:11904
	ds_write_b32 v249, v143 offset:16064
	s_cmp_lg_u32 s3, 0
	s_cbranch_scc1 .Lqk_noext1
	ds_read_b32 v138, v248 offset:4096
	s_waitcnt vmcnt(0)
	v_mfma_f32_16x16x4_f32 v[234:237], v218, v202, 0
	v_mfma_f32_16x16x4_f32 v[234:237], v219, v203, v[234:237]
	v_mfma_f32_16x16x4_f32 v[234:237], v220, v204, v[234:237]
	v_mfma_f32_16x16x4_f32 v[234:237], v221, v205, v[234:237]
	v_mfma_f32_16x16x4_f32 v[234:237], v222, v206, v[234:237]
	v_mfma_f32_16x16x4_f32 v[234:237], v223, v207, v[234:237]
	v_mfma_f32_16x16x4_f32 v[234:237], v224, v208, v[234:237]
	v_mfma_f32_16x16x4_f32 v[234:237], v225, v209, v[234:237]
	v_mfma_f32_16x16x4_f32 v[234:237], v226, v210, v[234:237]
	v_mfma_f32_16x16x4_f32 v[234:237], v227, v211, v[234:237]
	v_mfma_f32_16x16x4_f32 v[234:237], v228, v212, v[234:237]
	v_mfma_f32_16x16x4_f32 v[234:237], v229, v213, v[234:237]
	v_mfma_f32_16x16x4_f32 v[234:237], v230, v214, v[234:237]
	v_mfma_f32_16x16x4_f32 v[234:237], v231, v215, v[234:237]
	v_mfma_f32_16x16x4_f32 v[234:237], v232, v216, v[234:237]
	v_mfma_f32_16x16x4_f32 v[234:237], v233, v217, v[234:237]
	s_waitcnt lgkmcnt(0)
	s_nop 9
	v_sub_f32_e32 v140, v242, v138
	v_sub_f32_e32 v141, v243, v138
	v_sub_f32_e32 v142, v244, v138
	v_sub_f32_e32 v143, v245, v138
	v_fma_f32 v140, v140, s29, v234
	v_fma_f32 v141, v141, s29, v235
	v_fma_f32 v142, v142, s29, v236
	v_fma_f32 v143, v143, s29, v237
	ds_write_b32 v249, v140 offset:4096
	ds_write_b32 v249, v141 offset:8256
	ds_write_b32 v249, v142 offset:12416
	ds_write_b32 v249, v143 offset:16576
.Lqk_noext1:
	s_movk_i32 s3, 0x2080
	v_mad_u32_u24 v6, v50, s3, v165
	v_add_u32_e32 v7, 0, v6
	v_lshlrev_b32_e32 v8, 1, v50
	v_add_u32_e32 v0, 0x2100, v7
	v_mul_u32_u24_e32 v4, 0x2080, v50
	v_or_b32_e32 v1, 0x400, v8
	v_mov_b32_e32 v2, 0xff800000
	s_mov_b64 s[6:7], 0
	s_movk_i32 s3, 0x3cf
	v_mov_b32_e32 v5, v0
	v_mov_b32_e32 v9, v148
	v_mov_b32_e32 v3, 0xff800000
	s_waitcnt lgkmcnt(0)
	s_barrier
	s_branch .LBB0_1354
